# K-loop MMA heads: duplicate lgkmcnt(0) after s_setprio removed (one issue slot fewer per MFMA segment), plus 64B-aligned loop heads and earlier epilogue de-serialisations
# speedup vs baseline: 1.0070x; 1.0019x over previous
; #define PG8_STAGE(bufoff, gbase, voff) do { _Pragma("unroll") for (int _i = 0; _i < 2; ++_i) \
;         __builtin_amdgcn_global_load_lds((const unsigned*)((const char*)(gbase) + (voff)[_i]), (LAS unsigned*)(lds + (bufoff) + ldsw + _i * 8192), 16, 0, 0); } while (0)
; #define PG8_LDA(dst, b, h) do { _Pragma("unroll") for (int m = 0; m < 4; ++m) _Pragma("unroll") for (int k = 0; k < 2; ++k) dst[m][k] = *(const LAS bf16x8*)(lds + PG8_SA(b, h) + aoff + m * 2048 + k * 1024); } while (0)
; #define PG8_LDB(dst, b, h) do { _Pragma("unroll") for (int n = 0; n < 2; ++n) _Pragma("unroll") for (int k = 0; k < 2; ++k) dst[n][k] = *(const LAS bf16x8*)(lds + PG8_SB(b, h) + boff + n * 2048 + k * 1024); } while (0)
; #define PG8_MMA(ai, bj, At, Bt) do { __builtin_amdgcn_s_setprio(1); _Pragma("unroll") for (int m = 0; m < 4; ++m) _Pragma("unroll") for (int n = 0; n < 2; ++n) _Pragma("unroll") for (int k = 0; k < 2; ++k) \
;         acc[ai][bj][m][n] = __builtin_amdgcn_mfma_f32_16x16x32_bf16(Bt[n][k], At[m][k], acc[ai][bj][m][n], 0, 0, 0); __builtin_amdgcn_s_setprio(0); } while (0)
; #define PG8_WAIT_L(n) asm volatile("s_waitcnt lgkmcnt(" #n ")" ::: "memory")
; #define PG8_BAR __builtin_amdgcn_s_barrier()
; #define PG8_SCHED __builtin_amdgcn_sched_barrier(0)
; template <class Epi>
; __device__ __forceinline__ void gemm_phase(LAS unsigned char* lds, const Gemm g, const StaticOrder& S, const Epi& E) {
;     ...
;         for (int t = 0; t < nt; t += 2) {
;             const bool last = (t == nt - 2);
;             const char* a1 = cA + (size_t)(t + 1) * kstep;
;             const char* a2 = last ? nA : cA + (size_t)(t + 2) * kstep; const char* b2 = last ? nB : cB + (size_t)(t + 2) * kstep;
;             const char* a3 = a2 + kstep; const char* b3 = b2 + kstep;
;             PG8_LDB(B0, 0, 0); PG8_SCHED; PG8_LDA(At, 0, 0); PG8_STAGE(PG8_SA(1, 1), a1 + hstep, voffA);
;             PG8_WAIT_L(8); PG8_BAR; PG8_WAIT_L(0); PG8_MMA(0, 0, At, B0); PG8_BAR; PG8_SCHED;
.LBB0_259:
	ds_read_b128 v[160:163], v148
	ds_read_b128 v[166:169], v148 offset:1024
	ds_read_b128 v[170:173], v148 offset:2048
	ds_read_b128 v[174:177], v148 offset:3072
	s_add_u32 s18, s16, 0xfff80080
	s_addc_u32 s19, s17, -1
	s_cmp_eq_u32 s67, 28
	s_cselect_b32 s21, s9, s19
	s_cselect_b32 s20, s63, s18
	s_cselect_b32 s19, s7, s66
	s_cselect_b32 s18, s64, s65
	v_lshl_add_u64 v[212:213], s[16:17], 0, v[136:137]
	s_add_i32 m0, s35, 0xc000
	ds_read_b128 v[180:183], v149
	ds_read_b128 v[184:187], v149 offset:1024
	ds_read_b128 v[188:191], v149 offset:2048
	ds_read_b128 v[192:195], v149 offset:3072
	ds_read_b128 v[196:199], v149 offset:4096
	ds_read_b128 v[200:203], v149 offset:5120
	ds_read_b128 v[204:207], v149 offset:6144
	ds_read_b128 v[208:211], v149 offset:7168
	global_load_lds_dwordx4 v[212:213], off
	v_lshl_add_u64 v[212:213], s[16:17], 0, v[138:139]
	s_add_i32 m0, s35, 0xe000
	s_nop 0
	global_load_lds_dwordx4 v[212:213], off
	s_waitcnt lgkmcnt(8)
	s_barrier
	s_waitcnt lgkmcnt(0)
	s_setprio 1

; #define PG8_STAGE(bufoff, gbase, voff) do { _Pragma("unroll") for (int _i = 0; _i < 2; ++_i) \
;         __builtin_amdgcn_global_load_lds((const unsigned*)((const char*)(gbase) + (voff)[_i]), (LAS unsigned*)(lds + (bufoff) + ldsw + _i * 8192), 16, 0, 0); } while (0)
; #define PG8_LDB(dst, b, h) do { _Pragma("unroll") for (int n = 0; n < 2; ++n) _Pragma("unroll") for (int k = 0; k < 2; ++k) dst[n][k] = *(const LAS bf16x8*)(lds + PG8_SB(b, h) + boff + n * 2048 + k * 1024); } while (0)
; #define PG8_MMA(ai, bj, At, Bt) do { __builtin_amdgcn_s_setprio(1); _Pragma("unroll") for (int m = 0; m < 4; ++m) _Pragma("unroll") for (int n = 0; n < 2; ++n) _Pragma("unroll") for (int k = 0; k < 2; ++k) \
;         acc[ai][bj][m][n] = __builtin_amdgcn_mfma_f32_16x16x32_bf16(Bt[n][k], At[m][k], acc[ai][bj][m][n], 0, 0, 0); __builtin_amdgcn_s_setprio(0); } while (0)
; #define PG8_WAIT_L(n) asm volatile("s_waitcnt lgkmcnt(" #n ")" ::: "memory")
; #define PG8_BAR __builtin_amdgcn_s_barrier()
; #define PG8_SCHED __builtin_amdgcn_sched_barrier(0)
; template <class Epi>
; __device__ __forceinline__ void gemm_phase(LAS unsigned char* lds, const Gemm g, const StaticOrder& S, const Epi& E) {
;     ...
;             PG8_WAIT_L(8); PG8_BAR; PG8_WAIT_L(0); PG8_MMA(0, 0, At, B0); PG8_BAR; PG8_SCHED;
;             PG8_LDB(B1, 0, 1); PG8_STAGE(PG8_SB(0, 0), b2, voffB);
;             PG8_BAR; PG8_WAIT_L(0); PG8_MMA(0, 1, At, B1); PG8_BAR;
	v_mfma_f32_16x16x32_bf16 v[124:127], v[160:163], v[180:183], v[124:127]
	v_mfma_f32_16x16x32_bf16 v[116:119], v[170:173], v[180:183], v[116:119]
	v_mfma_f32_16x16x32_bf16 v[108:111], v[160:163], v[188:191], v[108:111]
	v_mfma_f32_16x16x32_bf16 v[100:103], v[170:173], v[188:191], v[100:103]
	v_mfma_f32_16x16x32_bf16 v[92:95], v[160:163], v[196:199], v[92:95]
	v_mfma_f32_16x16x32_bf16 v[84:87], v[170:173], v[196:199], v[84:87]
	v_mfma_f32_16x16x32_bf16 v[76:79], v[160:163], v[204:207], v[76:79]
	v_mfma_f32_16x16x32_bf16 v[68:71], v[170:173], v[204:207], v[68:71]
	v_mfma_f32_16x16x32_bf16 v[124:127], v[166:169], v[184:187], v[124:127]
	v_mfma_f32_16x16x32_bf16 v[116:119], v[174:177], v[184:187], v[116:119]
	v_mfma_f32_16x16x32_bf16 v[108:111], v[166:169], v[192:195], v[108:111]
	v_mfma_f32_16x16x32_bf16 v[100:103], v[174:177], v[192:195], v[100:103]
	v_mfma_f32_16x16x32_bf16 v[92:95], v[166:169], v[200:203], v[92:95]
	v_mfma_f32_16x16x32_bf16 v[84:87], v[174:177], v[200:203], v[84:87]
	v_mfma_f32_16x16x32_bf16 v[76:79], v[166:169], v[208:211], v[76:79]
	v_mfma_f32_16x16x32_bf16 v[68:71], v[174:177], v[208:211], v[68:71]
	s_setprio 0
	s_barrier
	s_add_i32 s68, s60, s31
	v_lshl_add_u64 v[228:229], s[18:19], 0, v[132:133]
	s_mov_b32 m0, s68
	ds_read_b128 v[212:215], v150
	ds_read_b128 v[216:219], v150 offset:1024
	ds_read_b128 v[220:223], v150 offset:2048
	ds_read_b128 v[224:227], v150 offset:3072
	global_load_lds_dwordx4 v[228:229], off
	v_lshl_add_u64 v[230:231], s[18:19], 0, v[128:129]
	s_add_i32 m0, s68, 0x2000
	s_nop 0
	global_load_lds_dwordx4 v[230:231], off
	s_barrier
	s_waitcnt lgkmcnt(0)
	s_setprio 1

; #define PG8_STAGE(bufoff, gbase, voff) do { _Pragma("unroll") for (int _i = 0; _i < 2; ++_i) \
;         __builtin_amdgcn_global_load_lds((const unsigned*)((const char*)(gbase) + (voff)[_i]), (LAS unsigned*)(lds + (bufoff) + ldsw + _i * 8192), 16, 0, 0); } while (0)
; #define PG8_LDA(dst, b, h) do { _Pragma("unroll") for (int m = 0; m < 4; ++m) _Pragma("unroll") for (int k = 0; k < 2; ++k) dst[m][k] = *(const LAS bf16x8*)(lds + PG8_SA(b, h) + aoff + m * 2048 + k * 1024); } while (0)
; #define PG8_MMA(ai, bj, At, Bt) do { __builtin_amdgcn_s_setprio(1); _Pragma("unroll") for (int m = 0; m < 4; ++m) _Pragma("unroll") for (int n = 0; n < 2; ++n) _Pragma("unroll") for (int k = 0; k < 2; ++k) \
;         acc[ai][bj][m][n] = __builtin_amdgcn_mfma_f32_16x16x32_bf16(Bt[n][k], At[m][k], acc[ai][bj][m][n], 0, 0, 0); __builtin_amdgcn_s_setprio(0); } while (0)
; #define PG8_WAIT_L(n) asm volatile("s_waitcnt lgkmcnt(" #n ")" ::: "memory")
; #define PG8_BAR __builtin_amdgcn_s_barrier()
; #define PG8_SCHED __builtin_amdgcn_sched_barrier(0)
; template <class Epi>
; __device__ __forceinline__ void gemm_phase(LAS unsigned char* lds, const Gemm g, const StaticOrder& S, const Epi& E) {
;     ...
;             PG8_BAR; PG8_WAIT_L(0); PG8_MMA(0, 1, At, B1); PG8_BAR;
;             PG8_LDA(At, 0, 1); PG8_STAGE(PG8_SA(0, 0), a2, voffA);
;             PG8_BAR; PG8_WAIT_L(0); PG8_MMA(1, 0, At, B0); PG8_BAR; PG8_SCHED;
	v_mfma_f32_16x16x32_bf16 v[120:123], v[212:215], v[180:183], v[120:123]
	v_mfma_f32_16x16x32_bf16 v[112:115], v[220:223], v[180:183], v[112:115]
	v_mfma_f32_16x16x32_bf16 v[104:107], v[212:215], v[188:191], v[104:107]
	v_mfma_f32_16x16x32_bf16 v[96:99], v[220:223], v[188:191], v[96:99]
	v_mfma_f32_16x16x32_bf16 v[88:91], v[212:215], v[196:199], v[88:91]
	v_mfma_f32_16x16x32_bf16 v[80:83], v[220:223], v[196:199], v[80:83]
	v_mfma_f32_16x16x32_bf16 v[72:75], v[212:215], v[204:207], v[72:75]
	v_mfma_f32_16x16x32_bf16 v[64:67], v[220:223], v[204:207], v[64:67]
	v_mfma_f32_16x16x32_bf16 v[120:123], v[216:219], v[184:187], v[120:123]
	v_mfma_f32_16x16x32_bf16 v[112:115], v[224:227], v[184:187], v[112:115]
	v_mfma_f32_16x16x32_bf16 v[104:107], v[216:219], v[192:195], v[104:107]
	v_mfma_f32_16x16x32_bf16 v[96:99], v[224:227], v[192:195], v[96:99]
	v_mfma_f32_16x16x32_bf16 v[88:91], v[216:219], v[200:203], v[88:91]
	v_mfma_f32_16x16x32_bf16 v[80:83], v[224:227], v[200:203], v[80:83]
	v_mfma_f32_16x16x32_bf16 v[72:75], v[216:219], v[208:211], v[72:75]
	v_mfma_f32_16x16x32_bf16 v[64:67], v[224:227], v[208:211], v[64:67]
	s_setprio 0
	s_mov_b32 m0, s35
	v_lshl_add_u64 v[232:233], s[20:21], 0, v[134:135]
	s_barrier
	ds_read_b128 v[180:183], v149 offset:16384
	ds_read_b128 v[184:187], v149 offset:17408
	ds_read_b128 v[188:191], v149 offset:18432
	ds_read_b128 v[192:195], v149 offset:19456
	ds_read_b128 v[196:199], v149 offset:20480
	ds_read_b128 v[200:203], v149 offset:21504
	ds_read_b128 v[204:207], v149 offset:22528
	ds_read_b128 v[208:211], v149 offset:23552
	global_load_lds_dwordx4 v[232:233], off
	v_lshl_add_u64 v[234:235], s[20:21], 0, v[130:131]
	s_mov_b32 m0, s38
	s_nop 0
	global_load_lds_dwordx4 v[234:235], off
	s_barrier
	s_waitcnt lgkmcnt(0)
	s_setprio 1

; #define PG8_STAGE(bufoff, gbase, voff) do { _Pragma("unroll") for (int _i = 0; _i < 2; ++_i) \
;         __builtin_amdgcn_global_load_lds((const unsigned*)((const char*)(gbase) + (voff)[_i]), (LAS unsigned*)(lds + (bufoff) + ldsw + _i * 8192), 16, 0, 0); } while (0)
; #define PG8_LDA(dst, b, h) do { _Pragma("unroll") for (int m = 0; m < 4; ++m) _Pragma("unroll") for (int k = 0; k < 2; ++k) dst[m][k] = *(const LAS bf16x8*)(lds + PG8_SA(b, h) + aoff + m * 2048 + k * 1024); } while (0)
; #define PG8_LDB(dst, b, h) do { _Pragma("unroll") for (int n = 0; n < 2; ++n) _Pragma("unroll") for (int k = 0; k < 2; ++k) dst[n][k] = *(const LAS bf16x8*)(lds + PG8_SB(b, h) + boff + n * 2048 + k * 1024); } while (0)
; #define PG8_MMA(ai, bj, At, Bt) do { __builtin_amdgcn_s_setprio(1); _Pragma("unroll") for (int m = 0; m < 4; ++m) _Pragma("unroll") for (int n = 0; n < 2; ++n) _Pragma("unroll") for (int k = 0; k < 2; ++k) \
;         acc[ai][bj][m][n] = __builtin_amdgcn_mfma_f32_16x16x32_bf16(Bt[n][k], At[m][k], acc[ai][bj][m][n], 0, 0, 0); __builtin_amdgcn_s_setprio(0); } while (0)
; #define PG8_WAIT_V(n) asm volatile("s_waitcnt vmcnt(" #n ")" ::: "memory")
; #define PG8_WAIT_L(n) asm volatile("s_waitcnt lgkmcnt(" #n ")" ::: "memory")
; #define PG8_BAR __builtin_amdgcn_s_barrier()
; #define PG8_SCHED __builtin_amdgcn_sched_barrier(0)
; template <class Epi>
; __device__ __forceinline__ void gemm_phase(LAS unsigned char* lds, const Gemm g, const StaticOrder& S, const Epi& E) {
;     ...
;             PG8_BAR; PG8_WAIT_L(0); PG8_MMA(1, 0, At, B0); PG8_BAR; PG8_SCHED;
;             PG8_STAGE(PG8_SB(0, 1), b2 + hstep, voffB);
;             PG8_WAIT_V(6); PG8_BAR; PG8_MMA(1, 1, At, B1); PG8_BAR;
;             PG8_LDB(B0, 1, 0); PG8_SCHED; PG8_LDA(At, 1, 0); PG8_STAGE(PG8_SA(0, 1), a2 + hstep, voffA);
;             PG8_WAIT_L(8); PG8_BAR; PG8_WAIT_L(0); PG8_MMA(0, 0, At, B0); PG8_BAR; PG8_SCHED;
	v_mfma_f32_16x16x32_bf16 v[60:63], v[160:163], v[180:183], v[60:63]
	v_mfma_f32_16x16x32_bf16 v[52:55], v[170:173], v[180:183], v[52:55]
	v_mfma_f32_16x16x32_bf16 v[44:47], v[160:163], v[188:191], v[44:47]
	v_mfma_f32_16x16x32_bf16 v[36:39], v[170:173], v[188:191], v[36:39]
	v_mfma_f32_16x16x32_bf16 v[28:31], v[160:163], v[196:199], v[28:31]
	v_mfma_f32_16x16x32_bf16 v[20:23], v[170:173], v[196:199], v[20:23]
	v_mfma_f32_16x16x32_bf16 v[12:15], v[160:163], v[204:207], v[12:15]
	v_mfma_f32_16x16x32_bf16 v[4:7], v[170:173], v[204:207], v[4:7]
	v_mfma_f32_16x16x32_bf16 v[60:63], v[166:169], v[184:187], v[60:63]
	v_mfma_f32_16x16x32_bf16 v[52:55], v[174:177], v[184:187], v[52:55]
	v_mfma_f32_16x16x32_bf16 v[44:47], v[166:169], v[192:195], v[44:47]
	v_mfma_f32_16x16x32_bf16 v[36:39], v[174:177], v[192:195], v[36:39]
	v_mfma_f32_16x16x32_bf16 v[28:31], v[166:169], v[200:203], v[28:31]
	v_mfma_f32_16x16x32_bf16 v[20:23], v[174:177], v[200:203], v[20:23]
	v_mfma_f32_16x16x32_bf16 v[12:15], v[166:169], v[208:211], v[12:15]
	v_mfma_f32_16x16x32_bf16 v[4:7], v[174:177], v[208:211], v[4:7]
	s_setprio 0
	s_barrier
	s_add_u32 s68, s18, 0x80000
	s_addc_u32 s69, s19, 0
	s_add_i32 s70, s61, s31
	v_lshl_add_u64 v[160:161], s[68:69], 0, v[132:133]
	s_mov_b32 m0, s70
	s_nop 0
	global_load_lds_dwordx4 v[160:161], off
	v_lshl_add_u64 v[160:161], s[68:69], 0, v[128:129]
	s_add_i32 m0, s70, 0x2000
	s_nop 0
	global_load_lds_dwordx4 v[160:161], off
	s_waitcnt vmcnt(6)
	s_barrier
	s_setprio 1
	v_mfma_f32_16x16x32_bf16 v[56:59], v[212:215], v[180:183], v[56:59]
	v_mfma_f32_16x16x32_bf16 v[48:51], v[220:223], v[180:183], v[48:51]
	v_mfma_f32_16x16x32_bf16 v[40:43], v[212:215], v[188:191], v[40:43]
	v_mfma_f32_16x16x32_bf16 v[32:35], v[220:223], v[188:191], v[32:35]
	v_mfma_f32_16x16x32_bf16 v[24:27], v[212:215], v[196:199], v[24:27]
	v_mfma_f32_16x16x32_bf16 v[16:19], v[220:223], v[196:199], v[16:19]
	v_mfma_f32_16x16x32_bf16 v[8:11], v[212:215], v[204:207], v[8:11]
	v_mfma_f32_16x16x32_bf16 v[0:3], v[220:223], v[204:207], v[0:3]
	v_mfma_f32_16x16x32_bf16 v[56:59], v[216:219], v[184:187], v[56:59]
	v_mfma_f32_16x16x32_bf16 v[48:51], v[224:227], v[184:187], v[48:51]
	v_mfma_f32_16x16x32_bf16 v[40:43], v[216:219], v[192:195], v[40:43]
	v_mfma_f32_16x16x32_bf16 v[32:35], v[224:227], v[192:195], v[32:35]
	v_mfma_f32_16x16x32_bf16 v[24:27], v[216:219], v[200:203], v[24:27]
	v_mfma_f32_16x16x32_bf16 v[16:19], v[224:227], v[200:203], v[16:19]
	v_mfma_f32_16x16x32_bf16 v[8:11], v[216:219], v[208:211], v[8:11]
	v_mfma_f32_16x16x32_bf16 v[0:3], v[224:227], v[208:211], v[0:3]
	s_setprio 0
	s_add_i32 s68, 0, 0x18000
	v_add_u32_e32 v165, s68, v146
	s_barrier
	ds_read_b128 v[160:163], v165
	ds_read_b128 v[166:169], v165 offset:1024
	ds_read_b128 v[170:173], v165 offset:2048
	ds_read_b128 v[174:177], v165 offset:3072
	s_add_u32 s20, s20, 0x80000
	s_addc_u32 s21, s21, 0
	s_mov_b32 m0, s39
	v_lshl_add_u64 v[212:213], s[20:21], 0, v[134:135]
	ds_read_b128 v[180:183], v149 offset:32768
	ds_read_b128 v[184:187], v149 offset:33792
	ds_read_b128 v[188:191], v149 offset:34816
	ds_read_b128 v[192:195], v149 offset:35840
	ds_read_b128 v[196:199], v149 offset:36864
	ds_read_b128 v[200:203], v149 offset:37888
	ds_read_b128 v[204:207], v149 offset:38912
	ds_read_b128 v[208:211], v149 offset:39936
	global_load_lds_dwordx4 v[212:213], off
	v_lshl_add_u64 v[212:213], s[20:21], 0, v[130:131]
	s_mov_b32 m0, s42
	s_nop 0
	global_load_lds_dwordx4 v[212:213], off
	s_waitcnt lgkmcnt(8)
	s_barrier
	s_waitcnt lgkmcnt(0)
	s_setprio 1

; #define PG8_STAGE(bufoff, gbase, voff) do { _Pragma("unroll") for (int _i = 0; _i < 2; ++_i) \
;         __builtin_amdgcn_global_load_lds((const unsigned*)((const char*)(gbase) + (voff)[_i]), (LAS unsigned*)(lds + (bufoff) + ldsw + _i * 8192), 16, 0, 0); } while (0)
; #define PG8_LDB(dst, b, h) do { _Pragma("unroll") for (int n = 0; n < 2; ++n) _Pragma("unroll") for (int k = 0; k < 2; ++k) dst[n][k] = *(const LAS bf16x8*)(lds + PG8_SB(b, h) + boff + n * 2048 + k * 1024); } while (0)
; #define PG8_MMA(ai, bj, At, Bt) do { __builtin_amdgcn_s_setprio(1); _Pragma("unroll") for (int m = 0; m < 4; ++m) _Pragma("unroll") for (int n = 0; n < 2; ++n) _Pragma("unroll") for (int k = 0; k < 2; ++k) \
;         acc[ai][bj][m][n] = __builtin_amdgcn_mfma_f32_16x16x32_bf16(Bt[n][k], At[m][k], acc[ai][bj][m][n], 0, 0, 0); __builtin_amdgcn_s_setprio(0); } while (0)
; #define PG8_WAIT_L(n) asm volatile("s_waitcnt lgkmcnt(" #n ")" ::: "memory")
; #define PG8_BAR __builtin_amdgcn_s_barrier()
; #define PG8_SCHED __builtin_amdgcn_sched_barrier(0)
; template <class Epi>
; __device__ __forceinline__ void gemm_phase(LAS unsigned char* lds, const Gemm g, const StaticOrder& S, const Epi& E) {
;     ...
;             PG8_WAIT_L(8); PG8_BAR; PG8_WAIT_L(0); PG8_MMA(0, 0, At, B0); PG8_BAR; PG8_SCHED;
;             PG8_LDB(B1, 1, 1); PG8_STAGE(PG8_SB(1, 0), b3, voffB);
;             PG8_BAR; PG8_WAIT_L(0); PG8_MMA(0, 1, At, B1); PG8_BAR;
	v_mfma_f32_16x16x32_bf16 v[124:127], v[160:163], v[180:183], v[124:127]
	v_mfma_f32_16x16x32_bf16 v[116:119], v[170:173], v[180:183], v[116:119]
	v_mfma_f32_16x16x32_bf16 v[108:111], v[160:163], v[188:191], v[108:111]
	v_mfma_f32_16x16x32_bf16 v[100:103], v[170:173], v[188:191], v[100:103]
	v_mfma_f32_16x16x32_bf16 v[92:95], v[160:163], v[196:199], v[92:95]
	v_mfma_f32_16x16x32_bf16 v[84:87], v[170:173], v[196:199], v[84:87]
	v_mfma_f32_16x16x32_bf16 v[76:79], v[160:163], v[204:207], v[76:79]
	v_mfma_f32_16x16x32_bf16 v[68:71], v[170:173], v[204:207], v[68:71]
	v_mfma_f32_16x16x32_bf16 v[124:127], v[166:169], v[184:187], v[124:127]
	v_mfma_f32_16x16x32_bf16 v[116:119], v[174:177], v[184:187], v[116:119]
	v_mfma_f32_16x16x32_bf16 v[108:111], v[166:169], v[192:195], v[108:111]
	v_mfma_f32_16x16x32_bf16 v[100:103], v[174:177], v[192:195], v[100:103]
	v_mfma_f32_16x16x32_bf16 v[92:95], v[166:169], v[200:203], v[92:95]
	v_mfma_f32_16x16x32_bf16 v[84:87], v[174:177], v[200:203], v[84:87]
	v_mfma_f32_16x16x32_bf16 v[76:79], v[166:169], v[208:211], v[76:79]
	v_mfma_f32_16x16x32_bf16 v[68:71], v[174:177], v[208:211], v[68:71]
	s_setprio 0
	s_barrier
	s_add_i32 s20, 0, 0x1c000
	s_add_i32 s21, s68, s31
	v_add_u32_e32 v165, s20, v146
	v_lshl_add_u64 v[228:229], v[228:229], 0, s[4:5]
	s_mov_b32 m0, s21
	ds_read_b128 v[212:215], v165
	ds_read_b128 v[216:219], v165 offset:1024
	ds_read_b128 v[220:223], v165 offset:2048
	ds_read_b128 v[224:227], v165 offset:3072
	global_load_lds_dwordx4 v[228:229], off
	v_lshl_add_u64 v[228:229], v[230:231], 0, s[4:5]
	s_add_i32 m0, s21, 0x2000
	s_nop 0
	global_load_lds_dwordx4 v[228:229], off
	s_barrier
	s_waitcnt lgkmcnt(0)
	s_setprio 1

; #define PG8_STAGE(bufoff, gbase, voff) do { _Pragma("unroll") for (int _i = 0; _i < 2; ++_i) \
;         __builtin_amdgcn_global_load_lds((const unsigned*)((const char*)(gbase) + (voff)[_i]), (LAS unsigned*)(lds + (bufoff) + ldsw + _i * 8192), 16, 0, 0); } while (0)
; #define PG8_LDA(dst, b, h) do { _Pragma("unroll") for (int m = 0; m < 4; ++m) _Pragma("unroll") for (int k = 0; k < 2; ++k) dst[m][k] = *(const LAS bf16x8*)(lds + PG8_SA(b, h) + aoff + m * 2048 + k * 1024); } while (0)
; #define PG8_MMA(ai, bj, At, Bt) do { __builtin_amdgcn_s_setprio(1); _Pragma("unroll") for (int m = 0; m < 4; ++m) _Pragma("unroll") for (int n = 0; n < 2; ++n) _Pragma("unroll") for (int k = 0; k < 2; ++k) \
;         acc[ai][bj][m][n] = __builtin_amdgcn_mfma_f32_16x16x32_bf16(Bt[n][k], At[m][k], acc[ai][bj][m][n], 0, 0, 0); __builtin_amdgcn_s_setprio(0); } while (0)
; #define PG8_WAIT_L(n) asm volatile("s_waitcnt lgkmcnt(" #n ")" ::: "memory")
; #define PG8_BAR __builtin_amdgcn_s_barrier()
; #define PG8_SCHED __builtin_amdgcn_sched_barrier(0)
; template <class Epi>
; __device__ __forceinline__ void gemm_phase(LAS unsigned char* lds, const Gemm g, const StaticOrder& S, const Epi& E) {
;     ...
;             PG8_BAR; PG8_WAIT_L(0); PG8_MMA(0, 1, At, B1); PG8_BAR;
;             PG8_LDA(At, 1, 1); PG8_STAGE(PG8_SA(1, 0), a3, voffA);
;             PG8_BAR; PG8_WAIT_L(0); PG8_MMA(1, 0, At, B0); PG8_BAR; PG8_SCHED;
	v_mfma_f32_16x16x32_bf16 v[120:123], v[212:215], v[180:183], v[120:123]
	v_mfma_f32_16x16x32_bf16 v[112:115], v[220:223], v[180:183], v[112:115]
	v_mfma_f32_16x16x32_bf16 v[104:107], v[212:215], v[188:191], v[104:107]
	v_mfma_f32_16x16x32_bf16 v[96:99], v[220:223], v[188:191], v[96:99]
	v_mfma_f32_16x16x32_bf16 v[88:91], v[212:215], v[196:199], v[88:91]
	v_mfma_f32_16x16x32_bf16 v[80:83], v[220:223], v[196:199], v[80:83]
	v_mfma_f32_16x16x32_bf16 v[72:75], v[212:215], v[204:207], v[72:75]
	v_mfma_f32_16x16x32_bf16 v[64:67], v[220:223], v[204:207], v[64:67]
	v_mfma_f32_16x16x32_bf16 v[120:123], v[216:219], v[184:187], v[120:123]
	v_mfma_f32_16x16x32_bf16 v[112:115], v[224:227], v[184:187], v[112:115]
	v_mfma_f32_16x16x32_bf16 v[104:107], v[216:219], v[192:195], v[104:107]
	v_mfma_f32_16x16x32_bf16 v[96:99], v[224:227], v[192:195], v[96:99]
	v_mfma_f32_16x16x32_bf16 v[88:91], v[216:219], v[200:203], v[88:91]
	v_mfma_f32_16x16x32_bf16 v[80:83], v[224:227], v[200:203], v[80:83]
	v_mfma_f32_16x16x32_bf16 v[72:75], v[216:219], v[208:211], v[72:75]
	v_mfma_f32_16x16x32_bf16 v[64:67], v[224:227], v[208:211], v[64:67]
	s_setprio 0
	s_mov_b32 m0, s56
	v_lshl_add_u64 v[228:229], v[232:233], 0, s[4:5]
	s_barrier
	ds_read_b128 v[180:183], v149 offset:49152
	ds_read_b128 v[184:187], v149 offset:50176
	ds_read_b128 v[188:191], v149 offset:51200
	ds_read_b128 v[192:195], v149 offset:52224
	ds_read_b128 v[196:199], v149 offset:53248
	ds_read_b128 v[200:203], v149 offset:54272
	ds_read_b128 v[204:207], v149 offset:55296
	ds_read_b128 v[208:211], v149 offset:56320
	global_load_lds_dwordx4 v[228:229], off
	v_lshl_add_u64 v[228:229], v[234:235], 0, s[4:5]
	s_mov_b32 m0, s57
	s_nop 0
	global_load_lds_dwordx4 v[228:229], off
	s_barrier
	s_waitcnt lgkmcnt(0)
	s_setprio 1

; __device__ __forceinline__ float sigmoidf_(float x) { return __builtin_amdgcn_rcpf(1.0f + fexp(-x)); }
; #define PG8_STAGE(bufoff, gbase, voff) do { _Pragma("unroll") for (int _i = 0; _i < 2; ++_i) \
;         __builtin_amdgcn_global_load_lds((const unsigned*)((const char*)(gbase) + (voff)[_i]), (LAS unsigned*)(lds + (bufoff) + ldsw + _i * 8192), 16, 0, 0); } while (0)
; #define PG8_MMA(ai, bj, At, Bt) do { __builtin_amdgcn_s_setprio(1); _Pragma("unroll") for (int m = 0; m < 4; ++m) _Pragma("unroll") for (int n = 0; n < 2; ++n) _Pragma("unroll") for (int k = 0; k < 2; ++k) \
;         acc[ai][bj][m][n] = __builtin_amdgcn_mfma_f32_16x16x32_bf16(Bt[n][k], At[m][k], acc[ai][bj][m][n], 0, 0, 0); __builtin_amdgcn_s_setprio(0); } while (0)
; #define PG8_WAIT_V(n) asm volatile("s_waitcnt vmcnt(" #n ")" ::: "memory")
; #define PG8_WAIT_L(n) asm volatile("s_waitcnt lgkmcnt(" #n ")" ::: "memory")
; #define PG8_BAR __builtin_amdgcn_s_barrier()
; #define PG8_SCHED __builtin_amdgcn_sched_barrier(0)
; template <class Epi>
; __device__ __forceinline__ void gemm_phase(LAS unsigned char* lds, const Gemm g, const StaticOrder& S, const Epi& E) {
;     ...
;             PG8_BAR; PG8_WAIT_L(0); PG8_MMA(1, 0, At, B0); PG8_BAR; PG8_SCHED;
;             PG8_STAGE(PG8_SB(1, 1), b3 + hstep, voffB);
;             PG8_WAIT_V(6); PG8_BAR; PG8_MMA(1, 1, At, B1); PG8_BAR;
;     __device__ __forceinline__ void operator()(const f32x4 (&acc)[2][2][4][2], const Unit& u, int wr, int wc, int fr, int fq, const Pre& P) const {
;         const int row0 = ROW_X + u.pm * BM + wr * 64 + fr, col0 = u.pn * HALF + wc * 32 + 8 * fq;
; #pragma unroll
;         for (int ai = 0; ai < 2; ++ai)
; #pragma unroll
;             for (int m = 0; m < 4; ++m) { const int r = row0 + ai * HALF + m * 16; const float rs = __builtin_amdgcn_rsqf(P.rs[ai * 4 + m] * (1.0f / DM) + RMS_EPS);
;                 float y[8];
; #pragma unroll
;                 for (int n = 0; n < 2; ++n)
; #pragma unroll
;                     for (int j = 0; j < 4; ++j) { const float a = acc[ai][0][m][n][j] * rs, b = acc[ai][1][m][n][j] * rs; y[n * 4 + j] = a * b * sigmoidf_(a); }
;                 u32x4 w; w.x = cvtpk(y[0], y[1]); w.y = cvtpk(y[2], y[3]); w.z = cvtpk(y[4], y[5]); w.w = cvtpk(y[6], y[7]);
;                 *(u32x4*)(O + (size_t)r * FF + col0) = w; }
	v_mfma_f32_16x16x32_bf16 v[60:63], v[160:163], v[180:183], v[60:63]
	v_mfma_f32_16x16x32_bf16 v[52:55], v[170:173], v[180:183], v[52:55]
	v_mfma_f32_16x16x32_bf16 v[44:47], v[160:163], v[188:191], v[44:47]
	v_mfma_f32_16x16x32_bf16 v[36:39], v[170:173], v[188:191], v[36:39]
	v_mfma_f32_16x16x32_bf16 v[28:31], v[160:163], v[196:199], v[28:31]
	v_mfma_f32_16x16x32_bf16 v[20:23], v[170:173], v[196:199], v[20:23]
	v_mfma_f32_16x16x32_bf16 v[12:15], v[160:163], v[204:207], v[12:15]
	v_mfma_f32_16x16x32_bf16 v[4:7], v[170:173], v[204:207], v[4:7]
	v_mfma_f32_16x16x32_bf16 v[60:63], v[166:169], v[184:187], v[60:63]
	v_mfma_f32_16x16x32_bf16 v[52:55], v[174:177], v[184:187], v[52:55]
	v_mfma_f32_16x16x32_bf16 v[44:47], v[166:169], v[192:195], v[44:47]
	v_mfma_f32_16x16x32_bf16 v[36:39], v[174:177], v[192:195], v[36:39]
	v_mfma_f32_16x16x32_bf16 v[28:31], v[166:169], v[200:203], v[28:31]
	v_mfma_f32_16x16x32_bf16 v[20:23], v[174:177], v[200:203], v[20:23]
	v_mfma_f32_16x16x32_bf16 v[12:15], v[166:169], v[208:211], v[12:15]
	v_mfma_f32_16x16x32_bf16 v[4:7], v[174:177], v[208:211], v[4:7]
	s_setprio 0
	s_barrier
	s_add_u32 s18, s18, 0x80080
	s_addc_u32 s19, s19, 0
	s_add_i32 s20, s20, s31
	v_lshl_add_u64 v[160:161], s[18:19], 0, v[132:133]
	s_mov_b32 m0, s20
	s_nop 0
	global_load_lds_dwordx4 v[160:161], off
	v_lshl_add_u64 v[160:161], s[18:19], 0, v[128:129]
	s_add_i32 m0, s20, 0x2000
	s_nop 0
	global_load_lds_dwordx4 v[160:161], off
	s_waitcnt vmcnt(6)
	s_barrier
	s_setprio 1
	v_mfma_f32_16x16x32_bf16 v[56:59], v[212:215], v[180:183], v[56:59]
	v_mfma_f32_16x16x32_bf16 v[48:51], v[220:223], v[180:183], v[48:51]
	v_mfma_f32_16x16x32_bf16 v[40:43], v[212:215], v[188:191], v[40:43]
	v_mfma_f32_16x16x32_bf16 v[32:35], v[220:223], v[188:191], v[32:35]
	v_mfma_f32_16x16x32_bf16 v[24:27], v[212:215], v[196:199], v[24:27]
	v_mfma_f32_16x16x32_bf16 v[16:19], v[220:223], v[196:199], v[16:19]
	v_mfma_f32_16x16x32_bf16 v[8:11], v[212:215], v[204:207], v[8:11]
	v_mfma_f32_16x16x32_bf16 v[0:3], v[220:223], v[204:207], v[0:3]
	v_mfma_f32_16x16x32_bf16 v[56:59], v[216:219], v[184:187], v[56:59]
	v_mfma_f32_16x16x32_bf16 v[48:51], v[224:227], v[184:187], v[48:51]
	v_mfma_f32_16x16x32_bf16 v[40:43], v[216:219], v[192:195], v[40:43]
	v_mfma_f32_16x16x32_bf16 v[32:35], v[224:227], v[192:195], v[32:35]
	v_mfma_f32_16x16x32_bf16 v[24:27], v[216:219], v[200:203], v[24:27]
	v_mfma_f32_16x16x32_bf16 v[16:19], v[224:227], v[200:203], v[16:19]
	v_mfma_f32_16x16x32_bf16 v[8:11], v[216:219], v[208:211], v[8:11]
	v_mfma_f32_16x16x32_bf16 v[0:3], v[224:227], v[208:211], v[0:3]
	s_setprio 0
	s_add_i32 s67, s67, 2
	s_add_u32 s16, s16, 0x100
	s_addc_u32 s17, s17, 0
	s_add_u32 s65, s65, 0x100
	s_addc_u32 s66, s66, 0
	s_cmp_gt_u32 s67, 29
	s_barrier
	s_cbranch_scc0 .LBB0_259
	s_waitcnt vmcnt(0)
	v_fmamk_f32 v159, v159, 0x3a000000, v151
	v_rsq_f32_e32 v166, v159
	v_lshl_or_b32 v162, s15, 7, v147
	v_lshl_add_u32 v160, s14, 8, v145
	v_ashrrev_i32_e32 v163, 31, v162
	v_pk_mul_f32 v[124:125], v[166:167], v[124:125] op_sel_hi:[0,1]
	v_pk_mul_f32 v[120:121], v[166:167], v[120:121] op_sel_hi:[0,1]
	v_mul_f32_e32 v159, 0xbfb8aa3b, v124
	v_pk_mul_f32 v[120:121], v[124:125], v[120:121]
	v_mul_f32_e32 v124, 0xbfb8aa3b, v125
	v_exp_f32_e32 v159, v159
	v_exp_f32_e32 v124, v124
	v_pk_mul_f32 v[122:123], v[166:167], v[122:123] op_sel_hi:[0,1]
	v_pk_mul_f32 v[116:117], v[166:167], v[116:117] op_sel_hi:[0,1]
	v_add_f32_e32 v159, 1.0, v159
	v_add_f32_e32 v124, 1.0, v124
	v_rcp_f32_e32 v168, v159
	v_rcp_f32_e32 v169, v124
	v_pk_mul_f32 v[124:125], v[166:167], v[126:127] op_sel_hi:[0,1]
	v_pk_mul_f32 v[122:123], v[124:125], v[122:123]
	v_pk_mul_f32 v[112:113], v[166:167], v[112:113] op_sel_hi:[0,1]
	v_pk_mul_f32 v[120:121], v[168:169], v[120:121]
	v_pk_mul_f32 v[112:113], v[116:117], v[112:113]
	v_cvt_pk_bf16_f32 v120, v120, v121
	v_mul_f32_e32 v121, 0xbfb8aa3b, v124
	v_exp_f32_e32 v121, v121
	v_pk_mul_f32 v[114:115], v[166:167], v[114:115] op_sel_hi:[0,1]
	s_and_b64 vcc, vcc, exec
	v_add_f32_e32 v121, 1.0, v121
	v_rcp_f32_e32 v126, v121
	v_mul_f32_e32 v121, 0xbfb8aa3b, v125
	v_exp_f32_e32 v121, v121
	s_nop 0
	v_add_f32_e32 v121, 1.0, v121
	v_rcp_f32_e32 v127, v121
	s_nop 0
	v_pk_mul_f32 v[122:123], v[126:127], v[122:123]
	s_nop 0
	v_cvt_pk_bf16_f32 v121, v122, v123
	v_mul_f32_e32 v122, 0xbfb8aa3b, v116
	v_mul_f32_e32 v116, 0xbfb8aa3b, v117
	v_exp_f32_e32 v122, v122
	v_exp_f32_e32 v116, v116
	v_add_f32_e32 v122, 1.0, v122
	v_add_f32_e32 v116, 1.0, v116
	v_rcp_f32_e32 v122, v122
	v_rcp_f32_e32 v123, v116
	s_nop 0
	v_pk_mul_f32 v[112:113], v[122:123], v[112:113]
	s_nop 0
	v_cvt_pk_bf16_f32 v122, v112, v113
	v_pk_mul_f32 v[112:113], v[166:167], v[118:119] op_sel_hi:[0,1]
	v_mul_f32_e32 v116, 0xbfb8aa3b, v112
	v_pk_mul_f32 v[114:115], v[112:113], v[114:115]
	v_mul_f32_e32 v112, 0xbfb8aa3b, v113
	v_exp_f32_e32 v116, v116
	v_exp_f32_e32 v112, v112
	v_add_f32_e32 v116, 1.0, v116
	v_add_f32_e32 v112, 1.0, v112
	v_rcp_f32_e32 v116, v116
	v_rcp_f32_e32 v117, v112
	s_nop 0
	v_pk_mul_f32 v[112:113], v[116:117], v[114:115]
	s_nop 0
	v_cvt_pk_bf16_f32 v123, v112, v113
	v_mov_b64_e32 v[112:113], s[0:1]
	v_mad_i64_i32 v[116:117], s[14:15], v160, s62, v[112:113]
	v_lshlrev_b64 v[114:115], 1, v[162:163]
	v_lshl_add_u64 v[116:117], v[116:117], 0, v[114:115]
	global_store_dwordx4 v[116:117], v[120:123], off
	v_fmamk_f32 v116, v158, 0x3a000000, v151
	v_rsq_f32_e32 v116, v116
	v_or_b32_e32 v117, 16, v160
	v_pk_mul_f32 v[108:109], v[116:117], v[108:109] op_sel_hi:[0,1]
	v_pk_mul_f32 v[104:105], v[116:117], v[104:105] op_sel_hi:[0,1]
	v_mul_f32_e32 v118, 0xbfb8aa3b, v108
	v_pk_mul_f32 v[104:105], v[108:109], v[104:105]
; __device__ __forceinline__ float sigmoidf_(float x) { return __builtin_amdgcn_rcpf(1.0f + fexp(-x)); }
;     __device__ __forceinline__ void operator()(const f32x4 (&acc)[2][2][4][2], const Unit& u, int wr, int wc, int fr, int fq, const Pre& P) const {
;         const int row0 = ROW_X + u.pm * BM + wr * 64 + fr, col0 = u.pn * HALF + wc * 32 + 8 * fq;
; #pragma unroll
;         for (int ai = 0; ai < 2; ++ai)
; #pragma unroll
;             for (int m = 0; m < 4; ++m) { const int r = row0 + ai * HALF + m * 16; const float rs = __builtin_amdgcn_rsqf(P.rs[ai * 4 + m] * (1.0f / DM) + RMS_EPS);
;                 float y[8];
; #pragma unroll
;                 for (int n = 0; n < 2; ++n)
; #pragma unroll
;                     for (int j = 0; j < 4; ++j) { const float a = acc[ai][0][m][n][j] * rs, b = acc[ai][1][m][n][j] * rs; y[n * 4 + j] = a * b * sigmoidf_(a); }
;                 u32x4 w; w.x = cvtpk(y[0], y[1]); w.y = cvtpk(y[2], y[3]); w.z = cvtpk(y[4], y[5]); w.w = cvtpk(y[6], y[7]);
;                 *(u32x4*)(O + (size_t)r * FF + col0) = w; }
	v_mul_f32_e32 v108, 0xbfb8aa3b, v109
	v_exp_f32_e32 v118, v118
	v_exp_f32_e32 v108, v108
	v_pk_mul_f32 v[106:107], v[116:117], v[106:107] op_sel_hi:[0,1]
	v_pk_mul_f32 v[100:101], v[116:117], v[100:101] op_sel_hi:[0,1]
	v_add_f32_e32 v118, 1.0, v118
	v_add_f32_e32 v108, 1.0, v108
	v_rcp_f32_e32 v118, v118
	v_rcp_f32_e32 v119, v108
	v_pk_mul_f32 v[108:109], v[116:117], v[110:111] op_sel_hi:[0,1]
	v_pk_mul_f32 v[106:107], v[108:109], v[106:107]
	v_pk_mul_f32 v[96:97], v[116:117], v[96:97] op_sel_hi:[0,1]
	v_pk_mul_f32 v[104:105], v[118:119], v[104:105]
	v_pk_mul_f32 v[96:97], v[100:101], v[96:97]
	v_cvt_pk_bf16_f32 v104, v104, v105
	v_mul_f32_e32 v105, 0xbfb8aa3b, v108
	v_exp_f32_e32 v105, v105
	v_pk_mul_f32 v[98:99], v[116:117], v[98:99] op_sel_hi:[0,1]
	v_add_f32_e32 v105, 1.0, v105
	v_rcp_f32_e32 v110, v105
	v_mul_f32_e32 v105, 0xbfb8aa3b, v109
	v_exp_f32_e32 v105, v105
	s_nop 0
	v_add_f32_e32 v105, 1.0, v105
	v_rcp_f32_e32 v111, v105
	s_nop 0
	v_pk_mul_f32 v[106:107], v[110:111], v[106:107]
	s_nop 0
	v_cvt_pk_bf16_f32 v105, v106, v107
	v_mul_f32_e32 v106, 0xbfb8aa3b, v100
	v_mul_f32_e32 v100, 0xbfb8aa3b, v101
	v_exp_f32_e32 v106, v106
	v_exp_f32_e32 v100, v100
	v_add_f32_e32 v106, 1.0, v106
	v_add_f32_e32 v100, 1.0, v100
	v_rcp_f32_e32 v106, v106
	v_rcp_f32_e32 v107, v100
	s_nop 0
	v_pk_mul_f32 v[96:97], v[106:107], v[96:97]
	s_nop 0
	v_cvt_pk_bf16_f32 v106, v96, v97
	v_pk_mul_f32 v[96:97], v[116:117], v[102:103] op_sel_hi:[0,1]
	v_mul_f32_e32 v100, 0xbfb8aa3b, v96
	v_pk_mul_f32 v[98:99], v[96:97], v[98:99]
	v_mul_f32_e32 v96, 0xbfb8aa3b, v97
	v_exp_f32_e32 v100, v100
	v_exp_f32_e32 v96, v96
	v_add_f32_e32 v100, 1.0, v100
	v_add_f32_e32 v96, 1.0, v96
	v_rcp_f32_e32 v100, v100
	v_rcp_f32_e32 v101, v96
	s_nop 0
	v_pk_mul_f32 v[96:97], v[100:101], v[98:99]
	s_nop 0
	v_cvt_pk_bf16_f32 v107, v96, v97
	v_mad_i64_i32 v[96:97], s[14:15], v117, s62, v[112:113]
	v_lshl_add_u64 v[96:97], v[96:97], 0, v[114:115]
	global_store_dwordx4 v[96:97], v[104:107], off
	v_fmamk_f32 v96, v157, 0x3a000000, v151
	v_rsq_f32_e32 v96, v96
	v_or_b32_e32 v97, 32, v160
	v_pk_mul_f32 v[92:93], v[96:97], v[92:93] op_sel_hi:[0,1]
	v_pk_mul_f32 v[88:89], v[96:97], v[88:89] op_sel_hi:[0,1]
	v_mul_f32_e32 v98, 0xbfb8aa3b, v92
	v_pk_mul_f32 v[88:89], v[92:93], v[88:89]
	v_mul_f32_e32 v92, 0xbfb8aa3b, v93
	v_exp_f32_e32 v98, v98
	v_exp_f32_e32 v92, v92
	v_pk_mul_f32 v[90:91], v[96:97], v[90:91] op_sel_hi:[0,1]
	v_pk_mul_f32 v[84:85], v[96:97], v[84:85] op_sel_hi:[0,1]
	v_add_f32_e32 v98, 1.0, v98
	v_add_f32_e32 v92, 1.0, v92
	v_rcp_f32_e32 v98, v98
	v_rcp_f32_e32 v99, v92
	v_pk_mul_f32 v[92:93], v[96:97], v[94:95] op_sel_hi:[0,1]
	v_pk_mul_f32 v[90:91], v[92:93], v[90:91]
	v_pk_mul_f32 v[80:81], v[96:97], v[80:81] op_sel_hi:[0,1]
	v_pk_mul_f32 v[88:89], v[98:99], v[88:89]
	v_pk_mul_f32 v[80:81], v[84:85], v[80:81]
	v_cvt_pk_bf16_f32 v88, v88, v89
	v_mul_f32_e32 v89, 0xbfb8aa3b, v92
	v_exp_f32_e32 v89, v89
	v_pk_mul_f32 v[82:83], v[96:97], v[82:83] op_sel_hi:[0,1]
	v_add_f32_e32 v89, 1.0, v89
	v_rcp_f32_e32 v94, v89
	v_mul_f32_e32 v89, 0xbfb8aa3b, v93
	v_exp_f32_e32 v89, v89
	s_nop 0
	v_add_f32_e32 v89, 1.0, v89
	v_rcp_f32_e32 v95, v89
	s_nop 0
	v_pk_mul_f32 v[90:91], v[94:95], v[90:91]
	s_nop 0
	v_cvt_pk_bf16_f32 v89, v90, v91
	v_mul_f32_e32 v90, 0xbfb8aa3b, v84
	v_mul_f32_e32 v84, 0xbfb8aa3b, v85
	v_exp_f32_e32 v90, v90
	v_exp_f32_e32 v84, v84
	v_add_f32_e32 v90, 1.0, v90
	v_add_f32_e32 v84, 1.0, v84
	v_rcp_f32_e32 v90, v90
	v_rcp_f32_e32 v91, v84
	s_nop 0
	v_pk_mul_f32 v[80:81], v[90:91], v[80:81]
	s_nop 0
	v_cvt_pk_bf16_f32 v90, v80, v81
	v_pk_mul_f32 v[80:81], v[96:97], v[86:87] op_sel_hi:[0,1]
	v_mul_f32_e32 v84, 0xbfb8aa3b, v80
	v_pk_mul_f32 v[82:83], v[80:81], v[82:83]
	v_mul_f32_e32 v80, 0xbfb8aa3b, v81
	v_exp_f32_e32 v84, v84
	v_exp_f32_e32 v80, v80
	v_add_f32_e32 v84, 1.0, v84
	v_add_f32_e32 v80, 1.0, v80
	v_rcp_f32_e32 v84, v84
	v_rcp_f32_e32 v85, v80
	s_nop 0
	v_pk_mul_f32 v[80:81], v[84:85], v[82:83]
	s_nop 0
	v_cvt_pk_bf16_f32 v91, v80, v81
	v_mad_i64_i32 v[80:81], s[14:15], v97, s62, v[112:113]
	v_lshl_add_u64 v[80:81], v[80:81], 0, v[114:115]
	global_store_dwordx4 v[80:81], v[88:91], off
	v_fmamk_f32 v80, v156, 0x3a000000, v151
	v_rsq_f32_e32 v80, v80
	v_or_b32_e32 v81, 48, v160
	v_pk_mul_f32 v[76:77], v[80:81], v[76:77] op_sel_hi:[0,1]
	v_pk_mul_f32 v[72:73], v[80:81], v[72:73] op_sel_hi:[0,1]
	v_mul_f32_e32 v82, 0xbfb8aa3b, v76
	v_pk_mul_f32 v[72:73], v[76:77], v[72:73]
	v_mul_f32_e32 v76, 0xbfb8aa3b, v77
	v_exp_f32_e32 v82, v82
	v_exp_f32_e32 v76, v76
	v_pk_mul_f32 v[74:75], v[80:81], v[74:75] op_sel_hi:[0,1]
	v_pk_mul_f32 v[68:69], v[80:81], v[68:69] op_sel_hi:[0,1]
	v_add_f32_e32 v82, 1.0, v82
	v_add_f32_e32 v76, 1.0, v76
	v_rcp_f32_e32 v82, v82
	v_rcp_f32_e32 v83, v76
	v_pk_mul_f32 v[76:77], v[80:81], v[78:79] op_sel_hi:[0,1]
	v_pk_mul_f32 v[74:75], v[76:77], v[74:75]
	v_pk_mul_f32 v[64:65], v[80:81], v[64:65] op_sel_hi:[0,1]
	v_pk_mul_f32 v[72:73], v[82:83], v[72:73]
	v_pk_mul_f32 v[64:65], v[68:69], v[64:65]
	v_cvt_pk_bf16_f32 v72, v72, v73
	v_mul_f32_e32 v73, 0xbfb8aa3b, v76
	v_exp_f32_e32 v73, v73
	v_pk_mul_f32 v[66:67], v[80:81], v[66:67] op_sel_hi:[0,1]
	v_add_f32_e32 v73, 1.0, v73
	v_rcp_f32_e32 v78, v73
	v_mul_f32_e32 v73, 0xbfb8aa3b, v77
	v_exp_f32_e32 v73, v73
	s_nop 0
	v_add_f32_e32 v73, 1.0, v73
	v_rcp_f32_e32 v79, v73
	s_nop 0
	v_pk_mul_f32 v[74:75], v[78:79], v[74:75]
	s_nop 0
	v_cvt_pk_bf16_f32 v73, v74, v75
	v_mul_f32_e32 v74, 0xbfb8aa3b, v68
	v_mul_f32_e32 v68, 0xbfb8aa3b, v69
	v_exp_f32_e32 v74, v74
	v_exp_f32_e32 v68, v68
	v_add_f32_e32 v74, 1.0, v74
	v_add_f32_e32 v68, 1.0, v68
	v_rcp_f32_e32 v74, v74
	v_rcp_f32_e32 v75, v68
; __device__ __forceinline__ float sigmoidf_(float x) { return __builtin_amdgcn_rcpf(1.0f + fexp(-x)); }
;     __device__ __forceinline__ void operator()(const f32x4 (&acc)[2][2][4][2], const Unit& u, int wr, int wc, int fr, int fq, const Pre& P) const {
;         const int row0 = ROW_X + u.pm * BM + wr * 64 + fr, col0 = u.pn * HALF + wc * 32 + 8 * fq;
; #pragma unroll
;         for (int ai = 0; ai < 2; ++ai)
; #pragma unroll
;             for (int m = 0; m < 4; ++m) { const int r = row0 + ai * HALF + m * 16; const float rs = __builtin_amdgcn_rsqf(P.rs[ai * 4 + m] * (1.0f / DM) + RMS_EPS);
;                 float y[8];
; #pragma unroll
;                 for (int n = 0; n < 2; ++n)
; #pragma unroll
;                     for (int j = 0; j < 4; ++j) { const float a = acc[ai][0][m][n][j] * rs, b = acc[ai][1][m][n][j] * rs; y[n * 4 + j] = a * b * sigmoidf_(a); }
;                 u32x4 w; w.x = cvtpk(y[0], y[1]); w.y = cvtpk(y[2], y[3]); w.z = cvtpk(y[4], y[5]); w.w = cvtpk(y[6], y[7]);
;                 *(u32x4*)(O + (size_t)r * FF + col0) = w; }
	s_nop 0
	v_pk_mul_f32 v[64:65], v[74:75], v[64:65]
	s_nop 0
	v_cvt_pk_bf16_f32 v74, v64, v65
	v_pk_mul_f32 v[64:65], v[80:81], v[70:71] op_sel_hi:[0,1]
	v_mul_f32_e32 v68, 0xbfb8aa3b, v64
	v_pk_mul_f32 v[66:67], v[64:65], v[66:67]
	v_mul_f32_e32 v64, 0xbfb8aa3b, v65
	v_exp_f32_e32 v68, v68
	v_exp_f32_e32 v64, v64
	v_add_f32_e32 v68, 1.0, v68
	v_add_f32_e32 v64, 1.0, v64
	v_rcp_f32_e32 v68, v68
	v_rcp_f32_e32 v69, v64
	s_nop 0
	v_pk_mul_f32 v[64:65], v[68:69], v[66:67]
	s_nop 0
	v_cvt_pk_bf16_f32 v75, v64, v65
	v_mad_i64_i32 v[64:65], s[14:15], v81, s62, v[112:113]
	v_lshl_add_u64 v[64:65], v[64:65], 0, v[114:115]
	global_store_dwordx4 v[64:65], v[72:75], off
	v_fmamk_f32 v64, v155, 0x3a000000, v151
	v_rsq_f32_e32 v64, v64
	v_add_u32_e32 v65, 0x80, v160
	v_pk_mul_f32 v[60:61], v[64:65], v[60:61] op_sel_hi:[0,1]
	v_pk_mul_f32 v[56:57], v[64:65], v[56:57] op_sel_hi:[0,1]
	v_mul_f32_e32 v66, 0xbfb8aa3b, v60
	v_pk_mul_f32 v[56:57], v[60:61], v[56:57]
	v_mul_f32_e32 v60, 0xbfb8aa3b, v61
	v_exp_f32_e32 v66, v66
	v_exp_f32_e32 v60, v60
	v_pk_mul_f32 v[58:59], v[64:65], v[58:59] op_sel_hi:[0,1]
	v_pk_mul_f32 v[52:53], v[64:65], v[52:53] op_sel_hi:[0,1]
	v_add_f32_e32 v66, 1.0, v66
	v_add_f32_e32 v60, 1.0, v60
	v_rcp_f32_e32 v66, v66
	v_rcp_f32_e32 v67, v60
	v_pk_mul_f32 v[60:61], v[64:65], v[62:63] op_sel_hi:[0,1]
	v_pk_mul_f32 v[58:59], v[60:61], v[58:59]
	v_pk_mul_f32 v[48:49], v[64:65], v[48:49] op_sel_hi:[0,1]
	v_pk_mul_f32 v[56:57], v[66:67], v[56:57]
	v_pk_mul_f32 v[48:49], v[52:53], v[48:49]
	v_cvt_pk_bf16_f32 v56, v56, v57
	v_mul_f32_e32 v57, 0xbfb8aa3b, v60
	v_exp_f32_e32 v57, v57
	v_pk_mul_f32 v[50:51], v[64:65], v[50:51] op_sel_hi:[0,1]
	v_add_f32_e32 v57, 1.0, v57
	v_rcp_f32_e32 v62, v57
	v_mul_f32_e32 v57, 0xbfb8aa3b, v61
	v_exp_f32_e32 v57, v57
	s_nop 0
	v_add_f32_e32 v57, 1.0, v57
	v_rcp_f32_e32 v63, v57
	s_nop 0
	v_pk_mul_f32 v[58:59], v[62:63], v[58:59]
	s_nop 0
	v_cvt_pk_bf16_f32 v57, v58, v59
	v_mul_f32_e32 v58, 0xbfb8aa3b, v52
	v_mul_f32_e32 v52, 0xbfb8aa3b, v53
	v_exp_f32_e32 v58, v58
	v_exp_f32_e32 v52, v52
	v_add_f32_e32 v58, 1.0, v58
	v_add_f32_e32 v52, 1.0, v52
	v_rcp_f32_e32 v58, v58
	v_rcp_f32_e32 v59, v52
	s_nop 0
	v_pk_mul_f32 v[48:49], v[58:59], v[48:49]
	s_nop 0
	v_cvt_pk_bf16_f32 v58, v48, v49
	v_pk_mul_f32 v[48:49], v[64:65], v[54:55] op_sel_hi:[0,1]
	v_mul_f32_e32 v52, 0xbfb8aa3b, v48
	v_pk_mul_f32 v[50:51], v[48:49], v[50:51]
	v_mul_f32_e32 v48, 0xbfb8aa3b, v49
	v_exp_f32_e32 v52, v52
	v_exp_f32_e32 v48, v48
	v_add_f32_e32 v52, 1.0, v52
	v_add_f32_e32 v48, 1.0, v48
	v_rcp_f32_e32 v52, v52
	v_rcp_f32_e32 v53, v48
	s_nop 0
	v_pk_mul_f32 v[48:49], v[52:53], v[50:51]
	s_nop 0
	v_cvt_pk_bf16_f32 v59, v48, v49
	v_mad_i64_i32 v[48:49], s[14:15], v65, s62, v[112:113]
	v_lshl_add_u64 v[48:49], v[48:49], 0, v[114:115]
	global_store_dwordx4 v[48:49], v[56:59], off
	v_fmamk_f32 v48, v154, 0x3a000000, v151
	v_rsq_f32_e32 v48, v48
	v_add_u32_e32 v49, 0x90, v160
	v_pk_mul_f32 v[44:45], v[48:49], v[44:45] op_sel_hi:[0,1]
	v_pk_mul_f32 v[40:41], v[48:49], v[40:41] op_sel_hi:[0,1]
	v_mul_f32_e32 v50, 0xbfb8aa3b, v44
	v_pk_mul_f32 v[40:41], v[44:45], v[40:41]
	v_mul_f32_e32 v44, 0xbfb8aa3b, v45
	v_exp_f32_e32 v50, v50
	v_exp_f32_e32 v44, v44
	v_pk_mul_f32 v[42:43], v[48:49], v[42:43] op_sel_hi:[0,1]
	v_pk_mul_f32 v[36:37], v[48:49], v[36:37] op_sel_hi:[0,1]
	v_add_f32_e32 v50, 1.0, v50
	v_add_f32_e32 v44, 1.0, v44
	v_rcp_f32_e32 v50, v50
	v_rcp_f32_e32 v51, v44
	v_pk_mul_f32 v[44:45], v[48:49], v[46:47] op_sel_hi:[0,1]
	v_pk_mul_f32 v[42:43], v[44:45], v[42:43]
	v_pk_mul_f32 v[32:33], v[48:49], v[32:33] op_sel_hi:[0,1]
	v_pk_mul_f32 v[40:41], v[50:51], v[40:41]
	v_pk_mul_f32 v[32:33], v[36:37], v[32:33]
	v_cvt_pk_bf16_f32 v40, v40, v41
	v_mul_f32_e32 v41, 0xbfb8aa3b, v44
	v_exp_f32_e32 v41, v41
	v_pk_mul_f32 v[34:35], v[48:49], v[34:35] op_sel_hi:[0,1]
	v_add_f32_e32 v41, 1.0, v41
	v_rcp_f32_e32 v46, v41
	v_mul_f32_e32 v41, 0xbfb8aa3b, v45
	v_exp_f32_e32 v41, v41
	s_nop 0
	v_add_f32_e32 v41, 1.0, v41
	v_rcp_f32_e32 v47, v41
	s_nop 0
	v_pk_mul_f32 v[42:43], v[46:47], v[42:43]
	s_nop 0
	v_cvt_pk_bf16_f32 v41, v42, v43
	v_mul_f32_e32 v42, 0xbfb8aa3b, v36
	v_mul_f32_e32 v36, 0xbfb8aa3b, v37
	v_exp_f32_e32 v42, v42
	v_exp_f32_e32 v36, v36
	v_add_f32_e32 v42, 1.0, v42
	v_add_f32_e32 v36, 1.0, v36
	v_rcp_f32_e32 v42, v42
	v_rcp_f32_e32 v43, v36
	s_nop 0
	v_pk_mul_f32 v[32:33], v[42:43], v[32:33]
	s_nop 0
	v_cvt_pk_bf16_f32 v42, v32, v33
	v_pk_mul_f32 v[32:33], v[48:49], v[38:39] op_sel_hi:[0,1]
	v_mul_f32_e32 v36, 0xbfb8aa3b, v32
	v_pk_mul_f32 v[34:35], v[32:33], v[34:35]
	v_mul_f32_e32 v32, 0xbfb8aa3b, v33
	v_exp_f32_e32 v36, v36
	v_exp_f32_e32 v32, v32
	v_add_f32_e32 v36, 1.0, v36
	v_add_f32_e32 v32, 1.0, v32
	v_rcp_f32_e32 v36, v36
	v_rcp_f32_e32 v37, v32
	s_nop 0
	v_pk_mul_f32 v[32:33], v[36:37], v[34:35]
	s_nop 0
	v_cvt_pk_bf16_f32 v43, v32, v33
	v_mad_i64_i32 v[32:33], s[14:15], v49, s62, v[112:113]
	v_lshl_add_u64 v[32:33], v[32:33], 0, v[114:115]
	global_store_dwordx4 v[32:33], v[40:43], off
	v_fmamk_f32 v32, v153, 0x3a000000, v151
	v_rsq_f32_e32 v32, v32
; __device__ __forceinline__ float sigmoidf_(float x) { return __builtin_amdgcn_rcpf(1.0f + fexp(-x)); }
; __device__ __forceinline__ PreRs load_rs(const float* ssq, int pm, int wr, int fr) { PreRs p;
; #pragma unroll
;     for (int ai = 0; ai < 2; ++ai)
; #pragma unroll
;         for (int m = 0; m < 4; ++m) p.rs[ai * 4 + m] = ssq[ROW_X + pm * BM + ai * HALF + wr * 64 + m * 16 + fr];
;     return p; }
;     __device__ __forceinline__ void operator()(const f32x4 (&acc)[2][2][4][2], const Unit& u, int wr, int wc, int fr, int fq, const Pre& P) const {
;         const int row0 = ROW_X + u.pm * BM + wr * 64 + fr, col0 = u.pn * HALF + wc * 32 + 8 * fq;
; #pragma unroll
;         for (int ai = 0; ai < 2; ++ai)
; #pragma unroll
;             for (int m = 0; m < 4; ++m) { const int r = row0 + ai * HALF + m * 16; const float rs = __builtin_amdgcn_rsqf(P.rs[ai * 4 + m] * (1.0f / DM) + RMS_EPS);
;                 float y[8];
; #pragma unroll
;                 for (int n = 0; n < 2; ++n)
; #pragma unroll
;                     for (int j = 0; j < 4; ++j) { const float a = acc[ai][0][m][n][j] * rs, b = acc[ai][1][m][n][j] * rs; y[n * 4 + j] = a * b * sigmoidf_(a); }
;                 u32x4 w; w.x = cvtpk(y[0], y[1]); w.y = cvtpk(y[2], y[3]); w.z = cvtpk(y[4], y[5]); w.w = cvtpk(y[6], y[7]);
;                 *(u32x4*)(O + (size_t)r * FF + col0) = w; }
	v_add_u32_e32 v33, 0xa0, v160
	v_pk_mul_f32 v[28:29], v[32:33], v[28:29] op_sel_hi:[0,1]
	v_pk_mul_f32 v[24:25], v[32:33], v[24:25] op_sel_hi:[0,1]
	v_mul_f32_e32 v34, 0xbfb8aa3b, v28
	v_pk_mul_f32 v[24:25], v[28:29], v[24:25]
	v_mul_f32_e32 v28, 0xbfb8aa3b, v29
	v_exp_f32_e32 v34, v34
	v_exp_f32_e32 v28, v28
	v_pk_mul_f32 v[26:27], v[32:33], v[26:27] op_sel_hi:[0,1]
	v_pk_mul_f32 v[20:21], v[32:33], v[20:21] op_sel_hi:[0,1]
	v_add_f32_e32 v34, 1.0, v34
	v_add_f32_e32 v28, 1.0, v28
	v_rcp_f32_e32 v34, v34
	v_rcp_f32_e32 v35, v28
	v_pk_mul_f32 v[28:29], v[32:33], v[30:31] op_sel_hi:[0,1]
	v_pk_mul_f32 v[26:27], v[28:29], v[26:27]
	v_pk_mul_f32 v[16:17], v[32:33], v[16:17] op_sel_hi:[0,1]
	v_pk_mul_f32 v[24:25], v[34:35], v[24:25]
	v_pk_mul_f32 v[16:17], v[20:21], v[16:17]
	v_cvt_pk_bf16_f32 v24, v24, v25
	v_mul_f32_e32 v25, 0xbfb8aa3b, v28
	v_exp_f32_e32 v25, v25
	v_pk_mul_f32 v[18:19], v[32:33], v[18:19] op_sel_hi:[0,1]
	v_add_f32_e32 v25, 1.0, v25
	v_rcp_f32_e32 v30, v25
	v_mul_f32_e32 v25, 0xbfb8aa3b, v29
	v_exp_f32_e32 v25, v25
	s_nop 0
	v_add_f32_e32 v25, 1.0, v25
	v_rcp_f32_e32 v31, v25
	s_nop 0
	v_pk_mul_f32 v[26:27], v[30:31], v[26:27]
	s_nop 0
	v_cvt_pk_bf16_f32 v25, v26, v27
	v_mul_f32_e32 v26, 0xbfb8aa3b, v20
	v_mul_f32_e32 v20, 0xbfb8aa3b, v21
	v_exp_f32_e32 v26, v26
	v_exp_f32_e32 v20, v20
	v_add_f32_e32 v26, 1.0, v26
	v_add_f32_e32 v20, 1.0, v20
	v_rcp_f32_e32 v26, v26
	v_rcp_f32_e32 v27, v20
	s_nop 0
	v_pk_mul_f32 v[16:17], v[26:27], v[16:17]
	s_nop 0
	v_cvt_pk_bf16_f32 v26, v16, v17
	v_pk_mul_f32 v[16:17], v[32:33], v[22:23] op_sel_hi:[0,1]
	v_mul_f32_e32 v20, 0xbfb8aa3b, v16
	v_pk_mul_f32 v[18:19], v[16:17], v[18:19]
	v_mul_f32_e32 v16, 0xbfb8aa3b, v17
	v_exp_f32_e32 v20, v20
	v_exp_f32_e32 v16, v16
	v_add_f32_e32 v20, 1.0, v20
	v_add_f32_e32 v16, 1.0, v16
	v_rcp_f32_e32 v20, v20
	v_rcp_f32_e32 v21, v16
	s_nop 0
	v_pk_mul_f32 v[16:17], v[20:21], v[18:19]
	s_nop 0
	v_cvt_pk_bf16_f32 v27, v16, v17
	v_mad_i64_i32 v[16:17], s[14:15], v33, s62, v[112:113]
	v_lshl_add_u64 v[16:17], v[16:17], 0, v[114:115]
	global_store_dwordx4 v[16:17], v[24:27], off
	v_fmamk_f32 v16, v152, 0x3a000000, v151
	v_rsq_f32_e32 v16, v16
	v_add_u32_e32 v17, 0xb0, v160
	v_pk_mul_f32 v[12:13], v[16:17], v[12:13] op_sel_hi:[0,1]
	v_pk_mul_f32 v[8:9], v[16:17], v[8:9] op_sel_hi:[0,1]
	v_mul_f32_e32 v18, 0xbfb8aa3b, v12
	v_pk_mul_f32 v[8:9], v[12:13], v[8:9]
	v_mul_f32_e32 v12, 0xbfb8aa3b, v13
	v_exp_f32_e32 v18, v18
	v_exp_f32_e32 v12, v12
	v_pk_mul_f32 v[10:11], v[16:17], v[10:11] op_sel_hi:[0,1]
	v_pk_mul_f32 v[4:5], v[16:17], v[4:5] op_sel_hi:[0,1]
	v_add_f32_e32 v18, 1.0, v18
	v_add_f32_e32 v12, 1.0, v12
	v_rcp_f32_e32 v18, v18
	v_rcp_f32_e32 v19, v12
	v_pk_mul_f32 v[12:13], v[16:17], v[14:15] op_sel_hi:[0,1]
	v_pk_mul_f32 v[10:11], v[12:13], v[10:11]
	v_pk_mul_f32 v[0:1], v[16:17], v[0:1] op_sel_hi:[0,1]
	v_pk_mul_f32 v[8:9], v[18:19], v[8:9]
	v_pk_mul_f32 v[0:1], v[4:5], v[0:1]
	v_cvt_pk_bf16_f32 v8, v8, v9
	v_mul_f32_e32 v9, 0xbfb8aa3b, v12
	v_exp_f32_e32 v9, v9
	v_pk_mul_f32 v[2:3], v[16:17], v[2:3] op_sel_hi:[0,1]
	v_add_f32_e32 v9, 1.0, v9
	v_rcp_f32_e32 v14, v9
	v_mul_f32_e32 v9, 0xbfb8aa3b, v13
	v_exp_f32_e32 v9, v9
	s_nop 0
	v_add_f32_e32 v9, 1.0, v9
	v_rcp_f32_e32 v15, v9
	s_nop 0
	v_pk_mul_f32 v[10:11], v[14:15], v[10:11]
	s_nop 0
	v_cvt_pk_bf16_f32 v9, v10, v11
	v_mul_f32_e32 v10, 0xbfb8aa3b, v4
	v_mul_f32_e32 v4, 0xbfb8aa3b, v5
	v_exp_f32_e32 v10, v10
	v_exp_f32_e32 v4, v4
	v_add_f32_e32 v10, 1.0, v10
	v_add_f32_e32 v4, 1.0, v4
	v_rcp_f32_e32 v10, v10
	v_rcp_f32_e32 v11, v4
	s_nop 0
	v_pk_mul_f32 v[0:1], v[10:11], v[0:1]
	s_nop 0
	v_cvt_pk_bf16_f32 v10, v0, v1
	v_pk_mul_f32 v[0:1], v[16:17], v[6:7] op_sel_hi:[0,1]
	v_mul_f32_e32 v4, 0xbfb8aa3b, v0
	v_pk_mul_f32 v[2:3], v[0:1], v[2:3]
	v_mul_f32_e32 v0, 0xbfb8aa3b, v1
	v_exp_f32_e32 v4, v4
	v_exp_f32_e32 v0, v0
	v_add_f32_e32 v4, 1.0, v4
	v_add_f32_e32 v0, 1.0, v0
	v_rcp_f32_e32 v4, v4
	v_rcp_f32_e32 v5, v0
	s_nop 0
	v_pk_mul_f32 v[0:1], v[4:5], v[2:3]
	s_nop 0
	v_cvt_pk_bf16_f32 v11, v0, v1
	v_mad_i64_i32 v[0:1], s[14:15], v17, s62, v[112:113]
	v_lshl_add_u64 v[0:1], v[0:1], 0, v[114:115]
	s_mov_b64 s[14:15], -1
	global_store_dwordx4 v[0:1], v[8:11], off
	s_cbranch_vccz .LBB0_255
	v_lshl_add_u32 v0, s8, 8, v145
	v_ashrrev_i32_e32 v1, 31, v0
	v_lshl_add_u64 v[2:3], v[0:1], 2, s[2:3]
	v_add_u32_e32 v4, 0x80, v0
	v_add_u32_e32 v6, 0x90, v0
	v_add_u32_e32 v8, 0xa0, v0
	v_add_u32_e32 v0, 0xb0, v0
	v_ashrrev_i32_e32 v5, 31, v4
	v_ashrrev_i32_e32 v7, 31, v6
	v_ashrrev_i32_e32 v9, 31, v8
	v_ashrrev_i32_e32 v1, 31, v0
	v_lshl_add_u64 v[4:5], v[4:5], 2, s[2:3]
	v_lshl_add_u64 v[6:7], v[6:7], 2, s[2:3]
	v_lshl_add_u64 v[8:9], v[8:9], 2, s[2:3]
	v_lshl_add_u64 v[0:1], v[0:1], 2, s[2:3]
	global_load_dword v159, v[2:3], off
	global_load_dword v158, v[2:3], off offset:64
	global_load_dword v157, v[2:3], off offset:128
	global_load_dword v156, v[2:3], off offset:192
	global_load_dword v155, v[4:5], off
	global_load_dword v154, v[6:7], off
	global_load_dword v153, v[8:9], off
	global_load_dword v152, v[0:1], off
	s_mov_b64 s[14:15], 0
	s_branch .LBB0_255

; #define PG8_STAGE(bufoff, gbase, voff) do { _Pragma("unroll") for (int _i = 0; _i < 2; ++_i) \
;         __builtin_amdgcn_global_load_lds((const unsigned*)((const char*)(gbase) + (voff)[_i]), (LAS unsigned*)(lds + (bufoff) + ldsw + _i * 8192), 16, 0, 0); } while (0)
; #define PG8_LDA(dst, b, h) do { _Pragma("unroll") for (int m = 0; m < 4; ++m) _Pragma("unroll") for (int k = 0; k < 2; ++k) dst[m][k] = *(const LAS bf16x8*)(lds + PG8_SA(b, h) + aoff + m * 2048 + k * 1024); } while (0)
; #define PG8_LDB(dst, b, h) do { _Pragma("unroll") for (int n = 0; n < 2; ++n) _Pragma("unroll") for (int k = 0; k < 2; ++k) dst[n][k] = *(const LAS bf16x8*)(lds + PG8_SB(b, h) + boff + n * 2048 + k * 1024); } while (0)
; #define PG8_MMA(ai, bj, At, Bt) do { __builtin_amdgcn_s_setprio(1); _Pragma("unroll") for (int m = 0; m < 4; ++m) _Pragma("unroll") for (int n = 0; n < 2; ++n) _Pragma("unroll") for (int k = 0; k < 2; ++k) \
;         acc[ai][bj][m][n] = __builtin_amdgcn_mfma_f32_16x16x32_bf16(Bt[n][k], At[m][k], acc[ai][bj][m][n], 0, 0, 0); __builtin_amdgcn_s_setprio(0); } while (0)
; #define PG8_WAIT_L(n) asm volatile("s_waitcnt lgkmcnt(" #n ")" ::: "memory")
; #define PG8_BAR __builtin_amdgcn_s_barrier()
; #define PG8_SCHED __builtin_amdgcn_sched_barrier(0)
; template <class Epi>
; __device__ __forceinline__ void gemm_phase(LAS unsigned char* lds, const Gemm g, const StaticOrder& S, const Epi& E) {
;     ...
;         for (int t = 0; t < nt; t += 2) {
;             const bool last = (t == nt - 2);
;             const char* a1 = cA + (size_t)(t + 1) * kstep;
;             const char* a2 = last ? nA : cA + (size_t)(t + 2) * kstep; const char* b2 = last ? nB : cB + (size_t)(t + 2) * kstep;
;             const char* a3 = a2 + kstep; const char* b3 = b2 + kstep;
;             PG8_LDB(B0, 0, 0); PG8_SCHED; PG8_LDA(At, 0, 0); PG8_STAGE(PG8_SA(1, 1), a1 + hstep, voffA);
;             PG8_WAIT_L(8); PG8_BAR; PG8_WAIT_L(0); PG8_MMA(0, 0, At, B0); PG8_BAR; PG8_SCHED;
.LBB0_364:
	ds_read_b128 v[128:131], v161
	ds_read_b128 v[132:135], v161 offset:1024
	ds_read_b128 v[152:155], v161 offset:2048
	ds_read_b128 v[166:169], v161 offset:3072
	s_add_u32 s16, s14, 0xffea8080
	s_addc_u32 s17, s15, -1
	s_cmpk_eq_i32 s65, 0x52
	s_cselect_b32 s19, s1, s17
	s_cselect_b32 s18, s0, s16
	s_cselect_b32 s17, s7, s64
	s_cselect_b32 s16, s6, s63
	v_lshl_add_u64 v[156:157], s[14:15], 0, v[144:145]
	s_add_i32 m0, s30, 0xc000
	ds_read_b128 v[170:173], v162
	ds_read_b128 v[174:177], v162 offset:1024
	ds_read_b128 v[180:183], v162 offset:2048
	ds_read_b128 v[184:187], v162 offset:3072
	ds_read_b128 v[188:191], v162 offset:4096
	ds_read_b128 v[192:195], v162 offset:5120
	ds_read_b128 v[196:199], v162 offset:6144
	ds_read_b128 v[200:203], v162 offset:7168
	global_load_lds_dwordx4 v[156:157], off
	v_lshl_add_u64 v[156:157], s[14:15], 0, v[146:147]
	s_add_i32 m0, s30, 0xe000
	s_nop 0
	global_load_lds_dwordx4 v[156:157], off
	s_waitcnt lgkmcnt(8)
	s_barrier
	s_waitcnt lgkmcnt(0)
	s_setprio 1

; #define PG8_STAGE(bufoff, gbase, voff) do { _Pragma("unroll") for (int _i = 0; _i < 2; ++_i) \
;         __builtin_amdgcn_global_load_lds((const unsigned*)((const char*)(gbase) + (voff)[_i]), (LAS unsigned*)(lds + (bufoff) + ldsw + _i * 8192), 16, 0, 0); } while (0)
; #define PG8_LDB(dst, b, h) do { _Pragma("unroll") for (int n = 0; n < 2; ++n) _Pragma("unroll") for (int k = 0; k < 2; ++k) dst[n][k] = *(const LAS bf16x8*)(lds + PG8_SB(b, h) + boff + n * 2048 + k * 1024); } while (0)
; #define PG8_MMA(ai, bj, At, Bt) do { __builtin_amdgcn_s_setprio(1); _Pragma("unroll") for (int m = 0; m < 4; ++m) _Pragma("unroll") for (int n = 0; n < 2; ++n) _Pragma("unroll") for (int k = 0; k < 2; ++k) \
;         acc[ai][bj][m][n] = __builtin_amdgcn_mfma_f32_16x16x32_bf16(Bt[n][k], At[m][k], acc[ai][bj][m][n], 0, 0, 0); __builtin_amdgcn_s_setprio(0); } while (0)
; #define PG8_WAIT_L(n) asm volatile("s_waitcnt lgkmcnt(" #n ")" ::: "memory")
; #define PG8_BAR __builtin_amdgcn_s_barrier()
; #define PG8_SCHED __builtin_amdgcn_sched_barrier(0)
; template <class Epi>
; __device__ __forceinline__ void gemm_phase(LAS unsigned char* lds, const Gemm g, const StaticOrder& S, const Epi& E) {
;     ...
;             PG8_WAIT_L(8); PG8_BAR; PG8_WAIT_L(0); PG8_MMA(0, 0, At, B0); PG8_BAR; PG8_SCHED;
;             PG8_LDB(B1, 0, 1); PG8_STAGE(PG8_SB(0, 0), b2, voffB);
;             PG8_BAR; PG8_WAIT_L(0); PG8_MMA(0, 1, At, B1); PG8_BAR;
	v_mfma_f32_16x16x32_bf16 v[124:127], v[128:131], v[170:173], v[124:127]
	v_mfma_f32_16x16x32_bf16 v[120:123], v[152:155], v[170:173], v[120:123]
	v_mfma_f32_16x16x32_bf16 v[108:111], v[128:131], v[180:183], v[108:111]
	v_mfma_f32_16x16x32_bf16 v[104:107], v[152:155], v[180:183], v[104:107]
	v_mfma_f32_16x16x32_bf16 v[92:95], v[128:131], v[188:191], v[92:95]
	v_mfma_f32_16x16x32_bf16 v[88:91], v[152:155], v[188:191], v[88:91]
	v_mfma_f32_16x16x32_bf16 v[76:79], v[128:131], v[196:199], v[76:79]
	v_mfma_f32_16x16x32_bf16 v[72:75], v[152:155], v[196:199], v[72:75]
	v_mfma_f32_16x16x32_bf16 v[124:127], v[132:135], v[174:177], v[124:127]
	v_mfma_f32_16x16x32_bf16 v[120:123], v[166:169], v[174:177], v[120:123]
	v_mfma_f32_16x16x32_bf16 v[108:111], v[132:135], v[184:187], v[108:111]
	v_mfma_f32_16x16x32_bf16 v[104:107], v[166:169], v[184:187], v[104:107]
	v_mfma_f32_16x16x32_bf16 v[92:95], v[132:135], v[192:195], v[92:95]
	v_mfma_f32_16x16x32_bf16 v[88:91], v[166:169], v[192:195], v[88:91]
	v_mfma_f32_16x16x32_bf16 v[76:79], v[132:135], v[200:203], v[76:79]
	v_mfma_f32_16x16x32_bf16 v[72:75], v[166:169], v[200:203], v[72:75]
	s_setprio 0
	s_barrier
	s_add_i32 s66, s57, s21
	v_lshl_add_u64 v[156:157], s[16:17], 0, v[138:139]
	s_mov_b32 m0, s66
	ds_read_b128 v[204:207], v163
	ds_read_b128 v[208:211], v163 offset:1024
	ds_read_b128 v[212:215], v163 offset:2048
	ds_read_b128 v[216:219], v163 offset:3072
	global_load_lds_dwordx4 v[156:157], off
	v_lshl_add_u64 v[220:221], s[16:17], 0, v[142:143]
	s_add_i32 m0, s66, 0x2000
	s_nop 0
	global_load_lds_dwordx4 v[220:221], off
	s_barrier
	s_waitcnt lgkmcnt(0)
	s_setprio 1

; #define PG8_STAGE(bufoff, gbase, voff) do { _Pragma("unroll") for (int _i = 0; _i < 2; ++_i) \
;         __builtin_amdgcn_global_load_lds((const unsigned*)((const char*)(gbase) + (voff)[_i]), (LAS unsigned*)(lds + (bufoff) + ldsw + _i * 8192), 16, 0, 0); } while (0)
; #define PG8_LDA(dst, b, h) do { _Pragma("unroll") for (int m = 0; m < 4; ++m) _Pragma("unroll") for (int k = 0; k < 2; ++k) dst[m][k] = *(const LAS bf16x8*)(lds + PG8_SA(b, h) + aoff + m * 2048 + k * 1024); } while (0)
; #define PG8_MMA(ai, bj, At, Bt) do { __builtin_amdgcn_s_setprio(1); _Pragma("unroll") for (int m = 0; m < 4; ++m) _Pragma("unroll") for (int n = 0; n < 2; ++n) _Pragma("unroll") for (int k = 0; k < 2; ++k) \
;         acc[ai][bj][m][n] = __builtin_amdgcn_mfma_f32_16x16x32_bf16(Bt[n][k], At[m][k], acc[ai][bj][m][n], 0, 0, 0); __builtin_amdgcn_s_setprio(0); } while (0)
; #define PG8_WAIT_L(n) asm volatile("s_waitcnt lgkmcnt(" #n ")" ::: "memory")
; #define PG8_BAR __builtin_amdgcn_s_barrier()
; #define PG8_SCHED __builtin_amdgcn_sched_barrier(0)
; template <class Epi>
; __device__ __forceinline__ void gemm_phase(LAS unsigned char* lds, const Gemm g, const StaticOrder& S, const Epi& E) {
;     ...
;             PG8_BAR; PG8_WAIT_L(0); PG8_MMA(0, 1, At, B1); PG8_BAR;
;             PG8_LDA(At, 0, 1); PG8_STAGE(PG8_SA(0, 0), a2, voffA);
;             PG8_BAR; PG8_WAIT_L(0); PG8_MMA(1, 0, At, B0); PG8_BAR; PG8_SCHED;
	v_mfma_f32_16x16x32_bf16 v[116:119], v[204:207], v[170:173], v[116:119]
	v_mfma_f32_16x16x32_bf16 v[112:115], v[212:215], v[170:173], v[112:115]
	v_mfma_f32_16x16x32_bf16 v[100:103], v[204:207], v[180:183], v[100:103]
	v_mfma_f32_16x16x32_bf16 v[96:99], v[212:215], v[180:183], v[96:99]
	v_mfma_f32_16x16x32_bf16 v[84:87], v[204:207], v[188:191], v[84:87]
	v_mfma_f32_16x16x32_bf16 v[80:83], v[212:215], v[188:191], v[80:83]
	v_mfma_f32_16x16x32_bf16 v[68:71], v[204:207], v[196:199], v[68:71]
	v_mfma_f32_16x16x32_bf16 v[64:67], v[212:215], v[196:199], v[64:67]
	v_mfma_f32_16x16x32_bf16 v[116:119], v[208:211], v[174:177], v[116:119]
	v_mfma_f32_16x16x32_bf16 v[112:115], v[216:219], v[174:177], v[112:115]
	v_mfma_f32_16x16x32_bf16 v[100:103], v[208:211], v[184:187], v[100:103]
	v_mfma_f32_16x16x32_bf16 v[96:99], v[216:219], v[184:187], v[96:99]
	v_mfma_f32_16x16x32_bf16 v[84:87], v[208:211], v[192:195], v[84:87]
	v_mfma_f32_16x16x32_bf16 v[80:83], v[216:219], v[192:195], v[80:83]
	v_mfma_f32_16x16x32_bf16 v[68:71], v[208:211], v[200:203], v[68:71]
	v_mfma_f32_16x16x32_bf16 v[64:67], v[216:219], v[200:203], v[64:67]
	s_setprio 0
	s_mov_b32 m0, s30
	v_lshl_add_u64 v[222:223], s[18:19], 0, v[136:137]
	s_barrier
	ds_read_b128 v[170:173], v162 offset:16384
	ds_read_b128 v[174:177], v162 offset:17408
	ds_read_b128 v[180:183], v162 offset:18432
	ds_read_b128 v[184:187], v162 offset:19456
	ds_read_b128 v[188:191], v162 offset:20480
	ds_read_b128 v[192:195], v162 offset:21504
	ds_read_b128 v[196:199], v162 offset:22528
	ds_read_b128 v[200:203], v162 offset:23552
	global_load_lds_dwordx4 v[222:223], off
	v_lshl_add_u64 v[224:225], s[18:19], 0, v[140:141]
	s_mov_b32 m0, s31
	s_nop 0
	global_load_lds_dwordx4 v[224:225], off
	s_barrier
	s_waitcnt lgkmcnt(0)
	s_setprio 1

; #define PG8_STAGE(bufoff, gbase, voff) do { _Pragma("unroll") for (int _i = 0; _i < 2; ++_i) \
;         __builtin_amdgcn_global_load_lds((const unsigned*)((const char*)(gbase) + (voff)[_i]), (LAS unsigned*)(lds + (bufoff) + ldsw + _i * 8192), 16, 0, 0); } while (0)
; #define PG8_LDA(dst, b, h) do { _Pragma("unroll") for (int m = 0; m < 4; ++m) _Pragma("unroll") for (int k = 0; k < 2; ++k) dst[m][k] = *(const LAS bf16x8*)(lds + PG8_SA(b, h) + aoff + m * 2048 + k * 1024); } while (0)
; #define PG8_LDB(dst, b, h) do { _Pragma("unroll") for (int n = 0; n < 2; ++n) _Pragma("unroll") for (int k = 0; k < 2; ++k) dst[n][k] = *(const LAS bf16x8*)(lds + PG8_SB(b, h) + boff + n * 2048 + k * 1024); } while (0)
; #define PG8_MMA(ai, bj, At, Bt) do { __builtin_amdgcn_s_setprio(1); _Pragma("unroll") for (int m = 0; m < 4; ++m) _Pragma("unroll") for (int n = 0; n < 2; ++n) _Pragma("unroll") for (int k = 0; k < 2; ++k) \
;         acc[ai][bj][m][n] = __builtin_amdgcn_mfma_f32_16x16x32_bf16(Bt[n][k], At[m][k], acc[ai][bj][m][n], 0, 0, 0); __builtin_amdgcn_s_setprio(0); } while (0)
; #define PG8_WAIT_V(n) asm volatile("s_waitcnt vmcnt(" #n ")" ::: "memory")
; #define PG8_WAIT_L(n) asm volatile("s_waitcnt lgkmcnt(" #n ")" ::: "memory")
; #define PG8_BAR __builtin_amdgcn_s_barrier()
; #define PG8_SCHED __builtin_amdgcn_sched_barrier(0)
; template <class Epi>
; __device__ __forceinline__ void gemm_phase(LAS unsigned char* lds, const Gemm g, const StaticOrder& S, const Epi& E) {
;     ...
;             PG8_BAR; PG8_WAIT_L(0); PG8_MMA(1, 0, At, B0); PG8_BAR; PG8_SCHED;
;             PG8_STAGE(PG8_SB(0, 1), b2 + hstep, voffB);
;             PG8_WAIT_V(6); PG8_BAR; PG8_MMA(1, 1, At, B1); PG8_BAR;
;             PG8_LDB(B0, 1, 0); PG8_SCHED; PG8_LDA(At, 1, 0); PG8_STAGE(PG8_SA(0, 1), a2 + hstep, voffA);
;             PG8_WAIT_L(8); PG8_BAR; PG8_WAIT_L(0); PG8_MMA(0, 0, At, B0); PG8_BAR; PG8_SCHED;
	v_mfma_f32_16x16x32_bf16 v[60:63], v[128:131], v[170:173], v[60:63]
	v_mfma_f32_16x16x32_bf16 v[56:59], v[152:155], v[170:173], v[56:59]
	v_mfma_f32_16x16x32_bf16 v[44:47], v[128:131], v[180:183], v[44:47]
	v_mfma_f32_16x16x32_bf16 v[40:43], v[152:155], v[180:183], v[40:43]
	v_mfma_f32_16x16x32_bf16 v[28:31], v[128:131], v[188:191], v[28:31]
	v_mfma_f32_16x16x32_bf16 v[24:27], v[152:155], v[188:191], v[24:27]
	v_mfma_f32_16x16x32_bf16 v[12:15], v[128:131], v[196:199], v[12:15]
	v_mfma_f32_16x16x32_bf16 v[8:11], v[152:155], v[196:199], v[8:11]
	v_mfma_f32_16x16x32_bf16 v[60:63], v[132:135], v[174:177], v[60:63]
	v_mfma_f32_16x16x32_bf16 v[56:59], v[166:169], v[174:177], v[56:59]
	v_mfma_f32_16x16x32_bf16 v[44:47], v[132:135], v[184:187], v[44:47]
	v_mfma_f32_16x16x32_bf16 v[40:43], v[166:169], v[184:187], v[40:43]
	v_mfma_f32_16x16x32_bf16 v[28:31], v[132:135], v[192:195], v[28:31]
	v_mfma_f32_16x16x32_bf16 v[24:27], v[166:169], v[192:195], v[24:27]
	v_mfma_f32_16x16x32_bf16 v[12:15], v[132:135], v[200:203], v[12:15]
	v_mfma_f32_16x16x32_bf16 v[8:11], v[166:169], v[200:203], v[8:11]
	s_setprio 0
	s_barrier
	s_add_u32 s66, s16, 0x158000
	s_addc_u32 s67, s17, 0
	s_add_i32 s68, s58, s21
	v_lshl_add_u64 v[128:129], s[66:67], 0, v[138:139]
	s_mov_b32 m0, s68
	s_nop 0
	global_load_lds_dwordx4 v[128:129], off
	v_lshl_add_u64 v[128:129], s[66:67], 0, v[142:143]
	s_add_i32 m0, s68, 0x2000
	s_nop 0
	global_load_lds_dwordx4 v[128:129], off
	s_waitcnt vmcnt(6)
	s_barrier
	s_setprio 1
	v_mfma_f32_16x16x32_bf16 v[52:55], v[204:207], v[170:173], v[52:55]
	v_mfma_f32_16x16x32_bf16 v[48:51], v[212:215], v[170:173], v[48:51]
	v_mfma_f32_16x16x32_bf16 v[36:39], v[204:207], v[180:183], v[36:39]
	v_mfma_f32_16x16x32_bf16 v[32:35], v[212:215], v[180:183], v[32:35]
	v_mfma_f32_16x16x32_bf16 v[20:23], v[204:207], v[188:191], v[20:23]
	v_mfma_f32_16x16x32_bf16 v[16:19], v[212:215], v[188:191], v[16:19]
	v_mfma_f32_16x16x32_bf16 v[4:7], v[204:207], v[196:199], v[4:7]
	v_mfma_f32_16x16x32_bf16 v[0:3], v[212:215], v[196:199], v[0:3]
	v_mfma_f32_16x16x32_bf16 v[52:55], v[208:211], v[174:177], v[52:55]
	v_mfma_f32_16x16x32_bf16 v[48:51], v[216:219], v[174:177], v[48:51]
	v_mfma_f32_16x16x32_bf16 v[36:39], v[208:211], v[184:187], v[36:39]
	v_mfma_f32_16x16x32_bf16 v[32:35], v[216:219], v[184:187], v[32:35]
	v_mfma_f32_16x16x32_bf16 v[20:23], v[208:211], v[192:195], v[20:23]
	v_mfma_f32_16x16x32_bf16 v[16:19], v[216:219], v[192:195], v[16:19]
	v_mfma_f32_16x16x32_bf16 v[4:7], v[208:211], v[200:203], v[4:7]
	v_mfma_f32_16x16x32_bf16 v[0:3], v[216:219], v[200:203], v[0:3]
	s_setprio 0
	s_add_i32 s66, 0, 0x18000
	v_add_u32_e32 v166, s66, v158
	s_barrier
	ds_read_b128 v[128:131], v166
	ds_read_b128 v[132:135], v166 offset:1024
	ds_read_b128 v[152:155], v166 offset:2048
	ds_read_b128 v[166:169], v166 offset:3072
	s_add_u32 s18, s18, 0x158000
	s_addc_u32 s19, s19, 0
	s_mov_b32 m0, s33
	v_lshl_add_u64 v[204:205], s[18:19], 0, v[136:137]
	ds_read_b128 v[170:173], v162 offset:32768
	ds_read_b128 v[174:177], v162 offset:33792
	ds_read_b128 v[180:183], v162 offset:34816
	ds_read_b128 v[184:187], v162 offset:35840
	ds_read_b128 v[188:191], v162 offset:36864
	ds_read_b128 v[192:195], v162 offset:37888
	ds_read_b128 v[196:199], v162 offset:38912
	ds_read_b128 v[200:203], v162 offset:39936
	global_load_lds_dwordx4 v[204:205], off
	v_lshl_add_u64 v[204:205], s[18:19], 0, v[140:141]
	s_mov_b32 m0, s34
	s_nop 0
	global_load_lds_dwordx4 v[204:205], off
	s_waitcnt lgkmcnt(8)
	s_barrier
	s_waitcnt lgkmcnt(0)
	s_setprio 1

; #define PG8_STAGE(bufoff, gbase, voff) do { _Pragma("unroll") for (int _i = 0; _i < 2; ++_i) \
;         __builtin_amdgcn_global_load_lds((const unsigned*)((const char*)(gbase) + (voff)[_i]), (LAS unsigned*)(lds + (bufoff) + ldsw + _i * 8192), 16, 0, 0); } while (0)
; #define PG8_LDB(dst, b, h) do { _Pragma("unroll") for (int n = 0; n < 2; ++n) _Pragma("unroll") for (int k = 0; k < 2; ++k) dst[n][k] = *(const LAS bf16x8*)(lds + PG8_SB(b, h) + boff + n * 2048 + k * 1024); } while (0)
; #define PG8_MMA(ai, bj, At, Bt) do { __builtin_amdgcn_s_setprio(1); _Pragma("unroll") for (int m = 0; m < 4; ++m) _Pragma("unroll") for (int n = 0; n < 2; ++n) _Pragma("unroll") for (int k = 0; k < 2; ++k) \
;         acc[ai][bj][m][n] = __builtin_amdgcn_mfma_f32_16x16x32_bf16(Bt[n][k], At[m][k], acc[ai][bj][m][n], 0, 0, 0); __builtin_amdgcn_s_setprio(0); } while (0)
; #define PG8_WAIT_L(n) asm volatile("s_waitcnt lgkmcnt(" #n ")" ::: "memory")
; #define PG8_BAR __builtin_amdgcn_s_barrier()
; #define PG8_SCHED __builtin_amdgcn_sched_barrier(0)
; template <class Epi>
; __device__ __forceinline__ void gemm_phase(LAS unsigned char* lds, const Gemm g, const StaticOrder& S, const Epi& E) {
;     ...
;             PG8_WAIT_L(8); PG8_BAR; PG8_WAIT_L(0); PG8_MMA(0, 0, At, B0); PG8_BAR; PG8_SCHED;
;             PG8_LDB(B1, 1, 1); PG8_STAGE(PG8_SB(1, 0), b3, voffB);
;             PG8_BAR; PG8_WAIT_L(0); PG8_MMA(0, 1, At, B1); PG8_BAR;
	v_mfma_f32_16x16x32_bf16 v[124:127], v[128:131], v[170:173], v[124:127]
	v_mfma_f32_16x16x32_bf16 v[120:123], v[152:155], v[170:173], v[120:123]
	v_mfma_f32_16x16x32_bf16 v[108:111], v[128:131], v[180:183], v[108:111]
	v_mfma_f32_16x16x32_bf16 v[104:107], v[152:155], v[180:183], v[104:107]
	v_mfma_f32_16x16x32_bf16 v[92:95], v[128:131], v[188:191], v[92:95]
	v_mfma_f32_16x16x32_bf16 v[88:91], v[152:155], v[188:191], v[88:91]
	v_mfma_f32_16x16x32_bf16 v[76:79], v[128:131], v[196:199], v[76:79]
	v_mfma_f32_16x16x32_bf16 v[72:75], v[152:155], v[196:199], v[72:75]
	v_mfma_f32_16x16x32_bf16 v[124:127], v[132:135], v[174:177], v[124:127]
	v_mfma_f32_16x16x32_bf16 v[120:123], v[166:169], v[174:177], v[120:123]
	v_mfma_f32_16x16x32_bf16 v[108:111], v[132:135], v[184:187], v[108:111]
	v_mfma_f32_16x16x32_bf16 v[104:107], v[166:169], v[184:187], v[104:107]
	v_mfma_f32_16x16x32_bf16 v[92:95], v[132:135], v[192:195], v[92:95]
	v_mfma_f32_16x16x32_bf16 v[88:91], v[166:169], v[192:195], v[88:91]
	v_mfma_f32_16x16x32_bf16 v[76:79], v[132:135], v[200:203], v[76:79]
	v_mfma_f32_16x16x32_bf16 v[72:75], v[166:169], v[200:203], v[72:75]
	s_setprio 0
	s_barrier
	s_add_i32 s18, 0, 0x1c000
	s_add_i32 s19, s66, s21
	v_add_u32_e32 v179, s18, v158
	v_lshl_add_u64 v[156:157], v[156:157], 0, s[12:13]
	s_mov_b32 m0, s19
	ds_read_b128 v[204:207], v179
	ds_read_b128 v[208:211], v179 offset:1024
	ds_read_b128 v[212:215], v179 offset:2048
	ds_read_b128 v[216:219], v179 offset:3072
	global_load_lds_dwordx4 v[156:157], off
	v_lshl_add_u64 v[156:157], v[220:221], 0, s[12:13]
	s_add_i32 m0, s19, 0x2000
	s_nop 0
	global_load_lds_dwordx4 v[156:157], off
	s_barrier
	s_waitcnt lgkmcnt(0)
	s_setprio 1

; #define PG8_STAGE(bufoff, gbase, voff) do { _Pragma("unroll") for (int _i = 0; _i < 2; ++_i) \
;         __builtin_amdgcn_global_load_lds((const unsigned*)((const char*)(gbase) + (voff)[_i]), (LAS unsigned*)(lds + (bufoff) + ldsw + _i * 8192), 16, 0, 0); } while (0)
; #define PG8_LDA(dst, b, h) do { _Pragma("unroll") for (int m = 0; m < 4; ++m) _Pragma("unroll") for (int k = 0; k < 2; ++k) dst[m][k] = *(const LAS bf16x8*)(lds + PG8_SA(b, h) + aoff + m * 2048 + k * 1024); } while (0)
; #define PG8_MMA(ai, bj, At, Bt) do { __builtin_amdgcn_s_setprio(1); _Pragma("unroll") for (int m = 0; m < 4; ++m) _Pragma("unroll") for (int n = 0; n < 2; ++n) _Pragma("unroll") for (int k = 0; k < 2; ++k) \
;         acc[ai][bj][m][n] = __builtin_amdgcn_mfma_f32_16x16x32_bf16(Bt[n][k], At[m][k], acc[ai][bj][m][n], 0, 0, 0); __builtin_amdgcn_s_setprio(0); } while (0)
; #define PG8_WAIT_L(n) asm volatile("s_waitcnt lgkmcnt(" #n ")" ::: "memory")
; #define PG8_BAR __builtin_amdgcn_s_barrier()
; #define PG8_SCHED __builtin_amdgcn_sched_barrier(0)
; template <class Epi>
; __device__ __forceinline__ void gemm_phase(LAS unsigned char* lds, const Gemm g, const StaticOrder& S, const Epi& E) {
;     ...
;             PG8_BAR; PG8_WAIT_L(0); PG8_MMA(0, 1, At, B1); PG8_BAR;
;             PG8_LDA(At, 1, 1); PG8_STAGE(PG8_SA(1, 0), a3, voffA);
;             PG8_BAR; PG8_WAIT_L(0); PG8_MMA(1, 0, At, B0); PG8_BAR; PG8_SCHED;
	v_mfma_f32_16x16x32_bf16 v[116:119], v[204:207], v[170:173], v[116:119]
	v_mfma_f32_16x16x32_bf16 v[112:115], v[212:215], v[170:173], v[112:115]
	v_mfma_f32_16x16x32_bf16 v[100:103], v[204:207], v[180:183], v[100:103]
	v_mfma_f32_16x16x32_bf16 v[96:99], v[212:215], v[180:183], v[96:99]
	v_mfma_f32_16x16x32_bf16 v[84:87], v[204:207], v[188:191], v[84:87]
	v_mfma_f32_16x16x32_bf16 v[80:83], v[212:215], v[188:191], v[80:83]
	v_mfma_f32_16x16x32_bf16 v[68:71], v[204:207], v[196:199], v[68:71]
	v_mfma_f32_16x16x32_bf16 v[64:67], v[212:215], v[196:199], v[64:67]
	v_mfma_f32_16x16x32_bf16 v[116:119], v[208:211], v[174:177], v[116:119]
	v_mfma_f32_16x16x32_bf16 v[112:115], v[216:219], v[174:177], v[112:115]
	v_mfma_f32_16x16x32_bf16 v[100:103], v[208:211], v[184:187], v[100:103]
	v_mfma_f32_16x16x32_bf16 v[96:99], v[216:219], v[184:187], v[96:99]
	v_mfma_f32_16x16x32_bf16 v[84:87], v[208:211], v[192:195], v[84:87]
	v_mfma_f32_16x16x32_bf16 v[80:83], v[216:219], v[192:195], v[80:83]
	v_mfma_f32_16x16x32_bf16 v[68:71], v[208:211], v[200:203], v[68:71]
	v_mfma_f32_16x16x32_bf16 v[64:67], v[216:219], v[200:203], v[64:67]
	s_setprio 0
	s_mov_b32 m0, s38
	v_lshl_add_u64 v[156:157], v[222:223], 0, s[12:13]
	s_barrier
	ds_read_b128 v[170:173], v162 offset:49152
	ds_read_b128 v[174:177], v162 offset:50176
	ds_read_b128 v[180:183], v162 offset:51200
	ds_read_b128 v[184:187], v162 offset:52224
	ds_read_b128 v[188:191], v162 offset:53248
	ds_read_b128 v[192:195], v162 offset:54272
	ds_read_b128 v[196:199], v162 offset:55296
	ds_read_b128 v[200:203], v162 offset:56320
	global_load_lds_dwordx4 v[156:157], off
	v_lshl_add_u64 v[156:157], v[224:225], 0, s[12:13]
	s_mov_b32 m0, s39
	s_nop 0
	global_load_lds_dwordx4 v[156:157], off
	s_barrier
	s_waitcnt lgkmcnt(0)
	s_setprio 1

; #define PG8_STAGE(bufoff, gbase, voff) do { _Pragma("unroll") for (int _i = 0; _i < 2; ++_i) \
;         __builtin_amdgcn_global_load_lds((const unsigned*)((const char*)(gbase) + (voff)[_i]), (LAS unsigned*)(lds + (bufoff) + ldsw + _i * 8192), 16, 0, 0); } while (0)
; #define PG8_MMA(ai, bj, At, Bt) do { __builtin_amdgcn_s_setprio(1); _Pragma("unroll") for (int m = 0; m < 4; ++m) _Pragma("unroll") for (int n = 0; n < 2; ++n) _Pragma("unroll") for (int k = 0; k < 2; ++k) \
;         acc[ai][bj][m][n] = __builtin_amdgcn_mfma_f32_16x16x32_bf16(Bt[n][k], At[m][k], acc[ai][bj][m][n], 0, 0, 0); __builtin_amdgcn_s_setprio(0); } while (0)
; #define PG8_WAIT_V(n) asm volatile("s_waitcnt vmcnt(" #n ")" ::: "memory")
; #define PG8_WAIT_L(n) asm volatile("s_waitcnt lgkmcnt(" #n ")" ::: "memory")
; #define PG8_BAR __builtin_amdgcn_s_barrier()
; #define PG8_SCHED __builtin_amdgcn_sched_barrier(0)
; template <class Epi>
; __device__ __forceinline__ void gemm_phase(LAS unsigned char* lds, const Gemm g, const StaticOrder& S, const Epi& E) {
;     ...
;             PG8_BAR; PG8_WAIT_L(0); PG8_MMA(1, 0, At, B0); PG8_BAR; PG8_SCHED;
;             PG8_STAGE(PG8_SB(1, 1), b3 + hstep, voffB);
;             PG8_WAIT_V(6); PG8_BAR; PG8_MMA(1, 1, At, B1); PG8_BAR;
	v_mfma_f32_16x16x32_bf16 v[60:63], v[128:131], v[170:173], v[60:63]
	v_mfma_f32_16x16x32_bf16 v[56:59], v[152:155], v[170:173], v[56:59]
	v_mfma_f32_16x16x32_bf16 v[44:47], v[128:131], v[180:183], v[44:47]
	v_mfma_f32_16x16x32_bf16 v[40:43], v[152:155], v[180:183], v[40:43]
	v_mfma_f32_16x16x32_bf16 v[28:31], v[128:131], v[188:191], v[28:31]
	v_mfma_f32_16x16x32_bf16 v[24:27], v[152:155], v[188:191], v[24:27]
	v_mfma_f32_16x16x32_bf16 v[12:15], v[128:131], v[196:199], v[12:15]
	v_mfma_f32_16x16x32_bf16 v[8:11], v[152:155], v[196:199], v[8:11]
	v_mfma_f32_16x16x32_bf16 v[60:63], v[132:135], v[174:177], v[60:63]
	v_mfma_f32_16x16x32_bf16 v[56:59], v[166:169], v[174:177], v[56:59]
	v_mfma_f32_16x16x32_bf16 v[44:47], v[132:135], v[184:187], v[44:47]
	v_mfma_f32_16x16x32_bf16 v[40:43], v[166:169], v[184:187], v[40:43]
	v_mfma_f32_16x16x32_bf16 v[28:31], v[132:135], v[192:195], v[28:31]
	v_mfma_f32_16x16x32_bf16 v[24:27], v[166:169], v[192:195], v[24:27]
	v_mfma_f32_16x16x32_bf16 v[12:15], v[132:135], v[200:203], v[12:15]
	v_mfma_f32_16x16x32_bf16 v[8:11], v[166:169], v[200:203], v[8:11]
	s_setprio 0
	s_barrier
	s_add_u32 s16, s16, 0x158080
	s_addc_u32 s17, s17, 0
	s_add_i32 s18, s18, s21
	v_lshl_add_u64 v[128:129], s[16:17], 0, v[138:139]
	s_mov_b32 m0, s18
	s_nop 0
	global_load_lds_dwordx4 v[128:129], off
	v_lshl_add_u64 v[128:129], s[16:17], 0, v[142:143]
	s_add_i32 m0, s18, 0x2000
	s_nop 0
	global_load_lds_dwordx4 v[128:129], off
	s_waitcnt vmcnt(6)
	s_barrier
	s_setprio 1
	v_mfma_f32_16x16x32_bf16 v[52:55], v[204:207], v[170:173], v[52:55]
	v_mfma_f32_16x16x32_bf16 v[48:51], v[212:215], v[170:173], v[48:51]
	v_mfma_f32_16x16x32_bf16 v[36:39], v[204:207], v[180:183], v[36:39]
	v_mfma_f32_16x16x32_bf16 v[32:35], v[212:215], v[180:183], v[32:35]
	v_mfma_f32_16x16x32_bf16 v[20:23], v[204:207], v[188:191], v[20:23]
	v_mfma_f32_16x16x32_bf16 v[16:19], v[212:215], v[188:191], v[16:19]
	v_mfma_f32_16x16x32_bf16 v[4:7], v[204:207], v[196:199], v[4:7]
	v_mfma_f32_16x16x32_bf16 v[0:3], v[212:215], v[196:199], v[0:3]
	v_mfma_f32_16x16x32_bf16 v[52:55], v[208:211], v[174:177], v[52:55]
	v_mfma_f32_16x16x32_bf16 v[48:51], v[216:219], v[174:177], v[48:51]
	v_mfma_f32_16x16x32_bf16 v[36:39], v[208:211], v[184:187], v[36:39]
	v_mfma_f32_16x16x32_bf16 v[32:35], v[216:219], v[184:187], v[32:35]
	v_mfma_f32_16x16x32_bf16 v[20:23], v[208:211], v[192:195], v[20:23]
	v_mfma_f32_16x16x32_bf16 v[16:19], v[216:219], v[192:195], v[16:19]
	v_mfma_f32_16x16x32_bf16 v[4:7], v[208:211], v[200:203], v[4:7]
	v_mfma_f32_16x16x32_bf16 v[0:3], v[216:219], v[200:203], v[0:3]
	s_setprio 0
	s_add_i32 s65, s65, 2
	s_add_u32 s14, s14, 0x100
	s_addc_u32 s15, s15, 0
	s_add_u32 s63, s63, 0x100
	s_addc_u32 s64, s64, 0
	s_cmpk_gt_u32 s65, 0x53
	s_barrier
	s_cbranch_scc0 .LBB0_364
; __device__ __forceinline__ float bflo(unsigned w) { return __uint_as_float(w << 16); }
; __device__ __forceinline__ float bfhi(unsigned w) { return __uint_as_float(w & 0xffff0000u); }
; #define ER_LOAD(g_, set_) do { const size_t off_ = (size_t)(row0 + ((g_) >> 2) * HALF + ((g_) & 3) * 16) * DM + col0; \
;         hv[set_][0] = *(const u32x4*)(HB + off_); hv[set_][1] = *(const u32x4*)(HB + off_ + HALF); } while (0)
;     __device__ __forceinline__ void operator()(const f32x4 (&acc)[2][2][4][2], const Unit& u, int wr, int wc, int fr, int fq, const Pre&) const {
;         const int row0 = ROW_X + u.pm * BM + wr * 64 + fr, col0 = u.pn * BM + wc * 32 + 8 * fq;
;         u32x4 hv[2][2]; float sprev = 0.f;
;     ...
;         ER_LOAD(0, 0);
; #pragma unroll
;         for (int g = 0; g < 8; ++g) { const int ai = g >> 2, m = g & 3; const int r = row0 + ai * HALF + m * 16; const size_t off = (size_t)r * DM + col0; float s = 0.f;
;             if (g + 1 < 8) ER_LOAD(g + 1, (g + 1) & 1);
; #pragma unroll
;             for (int bj = 0; bj < 2; ++bj) { const u32x4 w = hv[g & 1][bj];
;                 const f32x4 h0 = {bflo(w.x), bfhi(w.x), bflo(w.y), bfhi(w.y)}, h1 = {bflo(w.z), bfhi(w.z), bflo(w.w), bfhi(w.w)};
;                 const f32x4 o0 = h0 + acc[ai][bj][m][0] * alpha, o1 = h1 + acc[ai][bj][m][1] * alpha;
;                 if (FINAL) { float* op = OUT + (size_t)(r - ROW_X) * DM + col0 + bj * HALF; *(f32x4*)op = o0; *(f32x4*)(op + 4) = o1; }
;                 else { u32x4 q; q.x = cvtpk(o0[0], o0[1]); q.y = cvtpk(o0[2], o0[3]); q.z = cvtpk(o1[0], o1[1]); q.w = cvtpk(o1[2], o1[3]); *(u32x4*)(HB + off + bj * HALF) = q;
;                        s += ((o0[0] * o0[0] + o0[1] * o0[1]) + (o0[2] * o0[2] + o0[3] * o0[3])) + ((o1[0] * o1[0] + o1[1] * o1[1]) + (o1[2] * o1[2] + o1[3] * o1[3])); } }
;             if (!FINAL) { if (g > 0) { float t = sprev; t += __shfl_xor(t, 16); t += __shfl_xor(t, 32);
;                     if (fq == 0) __hip_atomic_fetch_add(ssq_out + row0 + ((g - 1) >> 2) * HALF + ((g - 1) & 3) * 16, t, __ATOMIC_RELAXED, __HIP_MEMORY_SCOPE_AGENT); }
;                 sprev = s; } }
	v_lshl_add_u32 v154, s61, 8, v159
	v_lshl_or_b32 v152, s62, 8, v160
	v_ashrrev_i32_e32 v155, 31, v154
	v_ashrrev_i32_e32 v153, 31, v152
	v_lshlrev_b64 v[128:129], 12, v[154:155]
	v_lshl_add_u64 v[128:129], s[8:9], 0, v[128:129]
	v_lshlrev_b64 v[130:131], 1, v[152:153]
	v_lshl_add_u64 v[184:185], v[128:129], 0, v[130:131]
	v_or_b32_e32 v128, 16, v154
	v_ashrrev_i32_e32 v129, 31, v128
	global_load_dwordx4 v[166:169], v[184:185], off
	global_load_dwordx4 v[170:173], v[184:185], off offset:256
	v_lshlrev_b64 v[128:129], 12, v[128:129]
	v_lshl_add_u64 v[128:129], s[8:9], 0, v[128:129]
	v_lshl_add_u64 v[186:187], v[128:129], 0, v[130:131]
	global_load_dwordx4 v[174:177], v[186:187], off
	global_load_dwordx4 v[180:183], v[186:187], off offset:256
	v_or_b32_e32 v128, 32, v154
	v_ashrrev_i32_e32 v129, 31, v128
	v_lshlrev_b64 v[128:129], 12, v[128:129]
	v_lshl_add_u64 v[128:129], s[8:9], 0, v[128:129]
	v_lshl_add_u64 v[156:157], v[128:129], 0, v[130:131]
	global_load_dwordx4 v[132:135], v[156:157], off
	global_load_dwordx4 v[128:131], v[156:157], off offset:256
	s_waitcnt vmcnt(0)
	v_lshlrev_b32_e32 v188, 16, v166
	v_and_b32_e32 v189, 0xffff0000, v166
	v_lshlrev_b32_e32 v166, 16, v167
	v_and_b32_e32 v167, 0xffff0000, v167
	v_lshlrev_b32_e32 v190, 16, v168
	v_and_b32_e32 v191, 0xffff0000, v168
	v_lshlrev_b32_e32 v168, 16, v169
	v_and_b32_e32 v169, 0xffff0000, v169
	v_lshlrev_b32_e32 v192, 16, v170
	v_and_b32_e32 v193, 0xffff0000, v170
	v_lshlrev_b32_e32 v170, 16, v171
	v_and_b32_e32 v171, 0xffff0000, v171
	v_lshlrev_b32_e32 v194, 16, v172
	v_and_b32_e32 v195, 0xffff0000, v172
	v_lshlrev_b32_e32 v172, 16, v173
	v_and_b32_e32 v173, 0xffff0000, v173
	v_pk_fma_f32 v[126:127], v[126:127], 0.5, v[166:167] op_sel_hi:[1,0,1]
	v_pk_fma_f32 v[124:125], v[124:125], 0.5, v[188:189] op_sel_hi:[1,0,1]
	v_pk_fma_f32 v[122:123], v[122:123], 0.5, v[168:169] op_sel_hi:[1,0,1]
	v_pk_fma_f32 v[166:167], v[120:121], 0.5, v[190:191] op_sel_hi:[1,0,1]
	v_pk_fma_f32 v[168:169], v[118:119], 0.5, v[170:171] op_sel_hi:[1,0,1]
	v_pk_fma_f32 v[170:171], v[116:117], 0.5, v[192:193] op_sel_hi:[1,0,1]
	v_pk_fma_f32 v[172:173], v[114:115], 0.5, v[172:173] op_sel_hi:[1,0,1]
	v_pk_fma_f32 v[188:189], v[112:113], 0.5, v[194:195] op_sel_hi:[1,0,1]
	v_cvt_pk_bf16_f32 v114, v124, v125
	v_cvt_pk_bf16_f32 v115, v126, v127
	v_cvt_pk_bf16_f32 v116, v166, v167
	v_cvt_pk_bf16_f32 v117, v122, v123
	v_mul_f32_e32 v125, v125, v125
	v_mul_f32_e32 v127, v127, v127
	v_mul_f32_e32 v167, v167, v167
	v_mul_f32_e32 v123, v123, v123
	v_cvt_pk_bf16_f32 v118, v170, v171
	v_cvt_pk_bf16_f32 v119, v168, v169
	v_cvt_pk_bf16_f32 v121, v172, v173
	v_mul_f32_e32 v171, v171, v171
	v_mul_f32_e32 v169, v169, v169
	v_mul_f32_e32 v179, v189, v189
	v_mul_f32_e32 v173, v173, v173
	v_lshlrev_b32_e32 v112, 16, v174
	v_and_b32_e32 v113, 0xffff0000, v174
	v_lshlrev_b32_e32 v190, 16, v176
	v_and_b32_e32 v191, 0xffff0000, v176
	v_lshlrev_b32_e32 v176, 16, v177
	v_and_b32_e32 v177, 0xffff0000, v177
	v_fmac_f32_e32 v125, v124, v124
	v_fmac_f32_e32 v127, v126, v126
	v_fmac_f32_e32 v167, v166, v166
	v_fmac_f32_e32 v123, v122, v122
	v_fmac_f32_e32 v171, v170, v170
	v_fmac_f32_e32 v169, v168, v168
	v_fmac_f32_e32 v179, v188, v188
	v_fmac_f32_e32 v173, v172, v172
	v_lshlrev_b32_e32 v174, 16, v175
	v_and_b32_e32 v175, 0xffff0000, v175
	v_pk_fma_f32 v[112:113], v[108:109], 0.5, v[112:113] op_sel_hi:[1,0,1]
	v_pk_fma_f32 v[108:109], v[106:107], 0.5, v[176:177] op_sel_hi:[1,0,1]
	global_store_dwordx4 v[184:185], v[114:117], off
	v_add_f32_e32 v106, v125, v127
	v_add_f32_e32 v107, v167, v123
	v_add_f32_e32 v114, v171, v169
	v_add_f32_e32 v115, v179, v173
	v_pk_fma_f32 v[110:111], v[110:111], 0.5, v[174:175] op_sel_hi:[1,0,1]
	v_add_f32_e32 v106, v106, v107
	v_add_f32_e32 v107, v114, v115
	v_pk_fma_f32 v[114:115], v[104:105], 0.5, v[190:191] op_sel_hi:[1,0,1]
	v_add_f32_e32 v125, v106, v107
	v_cvt_pk_bf16_f32 v104, v112, v113
	v_cvt_pk_bf16_f32 v105, v110, v111
	v_cvt_pk_bf16_f32 v106, v114, v115
	v_cvt_pk_bf16_f32 v107, v108, v109
	v_cvt_pk_bf16_f32 v120, v188, v189
	global_store_dwordx4 v[186:187], v[104:107], off
	global_store_dwordx4 v[184:185], v[118:121], off offset:256
	v_lshlrev_b32_e32 v122, 16, v182
	v_lshlrev_b32_e32 v104, 16, v180
	v_and_b32_e32 v105, 0xffff0000, v180
	v_pk_fma_f32 v[118:119], v[100:101], 0.5, v[104:105] op_sel_hi:[1,0,1]
	v_and_b32_e32 v101, 64, v165
	v_xor_b32_e32 v100, 16, v165
	v_add_u32_e32 v101, 64, v101
	v_cmp_lt_i32_e32 vcc, v100, v101
	v_and_b32_e32 v123, 0xffff0000, v182
	v_pk_fma_f32 v[122:123], v[96:97], 0.5, v[122:123] op_sel_hi:[1,0,1]
	v_cndmask_b32_e32 v100, v165, v100, vcc
	v_lshlrev_b32_e32 v124, 2, v100
	ds_bpermute_b32 v100, v124, v125
	v_xor_b32_e32 v97, 32, v165
	v_cmp_lt_i32_e32 vcc, v97, v101
	v_lshlrev_b32_e32 v106, 16, v181
	v_and_b32_e32 v107, 0xffff0000, v181
	v_cndmask_b32_e32 v97, v165, v97, vcc
	s_waitcnt lgkmcnt(0)
	v_add_f32_e32 v96, v125, v100
	v_lshlrev_b32_e32 v125, 2, v97
	ds_bpermute_b32 v97, v125, v96
	v_lshlrev_b32_e32 v120, 16, v183
	v_and_b32_e32 v121, 0xffff0000, v183
	v_pk_fma_f32 v[116:117], v[102:103], 0.5, v[106:107] op_sel_hi:[1,0,1]
	v_pk_fma_f32 v[120:121], v[98:99], 0.5, v[120:121] op_sel_hi:[1,0,1]
	v_cvt_pk_bf16_f32 v98, v118, v119
	v_cvt_pk_bf16_f32 v99, v116, v117
	v_cvt_pk_bf16_f32 v100, v122, v123
	v_cvt_pk_bf16_f32 v101, v120, v121
	v_lshl_add_u64 v[104:105], v[154:155], 2, s[10:11]
	global_store_dwordx4 v[186:187], v[98:101], off offset:256
	s_and_saveexec_b64 s[14:15], s[2:3]
	s_cbranch_execz .LBB0_367
	s_waitcnt lgkmcnt(0)
	v_add_f32_e32 v96, v96, v97
	global_atomic_add_f32 v[104:105], v96, off

; #define PG8_STAGE(bufoff, gbase, voff) do { _Pragma("unroll") for (int _i = 0; _i < 2; ++_i) \
;         __builtin_amdgcn_global_load_lds((const unsigned*)((const char*)(gbase) + (voff)[_i]), (LAS unsigned*)(lds + (bufoff) + ldsw + _i * 8192), 16, 0, 0); } while (0)
; #define PG8_LDA(dst, b, h) do { _Pragma("unroll") for (int m = 0; m < 4; ++m) _Pragma("unroll") for (int k = 0; k < 2; ++k) dst[m][k] = *(const LAS bf16x8*)(lds + PG8_SA(b, h) + aoff + m * 2048 + k * 1024); } while (0)
; #define PG8_LDB(dst, b, h) do { _Pragma("unroll") for (int n = 0; n < 2; ++n) _Pragma("unroll") for (int k = 0; k < 2; ++k) dst[n][k] = *(const LAS bf16x8*)(lds + PG8_SB(b, h) + boff + n * 2048 + k * 1024); } while (0)
; #define PG8_MMA(ai, bj, At, Bt) do { __builtin_amdgcn_s_setprio(1); _Pragma("unroll") for (int m = 0; m < 4; ++m) _Pragma("unroll") for (int n = 0; n < 2; ++n) _Pragma("unroll") for (int k = 0; k < 2; ++k) \
;         acc[ai][bj][m][n] = __builtin_amdgcn_mfma_f32_16x16x32_bf16(Bt[n][k], At[m][k], acc[ai][bj][m][n], 0, 0, 0); __builtin_amdgcn_s_setprio(0); } while (0)
; #define PG8_WAIT_L(n) asm volatile("s_waitcnt lgkmcnt(" #n ")" ::: "memory")
; #define PG8_BAR __builtin_amdgcn_s_barrier()
; #define PG8_SCHED __builtin_amdgcn_sched_barrier(0)
; template <class Epi>
; __device__ __forceinline__ void gemm_phase(LAS unsigned char* lds, const Gemm g, const StaticOrder& S, const Epi& E) {
;     ...
;         for (int t = 0; t < nt; t += 2) {
;             const bool last = (t == nt - 2);
;             const char* a1 = cA + (size_t)(t + 1) * kstep;
;             const char* a2 = last ? nA : cA + (size_t)(t + 2) * kstep; const char* b2 = last ? nB : cB + (size_t)(t + 2) * kstep;
;             const char* a3 = a2 + kstep; const char* b3 = b2 + kstep;
;             PG8_LDB(B0, 0, 0); PG8_SCHED; PG8_LDA(At, 0, 0); PG8_STAGE(PG8_SA(1, 1), a1 + hstep, voffA);
;             PG8_WAIT_L(8); PG8_BAR; PG8_WAIT_L(0); PG8_MMA(0, 0, At, B0); PG8_BAR; PG8_SCHED;
.LBB0_691:
	ds_read_b128 v[150:153], v167
	ds_read_b128 v[154:157], v167 offset:1024
	ds_read_b128 v[158:161], v167 offset:2048
	ds_read_b128 v[180:183], v167 offset:3072
	s_add_u32 s8, s6, 0xfff80080
	s_addc_u32 s9, s7, -1
	s_cmp_eq_u32 s63, 28
	s_cselect_b32 s11, s1, s9
	s_cselect_b32 s10, s5, s8
	s_cselect_b32 s9, s12, s61
	s_cselect_b32 s8, s13, s33
	v_lshl_add_u64 v[162:163], s[6:7], 0, v[140:141]
	s_add_i32 m0, s74, 0xc000
	ds_read_b128 v[184:187], v168
	ds_read_b128 v[188:191], v168 offset:1024
	ds_read_b128 v[192:195], v168 offset:2048
	ds_read_b128 v[196:199], v168 offset:3072
	ds_read_b128 v[200:203], v168 offset:4096
	ds_read_b128 v[204:207], v168 offset:5120
	ds_read_b128 v[208:211], v168 offset:6144
	ds_read_b128 v[212:215], v168 offset:7168
	global_load_lds_dwordx4 v[162:163], off
	v_lshl_add_u64 v[162:163], s[6:7], 0, v[142:143]
	s_add_i32 m0, s74, 0xe000
	s_nop 0
	global_load_lds_dwordx4 v[162:163], off
	s_waitcnt lgkmcnt(8)
	s_barrier
	s_waitcnt lgkmcnt(0)
	s_setprio 1

; #define PG8_STAGE(bufoff, gbase, voff) do { _Pragma("unroll") for (int _i = 0; _i < 2; ++_i) \
;         __builtin_amdgcn_global_load_lds((const unsigned*)((const char*)(gbase) + (voff)[_i]), (LAS unsigned*)(lds + (bufoff) + ldsw + _i * 8192), 16, 0, 0); } while (0)
; #define PG8_LDB(dst, b, h) do { _Pragma("unroll") for (int n = 0; n < 2; ++n) _Pragma("unroll") for (int k = 0; k < 2; ++k) dst[n][k] = *(const LAS bf16x8*)(lds + PG8_SB(b, h) + boff + n * 2048 + k * 1024); } while (0)
; #define PG8_MMA(ai, bj, At, Bt) do { __builtin_amdgcn_s_setprio(1); _Pragma("unroll") for (int m = 0; m < 4; ++m) _Pragma("unroll") for (int n = 0; n < 2; ++n) _Pragma("unroll") for (int k = 0; k < 2; ++k) \
;         acc[ai][bj][m][n] = __builtin_amdgcn_mfma_f32_16x16x32_bf16(Bt[n][k], At[m][k], acc[ai][bj][m][n], 0, 0, 0); __builtin_amdgcn_s_setprio(0); } while (0)
; #define PG8_WAIT_L(n) asm volatile("s_waitcnt lgkmcnt(" #n ")" ::: "memory")
; #define PG8_BAR __builtin_amdgcn_s_barrier()
; #define PG8_SCHED __builtin_amdgcn_sched_barrier(0)
; template <class Epi>
; __device__ __forceinline__ void gemm_phase(LAS unsigned char* lds, const Gemm g, const StaticOrder& S, const Epi& E) {
;     ...
;             PG8_WAIT_L(8); PG8_BAR; PG8_WAIT_L(0); PG8_MMA(0, 0, At, B0); PG8_BAR; PG8_SCHED;
;             PG8_LDB(B1, 0, 1); PG8_STAGE(PG8_SB(0, 0), b2, voffB);
;             PG8_BAR; PG8_WAIT_L(0); PG8_MMA(0, 1, At, B1); PG8_BAR;
	v_mfma_f32_16x16x32_bf16 v[124:127], v[150:153], v[184:187], v[124:127]
	v_mfma_f32_16x16x32_bf16 v[120:123], v[158:161], v[184:187], v[120:123]
	v_mfma_f32_16x16x32_bf16 v[108:111], v[150:153], v[192:195], v[108:111]
	v_mfma_f32_16x16x32_bf16 v[104:107], v[158:161], v[192:195], v[104:107]
	v_mfma_f32_16x16x32_bf16 v[92:95], v[150:153], v[200:203], v[92:95]
	v_mfma_f32_16x16x32_bf16 v[88:91], v[158:161], v[200:203], v[88:91]
	v_mfma_f32_16x16x32_bf16 v[76:79], v[150:153], v[208:211], v[76:79]
	v_mfma_f32_16x16x32_bf16 v[72:75], v[158:161], v[208:211], v[72:75]
	v_mfma_f32_16x16x32_bf16 v[124:127], v[154:157], v[188:191], v[124:127]
	v_mfma_f32_16x16x32_bf16 v[120:123], v[180:183], v[188:191], v[120:123]
	v_mfma_f32_16x16x32_bf16 v[108:111], v[154:157], v[196:199], v[108:111]
	v_mfma_f32_16x16x32_bf16 v[104:107], v[180:183], v[196:199], v[104:107]
	v_mfma_f32_16x16x32_bf16 v[92:95], v[154:157], v[204:207], v[92:95]
	v_mfma_f32_16x16x32_bf16 v[88:91], v[180:183], v[204:207], v[88:91]
	v_mfma_f32_16x16x32_bf16 v[76:79], v[154:157], v[212:215], v[76:79]
	v_mfma_f32_16x16x32_bf16 v[72:75], v[180:183], v[212:215], v[72:75]
	s_setprio 0
	s_barrier
	s_add_i32 s89, s84, s69
	v_lshl_add_u64 v[162:163], s[8:9], 0, v[130:131]
	s_mov_b32 m0, s89
	ds_read_b128 v[216:219], v169
	ds_read_b128 v[220:223], v169 offset:1024
	ds_read_b128 v[224:227], v169 offset:2048
	ds_read_b128 v[228:231], v169 offset:3072
	global_load_lds_dwordx4 v[162:163], off
	v_lshl_add_u64 v[232:233], s[8:9], 0, v[134:135]
	s_add_i32 m0, s89, 0x2000
	s_nop 0
	global_load_lds_dwordx4 v[232:233], off
	s_barrier
	s_waitcnt lgkmcnt(0)
	s_setprio 1

; #define PG8_STAGE(bufoff, gbase, voff) do { _Pragma("unroll") for (int _i = 0; _i < 2; ++_i) \
;         __builtin_amdgcn_global_load_lds((const unsigned*)((const char*)(gbase) + (voff)[_i]), (LAS unsigned*)(lds + (bufoff) + ldsw + _i * 8192), 16, 0, 0); } while (0)
; #define PG8_LDA(dst, b, h) do { _Pragma("unroll") for (int m = 0; m < 4; ++m) _Pragma("unroll") for (int k = 0; k < 2; ++k) dst[m][k] = *(const LAS bf16x8*)(lds + PG8_SA(b, h) + aoff + m * 2048 + k * 1024); } while (0)
; #define PG8_MMA(ai, bj, At, Bt) do { __builtin_amdgcn_s_setprio(1); _Pragma("unroll") for (int m = 0; m < 4; ++m) _Pragma("unroll") for (int n = 0; n < 2; ++n) _Pragma("unroll") for (int k = 0; k < 2; ++k) \
;         acc[ai][bj][m][n] = __builtin_amdgcn_mfma_f32_16x16x32_bf16(Bt[n][k], At[m][k], acc[ai][bj][m][n], 0, 0, 0); __builtin_amdgcn_s_setprio(0); } while (0)
; #define PG8_WAIT_L(n) asm volatile("s_waitcnt lgkmcnt(" #n ")" ::: "memory")
; #define PG8_BAR __builtin_amdgcn_s_barrier()
; #define PG8_SCHED __builtin_amdgcn_sched_barrier(0)
; template <class Epi>
; __device__ __forceinline__ void gemm_phase(LAS unsigned char* lds, const Gemm g, const StaticOrder& S, const Epi& E) {
;     ...
;             PG8_BAR; PG8_WAIT_L(0); PG8_MMA(0, 1, At, B1); PG8_BAR;
;             PG8_LDA(At, 0, 1); PG8_STAGE(PG8_SA(0, 0), a2, voffA);
;             PG8_BAR; PG8_WAIT_L(0); PG8_MMA(1, 0, At, B0); PG8_BAR; PG8_SCHED;
	v_mfma_f32_16x16x32_bf16 v[116:119], v[216:219], v[184:187], v[116:119]
	v_mfma_f32_16x16x32_bf16 v[112:115], v[224:227], v[184:187], v[112:115]
	v_mfma_f32_16x16x32_bf16 v[100:103], v[216:219], v[192:195], v[100:103]
	v_mfma_f32_16x16x32_bf16 v[96:99], v[224:227], v[192:195], v[96:99]
	v_mfma_f32_16x16x32_bf16 v[84:87], v[216:219], v[200:203], v[84:87]
	v_mfma_f32_16x16x32_bf16 v[80:83], v[224:227], v[200:203], v[80:83]
	v_mfma_f32_16x16x32_bf16 v[68:71], v[216:219], v[208:211], v[68:71]
	v_mfma_f32_16x16x32_bf16 v[64:67], v[224:227], v[208:211], v[64:67]
	v_mfma_f32_16x16x32_bf16 v[116:119], v[220:223], v[188:191], v[116:119]
	v_mfma_f32_16x16x32_bf16 v[112:115], v[228:231], v[188:191], v[112:115]
	v_mfma_f32_16x16x32_bf16 v[100:103], v[220:223], v[196:199], v[100:103]
	v_mfma_f32_16x16x32_bf16 v[96:99], v[228:231], v[196:199], v[96:99]
	v_mfma_f32_16x16x32_bf16 v[84:87], v[220:223], v[204:207], v[84:87]
	v_mfma_f32_16x16x32_bf16 v[80:83], v[228:231], v[204:207], v[80:83]
	v_mfma_f32_16x16x32_bf16 v[68:71], v[220:223], v[212:215], v[68:71]
	v_mfma_f32_16x16x32_bf16 v[64:67], v[228:231], v[212:215], v[64:67]
	s_setprio 0
	s_mov_b32 m0, s74
	v_lshl_add_u64 v[234:235], s[10:11], 0, v[128:129]
	s_barrier
	ds_read_b128 v[184:187], v168 offset:16384
	ds_read_b128 v[188:191], v168 offset:17408
	ds_read_b128 v[192:195], v168 offset:18432
	ds_read_b128 v[196:199], v168 offset:19456
	ds_read_b128 v[200:203], v168 offset:20480
	ds_read_b128 v[204:207], v168 offset:21504
	ds_read_b128 v[208:211], v168 offset:22528
	ds_read_b128 v[212:215], v168 offset:23552
	global_load_lds_dwordx4 v[234:235], off
	v_lshl_add_u64 v[236:237], s[10:11], 0, v[132:133]
	s_mov_b32 m0, s75
	s_nop 0
	global_load_lds_dwordx4 v[236:237], off
	s_barrier
	s_waitcnt lgkmcnt(0)
	s_setprio 1

; #define PG8_STAGE(bufoff, gbase, voff) do { _Pragma("unroll") for (int _i = 0; _i < 2; ++_i) \
;         __builtin_amdgcn_global_load_lds((const unsigned*)((const char*)(gbase) + (voff)[_i]), (LAS unsigned*)(lds + (bufoff) + ldsw + _i * 8192), 16, 0, 0); } while (0)
; #define PG8_LDA(dst, b, h) do { _Pragma("unroll") for (int m = 0; m < 4; ++m) _Pragma("unroll") for (int k = 0; k < 2; ++k) dst[m][k] = *(const LAS bf16x8*)(lds + PG8_SA(b, h) + aoff + m * 2048 + k * 1024); } while (0)
; #define PG8_LDB(dst, b, h) do { _Pragma("unroll") for (int n = 0; n < 2; ++n) _Pragma("unroll") for (int k = 0; k < 2; ++k) dst[n][k] = *(const LAS bf16x8*)(lds + PG8_SB(b, h) + boff + n * 2048 + k * 1024); } while (0)
; #define PG8_MMA(ai, bj, At, Bt) do { __builtin_amdgcn_s_setprio(1); _Pragma("unroll") for (int m = 0; m < 4; ++m) _Pragma("unroll") for (int n = 0; n < 2; ++n) _Pragma("unroll") for (int k = 0; k < 2; ++k) \
;         acc[ai][bj][m][n] = __builtin_amdgcn_mfma_f32_16x16x32_bf16(Bt[n][k], At[m][k], acc[ai][bj][m][n], 0, 0, 0); __builtin_amdgcn_s_setprio(0); } while (0)
; #define PG8_WAIT_V(n) asm volatile("s_waitcnt vmcnt(" #n ")" ::: "memory")
; #define PG8_WAIT_L(n) asm volatile("s_waitcnt lgkmcnt(" #n ")" ::: "memory")
; #define PG8_BAR __builtin_amdgcn_s_barrier()
; #define PG8_SCHED __builtin_amdgcn_sched_barrier(0)
; template <class Epi>
; __device__ __forceinline__ void gemm_phase(LAS unsigned char* lds, const Gemm g, const StaticOrder& S, const Epi& E) {
;     ...
;             PG8_BAR; PG8_WAIT_L(0); PG8_MMA(1, 0, At, B0); PG8_BAR; PG8_SCHED;
;             PG8_STAGE(PG8_SB(0, 1), b2 + hstep, voffB);
;             PG8_WAIT_V(6); PG8_BAR; PG8_MMA(1, 1, At, B1); PG8_BAR;
;             PG8_LDB(B0, 1, 0); PG8_SCHED; PG8_LDA(At, 1, 0); PG8_STAGE(PG8_SA(0, 1), a2 + hstep, voffA);
;             PG8_WAIT_L(8); PG8_BAR; PG8_WAIT_L(0); PG8_MMA(0, 0, At, B0); PG8_BAR; PG8_SCHED;
	v_mfma_f32_16x16x32_bf16 v[60:63], v[150:153], v[184:187], v[60:63]
	v_mfma_f32_16x16x32_bf16 v[56:59], v[158:161], v[184:187], v[56:59]
	v_mfma_f32_16x16x32_bf16 v[44:47], v[150:153], v[192:195], v[44:47]
	v_mfma_f32_16x16x32_bf16 v[40:43], v[158:161], v[192:195], v[40:43]
	v_mfma_f32_16x16x32_bf16 v[28:31], v[150:153], v[200:203], v[28:31]
	v_mfma_f32_16x16x32_bf16 v[24:27], v[158:161], v[200:203], v[24:27]
	v_mfma_f32_16x16x32_bf16 v[12:15], v[150:153], v[208:211], v[12:15]
	v_mfma_f32_16x16x32_bf16 v[8:11], v[158:161], v[208:211], v[8:11]
	v_mfma_f32_16x16x32_bf16 v[60:63], v[154:157], v[188:191], v[60:63]
	v_mfma_f32_16x16x32_bf16 v[56:59], v[180:183], v[188:191], v[56:59]
	v_mfma_f32_16x16x32_bf16 v[44:47], v[154:157], v[196:199], v[44:47]
	v_mfma_f32_16x16x32_bf16 v[40:43], v[180:183], v[196:199], v[40:43]
	v_mfma_f32_16x16x32_bf16 v[28:31], v[154:157], v[204:207], v[28:31]
	v_mfma_f32_16x16x32_bf16 v[24:27], v[180:183], v[204:207], v[24:27]
	v_mfma_f32_16x16x32_bf16 v[12:15], v[154:157], v[212:215], v[12:15]
	v_mfma_f32_16x16x32_bf16 v[8:11], v[180:183], v[212:215], v[8:11]
	s_setprio 0
	s_barrier
	s_add_u32 s90, s8, 0x80000
	s_addc_u32 s91, s9, 0
	s_add_i32 s89, s85, s69
	v_lshl_add_u64 v[150:151], s[90:91], 0, v[130:131]
	s_mov_b32 m0, s89
	s_nop 0
	global_load_lds_dwordx4 v[150:151], off
	v_lshl_add_u64 v[150:151], s[90:91], 0, v[134:135]
	s_add_i32 m0, s89, 0x2000
	s_nop 0
	global_load_lds_dwordx4 v[150:151], off
	s_waitcnt vmcnt(6)
	s_barrier
	s_setprio 1
	v_mfma_f32_16x16x32_bf16 v[52:55], v[216:219], v[184:187], v[52:55]
	v_mfma_f32_16x16x32_bf16 v[48:51], v[224:227], v[184:187], v[48:51]
	v_mfma_f32_16x16x32_bf16 v[36:39], v[216:219], v[192:195], v[36:39]
	v_mfma_f32_16x16x32_bf16 v[32:35], v[224:227], v[192:195], v[32:35]
	v_mfma_f32_16x16x32_bf16 v[20:23], v[216:219], v[200:203], v[20:23]
	v_mfma_f32_16x16x32_bf16 v[16:19], v[224:227], v[200:203], v[16:19]
	v_mfma_f32_16x16x32_bf16 v[4:7], v[216:219], v[208:211], v[4:7]
	v_mfma_f32_16x16x32_bf16 v[0:3], v[224:227], v[208:211], v[0:3]
	v_mfma_f32_16x16x32_bf16 v[52:55], v[220:223], v[188:191], v[52:55]
	v_mfma_f32_16x16x32_bf16 v[48:51], v[228:231], v[188:191], v[48:51]
	v_mfma_f32_16x16x32_bf16 v[36:39], v[220:223], v[196:199], v[36:39]
	v_mfma_f32_16x16x32_bf16 v[32:35], v[228:231], v[196:199], v[32:35]
	v_mfma_f32_16x16x32_bf16 v[20:23], v[220:223], v[204:207], v[20:23]
	v_mfma_f32_16x16x32_bf16 v[16:19], v[228:231], v[204:207], v[16:19]
	v_mfma_f32_16x16x32_bf16 v[4:7], v[220:223], v[212:215], v[4:7]
	v_mfma_f32_16x16x32_bf16 v[0:3], v[228:231], v[212:215], v[0:3]
	s_setprio 0
	s_add_i32 s89, 0, 0x18000
	v_add_u32_e32 v138, s89, v165
	s_barrier
	ds_read_b128 v[150:153], v138
	ds_read_b128 v[154:157], v138 offset:1024
	ds_read_b128 v[158:161], v138 offset:2048
	ds_read_b128 v[180:183], v138 offset:3072
	s_add_u32 s10, s10, 0x80000
	s_addc_u32 s11, s11, 0
	s_mov_b32 m0, s76
	v_lshl_add_u64 v[216:217], s[10:11], 0, v[128:129]
	ds_read_b128 v[184:187], v168 offset:32768
	ds_read_b128 v[188:191], v168 offset:33792
	ds_read_b128 v[192:195], v168 offset:34816
	ds_read_b128 v[196:199], v168 offset:35840
	ds_read_b128 v[200:203], v168 offset:36864
	ds_read_b128 v[204:207], v168 offset:37888
	ds_read_b128 v[208:211], v168 offset:38912
	ds_read_b128 v[212:215], v168 offset:39936
	global_load_lds_dwordx4 v[216:217], off
	v_lshl_add_u64 v[216:217], s[10:11], 0, v[132:133]
	s_mov_b32 m0, s77
	s_nop 0
	global_load_lds_dwordx4 v[216:217], off
	s_waitcnt lgkmcnt(8)
	s_barrier
	s_waitcnt lgkmcnt(0)
	s_setprio 1

; #define PG8_STAGE(bufoff, gbase, voff) do { _Pragma("unroll") for (int _i = 0; _i < 2; ++_i) \
;         __builtin_amdgcn_global_load_lds((const unsigned*)((const char*)(gbase) + (voff)[_i]), (LAS unsigned*)(lds + (bufoff) + ldsw + _i * 8192), 16, 0, 0); } while (0)
; #define PG8_LDB(dst, b, h) do { _Pragma("unroll") for (int n = 0; n < 2; ++n) _Pragma("unroll") for (int k = 0; k < 2; ++k) dst[n][k] = *(const LAS bf16x8*)(lds + PG8_SB(b, h) + boff + n * 2048 + k * 1024); } while (0)
; #define PG8_MMA(ai, bj, At, Bt) do { __builtin_amdgcn_s_setprio(1); _Pragma("unroll") for (int m = 0; m < 4; ++m) _Pragma("unroll") for (int n = 0; n < 2; ++n) _Pragma("unroll") for (int k = 0; k < 2; ++k) \
;         acc[ai][bj][m][n] = __builtin_amdgcn_mfma_f32_16x16x32_bf16(Bt[n][k], At[m][k], acc[ai][bj][m][n], 0, 0, 0); __builtin_amdgcn_s_setprio(0); } while (0)
; #define PG8_WAIT_L(n) asm volatile("s_waitcnt lgkmcnt(" #n ")" ::: "memory")
; #define PG8_BAR __builtin_amdgcn_s_barrier()
; #define PG8_SCHED __builtin_amdgcn_sched_barrier(0)
; template <class Epi>
; __device__ __forceinline__ void gemm_phase(LAS unsigned char* lds, const Gemm g, const StaticOrder& S, const Epi& E) {
;     ...
;             PG8_WAIT_L(8); PG8_BAR; PG8_WAIT_L(0); PG8_MMA(0, 0, At, B0); PG8_BAR; PG8_SCHED;
;             PG8_LDB(B1, 1, 1); PG8_STAGE(PG8_SB(1, 0), b3, voffB);
;             PG8_BAR; PG8_WAIT_L(0); PG8_MMA(0, 1, At, B1); PG8_BAR;
	v_mfma_f32_16x16x32_bf16 v[124:127], v[150:153], v[184:187], v[124:127]
	v_mfma_f32_16x16x32_bf16 v[120:123], v[158:161], v[184:187], v[120:123]
	v_mfma_f32_16x16x32_bf16 v[108:111], v[150:153], v[192:195], v[108:111]
	v_mfma_f32_16x16x32_bf16 v[104:107], v[158:161], v[192:195], v[104:107]
	v_mfma_f32_16x16x32_bf16 v[92:95], v[150:153], v[200:203], v[92:95]
	v_mfma_f32_16x16x32_bf16 v[88:91], v[158:161], v[200:203], v[88:91]
	v_mfma_f32_16x16x32_bf16 v[76:79], v[150:153], v[208:211], v[76:79]
	v_mfma_f32_16x16x32_bf16 v[72:75], v[158:161], v[208:211], v[72:75]
	v_mfma_f32_16x16x32_bf16 v[124:127], v[154:157], v[188:191], v[124:127]
	v_mfma_f32_16x16x32_bf16 v[120:123], v[180:183], v[188:191], v[120:123]
	v_mfma_f32_16x16x32_bf16 v[108:111], v[154:157], v[196:199], v[108:111]
	v_mfma_f32_16x16x32_bf16 v[104:107], v[180:183], v[196:199], v[104:107]
	v_mfma_f32_16x16x32_bf16 v[92:95], v[154:157], v[204:207], v[92:95]
	v_mfma_f32_16x16x32_bf16 v[88:91], v[180:183], v[204:207], v[88:91]
	v_mfma_f32_16x16x32_bf16 v[76:79], v[154:157], v[212:215], v[76:79]
	v_mfma_f32_16x16x32_bf16 v[72:75], v[180:183], v[212:215], v[72:75]
	s_setprio 0
	s_barrier
	s_add_i32 s10, 0, 0x1c000
	s_add_i32 s11, s89, s69
	v_add_u32_e32 v138, s10, v165
	v_lshl_add_u64 v[162:163], v[162:163], 0, s[34:35]
	s_mov_b32 m0, s11
	ds_read_b128 v[216:219], v138
	ds_read_b128 v[220:223], v138 offset:1024
	ds_read_b128 v[224:227], v138 offset:2048
	ds_read_b128 v[228:231], v138 offset:3072
	global_load_lds_dwordx4 v[162:163], off
	v_lshl_add_u64 v[162:163], v[232:233], 0, s[34:35]
	s_add_i32 m0, s11, 0x2000
	s_nop 0
	global_load_lds_dwordx4 v[162:163], off
	s_barrier
	s_waitcnt lgkmcnt(0)
	s_setprio 1

; #define PG8_STAGE(bufoff, gbase, voff) do { _Pragma("unroll") for (int _i = 0; _i < 2; ++_i) \
;         __builtin_amdgcn_global_load_lds((const unsigned*)((const char*)(gbase) + (voff)[_i]), (LAS unsigned*)(lds + (bufoff) + ldsw + _i * 8192), 16, 0, 0); } while (0)
; #define PG8_LDA(dst, b, h) do { _Pragma("unroll") for (int m = 0; m < 4; ++m) _Pragma("unroll") for (int k = 0; k < 2; ++k) dst[m][k] = *(const LAS bf16x8*)(lds + PG8_SA(b, h) + aoff + m * 2048 + k * 1024); } while (0)
; #define PG8_MMA(ai, bj, At, Bt) do { __builtin_amdgcn_s_setprio(1); _Pragma("unroll") for (int m = 0; m < 4; ++m) _Pragma("unroll") for (int n = 0; n < 2; ++n) _Pragma("unroll") for (int k = 0; k < 2; ++k) \
;         acc[ai][bj][m][n] = __builtin_amdgcn_mfma_f32_16x16x32_bf16(Bt[n][k], At[m][k], acc[ai][bj][m][n], 0, 0, 0); __builtin_amdgcn_s_setprio(0); } while (0)
; #define PG8_WAIT_L(n) asm volatile("s_waitcnt lgkmcnt(" #n ")" ::: "memory")
; #define PG8_BAR __builtin_amdgcn_s_barrier()
; #define PG8_SCHED __builtin_amdgcn_sched_barrier(0)
; template <class Epi>
; __device__ __forceinline__ void gemm_phase(LAS unsigned char* lds, const Gemm g, const StaticOrder& S, const Epi& E) {
;     ...
;             PG8_BAR; PG8_WAIT_L(0); PG8_MMA(0, 1, At, B1); PG8_BAR;
;             PG8_LDA(At, 1, 1); PG8_STAGE(PG8_SA(1, 0), a3, voffA);
;             PG8_BAR; PG8_WAIT_L(0); PG8_MMA(1, 0, At, B0); PG8_BAR; PG8_SCHED;
	v_mfma_f32_16x16x32_bf16 v[116:119], v[216:219], v[184:187], v[116:119]
	v_mfma_f32_16x16x32_bf16 v[112:115], v[224:227], v[184:187], v[112:115]
	v_mfma_f32_16x16x32_bf16 v[100:103], v[216:219], v[192:195], v[100:103]
	v_mfma_f32_16x16x32_bf16 v[96:99], v[224:227], v[192:195], v[96:99]
	v_mfma_f32_16x16x32_bf16 v[84:87], v[216:219], v[200:203], v[84:87]
	v_mfma_f32_16x16x32_bf16 v[80:83], v[224:227], v[200:203], v[80:83]
	v_mfma_f32_16x16x32_bf16 v[68:71], v[216:219], v[208:211], v[68:71]
	v_mfma_f32_16x16x32_bf16 v[64:67], v[224:227], v[208:211], v[64:67]
	v_mfma_f32_16x16x32_bf16 v[116:119], v[220:223], v[188:191], v[116:119]
	v_mfma_f32_16x16x32_bf16 v[112:115], v[228:231], v[188:191], v[112:115]
	v_mfma_f32_16x16x32_bf16 v[100:103], v[220:223], v[196:199], v[100:103]
	v_mfma_f32_16x16x32_bf16 v[96:99], v[228:231], v[196:199], v[96:99]
	v_mfma_f32_16x16x32_bf16 v[84:87], v[220:223], v[204:207], v[84:87]
	v_mfma_f32_16x16x32_bf16 v[80:83], v[228:231], v[204:207], v[80:83]
	v_mfma_f32_16x16x32_bf16 v[68:71], v[220:223], v[212:215], v[68:71]
	v_mfma_f32_16x16x32_bf16 v[64:67], v[228:231], v[212:215], v[64:67]
	s_setprio 0
	s_mov_b32 m0, s79
	v_lshl_add_u64 v[162:163], v[234:235], 0, s[34:35]
	s_barrier
	ds_read_b128 v[184:187], v168 offset:49152
	ds_read_b128 v[188:191], v168 offset:50176
	ds_read_b128 v[192:195], v168 offset:51200
	ds_read_b128 v[196:199], v168 offset:52224
	ds_read_b128 v[200:203], v168 offset:53248
	ds_read_b128 v[204:207], v168 offset:54272
	ds_read_b128 v[208:211], v168 offset:55296
	ds_read_b128 v[212:215], v168 offset:56320
	global_load_lds_dwordx4 v[162:163], off
	v_lshl_add_u64 v[162:163], v[236:237], 0, s[34:35]
	s_mov_b32 m0, s80
	s_nop 0
	global_load_lds_dwordx4 v[162:163], off
	s_barrier
	s_waitcnt lgkmcnt(0)
	s_setprio 1

; __device__ __forceinline__ float sigmoidf_(float x) { return __builtin_amdgcn_rcpf(1.0f + fexp(-x)); }
; #define PG8_STAGE(bufoff, gbase, voff) do { _Pragma("unroll") for (int _i = 0; _i < 2; ++_i) \
;         __builtin_amdgcn_global_load_lds((const unsigned*)((const char*)(gbase) + (voff)[_i]), (LAS unsigned*)(lds + (bufoff) + ldsw + _i * 8192), 16, 0, 0); } while (0)
; #define PG8_MMA(ai, bj, At, Bt) do { __builtin_amdgcn_s_setprio(1); _Pragma("unroll") for (int m = 0; m < 4; ++m) _Pragma("unroll") for (int n = 0; n < 2; ++n) _Pragma("unroll") for (int k = 0; k < 2; ++k) \
;         acc[ai][bj][m][n] = __builtin_amdgcn_mfma_f32_16x16x32_bf16(Bt[n][k], At[m][k], acc[ai][bj][m][n], 0, 0, 0); __builtin_amdgcn_s_setprio(0); } while (0)
; #define PG8_WAIT_V(n) asm volatile("s_waitcnt vmcnt(" #n ")" ::: "memory")
; template <class Epi>
; __device__ __forceinline__ void gemm_phase(LAS unsigned char* lds, const Gemm g, const StaticOrder& S, const Epi& E) {
;     ...
;             PG8_BAR; PG8_WAIT_L(0); PG8_MMA(1, 0, At, B0); PG8_BAR; PG8_SCHED;
;             PG8_STAGE(PG8_SB(1, 1), b3 + hstep, voffB);
;             PG8_WAIT_V(6); PG8_BAR; PG8_MMA(1, 1, At, B1); PG8_BAR;
;     __device__ __forceinline__ void operator()(const f32x4 (&acc)[2][2][4][2], const Unit& u, int wr, int wc, int fr, int fq, const Pre& P) const {
;         const int sec = u.pn >> 3, row0 = ROW_X + u.pm * BM + wr * 64 + fr, colb = (u.pn & 7) * BM + wc * 32 + 8 * fq;
; #pragma unroll
;         for (int ai = 0; ai < 2; ++ai)
; #pragma unroll
;             for (int m = 0; m < 4; ++m) { const int r = row0 + ai * HALF + m * 16; const float rs = __builtin_amdgcn_rsqf(P.rs[ai * 4 + m] * (1.0f / DM) + RMS_EPS);
; #pragma unroll
;                 for (int bj = 0; bj < 2; ++bj) { const int c = colb + bj * HALF; const size_t off = (size_t)r * DM + c; float x[8], y[8];
; #pragma unroll
;                     for (int n = 0; n < 2; ++n)
; #pragma unroll
;                         for (int j = 0; j < 4; ++j) x[n * 4 + j] = acc[ai][bj][m][n][j] * rs;
;                     bf16_t* dst;
;                     if (sec == 0) { dst = QB;
; #pragma unroll
;                         for (int j = 0; j < 8; ++j) y[j] = x[j] * sigmoidf_(x[j]); }
;                     else if (sec == 1) { dst = KB; const f32x4 l0 = *(const f32x4*)(LBv + c), l1 = *(const f32x4*)(LBv + c + 4); float lf[8];
	v_mfma_f32_16x16x32_bf16 v[60:63], v[150:153], v[184:187], v[60:63]
	v_mfma_f32_16x16x32_bf16 v[56:59], v[158:161], v[184:187], v[56:59]
	v_mfma_f32_16x16x32_bf16 v[44:47], v[150:153], v[192:195], v[44:47]
	v_mfma_f32_16x16x32_bf16 v[40:43], v[158:161], v[192:195], v[40:43]
	v_mfma_f32_16x16x32_bf16 v[28:31], v[150:153], v[200:203], v[28:31]
	v_mfma_f32_16x16x32_bf16 v[24:27], v[158:161], v[200:203], v[24:27]
	v_mfma_f32_16x16x32_bf16 v[12:15], v[150:153], v[208:211], v[12:15]
	v_mfma_f32_16x16x32_bf16 v[8:11], v[158:161], v[208:211], v[8:11]
	v_mfma_f32_16x16x32_bf16 v[60:63], v[154:157], v[188:191], v[60:63]
	v_mfma_f32_16x16x32_bf16 v[56:59], v[180:183], v[188:191], v[56:59]
	v_mfma_f32_16x16x32_bf16 v[44:47], v[154:157], v[196:199], v[44:47]
	v_mfma_f32_16x16x32_bf16 v[40:43], v[180:183], v[196:199], v[40:43]
	v_mfma_f32_16x16x32_bf16 v[28:31], v[154:157], v[204:207], v[28:31]
	v_mfma_f32_16x16x32_bf16 v[24:27], v[180:183], v[204:207], v[24:27]
	v_mfma_f32_16x16x32_bf16 v[12:15], v[154:157], v[212:215], v[12:15]
	v_mfma_f32_16x16x32_bf16 v[8:11], v[180:183], v[212:215], v[8:11]
	s_setprio 0
	s_barrier
	s_add_u32 s8, s8, 0x80080
	s_addc_u32 s9, s9, 0
	s_add_i32 s10, s10, s69
	v_lshl_add_u64 v[150:151], s[8:9], 0, v[130:131]
	s_mov_b32 m0, s10
	s_nop 0
	global_load_lds_dwordx4 v[150:151], off
	v_lshl_add_u64 v[150:151], s[8:9], 0, v[134:135]
	s_add_i32 m0, s10, 0x2000
	s_nop 0
	global_load_lds_dwordx4 v[150:151], off
	s_waitcnt vmcnt(6)
	s_barrier
	s_setprio 1
	v_mfma_f32_16x16x32_bf16 v[52:55], v[216:219], v[184:187], v[52:55]
	v_mfma_f32_16x16x32_bf16 v[48:51], v[224:227], v[184:187], v[48:51]
	v_mfma_f32_16x16x32_bf16 v[36:39], v[216:219], v[192:195], v[36:39]
	v_mfma_f32_16x16x32_bf16 v[32:35], v[224:227], v[192:195], v[32:35]
	v_mfma_f32_16x16x32_bf16 v[20:23], v[216:219], v[200:203], v[20:23]
	v_mfma_f32_16x16x32_bf16 v[16:19], v[224:227], v[200:203], v[16:19]
	v_mfma_f32_16x16x32_bf16 v[4:7], v[216:219], v[208:211], v[4:7]
	v_mfma_f32_16x16x32_bf16 v[0:3], v[224:227], v[208:211], v[0:3]
	v_mfma_f32_16x16x32_bf16 v[52:55], v[220:223], v[188:191], v[52:55]
	v_mfma_f32_16x16x32_bf16 v[48:51], v[228:231], v[188:191], v[48:51]
	v_mfma_f32_16x16x32_bf16 v[36:39], v[220:223], v[196:199], v[36:39]
	v_mfma_f32_16x16x32_bf16 v[32:35], v[228:231], v[196:199], v[32:35]
	v_mfma_f32_16x16x32_bf16 v[20:23], v[220:223], v[204:207], v[20:23]
	v_mfma_f32_16x16x32_bf16 v[16:19], v[228:231], v[204:207], v[16:19]
	v_mfma_f32_16x16x32_bf16 v[4:7], v[220:223], v[212:215], v[4:7]
	v_mfma_f32_16x16x32_bf16 v[0:3], v[228:231], v[212:215], v[0:3]
	s_setprio 0
	s_add_i32 s63, s63, 2
	s_add_u32 s6, s6, 0x100
	s_addc_u32 s7, s7, 0
	s_add_u32 s33, s33, 0x100
	s_addc_u32 s61, s61, 0
	s_cmp_gt_u32 s63, 29
	s_barrier
	s_cbranch_scc0 .LBB0_691
	v_fmamk_f32 v149, v149, 0x3a000000, v170
	s_lshl_b32 s1, s0, 8
	v_rsq_f32_e32 v152, v149
	s_ashr_i32 s61, s0, 3
	v_lshl_add_u32 v148, s4, 8, v137
	s_and_b32 s1, s1, 0x700
	s_cmp_gt_u32 s0, 7
	v_ashrrev_i32_e32 v149, 31, v148
	v_or_b32_e32 v138, s1, v166
	v_lshlrev_b32_e32 v254, 2, v138
	global_load_dwordx4 v[238:241], v254, s[24:25]
	global_load_dwordx4 v[242:245], v254, s[24:25] offset:16
	global_load_dwordx4 v[246:249], v254, s[24:25] offset:512
	global_load_dwordx4 v[250:253], v254, s[24:25] offset:528
	s_cselect_b64 s[12:13], -1, 0
	v_lshlrev_b64 v[150:151], 11, v[148:149]
	v_pk_mul_f32 v[124:125], v[152:153], v[124:125] op_sel_hi:[0,1]
	v_pk_mul_f32 v[126:127], v[152:153], v[126:127] op_sel_hi:[0,1]
	v_pk_mul_f32 v[154:155], v[152:153], v[120:121] op_sel_hi:[0,1]
	v_pk_mul_f32 v[122:123], v[152:153], v[122:123] op_sel_hi:[0,1]
	v_or_b32_e32 v120, v150, v138
	v_mov_b32_e32 v121, v151
	s_mov_b64 s[0:1], -1
	s_and_b64 vcc, exec, s[12:13]
	s_cbranch_vccz .LBB0_704
	s_mov_b64 s[6:7], -1
	s_mov_b64 s[0:1], 0
	s_cmp_lt_i32 s61, 2
	s_mov_b64 s[4:5], 0
	s_cbranch_scc1 .LBB0_699
	s_cmp_eq_u32 s61, 2
	s_mov_b64 s[4:5], -1
	s_cbranch_scc0 .LBB0_696
	s_mov_b64 s[4:5], 0
	v_mov_b32_e32 v161, v123
	v_mov_b32_e32 v160, v122
	v_mov_b32_e32 v163, v155
	v_mov_b32_e32 v162, v154
	v_mov_b32_e32 v157, v127
	v_mov_b32_e32 v156, v126
	v_mov_b32_e32 v159, v125
	v_mov_b32_e32 v158, v124

; #define PG8_STAGE(bufoff, gbase, voff) do { _Pragma("unroll") for (int _i = 0; _i < 2; ++_i) \
;         __builtin_amdgcn_global_load_lds((const unsigned*)((const char*)(gbase) + (voff)[_i]), (LAS unsigned*)(lds + (bufoff) + ldsw + _i * 8192), 16, 0, 0); } while (0)
; #define PG8_LDA(dst, b, h) do { _Pragma("unroll") for (int m = 0; m < 4; ++m) _Pragma("unroll") for (int k = 0; k < 2; ++k) dst[m][k] = *(const LAS bf16x8*)(lds + PG8_SA(b, h) + aoff + m * 2048 + k * 1024); } while (0)
; #define PG8_LDB(dst, b, h) do { _Pragma("unroll") for (int n = 0; n < 2; ++n) _Pragma("unroll") for (int k = 0; k < 2; ++k) dst[n][k] = *(const LAS bf16x8*)(lds + PG8_SB(b, h) + boff + n * 2048 + k * 1024); } while (0)
; #define PG8_MMA(ai, bj, At, Bt) do { __builtin_amdgcn_s_setprio(1); _Pragma("unroll") for (int m = 0; m < 4; ++m) _Pragma("unroll") for (int n = 0; n < 2; ++n) _Pragma("unroll") for (int k = 0; k < 2; ++k) \
;         acc[ai][bj][m][n] = __builtin_amdgcn_mfma_f32_16x16x32_bf16(Bt[n][k], At[m][k], acc[ai][bj][m][n], 0, 0, 0); __builtin_amdgcn_s_setprio(0); } while (0)
; #define PG8_WAIT_L(n) asm volatile("s_waitcnt lgkmcnt(" #n ")" ::: "memory")
; #define PG8_BAR __builtin_amdgcn_s_barrier()
; #define PG8_SCHED __builtin_amdgcn_sched_barrier(0)
; template <class Epi>
; __device__ __forceinline__ void gemm_phase(LAS unsigned char* lds, const Gemm g, const StaticOrder& S, const Epi& E) {
;     ...
;         for (int t = 0; t < nt; t += 2) {
;             const bool last = (t == nt - 2);
;             const char* a1 = cA + (size_t)(t + 1) * kstep;
;             const char* a2 = last ? nA : cA + (size_t)(t + 2) * kstep; const char* b2 = last ? nB : cB + (size_t)(t + 2) * kstep;
;             const char* a3 = a2 + kstep; const char* b3 = b2 + kstep;
;             PG8_LDB(B0, 0, 0); PG8_SCHED; PG8_LDA(At, 0, 0); PG8_STAGE(PG8_SA(1, 1), a1 + hstep, voffA);
;             PG8_WAIT_L(8); PG8_BAR; PG8_WAIT_L(0); PG8_MMA(0, 0, At, B0); PG8_BAR; PG8_SCHED;
.LBB0_1220:
	ds_read_b128 v[128:131], v162
	ds_read_b128 v[132:135], v162 offset:1024
	ds_read_b128 v[154:157], v162 offset:2048
	ds_read_b128 v[168:171], v162 offset:3072
	s_add_u32 s24, s22, 0xfff80080
	s_addc_u32 s25, s23, -1
	s_cmp_eq_u32 s67, 28
	s_cselect_b32 s31, s13, s25
	s_cselect_b32 s30, s19, s24
	s_cselect_b32 s25, s11, s66
	s_cselect_b32 s24, s64, s65
	v_lshl_add_u64 v[158:159], s[22:23], 0, v[146:147]
	s_add_i32 m0, s21, 0xc000
	ds_read_b128 v[172:175], v163
	ds_read_b128 v[180:183], v163 offset:1024
	ds_read_b128 v[184:187], v163 offset:2048
	ds_read_b128 v[188:191], v163 offset:3072
	ds_read_b128 v[192:195], v163 offset:4096
	ds_read_b128 v[196:199], v163 offset:5120
	ds_read_b128 v[200:203], v163 offset:6144
	ds_read_b128 v[204:207], v163 offset:7168
	global_load_lds_dwordx4 v[158:159], off
	v_lshl_add_u64 v[158:159], s[22:23], 0, v[148:149]
	s_add_i32 m0, s21, 0xe000
	s_nop 0
	global_load_lds_dwordx4 v[158:159], off
	s_waitcnt lgkmcnt(8)
	s_barrier
	s_waitcnt lgkmcnt(0)
	s_setprio 1

; #define PG8_STAGE(bufoff, gbase, voff) do { _Pragma("unroll") for (int _i = 0; _i < 2; ++_i) \
;         __builtin_amdgcn_global_load_lds((const unsigned*)((const char*)(gbase) + (voff)[_i]), (LAS unsigned*)(lds + (bufoff) + ldsw + _i * 8192), 16, 0, 0); } while (0)
; #define PG8_LDB(dst, b, h) do { _Pragma("unroll") for (int n = 0; n < 2; ++n) _Pragma("unroll") for (int k = 0; k < 2; ++k) dst[n][k] = *(const LAS bf16x8*)(lds + PG8_SB(b, h) + boff + n * 2048 + k * 1024); } while (0)
; #define PG8_MMA(ai, bj, At, Bt) do { __builtin_amdgcn_s_setprio(1); _Pragma("unroll") for (int m = 0; m < 4; ++m) _Pragma("unroll") for (int n = 0; n < 2; ++n) _Pragma("unroll") for (int k = 0; k < 2; ++k) \
;         acc[ai][bj][m][n] = __builtin_amdgcn_mfma_f32_16x16x32_bf16(Bt[n][k], At[m][k], acc[ai][bj][m][n], 0, 0, 0); __builtin_amdgcn_s_setprio(0); } while (0)
; #define PG8_WAIT_L(n) asm volatile("s_waitcnt lgkmcnt(" #n ")" ::: "memory")
; #define PG8_BAR __builtin_amdgcn_s_barrier()
; #define PG8_SCHED __builtin_amdgcn_sched_barrier(0)
; template <class Epi>
; __device__ __forceinline__ void gemm_phase(LAS unsigned char* lds, const Gemm g, const StaticOrder& S, const Epi& E) {
;     ...
;             PG8_WAIT_L(8); PG8_BAR; PG8_WAIT_L(0); PG8_MMA(0, 0, At, B0); PG8_BAR; PG8_SCHED;
;             PG8_LDB(B1, 0, 1); PG8_STAGE(PG8_SB(0, 0), b2, voffB);
;             PG8_BAR; PG8_WAIT_L(0); PG8_MMA(0, 1, At, B1); PG8_BAR;
	v_mfma_f32_16x16x32_bf16 v[124:127], v[128:131], v[172:175], v[124:127]
	v_mfma_f32_16x16x32_bf16 v[120:123], v[154:157], v[172:175], v[120:123]
	v_mfma_f32_16x16x32_bf16 v[108:111], v[128:131], v[184:187], v[108:111]
	v_mfma_f32_16x16x32_bf16 v[104:107], v[154:157], v[184:187], v[104:107]
	v_mfma_f32_16x16x32_bf16 v[92:95], v[128:131], v[192:195], v[92:95]
	v_mfma_f32_16x16x32_bf16 v[88:91], v[154:157], v[192:195], v[88:91]
	v_mfma_f32_16x16x32_bf16 v[76:79], v[128:131], v[200:203], v[76:79]
	v_mfma_f32_16x16x32_bf16 v[72:75], v[154:157], v[200:203], v[72:75]
	v_mfma_f32_16x16x32_bf16 v[124:127], v[132:135], v[180:183], v[124:127]
	v_mfma_f32_16x16x32_bf16 v[120:123], v[168:171], v[180:183], v[120:123]
	v_mfma_f32_16x16x32_bf16 v[108:111], v[132:135], v[188:191], v[108:111]
	v_mfma_f32_16x16x32_bf16 v[104:107], v[168:171], v[188:191], v[104:107]
	v_mfma_f32_16x16x32_bf16 v[92:95], v[132:135], v[196:199], v[92:95]
	v_mfma_f32_16x16x32_bf16 v[88:91], v[168:171], v[196:199], v[88:91]
	v_mfma_f32_16x16x32_bf16 v[76:79], v[132:135], v[204:207], v[76:79]
	v_mfma_f32_16x16x32_bf16 v[72:75], v[168:171], v[204:207], v[72:75]
	s_setprio 0
	s_barrier
	s_add_i32 s68, s62, s36
	v_lshl_add_u64 v[158:159], s[24:25], 0, v[140:141]
	s_mov_b32 m0, s68
	ds_read_b128 v[208:211], v165
	ds_read_b128 v[212:215], v165 offset:1024
	ds_read_b128 v[216:219], v165 offset:2048
	ds_read_b128 v[220:223], v165 offset:3072
	global_load_lds_dwordx4 v[158:159], off
	v_lshl_add_u64 v[176:177], s[24:25], 0, v[144:145]
	s_add_i32 m0, s68, 0x2000
	s_nop 0
	global_load_lds_dwordx4 v[176:177], off
	s_barrier
	s_waitcnt lgkmcnt(0)
	s_setprio 1

; #define PG8_STAGE(bufoff, gbase, voff) do { _Pragma("unroll") for (int _i = 0; _i < 2; ++_i) \
;         __builtin_amdgcn_global_load_lds((const unsigned*)((const char*)(gbase) + (voff)[_i]), (LAS unsigned*)(lds + (bufoff) + ldsw + _i * 8192), 16, 0, 0); } while (0)
; #define PG8_LDA(dst, b, h) do { _Pragma("unroll") for (int m = 0; m < 4; ++m) _Pragma("unroll") for (int k = 0; k < 2; ++k) dst[m][k] = *(const LAS bf16x8*)(lds + PG8_SA(b, h) + aoff + m * 2048 + k * 1024); } while (0)
; #define PG8_MMA(ai, bj, At, Bt) do { __builtin_amdgcn_s_setprio(1); _Pragma("unroll") for (int m = 0; m < 4; ++m) _Pragma("unroll") for (int n = 0; n < 2; ++n) _Pragma("unroll") for (int k = 0; k < 2; ++k) \
;         acc[ai][bj][m][n] = __builtin_amdgcn_mfma_f32_16x16x32_bf16(Bt[n][k], At[m][k], acc[ai][bj][m][n], 0, 0, 0); __builtin_amdgcn_s_setprio(0); } while (0)
; #define PG8_WAIT_L(n) asm volatile("s_waitcnt lgkmcnt(" #n ")" ::: "memory")
; #define PG8_BAR __builtin_amdgcn_s_barrier()
; #define PG8_SCHED __builtin_amdgcn_sched_barrier(0)
; template <class Epi>
; __device__ __forceinline__ void gemm_phase(LAS unsigned char* lds, const Gemm g, const StaticOrder& S, const Epi& E) {
;     ...
;             PG8_BAR; PG8_WAIT_L(0); PG8_MMA(0, 1, At, B1); PG8_BAR;
;             PG8_LDA(At, 0, 1); PG8_STAGE(PG8_SA(0, 0), a2, voffA);
;             PG8_BAR; PG8_WAIT_L(0); PG8_MMA(1, 0, At, B0); PG8_BAR; PG8_SCHED;
	v_mfma_f32_16x16x32_bf16 v[116:119], v[208:211], v[172:175], v[116:119]
	v_mfma_f32_16x16x32_bf16 v[112:115], v[216:219], v[172:175], v[112:115]
	v_mfma_f32_16x16x32_bf16 v[100:103], v[208:211], v[184:187], v[100:103]
	v_mfma_f32_16x16x32_bf16 v[96:99], v[216:219], v[184:187], v[96:99]
	v_mfma_f32_16x16x32_bf16 v[84:87], v[208:211], v[192:195], v[84:87]
	v_mfma_f32_16x16x32_bf16 v[80:83], v[216:219], v[192:195], v[80:83]
	v_mfma_f32_16x16x32_bf16 v[68:71], v[208:211], v[200:203], v[68:71]
	v_mfma_f32_16x16x32_bf16 v[64:67], v[216:219], v[200:203], v[64:67]
	v_mfma_f32_16x16x32_bf16 v[116:119], v[212:215], v[180:183], v[116:119]
	v_mfma_f32_16x16x32_bf16 v[112:115], v[220:223], v[180:183], v[112:115]
	v_mfma_f32_16x16x32_bf16 v[100:103], v[212:215], v[188:191], v[100:103]
	v_mfma_f32_16x16x32_bf16 v[96:99], v[220:223], v[188:191], v[96:99]
	v_mfma_f32_16x16x32_bf16 v[84:87], v[212:215], v[196:199], v[84:87]
	v_mfma_f32_16x16x32_bf16 v[80:83], v[220:223], v[196:199], v[80:83]
	v_mfma_f32_16x16x32_bf16 v[68:71], v[212:215], v[204:207], v[68:71]
	v_mfma_f32_16x16x32_bf16 v[64:67], v[220:223], v[204:207], v[64:67]
	s_setprio 0
	s_mov_b32 m0, s21
	v_lshl_add_u64 v[224:225], s[30:31], 0, v[138:139]
	s_barrier
	ds_read_b128 v[172:175], v163 offset:16384
	ds_read_b128 v[180:183], v163 offset:17408
	ds_read_b128 v[184:187], v163 offset:18432
	ds_read_b128 v[188:191], v163 offset:19456
	ds_read_b128 v[192:195], v163 offset:20480
	ds_read_b128 v[196:199], v163 offset:21504
	ds_read_b128 v[200:203], v163 offset:22528
	ds_read_b128 v[204:207], v163 offset:23552
	global_load_lds_dwordx4 v[224:225], off
	v_lshl_add_u64 v[226:227], s[30:31], 0, v[142:143]
	s_mov_b32 m0, s39
	s_nop 0
	global_load_lds_dwordx4 v[226:227], off
	s_barrier
	s_waitcnt lgkmcnt(0)
	s_setprio 1

; #define PG8_STAGE(bufoff, gbase, voff) do { _Pragma("unroll") for (int _i = 0; _i < 2; ++_i) \
;         __builtin_amdgcn_global_load_lds((const unsigned*)((const char*)(gbase) + (voff)[_i]), (LAS unsigned*)(lds + (bufoff) + ldsw + _i * 8192), 16, 0, 0); } while (0)
; #define PG8_LDA(dst, b, h) do { _Pragma("unroll") for (int m = 0; m < 4; ++m) _Pragma("unroll") for (int k = 0; k < 2; ++k) dst[m][k] = *(const LAS bf16x8*)(lds + PG8_SA(b, h) + aoff + m * 2048 + k * 1024); } while (0)
; #define PG8_LDB(dst, b, h) do { _Pragma("unroll") for (int n = 0; n < 2; ++n) _Pragma("unroll") for (int k = 0; k < 2; ++k) dst[n][k] = *(const LAS bf16x8*)(lds + PG8_SB(b, h) + boff + n * 2048 + k * 1024); } while (0)
; #define PG8_MMA(ai, bj, At, Bt) do { __builtin_amdgcn_s_setprio(1); _Pragma("unroll") for (int m = 0; m < 4; ++m) _Pragma("unroll") for (int n = 0; n < 2; ++n) _Pragma("unroll") for (int k = 0; k < 2; ++k) \
;         acc[ai][bj][m][n] = __builtin_amdgcn_mfma_f32_16x16x32_bf16(Bt[n][k], At[m][k], acc[ai][bj][m][n], 0, 0, 0); __builtin_amdgcn_s_setprio(0); } while (0)
; #define PG8_WAIT_V(n) asm volatile("s_waitcnt vmcnt(" #n ")" ::: "memory")
; #define PG8_WAIT_L(n) asm volatile("s_waitcnt lgkmcnt(" #n ")" ::: "memory")
; #define PG8_BAR __builtin_amdgcn_s_barrier()
; #define PG8_SCHED __builtin_amdgcn_sched_barrier(0)
; template <class Epi>
; __device__ __forceinline__ void gemm_phase(LAS unsigned char* lds, const Gemm g, const StaticOrder& S, const Epi& E) {
;     ...
;             PG8_BAR; PG8_WAIT_L(0); PG8_MMA(1, 0, At, B0); PG8_BAR; PG8_SCHED;
;             PG8_STAGE(PG8_SB(0, 1), b2 + hstep, voffB);
;             PG8_WAIT_V(6); PG8_BAR; PG8_MMA(1, 1, At, B1); PG8_BAR;
;             PG8_LDB(B0, 1, 0); PG8_SCHED; PG8_LDA(At, 1, 0); PG8_STAGE(PG8_SA(0, 1), a2 + hstep, voffA);
;             PG8_WAIT_L(8); PG8_BAR; PG8_WAIT_L(0); PG8_MMA(0, 0, At, B0); PG8_BAR; PG8_SCHED;
	v_mfma_f32_16x16x32_bf16 v[60:63], v[128:131], v[172:175], v[60:63]
	v_mfma_f32_16x16x32_bf16 v[56:59], v[154:157], v[172:175], v[56:59]
	v_mfma_f32_16x16x32_bf16 v[44:47], v[128:131], v[184:187], v[44:47]
	v_mfma_f32_16x16x32_bf16 v[40:43], v[154:157], v[184:187], v[40:43]
	v_mfma_f32_16x16x32_bf16 v[28:31], v[128:131], v[192:195], v[28:31]
	v_mfma_f32_16x16x32_bf16 v[24:27], v[154:157], v[192:195], v[24:27]
	v_mfma_f32_16x16x32_bf16 v[12:15], v[128:131], v[200:203], v[12:15]
	v_mfma_f32_16x16x32_bf16 v[8:11], v[154:157], v[200:203], v[8:11]
	v_mfma_f32_16x16x32_bf16 v[60:63], v[132:135], v[180:183], v[60:63]
	v_mfma_f32_16x16x32_bf16 v[56:59], v[168:171], v[180:183], v[56:59]
	v_mfma_f32_16x16x32_bf16 v[44:47], v[132:135], v[188:191], v[44:47]
	v_mfma_f32_16x16x32_bf16 v[40:43], v[168:171], v[188:191], v[40:43]
	v_mfma_f32_16x16x32_bf16 v[28:31], v[132:135], v[196:199], v[28:31]
	v_mfma_f32_16x16x32_bf16 v[24:27], v[168:171], v[196:199], v[24:27]
	v_mfma_f32_16x16x32_bf16 v[12:15], v[132:135], v[204:207], v[12:15]
	v_mfma_f32_16x16x32_bf16 v[8:11], v[168:171], v[204:207], v[8:11]
	s_setprio 0
	s_barrier
	s_add_u32 s68, s24, 0x80000
	s_addc_u32 s69, s25, 0
	s_add_i32 s70, s63, s36
	v_lshl_add_u64 v[128:129], s[68:69], 0, v[140:141]
	s_mov_b32 m0, s70
	s_nop 0
	global_load_lds_dwordx4 v[128:129], off
	v_lshl_add_u64 v[128:129], s[68:69], 0, v[144:145]
	s_add_i32 m0, s70, 0x2000
	s_nop 0
	global_load_lds_dwordx4 v[128:129], off
	s_waitcnt vmcnt(6)
	s_barrier
	s_setprio 1
	v_mfma_f32_16x16x32_bf16 v[52:55], v[208:211], v[172:175], v[52:55]
	v_mfma_f32_16x16x32_bf16 v[48:51], v[216:219], v[172:175], v[48:51]
	v_mfma_f32_16x16x32_bf16 v[36:39], v[208:211], v[184:187], v[36:39]
	v_mfma_f32_16x16x32_bf16 v[32:35], v[216:219], v[184:187], v[32:35]
	v_mfma_f32_16x16x32_bf16 v[20:23], v[208:211], v[192:195], v[20:23]
	v_mfma_f32_16x16x32_bf16 v[16:19], v[216:219], v[192:195], v[16:19]
	v_mfma_f32_16x16x32_bf16 v[4:7], v[208:211], v[200:203], v[4:7]
	v_mfma_f32_16x16x32_bf16 v[0:3], v[216:219], v[200:203], v[0:3]
	v_mfma_f32_16x16x32_bf16 v[52:55], v[212:215], v[180:183], v[52:55]
	v_mfma_f32_16x16x32_bf16 v[48:51], v[220:223], v[180:183], v[48:51]
	v_mfma_f32_16x16x32_bf16 v[36:39], v[212:215], v[188:191], v[36:39]
	v_mfma_f32_16x16x32_bf16 v[32:35], v[220:223], v[188:191], v[32:35]
	v_mfma_f32_16x16x32_bf16 v[20:23], v[212:215], v[196:199], v[20:23]
	v_mfma_f32_16x16x32_bf16 v[16:19], v[220:223], v[196:199], v[16:19]
	v_mfma_f32_16x16x32_bf16 v[4:7], v[212:215], v[204:207], v[4:7]
	v_mfma_f32_16x16x32_bf16 v[0:3], v[220:223], v[204:207], v[0:3]
	s_setprio 0
	s_add_i32 s68, 0, 0x18000
	v_add_u32_e32 v167, s68, v137
	s_barrier
	ds_read_b128 v[128:131], v167
	ds_read_b128 v[132:135], v167 offset:1024
	ds_read_b128 v[154:157], v167 offset:2048
	ds_read_b128 v[168:171], v167 offset:3072
	s_add_u32 s30, s30, 0x80000
	s_addc_u32 s31, s31, 0
	s_mov_b32 m0, s42
	v_lshl_add_u64 v[208:209], s[30:31], 0, v[138:139]
	ds_read_b128 v[172:175], v163 offset:32768
	ds_read_b128 v[180:183], v163 offset:33792
	ds_read_b128 v[184:187], v163 offset:34816
	ds_read_b128 v[188:191], v163 offset:35840
	ds_read_b128 v[192:195], v163 offset:36864
	ds_read_b128 v[196:199], v163 offset:37888
	ds_read_b128 v[200:203], v163 offset:38912
	ds_read_b128 v[204:207], v163 offset:39936
	global_load_lds_dwordx4 v[208:209], off
	v_lshl_add_u64 v[208:209], s[30:31], 0, v[142:143]
	s_mov_b32 m0, s43
	s_nop 0
	global_load_lds_dwordx4 v[208:209], off
	s_waitcnt lgkmcnt(8)
	s_barrier
	s_waitcnt lgkmcnt(0)
	s_setprio 1

; #define PG8_STAGE(bufoff, gbase, voff) do { _Pragma("unroll") for (int _i = 0; _i < 2; ++_i) \
;         __builtin_amdgcn_global_load_lds((const unsigned*)((const char*)(gbase) + (voff)[_i]), (LAS unsigned*)(lds + (bufoff) + ldsw + _i * 8192), 16, 0, 0); } while (0)
; #define PG8_LDB(dst, b, h) do { _Pragma("unroll") for (int n = 0; n < 2; ++n) _Pragma("unroll") for (int k = 0; k < 2; ++k) dst[n][k] = *(const LAS bf16x8*)(lds + PG8_SB(b, h) + boff + n * 2048 + k * 1024); } while (0)
; #define PG8_MMA(ai, bj, At, Bt) do { __builtin_amdgcn_s_setprio(1); _Pragma("unroll") for (int m = 0; m < 4; ++m) _Pragma("unroll") for (int n = 0; n < 2; ++n) _Pragma("unroll") for (int k = 0; k < 2; ++k) \
;         acc[ai][bj][m][n] = __builtin_amdgcn_mfma_f32_16x16x32_bf16(Bt[n][k], At[m][k], acc[ai][bj][m][n], 0, 0, 0); __builtin_amdgcn_s_setprio(0); } while (0)
; #define PG8_WAIT_L(n) asm volatile("s_waitcnt lgkmcnt(" #n ")" ::: "memory")
; #define PG8_BAR __builtin_amdgcn_s_barrier()
; #define PG8_SCHED __builtin_amdgcn_sched_barrier(0)
; template <class Epi>
; __device__ __forceinline__ void gemm_phase(LAS unsigned char* lds, const Gemm g, const StaticOrder& S, const Epi& E) {
;     ...
;             PG8_WAIT_L(8); PG8_BAR; PG8_WAIT_L(0); PG8_MMA(0, 0, At, B0); PG8_BAR; PG8_SCHED;
;             PG8_LDB(B1, 1, 1); PG8_STAGE(PG8_SB(1, 0), b3, voffB);
;             PG8_BAR; PG8_WAIT_L(0); PG8_MMA(0, 1, At, B1); PG8_BAR;
	v_mfma_f32_16x16x32_bf16 v[124:127], v[128:131], v[172:175], v[124:127]
	v_mfma_f32_16x16x32_bf16 v[120:123], v[154:157], v[172:175], v[120:123]
	v_mfma_f32_16x16x32_bf16 v[108:111], v[128:131], v[184:187], v[108:111]
	v_mfma_f32_16x16x32_bf16 v[104:107], v[154:157], v[184:187], v[104:107]
	v_mfma_f32_16x16x32_bf16 v[92:95], v[128:131], v[192:195], v[92:95]
	v_mfma_f32_16x16x32_bf16 v[88:91], v[154:157], v[192:195], v[88:91]
	v_mfma_f32_16x16x32_bf16 v[76:79], v[128:131], v[200:203], v[76:79]
	v_mfma_f32_16x16x32_bf16 v[72:75], v[154:157], v[200:203], v[72:75]
	v_mfma_f32_16x16x32_bf16 v[124:127], v[132:135], v[180:183], v[124:127]
	v_mfma_f32_16x16x32_bf16 v[120:123], v[168:171], v[180:183], v[120:123]
	v_mfma_f32_16x16x32_bf16 v[108:111], v[132:135], v[188:191], v[108:111]
	v_mfma_f32_16x16x32_bf16 v[104:107], v[168:171], v[188:191], v[104:107]
	v_mfma_f32_16x16x32_bf16 v[92:95], v[132:135], v[196:199], v[92:95]
	v_mfma_f32_16x16x32_bf16 v[88:91], v[168:171], v[196:199], v[88:91]
	v_mfma_f32_16x16x32_bf16 v[76:79], v[132:135], v[204:207], v[76:79]
	v_mfma_f32_16x16x32_bf16 v[72:75], v[168:171], v[204:207], v[72:75]
	s_setprio 0
	s_barrier
	s_add_i32 s30, 0, 0x1c000
	s_add_i32 s31, s68, s36
	v_add_u32_e32 v167, s30, v137
	v_lshl_add_u64 v[158:159], v[158:159], 0, s[8:9]
	s_mov_b32 m0, s31
	ds_read_b128 v[208:211], v167
	ds_read_b128 v[212:215], v167 offset:1024
	ds_read_b128 v[216:219], v167 offset:2048
	ds_read_b128 v[220:223], v167 offset:3072
	global_load_lds_dwordx4 v[158:159], off
	v_lshl_add_u64 v[158:159], v[176:177], 0, s[8:9]
	s_add_i32 m0, s31, 0x2000
	s_nop 0
	global_load_lds_dwordx4 v[158:159], off
	s_barrier
	s_waitcnt lgkmcnt(0)
	s_setprio 1

; #define PG8_STAGE(bufoff, gbase, voff) do { _Pragma("unroll") for (int _i = 0; _i < 2; ++_i) \
;         __builtin_amdgcn_global_load_lds((const unsigned*)((const char*)(gbase) + (voff)[_i]), (LAS unsigned*)(lds + (bufoff) + ldsw + _i * 8192), 16, 0, 0); } while (0)
; #define PG8_LDA(dst, b, h) do { _Pragma("unroll") for (int m = 0; m < 4; ++m) _Pragma("unroll") for (int k = 0; k < 2; ++k) dst[m][k] = *(const LAS bf16x8*)(lds + PG8_SA(b, h) + aoff + m * 2048 + k * 1024); } while (0)
; #define PG8_MMA(ai, bj, At, Bt) do { __builtin_amdgcn_s_setprio(1); _Pragma("unroll") for (int m = 0; m < 4; ++m) _Pragma("unroll") for (int n = 0; n < 2; ++n) _Pragma("unroll") for (int k = 0; k < 2; ++k) \
;         acc[ai][bj][m][n] = __builtin_amdgcn_mfma_f32_16x16x32_bf16(Bt[n][k], At[m][k], acc[ai][bj][m][n], 0, 0, 0); __builtin_amdgcn_s_setprio(0); } while (0)
; #define PG8_WAIT_L(n) asm volatile("s_waitcnt lgkmcnt(" #n ")" ::: "memory")
; #define PG8_BAR __builtin_amdgcn_s_barrier()
; #define PG8_SCHED __builtin_amdgcn_sched_barrier(0)
; template <class Epi>
; __device__ __forceinline__ void gemm_phase(LAS unsigned char* lds, const Gemm g, const StaticOrder& S, const Epi& E) {
;     ...
;             PG8_BAR; PG8_WAIT_L(0); PG8_MMA(0, 1, At, B1); PG8_BAR;
;             PG8_LDA(At, 1, 1); PG8_STAGE(PG8_SA(1, 0), a3, voffA);
;             PG8_BAR; PG8_WAIT_L(0); PG8_MMA(1, 0, At, B0); PG8_BAR; PG8_SCHED;
	v_mfma_f32_16x16x32_bf16 v[116:119], v[208:211], v[172:175], v[116:119]
	v_mfma_f32_16x16x32_bf16 v[112:115], v[216:219], v[172:175], v[112:115]
	v_mfma_f32_16x16x32_bf16 v[100:103], v[208:211], v[184:187], v[100:103]
	v_mfma_f32_16x16x32_bf16 v[96:99], v[216:219], v[184:187], v[96:99]
	v_mfma_f32_16x16x32_bf16 v[84:87], v[208:211], v[192:195], v[84:87]
	v_mfma_f32_16x16x32_bf16 v[80:83], v[216:219], v[192:195], v[80:83]
	v_mfma_f32_16x16x32_bf16 v[68:71], v[208:211], v[200:203], v[68:71]
	v_mfma_f32_16x16x32_bf16 v[64:67], v[216:219], v[200:203], v[64:67]
	v_mfma_f32_16x16x32_bf16 v[116:119], v[212:215], v[180:183], v[116:119]
	v_mfma_f32_16x16x32_bf16 v[112:115], v[220:223], v[180:183], v[112:115]
	v_mfma_f32_16x16x32_bf16 v[100:103], v[212:215], v[188:191], v[100:103]
	v_mfma_f32_16x16x32_bf16 v[96:99], v[220:223], v[188:191], v[96:99]
	v_mfma_f32_16x16x32_bf16 v[84:87], v[212:215], v[196:199], v[84:87]
	v_mfma_f32_16x16x32_bf16 v[80:83], v[220:223], v[196:199], v[80:83]
	v_mfma_f32_16x16x32_bf16 v[68:71], v[212:215], v[204:207], v[68:71]
	v_mfma_f32_16x16x32_bf16 v[64:67], v[220:223], v[204:207], v[64:67]
	s_setprio 0
	s_mov_b32 m0, s57
	v_lshl_add_u64 v[158:159], v[224:225], 0, s[8:9]
	s_barrier
	ds_read_b128 v[172:175], v163 offset:49152
	ds_read_b128 v[180:183], v163 offset:50176
	ds_read_b128 v[184:187], v163 offset:51200
	ds_read_b128 v[188:191], v163 offset:52224
	ds_read_b128 v[192:195], v163 offset:53248
	ds_read_b128 v[196:199], v163 offset:54272
	ds_read_b128 v[200:203], v163 offset:55296
	ds_read_b128 v[204:207], v163 offset:56320
	global_load_lds_dwordx4 v[158:159], off
	v_lshl_add_u64 v[158:159], v[226:227], 0, s[8:9]
	s_mov_b32 m0, s58
	s_nop 0
	global_load_lds_dwordx4 v[158:159], off
	s_barrier
	s_waitcnt lgkmcnt(0)
	s_setprio 1

; #define PG8_STAGE(bufoff, gbase, voff) do { _Pragma("unroll") for (int _i = 0; _i < 2; ++_i) \
;         __builtin_amdgcn_global_load_lds((const unsigned*)((const char*)(gbase) + (voff)[_i]), (LAS unsigned*)(lds + (bufoff) + ldsw + _i * 8192), 16, 0, 0); } while (0)
; #define PG8_MMA(ai, bj, At, Bt) do { __builtin_amdgcn_s_setprio(1); _Pragma("unroll") for (int m = 0; m < 4; ++m) _Pragma("unroll") for (int n = 0; n < 2; ++n) _Pragma("unroll") for (int k = 0; k < 2; ++k) \
;         acc[ai][bj][m][n] = __builtin_amdgcn_mfma_f32_16x16x32_bf16(Bt[n][k], At[m][k], acc[ai][bj][m][n], 0, 0, 0); __builtin_amdgcn_s_setprio(0); } while (0)
; #define PG8_WAIT_V(n) asm volatile("s_waitcnt vmcnt(" #n ")" ::: "memory")
; #define PG8_WAIT_L(n) asm volatile("s_waitcnt lgkmcnt(" #n ")" ::: "memory")
; #define PG8_BAR __builtin_amdgcn_s_barrier()
; #define PG8_SCHED __builtin_amdgcn_sched_barrier(0)
; template <class Epi>
; __device__ __forceinline__ void gemm_phase(LAS unsigned char* lds, const Gemm g, const StaticOrder& S, const Epi& E) {
;     ...
;             PG8_BAR; PG8_WAIT_L(0); PG8_MMA(1, 0, At, B0); PG8_BAR; PG8_SCHED;
;             PG8_STAGE(PG8_SB(1, 1), b3 + hstep, voffB);
;             PG8_WAIT_V(6); PG8_BAR; PG8_MMA(1, 1, At, B1); PG8_BAR;
	v_mfma_f32_16x16x32_bf16 v[60:63], v[128:131], v[172:175], v[60:63]
	v_mfma_f32_16x16x32_bf16 v[56:59], v[154:157], v[172:175], v[56:59]
	v_mfma_f32_16x16x32_bf16 v[44:47], v[128:131], v[184:187], v[44:47]
	v_mfma_f32_16x16x32_bf16 v[40:43], v[154:157], v[184:187], v[40:43]
	v_mfma_f32_16x16x32_bf16 v[28:31], v[128:131], v[192:195], v[28:31]
	v_mfma_f32_16x16x32_bf16 v[24:27], v[154:157], v[192:195], v[24:27]
	v_mfma_f32_16x16x32_bf16 v[12:15], v[128:131], v[200:203], v[12:15]
	v_mfma_f32_16x16x32_bf16 v[8:11], v[154:157], v[200:203], v[8:11]
	v_mfma_f32_16x16x32_bf16 v[60:63], v[132:135], v[180:183], v[60:63]
	v_mfma_f32_16x16x32_bf16 v[56:59], v[168:171], v[180:183], v[56:59]
	v_mfma_f32_16x16x32_bf16 v[44:47], v[132:135], v[188:191], v[44:47]
	v_mfma_f32_16x16x32_bf16 v[40:43], v[168:171], v[188:191], v[40:43]
	v_mfma_f32_16x16x32_bf16 v[28:31], v[132:135], v[196:199], v[28:31]
	v_mfma_f32_16x16x32_bf16 v[24:27], v[168:171], v[196:199], v[24:27]
	v_mfma_f32_16x16x32_bf16 v[12:15], v[132:135], v[204:207], v[12:15]
	v_mfma_f32_16x16x32_bf16 v[8:11], v[168:171], v[204:207], v[8:11]
	s_setprio 0
	s_barrier
	s_add_u32 s24, s24, 0x80080
	s_addc_u32 s25, s25, 0
	s_add_i32 s30, s30, s36
	v_lshl_add_u64 v[128:129], s[24:25], 0, v[140:141]
	s_mov_b32 m0, s30
	s_nop 0
	global_load_lds_dwordx4 v[128:129], off
	v_lshl_add_u64 v[128:129], s[24:25], 0, v[144:145]
	s_add_i32 m0, s30, 0x2000
	s_nop 0
	global_load_lds_dwordx4 v[128:129], off
	s_waitcnt vmcnt(6)
	s_barrier
	s_setprio 1
	v_mfma_f32_16x16x32_bf16 v[52:55], v[208:211], v[172:175], v[52:55]
	v_mfma_f32_16x16x32_bf16 v[48:51], v[216:219], v[172:175], v[48:51]
	v_mfma_f32_16x16x32_bf16 v[36:39], v[208:211], v[184:187], v[36:39]
	v_mfma_f32_16x16x32_bf16 v[32:35], v[216:219], v[184:187], v[32:35]
	v_mfma_f32_16x16x32_bf16 v[20:23], v[208:211], v[192:195], v[20:23]
	v_mfma_f32_16x16x32_bf16 v[16:19], v[216:219], v[192:195], v[16:19]
	v_mfma_f32_16x16x32_bf16 v[4:7], v[208:211], v[200:203], v[4:7]
	v_mfma_f32_16x16x32_bf16 v[0:3], v[216:219], v[200:203], v[0:3]
	v_mfma_f32_16x16x32_bf16 v[52:55], v[212:215], v[180:183], v[52:55]
	v_mfma_f32_16x16x32_bf16 v[48:51], v[220:223], v[180:183], v[48:51]
	v_mfma_f32_16x16x32_bf16 v[36:39], v[212:215], v[188:191], v[36:39]
	v_mfma_f32_16x16x32_bf16 v[32:35], v[220:223], v[188:191], v[32:35]
	v_mfma_f32_16x16x32_bf16 v[20:23], v[212:215], v[196:199], v[20:23]
	v_mfma_f32_16x16x32_bf16 v[16:19], v[220:223], v[196:199], v[16:19]
	v_mfma_f32_16x16x32_bf16 v[4:7], v[212:215], v[204:207], v[4:7]
	v_mfma_f32_16x16x32_bf16 v[0:3], v[220:223], v[204:207], v[0:3]
	s_setprio 0
	s_add_i32 s67, s67, 2
	s_add_u32 s22, s22, 0x100
	s_addc_u32 s23, s23, 0
	s_add_u32 s65, s65, 0x100
	s_addc_u32 s66, s66, 0
	s_cmp_gt_u32 s67, 29
	s_barrier
	s_cbranch_scc0 .LBB0_1220
; __device__ __forceinline__ float bflo(unsigned w) { return __uint_as_float(w << 16); }
; __device__ __forceinline__ float bfhi(unsigned w) { return __uint_as_float(w & 0xffff0000u); }
; #define ER_LOAD(g_, set_) do { const size_t off_ = (size_t)(row0 + ((g_) >> 2) * HALF + ((g_) & 3) * 16) * DM + col0; \
;         hv[set_][0] = *(const u32x4*)(HB + off_); hv[set_][1] = *(const u32x4*)(HB + off_ + HALF); } while (0)
;     __device__ __forceinline__ void operator()(const f32x4 (&acc)[2][2][4][2], const Unit& u, int wr, int wc, int fr, int fq, const Pre&) const {
;         const int row0 = ROW_X + u.pm * BM + wr * 64 + fr, col0 = u.pn * BM + wc * 32 + 8 * fq;
;         u32x4 hv[2][2]; float sprev = 0.f;
;     ...
;         ER_LOAD(0, 0);
; #pragma unroll
;         for (int g = 0; g < 8; ++g) { const int ai = g >> 2, m = g & 3; const int r = row0 + ai * HALF + m * 16; const size_t off = (size_t)r * DM + col0; float s = 0.f;
;             if (g + 1 < 8) ER_LOAD(g + 1, (g + 1) & 1);
; #pragma unroll
;             for (int bj = 0; bj < 2; ++bj) { const u32x4 w = hv[g & 1][bj];
;                 const f32x4 h0 = {bflo(w.x), bfhi(w.x), bflo(w.y), bfhi(w.y)}, h1 = {bflo(w.z), bfhi(w.z), bflo(w.w), bfhi(w.w)};
;                 const f32x4 o0 = h0 + acc[ai][bj][m][0] * alpha, o1 = h1 + acc[ai][bj][m][1] * alpha;
;                 if (FINAL) { float* op = OUT + (size_t)(r - ROW_X) * DM + col0 + bj * HALF; *(f32x4*)op = o0; *(f32x4*)(op + 4) = o1; }
;                 else { u32x4 q; q.x = cvtpk(o0[0], o0[1]); q.y = cvtpk(o0[2], o0[3]); q.z = cvtpk(o1[0], o1[1]); q.w = cvtpk(o1[2], o1[3]); *(u32x4*)(HB + off + bj * HALF) = q;
;                        s += ((o0[0] * o0[0] + o0[1] * o0[1]) + (o0[2] * o0[2] + o0[3] * o0[3])) + ((o1[0] * o1[0] + o1[1] * o1[1]) + (o1[2] * o1[2] + o1[3] * o1[3])); } }
;             if (!FINAL) { if (g > 0) { float t = sprev; t += __shfl_xor(t, 16); t += __shfl_xor(t, 32);
;                     if (fq == 0) __hip_atomic_fetch_add(ssq_out + row0 + ((g - 1) >> 2) * HALF + ((g - 1) & 3) * 16, t, __ATOMIC_RELAXED, __HIP_MEMORY_SCOPE_AGENT); }
;                 sprev = s; } }
	v_lshl_add_u32 v156, s18, 8, v160
	v_lshl_or_b32 v154, s20, 8, v161
	v_ashrrev_i32_e32 v157, 31, v156
	v_ashrrev_i32_e32 v155, 31, v154
	v_lshlrev_b64 v[128:129], 12, v[156:157]
	v_lshl_add_u64 v[128:129], s[0:1], 0, v[128:129]
	v_lshlrev_b64 v[130:131], 1, v[154:155]
	v_lshl_add_u64 v[176:177], v[128:129], 0, v[130:131]
	v_or_b32_e32 v128, 16, v156
	v_ashrrev_i32_e32 v129, 31, v128
	global_load_dwordx4 v[168:171], v[176:177], off
	global_load_dwordx4 v[172:175], v[176:177], off offset:256
	v_lshlrev_b64 v[128:129], 12, v[128:129]
	v_lshl_add_u64 v[128:129], s[0:1], 0, v[128:129]
	v_lshl_add_u64 v[188:189], v[128:129], 0, v[130:131]
	global_load_dwordx4 v[180:183], v[188:189], off
	global_load_dwordx4 v[184:187], v[188:189], off offset:256
	v_or_b32_e32 v128, 32, v156
	v_ashrrev_i32_e32 v129, 31, v128
	v_lshlrev_b64 v[128:129], 12, v[128:129]
	v_lshl_add_u64 v[128:129], s[0:1], 0, v[128:129]
	v_lshl_add_u64 v[158:159], v[128:129], 0, v[130:131]
	global_load_dwordx4 v[132:135], v[158:159], off
	global_load_dwordx4 v[128:131], v[158:159], off offset:256
	s_waitcnt vmcnt(0)
	v_lshlrev_b32_e32 v190, 16, v168
	v_and_b32_e32 v191, 0xffff0000, v168
	v_lshlrev_b32_e32 v168, 16, v169
	v_and_b32_e32 v169, 0xffff0000, v169
	v_lshlrev_b32_e32 v192, 16, v170
	v_and_b32_e32 v193, 0xffff0000, v170
	v_lshlrev_b32_e32 v170, 16, v171
	v_and_b32_e32 v171, 0xffff0000, v171
	v_lshlrev_b32_e32 v194, 16, v172
	v_and_b32_e32 v195, 0xffff0000, v172
	v_lshlrev_b32_e32 v172, 16, v173
	v_and_b32_e32 v173, 0xffff0000, v173
	v_lshlrev_b32_e32 v196, 16, v174
	v_and_b32_e32 v197, 0xffff0000, v174
	v_lshlrev_b32_e32 v174, 16, v175
	v_and_b32_e32 v175, 0xffff0000, v175
	v_pk_add_f32 v[126:127], v[126:127], v[168:169]
	v_pk_add_f32 v[124:125], v[124:125], v[190:191]
	v_pk_add_f32 v[122:123], v[122:123], v[170:171]
	v_pk_add_f32 v[168:169], v[120:121], v[192:193]
	v_pk_add_f32 v[170:171], v[118:119], v[172:173]
	v_pk_add_f32 v[172:173], v[116:117], v[194:195]
	v_pk_add_f32 v[174:175], v[114:115], v[174:175]
	v_pk_add_f32 v[190:191], v[112:113], v[196:197]
	v_cvt_pk_bf16_f32 v114, v124, v125
	v_cvt_pk_bf16_f32 v115, v126, v127
	v_cvt_pk_bf16_f32 v116, v168, v169
	v_cvt_pk_bf16_f32 v117, v122, v123
	v_mul_f32_e32 v125, v125, v125
	v_mul_f32_e32 v127, v127, v127
	v_mul_f32_e32 v167, v169, v169
	v_mul_f32_e32 v123, v123, v123
	v_cvt_pk_bf16_f32 v118, v172, v173
	v_cvt_pk_bf16_f32 v119, v170, v171
	v_cvt_pk_bf16_f32 v121, v174, v175
	v_mul_f32_e32 v169, v173, v173
	v_mul_f32_e32 v171, v171, v171
	v_mul_f32_e32 v173, v191, v191
	v_mul_f32_e32 v175, v175, v175
	v_lshlrev_b32_e32 v112, 16, v180
	v_and_b32_e32 v113, 0xffff0000, v180
	v_lshlrev_b32_e32 v192, 16, v182
	v_and_b32_e32 v193, 0xffff0000, v182
	v_lshlrev_b32_e32 v182, 16, v183
	v_and_b32_e32 v183, 0xffff0000, v183
	v_fmac_f32_e32 v125, v124, v124
	v_fmac_f32_e32 v127, v126, v126
	v_fmac_f32_e32 v167, v168, v168
	v_fmac_f32_e32 v123, v122, v122
	v_fmac_f32_e32 v169, v172, v172
	v_fmac_f32_e32 v171, v170, v170
	v_fmac_f32_e32 v173, v190, v190
	v_fmac_f32_e32 v175, v174, v174
	v_lshlrev_b32_e32 v180, 16, v181
	v_and_b32_e32 v181, 0xffff0000, v181
	v_pk_add_f32 v[112:113], v[108:109], v[112:113]
	v_pk_add_f32 v[108:109], v[106:107], v[182:183]
	global_store_dwordx4 v[176:177], v[114:117], off
	v_add_f32_e32 v106, v125, v127
	v_add_f32_e32 v107, v167, v123
	v_add_f32_e32 v114, v169, v171
	v_add_f32_e32 v115, v173, v175
	v_pk_add_f32 v[110:111], v[110:111], v[180:181]
	v_add_f32_e32 v106, v106, v107
	v_add_f32_e32 v107, v114, v115
	v_pk_add_f32 v[114:115], v[104:105], v[192:193]
	v_add_f32_e32 v125, v106, v107
	v_cvt_pk_bf16_f32 v104, v112, v113
	v_cvt_pk_bf16_f32 v105, v110, v111
	v_cvt_pk_bf16_f32 v106, v114, v115
	v_cvt_pk_bf16_f32 v107, v108, v109
	v_cvt_pk_bf16_f32 v120, v190, v191
	global_store_dwordx4 v[188:189], v[104:107], off
	global_store_dwordx4 v[176:177], v[118:121], off offset:256
	v_lshlrev_b32_e32 v122, 16, v186
	v_lshlrev_b32_e32 v104, 16, v184
	v_and_b32_e32 v105, 0xffff0000, v184
	v_pk_add_f32 v[118:119], v[100:101], v[104:105]
	v_and_b32_e32 v101, 64, v166
	v_xor_b32_e32 v100, 16, v166
	v_add_u32_e32 v101, 64, v101
	v_cmp_lt_i32_e32 vcc, v100, v101
	v_and_b32_e32 v123, 0xffff0000, v186
	v_pk_add_f32 v[122:123], v[96:97], v[122:123]
	v_cndmask_b32_e32 v100, v166, v100, vcc
	v_lshlrev_b32_e32 v124, 2, v100
	ds_bpermute_b32 v100, v124, v125
	v_xor_b32_e32 v97, 32, v166
	v_cmp_lt_i32_e32 vcc, v97, v101
	v_lshlrev_b32_e32 v106, 16, v185
	v_and_b32_e32 v107, 0xffff0000, v185
	v_cndmask_b32_e32 v97, v166, v97, vcc
	s_waitcnt lgkmcnt(0)
	v_add_f32_e32 v96, v125, v100
	v_lshlrev_b32_e32 v125, 2, v97
	ds_bpermute_b32 v97, v125, v96
	v_lshlrev_b32_e32 v120, 16, v187
	v_and_b32_e32 v121, 0xffff0000, v187
	v_pk_add_f32 v[116:117], v[102:103], v[106:107]
	v_pk_add_f32 v[120:121], v[98:99], v[120:121]
	v_cvt_pk_bf16_f32 v98, v118, v119
	v_cvt_pk_bf16_f32 v99, v116, v117
	v_cvt_pk_bf16_f32 v100, v122, v123
	v_cvt_pk_bf16_f32 v101, v120, v121
	v_lshl_add_u64 v[104:105], v[156:157], 2, s[6:7]
	global_store_dwordx4 v[188:189], v[98:101], off offset:256
	s_and_saveexec_b64 s[18:19], s[2:3]
	s_cbranch_execz .LBB0_1223
	s_waitcnt lgkmcnt(0)
	v_add_f32_e32 v96, v96, v97
	global_atomic_add_f32 v[104:105], v96, off

; #define PG8_STAGE(bufoff, gbase, voff) do { _Pragma("unroll") for (int _i = 0; _i < 2; ++_i) \
;         __builtin_amdgcn_global_load_lds((const unsigned*)((const char*)(gbase) + (voff)[_i]), (LAS unsigned*)(lds + (bufoff) + ldsw + _i * 8192), 16, 0, 0); } while (0)
; #define PG8_LDA(dst, b, h) do { _Pragma("unroll") for (int m = 0; m < 4; ++m) _Pragma("unroll") for (int k = 0; k < 2; ++k) dst[m][k] = *(const LAS bf16x8*)(lds + PG8_SA(b, h) + aoff + m * 2048 + k * 1024); } while (0)
; #define PG8_LDB(dst, b, h) do { _Pragma("unroll") for (int n = 0; n < 2; ++n) _Pragma("unroll") for (int k = 0; k < 2; ++k) dst[n][k] = *(const LAS bf16x8*)(lds + PG8_SB(b, h) + boff + n * 2048 + k * 1024); } while (0)
; #define PG8_MMA(ai, bj, At, Bt) do { __builtin_amdgcn_s_setprio(1); _Pragma("unroll") for (int m = 0; m < 4; ++m) _Pragma("unroll") for (int n = 0; n < 2; ++n) _Pragma("unroll") for (int k = 0; k < 2; ++k) \
;         acc[ai][bj][m][n] = __builtin_amdgcn_mfma_f32_16x16x32_bf16(Bt[n][k], At[m][k], acc[ai][bj][m][n], 0, 0, 0); __builtin_amdgcn_s_setprio(0); } while (0)
; #define PG8_WAIT_L(n) asm volatile("s_waitcnt lgkmcnt(" #n ")" ::: "memory")
; #define PG8_BAR __builtin_amdgcn_s_barrier()
; #define PG8_SCHED __builtin_amdgcn_sched_barrier(0)
; template <class Epi>
; __device__ __forceinline__ void gemm_phase(LAS unsigned char* lds, const Gemm g, const StaticOrder& S, const Epi& E) {
;     ...
;         for (int t = 0; t < nt; t += 2) {
;             const bool last = (t == nt - 2);
;             const char* a1 = cA + (size_t)(t + 1) * kstep;
;             const char* a2 = last ? nA : cA + (size_t)(t + 2) * kstep; const char* b2 = last ? nB : cB + (size_t)(t + 2) * kstep;
;             const char* a3 = a2 + kstep; const char* b3 = b2 + kstep;
;             PG8_LDB(B0, 0, 0); PG8_SCHED; PG8_LDA(At, 0, 0); PG8_STAGE(PG8_SA(1, 1), a1 + hstep, voffA);
;             PG8_WAIT_L(8); PG8_BAR; PG8_WAIT_L(0); PG8_MMA(0, 0, At, B0); PG8_BAR; PG8_SCHED;
.LBB0_1306:
	ds_read_b128 v[166:169], v149
	ds_read_b128 v[170:173], v149 offset:1024
	ds_read_b128 v[174:177], v149 offset:2048
	ds_read_b128 v[180:183], v149 offset:3072
	s_add_u32 s18, s16, 0xfff80080
	s_addc_u32 s19, s17, -1
	s_cmp_eq_u32 s65, 28
	s_cselect_b32 s21, s9, s19
	s_cselect_b32 s20, s61, s18
	s_cselect_b32 s19, s7, s64
	s_cselect_b32 s18, s62, s63
	v_lshl_add_u64 v[162:163], s[16:17], 0, v[138:139]
	s_add_i32 m0, s35, 0xc000
	ds_read_b128 v[184:187], v150
	ds_read_b128 v[188:191], v150 offset:1024
	ds_read_b128 v[192:195], v150 offset:2048
	ds_read_b128 v[196:199], v150 offset:3072
	ds_read_b128 v[200:203], v150 offset:4096
	ds_read_b128 v[204:207], v150 offset:5120
	ds_read_b128 v[208:211], v150 offset:6144
	ds_read_b128 v[212:215], v150 offset:7168
	global_load_lds_dwordx4 v[162:163], off
	v_lshl_add_u64 v[162:163], s[16:17], 0, v[140:141]
	s_add_i32 m0, s35, 0xe000
	s_nop 0
	global_load_lds_dwordx4 v[162:163], off
	s_waitcnt lgkmcnt(8)
	s_barrier
	s_waitcnt lgkmcnt(0)
	s_setprio 1

; #define PG8_STAGE(bufoff, gbase, voff) do { _Pragma("unroll") for (int _i = 0; _i < 2; ++_i) \
;         __builtin_amdgcn_global_load_lds((const unsigned*)((const char*)(gbase) + (voff)[_i]), (LAS unsigned*)(lds + (bufoff) + ldsw + _i * 8192), 16, 0, 0); } while (0)
; #define PG8_LDB(dst, b, h) do { _Pragma("unroll") for (int n = 0; n < 2; ++n) _Pragma("unroll") for (int k = 0; k < 2; ++k) dst[n][k] = *(const LAS bf16x8*)(lds + PG8_SB(b, h) + boff + n * 2048 + k * 1024); } while (0)
; #define PG8_MMA(ai, bj, At, Bt) do { __builtin_amdgcn_s_setprio(1); _Pragma("unroll") for (int m = 0; m < 4; ++m) _Pragma("unroll") for (int n = 0; n < 2; ++n) _Pragma("unroll") for (int k = 0; k < 2; ++k) \
;         acc[ai][bj][m][n] = __builtin_amdgcn_mfma_f32_16x16x32_bf16(Bt[n][k], At[m][k], acc[ai][bj][m][n], 0, 0, 0); __builtin_amdgcn_s_setprio(0); } while (0)
; #define PG8_WAIT_L(n) asm volatile("s_waitcnt lgkmcnt(" #n ")" ::: "memory")
; #define PG8_BAR __builtin_amdgcn_s_barrier()
; #define PG8_SCHED __builtin_amdgcn_sched_barrier(0)
; template <class Epi>
; __device__ __forceinline__ void gemm_phase(LAS unsigned char* lds, const Gemm g, const StaticOrder& S, const Epi& E) {
;     ...
;             PG8_WAIT_L(8); PG8_BAR; PG8_WAIT_L(0); PG8_MMA(0, 0, At, B0); PG8_BAR; PG8_SCHED;
;             PG8_LDB(B1, 0, 1); PG8_STAGE(PG8_SB(0, 0), b2, voffB);
;             PG8_BAR; PG8_WAIT_L(0); PG8_MMA(0, 1, At, B1); PG8_BAR;
	v_mfma_f32_16x16x32_bf16 v[124:127], v[166:169], v[184:187], v[124:127]
	v_mfma_f32_16x16x32_bf16 v[116:119], v[174:177], v[184:187], v[116:119]
	v_mfma_f32_16x16x32_bf16 v[108:111], v[166:169], v[192:195], v[108:111]
	v_mfma_f32_16x16x32_bf16 v[100:103], v[174:177], v[192:195], v[100:103]
	v_mfma_f32_16x16x32_bf16 v[92:95], v[166:169], v[200:203], v[92:95]
	v_mfma_f32_16x16x32_bf16 v[84:87], v[174:177], v[200:203], v[84:87]
	v_mfma_f32_16x16x32_bf16 v[76:79], v[166:169], v[208:211], v[76:79]
	v_mfma_f32_16x16x32_bf16 v[68:71], v[174:177], v[208:211], v[68:71]
	v_mfma_f32_16x16x32_bf16 v[124:127], v[170:173], v[188:191], v[124:127]
	v_mfma_f32_16x16x32_bf16 v[116:119], v[180:183], v[188:191], v[116:119]
	v_mfma_f32_16x16x32_bf16 v[108:111], v[170:173], v[196:199], v[108:111]
	v_mfma_f32_16x16x32_bf16 v[100:103], v[180:183], v[196:199], v[100:103]
	v_mfma_f32_16x16x32_bf16 v[92:95], v[170:173], v[204:207], v[92:95]
	v_mfma_f32_16x16x32_bf16 v[84:87], v[180:183], v[204:207], v[84:87]
	v_mfma_f32_16x16x32_bf16 v[76:79], v[170:173], v[212:215], v[76:79]
	v_mfma_f32_16x16x32_bf16 v[68:71], v[180:183], v[212:215], v[68:71]
	s_setprio 0
	s_barrier
	s_add_i32 s66, s58, s31
	v_lshl_add_u64 v[162:163], s[18:19], 0, v[132:133]
	s_mov_b32 m0, s66
	ds_read_b128 v[216:219], v152
	ds_read_b128 v[220:223], v152 offset:1024
	ds_read_b128 v[224:227], v152 offset:2048
	ds_read_b128 v[228:231], v152 offset:3072
	global_load_lds_dwordx4 v[162:163], off
	v_lshl_add_u64 v[232:233], s[18:19], 0, v[128:129]
	s_add_i32 m0, s66, 0x2000
	s_nop 0
	global_load_lds_dwordx4 v[232:233], off
	s_barrier
	s_waitcnt lgkmcnt(0)
	s_setprio 1

; #define PG8_STAGE(bufoff, gbase, voff) do { _Pragma("unroll") for (int _i = 0; _i < 2; ++_i) \
;         __builtin_amdgcn_global_load_lds((const unsigned*)((const char*)(gbase) + (voff)[_i]), (LAS unsigned*)(lds + (bufoff) + ldsw + _i * 8192), 16, 0, 0); } while (0)
; #define PG8_LDA(dst, b, h) do { _Pragma("unroll") for (int m = 0; m < 4; ++m) _Pragma("unroll") for (int k = 0; k < 2; ++k) dst[m][k] = *(const LAS bf16x8*)(lds + PG8_SA(b, h) + aoff + m * 2048 + k * 1024); } while (0)
; #define PG8_MMA(ai, bj, At, Bt) do { __builtin_amdgcn_s_setprio(1); _Pragma("unroll") for (int m = 0; m < 4; ++m) _Pragma("unroll") for (int n = 0; n < 2; ++n) _Pragma("unroll") for (int k = 0; k < 2; ++k) \
;         acc[ai][bj][m][n] = __builtin_amdgcn_mfma_f32_16x16x32_bf16(Bt[n][k], At[m][k], acc[ai][bj][m][n], 0, 0, 0); __builtin_amdgcn_s_setprio(0); } while (0)
; #define PG8_WAIT_L(n) asm volatile("s_waitcnt lgkmcnt(" #n ")" ::: "memory")
; #define PG8_BAR __builtin_amdgcn_s_barrier()
; #define PG8_SCHED __builtin_amdgcn_sched_barrier(0)
; template <class Epi>
; __device__ __forceinline__ void gemm_phase(LAS unsigned char* lds, const Gemm g, const StaticOrder& S, const Epi& E) {
;     ...
;             PG8_BAR; PG8_WAIT_L(0); PG8_MMA(0, 1, At, B1); PG8_BAR;
;             PG8_LDA(At, 0, 1); PG8_STAGE(PG8_SA(0, 0), a2, voffA);
;             PG8_BAR; PG8_WAIT_L(0); PG8_MMA(1, 0, At, B0); PG8_BAR; PG8_SCHED;
	v_mfma_f32_16x16x32_bf16 v[120:123], v[216:219], v[184:187], v[120:123]
	v_mfma_f32_16x16x32_bf16 v[112:115], v[224:227], v[184:187], v[112:115]
	v_mfma_f32_16x16x32_bf16 v[104:107], v[216:219], v[192:195], v[104:107]
	v_mfma_f32_16x16x32_bf16 v[96:99], v[224:227], v[192:195], v[96:99]
	v_mfma_f32_16x16x32_bf16 v[88:91], v[216:219], v[200:203], v[88:91]
	v_mfma_f32_16x16x32_bf16 v[80:83], v[224:227], v[200:203], v[80:83]
	v_mfma_f32_16x16x32_bf16 v[72:75], v[216:219], v[208:211], v[72:75]
	v_mfma_f32_16x16x32_bf16 v[64:67], v[224:227], v[208:211], v[64:67]
	v_mfma_f32_16x16x32_bf16 v[120:123], v[220:223], v[188:191], v[120:123]
	v_mfma_f32_16x16x32_bf16 v[112:115], v[228:231], v[188:191], v[112:115]
	v_mfma_f32_16x16x32_bf16 v[104:107], v[220:223], v[196:199], v[104:107]
	v_mfma_f32_16x16x32_bf16 v[96:99], v[228:231], v[196:199], v[96:99]
	v_mfma_f32_16x16x32_bf16 v[88:91], v[220:223], v[204:207], v[88:91]
	v_mfma_f32_16x16x32_bf16 v[80:83], v[228:231], v[204:207], v[80:83]
	v_mfma_f32_16x16x32_bf16 v[72:75], v[220:223], v[212:215], v[72:75]
	v_mfma_f32_16x16x32_bf16 v[64:67], v[228:231], v[212:215], v[64:67]
	s_setprio 0
	s_mov_b32 m0, s35
	v_lshl_add_u64 v[234:235], s[20:21], 0, v[134:135]
	s_barrier
	ds_read_b128 v[184:187], v150 offset:16384
	ds_read_b128 v[188:191], v150 offset:17408
	ds_read_b128 v[192:195], v150 offset:18432
	ds_read_b128 v[196:199], v150 offset:19456
	ds_read_b128 v[200:203], v150 offset:20480
	ds_read_b128 v[204:207], v150 offset:21504
	ds_read_b128 v[208:211], v150 offset:22528
	ds_read_b128 v[212:215], v150 offset:23552
	global_load_lds_dwordx4 v[234:235], off
	v_lshl_add_u64 v[236:237], s[20:21], 0, v[130:131]
	s_mov_b32 m0, s36
	s_nop 0
	global_load_lds_dwordx4 v[236:237], off
	s_barrier
	s_waitcnt lgkmcnt(0)
	s_setprio 1

; #define PG8_STAGE(bufoff, gbase, voff) do { _Pragma("unroll") for (int _i = 0; _i < 2; ++_i) \
;         __builtin_amdgcn_global_load_lds((const unsigned*)((const char*)(gbase) + (voff)[_i]), (LAS unsigned*)(lds + (bufoff) + ldsw + _i * 8192), 16, 0, 0); } while (0)
; #define PG8_LDA(dst, b, h) do { _Pragma("unroll") for (int m = 0; m < 4; ++m) _Pragma("unroll") for (int k = 0; k < 2; ++k) dst[m][k] = *(const LAS bf16x8*)(lds + PG8_SA(b, h) + aoff + m * 2048 + k * 1024); } while (0)
; #define PG8_LDB(dst, b, h) do { _Pragma("unroll") for (int n = 0; n < 2; ++n) _Pragma("unroll") for (int k = 0; k < 2; ++k) dst[n][k] = *(const LAS bf16x8*)(lds + PG8_SB(b, h) + boff + n * 2048 + k * 1024); } while (0)
; #define PG8_MMA(ai, bj, At, Bt) do { __builtin_amdgcn_s_setprio(1); _Pragma("unroll") for (int m = 0; m < 4; ++m) _Pragma("unroll") for (int n = 0; n < 2; ++n) _Pragma("unroll") for (int k = 0; k < 2; ++k) \
;         acc[ai][bj][m][n] = __builtin_amdgcn_mfma_f32_16x16x32_bf16(Bt[n][k], At[m][k], acc[ai][bj][m][n], 0, 0, 0); __builtin_amdgcn_s_setprio(0); } while (0)
; #define PG8_WAIT_V(n) asm volatile("s_waitcnt vmcnt(" #n ")" ::: "memory")
; #define PG8_WAIT_L(n) asm volatile("s_waitcnt lgkmcnt(" #n ")" ::: "memory")
; #define PG8_BAR __builtin_amdgcn_s_barrier()
; #define PG8_SCHED __builtin_amdgcn_sched_barrier(0)
; template <class Epi>
; __device__ __forceinline__ void gemm_phase(LAS unsigned char* lds, const Gemm g, const StaticOrder& S, const Epi& E) {
;     ...
;             PG8_BAR; PG8_WAIT_L(0); PG8_MMA(1, 0, At, B0); PG8_BAR; PG8_SCHED;
;             PG8_STAGE(PG8_SB(0, 1), b2 + hstep, voffB);
;             PG8_WAIT_V(6); PG8_BAR; PG8_MMA(1, 1, At, B1); PG8_BAR;
;             PG8_LDB(B0, 1, 0); PG8_SCHED; PG8_LDA(At, 1, 0); PG8_STAGE(PG8_SA(0, 1), a2 + hstep, voffA);
;             PG8_WAIT_L(8); PG8_BAR; PG8_WAIT_L(0); PG8_MMA(0, 0, At, B0); PG8_BAR; PG8_SCHED;
	v_mfma_f32_16x16x32_bf16 v[60:63], v[166:169], v[184:187], v[60:63]
	v_mfma_f32_16x16x32_bf16 v[52:55], v[174:177], v[184:187], v[52:55]
	v_mfma_f32_16x16x32_bf16 v[44:47], v[166:169], v[192:195], v[44:47]
	v_mfma_f32_16x16x32_bf16 v[36:39], v[174:177], v[192:195], v[36:39]
	v_mfma_f32_16x16x32_bf16 v[28:31], v[166:169], v[200:203], v[28:31]
	v_mfma_f32_16x16x32_bf16 v[20:23], v[174:177], v[200:203], v[20:23]
	v_mfma_f32_16x16x32_bf16 v[12:15], v[166:169], v[208:211], v[12:15]
	v_mfma_f32_16x16x32_bf16 v[4:7], v[174:177], v[208:211], v[4:7]
	v_mfma_f32_16x16x32_bf16 v[60:63], v[170:173], v[188:191], v[60:63]
	v_mfma_f32_16x16x32_bf16 v[52:55], v[180:183], v[188:191], v[52:55]
	v_mfma_f32_16x16x32_bf16 v[44:47], v[170:173], v[196:199], v[44:47]
	v_mfma_f32_16x16x32_bf16 v[36:39], v[180:183], v[196:199], v[36:39]
	v_mfma_f32_16x16x32_bf16 v[28:31], v[170:173], v[204:207], v[28:31]
	v_mfma_f32_16x16x32_bf16 v[20:23], v[180:183], v[204:207], v[20:23]
	v_mfma_f32_16x16x32_bf16 v[12:15], v[170:173], v[212:215], v[12:15]
	v_mfma_f32_16x16x32_bf16 v[4:7], v[180:183], v[212:215], v[4:7]
	s_setprio 0
	s_barrier
	s_add_u32 s66, s18, 0x80000
	s_addc_u32 s67, s19, 0
	s_add_i32 s68, s59, s31
	v_lshl_add_u64 v[166:167], s[66:67], 0, v[132:133]
	s_mov_b32 m0, s68
	s_nop 0
	global_load_lds_dwordx4 v[166:167], off
	v_lshl_add_u64 v[166:167], s[66:67], 0, v[128:129]
	s_add_i32 m0, s68, 0x2000
	s_nop 0
	global_load_lds_dwordx4 v[166:167], off
	s_waitcnt vmcnt(6)
	s_barrier
	s_setprio 1
	v_mfma_f32_16x16x32_bf16 v[56:59], v[216:219], v[184:187], v[56:59]
	v_mfma_f32_16x16x32_bf16 v[48:51], v[224:227], v[184:187], v[48:51]
	v_mfma_f32_16x16x32_bf16 v[40:43], v[216:219], v[192:195], v[40:43]
	v_mfma_f32_16x16x32_bf16 v[32:35], v[224:227], v[192:195], v[32:35]
	v_mfma_f32_16x16x32_bf16 v[24:27], v[216:219], v[200:203], v[24:27]
	v_mfma_f32_16x16x32_bf16 v[16:19], v[224:227], v[200:203], v[16:19]
	v_mfma_f32_16x16x32_bf16 v[8:11], v[216:219], v[208:211], v[8:11]
	v_mfma_f32_16x16x32_bf16 v[0:3], v[224:227], v[208:211], v[0:3]
	v_mfma_f32_16x16x32_bf16 v[56:59], v[220:223], v[188:191], v[56:59]
	v_mfma_f32_16x16x32_bf16 v[48:51], v[228:231], v[188:191], v[48:51]
	v_mfma_f32_16x16x32_bf16 v[40:43], v[220:223], v[196:199], v[40:43]
	v_mfma_f32_16x16x32_bf16 v[32:35], v[228:231], v[196:199], v[32:35]
	v_mfma_f32_16x16x32_bf16 v[24:27], v[220:223], v[204:207], v[24:27]
	v_mfma_f32_16x16x32_bf16 v[16:19], v[228:231], v[204:207], v[16:19]
	v_mfma_f32_16x16x32_bf16 v[8:11], v[220:223], v[212:215], v[8:11]
	v_mfma_f32_16x16x32_bf16 v[0:3], v[228:231], v[212:215], v[0:3]
	s_setprio 0
	s_add_i32 s66, 0, 0x18000
	v_add_u32_e32 v161, s66, v147
	s_barrier
	ds_read_b128 v[166:169], v161
	ds_read_b128 v[170:173], v161 offset:1024
	ds_read_b128 v[174:177], v161 offset:2048
	ds_read_b128 v[180:183], v161 offset:3072
	s_add_u32 s20, s20, 0x80000
	s_addc_u32 s21, s21, 0
	s_mov_b32 m0, s37
	v_lshl_add_u64 v[216:217], s[20:21], 0, v[134:135]
	ds_read_b128 v[184:187], v150 offset:32768
	ds_read_b128 v[188:191], v150 offset:33792
	ds_read_b128 v[192:195], v150 offset:34816
	ds_read_b128 v[196:199], v150 offset:35840
	ds_read_b128 v[200:203], v150 offset:36864
	ds_read_b128 v[204:207], v150 offset:37888
	ds_read_b128 v[208:211], v150 offset:38912
	ds_read_b128 v[212:215], v150 offset:39936
	global_load_lds_dwordx4 v[216:217], off
	v_lshl_add_u64 v[216:217], s[20:21], 0, v[130:131]
	s_mov_b32 m0, s38
	s_nop 0
	global_load_lds_dwordx4 v[216:217], off
	s_waitcnt lgkmcnt(8)
	s_barrier
	s_waitcnt lgkmcnt(0)
	s_setprio 1

; #define PG8_STAGE(bufoff, gbase, voff) do { _Pragma("unroll") for (int _i = 0; _i < 2; ++_i) \
;         __builtin_amdgcn_global_load_lds((const unsigned*)((const char*)(gbase) + (voff)[_i]), (LAS unsigned*)(lds + (bufoff) + ldsw + _i * 8192), 16, 0, 0); } while (0)
; #define PG8_LDB(dst, b, h) do { _Pragma("unroll") for (int n = 0; n < 2; ++n) _Pragma("unroll") for (int k = 0; k < 2; ++k) dst[n][k] = *(const LAS bf16x8*)(lds + PG8_SB(b, h) + boff + n * 2048 + k * 1024); } while (0)
; #define PG8_MMA(ai, bj, At, Bt) do { __builtin_amdgcn_s_setprio(1); _Pragma("unroll") for (int m = 0; m < 4; ++m) _Pragma("unroll") for (int n = 0; n < 2; ++n) _Pragma("unroll") for (int k = 0; k < 2; ++k) \
;         acc[ai][bj][m][n] = __builtin_amdgcn_mfma_f32_16x16x32_bf16(Bt[n][k], At[m][k], acc[ai][bj][m][n], 0, 0, 0); __builtin_amdgcn_s_setprio(0); } while (0)
; #define PG8_WAIT_L(n) asm volatile("s_waitcnt lgkmcnt(" #n ")" ::: "memory")
; #define PG8_BAR __builtin_amdgcn_s_barrier()
; #define PG8_SCHED __builtin_amdgcn_sched_barrier(0)
; template <class Epi>
; __device__ __forceinline__ void gemm_phase(LAS unsigned char* lds, const Gemm g, const StaticOrder& S, const Epi& E) {
;     ...
;             PG8_WAIT_L(8); PG8_BAR; PG8_WAIT_L(0); PG8_MMA(0, 0, At, B0); PG8_BAR; PG8_SCHED;
;             PG8_LDB(B1, 1, 1); PG8_STAGE(PG8_SB(1, 0), b3, voffB);
;             PG8_BAR; PG8_WAIT_L(0); PG8_MMA(0, 1, At, B1); PG8_BAR;
	v_mfma_f32_16x16x32_bf16 v[124:127], v[166:169], v[184:187], v[124:127]
	v_mfma_f32_16x16x32_bf16 v[116:119], v[174:177], v[184:187], v[116:119]
	v_mfma_f32_16x16x32_bf16 v[108:111], v[166:169], v[192:195], v[108:111]
	v_mfma_f32_16x16x32_bf16 v[100:103], v[174:177], v[192:195], v[100:103]
	v_mfma_f32_16x16x32_bf16 v[92:95], v[166:169], v[200:203], v[92:95]
	v_mfma_f32_16x16x32_bf16 v[84:87], v[174:177], v[200:203], v[84:87]
	v_mfma_f32_16x16x32_bf16 v[76:79], v[166:169], v[208:211], v[76:79]
	v_mfma_f32_16x16x32_bf16 v[68:71], v[174:177], v[208:211], v[68:71]
	v_mfma_f32_16x16x32_bf16 v[124:127], v[170:173], v[188:191], v[124:127]
	v_mfma_f32_16x16x32_bf16 v[116:119], v[180:183], v[188:191], v[116:119]
	v_mfma_f32_16x16x32_bf16 v[108:111], v[170:173], v[196:199], v[108:111]
	v_mfma_f32_16x16x32_bf16 v[100:103], v[180:183], v[196:199], v[100:103]
	v_mfma_f32_16x16x32_bf16 v[92:95], v[170:173], v[204:207], v[92:95]
	v_mfma_f32_16x16x32_bf16 v[84:87], v[180:183], v[204:207], v[84:87]
	v_mfma_f32_16x16x32_bf16 v[76:79], v[170:173], v[212:215], v[76:79]
	v_mfma_f32_16x16x32_bf16 v[68:71], v[180:183], v[212:215], v[68:71]
	s_setprio 0
	s_barrier
	s_add_i32 s20, 0, 0x1c000
	s_add_i32 s21, s66, s31
	v_add_u32_e32 v161, s20, v147
	v_lshl_add_u64 v[162:163], v[162:163], 0, s[4:5]
	s_mov_b32 m0, s21
	ds_read_b128 v[216:219], v161
	ds_read_b128 v[220:223], v161 offset:1024
	ds_read_b128 v[224:227], v161 offset:2048
	ds_read_b128 v[228:231], v161 offset:3072
	global_load_lds_dwordx4 v[162:163], off
	v_lshl_add_u64 v[162:163], v[232:233], 0, s[4:5]
	s_add_i32 m0, s21, 0x2000
	s_nop 0
	global_load_lds_dwordx4 v[162:163], off
	s_barrier
	s_waitcnt lgkmcnt(0)
	s_setprio 1

; #define PG8_STAGE(bufoff, gbase, voff) do { _Pragma("unroll") for (int _i = 0; _i < 2; ++_i) \
;         __builtin_amdgcn_global_load_lds((const unsigned*)((const char*)(gbase) + (voff)[_i]), (LAS unsigned*)(lds + (bufoff) + ldsw + _i * 8192), 16, 0, 0); } while (0)
; #define PG8_LDA(dst, b, h) do { _Pragma("unroll") for (int m = 0; m < 4; ++m) _Pragma("unroll") for (int k = 0; k < 2; ++k) dst[m][k] = *(const LAS bf16x8*)(lds + PG8_SA(b, h) + aoff + m * 2048 + k * 1024); } while (0)
; #define PG8_MMA(ai, bj, At, Bt) do { __builtin_amdgcn_s_setprio(1); _Pragma("unroll") for (int m = 0; m < 4; ++m) _Pragma("unroll") for (int n = 0; n < 2; ++n) _Pragma("unroll") for (int k = 0; k < 2; ++k) \
;         acc[ai][bj][m][n] = __builtin_amdgcn_mfma_f32_16x16x32_bf16(Bt[n][k], At[m][k], acc[ai][bj][m][n], 0, 0, 0); __builtin_amdgcn_s_setprio(0); } while (0)
; #define PG8_WAIT_L(n) asm volatile("s_waitcnt lgkmcnt(" #n ")" ::: "memory")
; #define PG8_BAR __builtin_amdgcn_s_barrier()
; #define PG8_SCHED __builtin_amdgcn_sched_barrier(0)
; template <class Epi>
; __device__ __forceinline__ void gemm_phase(LAS unsigned char* lds, const Gemm g, const StaticOrder& S, const Epi& E) {
;     ...
;             PG8_BAR; PG8_WAIT_L(0); PG8_MMA(0, 1, At, B1); PG8_BAR;
;             PG8_LDA(At, 1, 1); PG8_STAGE(PG8_SA(1, 0), a3, voffA);
;             PG8_BAR; PG8_WAIT_L(0); PG8_MMA(1, 0, At, B0); PG8_BAR; PG8_SCHED;
	v_mfma_f32_16x16x32_bf16 v[120:123], v[216:219], v[184:187], v[120:123]
	v_mfma_f32_16x16x32_bf16 v[112:115], v[224:227], v[184:187], v[112:115]
	v_mfma_f32_16x16x32_bf16 v[104:107], v[216:219], v[192:195], v[104:107]
	v_mfma_f32_16x16x32_bf16 v[96:99], v[224:227], v[192:195], v[96:99]
	v_mfma_f32_16x16x32_bf16 v[88:91], v[216:219], v[200:203], v[88:91]
	v_mfma_f32_16x16x32_bf16 v[80:83], v[224:227], v[200:203], v[80:83]
	v_mfma_f32_16x16x32_bf16 v[72:75], v[216:219], v[208:211], v[72:75]
	v_mfma_f32_16x16x32_bf16 v[64:67], v[224:227], v[208:211], v[64:67]
	v_mfma_f32_16x16x32_bf16 v[120:123], v[220:223], v[188:191], v[120:123]
	v_mfma_f32_16x16x32_bf16 v[112:115], v[228:231], v[188:191], v[112:115]
	v_mfma_f32_16x16x32_bf16 v[104:107], v[220:223], v[196:199], v[104:107]
	v_mfma_f32_16x16x32_bf16 v[96:99], v[228:231], v[196:199], v[96:99]
	v_mfma_f32_16x16x32_bf16 v[88:91], v[220:223], v[204:207], v[88:91]
	v_mfma_f32_16x16x32_bf16 v[80:83], v[228:231], v[204:207], v[80:83]
	v_mfma_f32_16x16x32_bf16 v[72:75], v[220:223], v[212:215], v[72:75]
	v_mfma_f32_16x16x32_bf16 v[64:67], v[228:231], v[212:215], v[64:67]
	s_setprio 0
	s_mov_b32 m0, s42
	v_lshl_add_u64 v[162:163], v[234:235], 0, s[4:5]
	s_barrier
	ds_read_b128 v[184:187], v150 offset:49152
	ds_read_b128 v[188:191], v150 offset:50176
	ds_read_b128 v[192:195], v150 offset:51200
	ds_read_b128 v[196:199], v150 offset:52224
	ds_read_b128 v[200:203], v150 offset:53248
	ds_read_b128 v[204:207], v150 offset:54272
	ds_read_b128 v[208:211], v150 offset:55296
	ds_read_b128 v[212:215], v150 offset:56320
	global_load_lds_dwordx4 v[162:163], off
	v_lshl_add_u64 v[162:163], v[236:237], 0, s[4:5]
	s_mov_b32 m0, s43
	s_nop 0
	global_load_lds_dwordx4 v[162:163], off
	s_barrier
	s_waitcnt lgkmcnt(0)
	s_setprio 1

; __device__ __forceinline__ float sigmoidf_(float x) { return __builtin_amdgcn_rcpf(1.0f + fexp(-x)); }
; #define PG8_STAGE(bufoff, gbase, voff) do { _Pragma("unroll") for (int _i = 0; _i < 2; ++_i) \
;         __builtin_amdgcn_global_load_lds((const unsigned*)((const char*)(gbase) + (voff)[_i]), (LAS unsigned*)(lds + (bufoff) + ldsw + _i * 8192), 16, 0, 0); } while (0)
; #define PG8_MMA(ai, bj, At, Bt) do { __builtin_amdgcn_s_setprio(1); _Pragma("unroll") for (int m = 0; m < 4; ++m) _Pragma("unroll") for (int n = 0; n < 2; ++n) _Pragma("unroll") for (int k = 0; k < 2; ++k) \
;         acc[ai][bj][m][n] = __builtin_amdgcn_mfma_f32_16x16x32_bf16(Bt[n][k], At[m][k], acc[ai][bj][m][n], 0, 0, 0); __builtin_amdgcn_s_setprio(0); } while (0)
; #define PG8_WAIT_V(n) asm volatile("s_waitcnt vmcnt(" #n ")" ::: "memory")
; #define PG8_WAIT_L(n) asm volatile("s_waitcnt lgkmcnt(" #n ")" ::: "memory")
; #define PG8_BAR __builtin_amdgcn_s_barrier()
; #define PG8_SCHED __builtin_amdgcn_sched_barrier(0)
; template <class Epi>
; __device__ __forceinline__ void gemm_phase(LAS unsigned char* lds, const Gemm g, const StaticOrder& S, const Epi& E) {
;     ...
;             PG8_BAR; PG8_WAIT_L(0); PG8_MMA(1, 0, At, B0); PG8_BAR; PG8_SCHED;
;             PG8_STAGE(PG8_SB(1, 1), b3 + hstep, voffB);
;             PG8_WAIT_V(6); PG8_BAR; PG8_MMA(1, 1, At, B1); PG8_BAR;
;     __device__ __forceinline__ void operator()(const f32x4 (&acc)[2][2][4][2], const Unit& u, int wr, int wc, int fr, int fq, const Pre& P) const {
;         const int row0 = ROW_X + u.pm * BM + wr * 64 + fr, col0 = u.pn * HALF + wc * 32 + 8 * fq;
; #pragma unroll
;         for (int ai = 0; ai < 2; ++ai)
; #pragma unroll
;             for (int m = 0; m < 4; ++m) { const int r = row0 + ai * HALF + m * 16; const float rs = __builtin_amdgcn_rsqf(P.rs[ai * 4 + m] * (1.0f / DM) + RMS_EPS);
;                 float y[8];
; #pragma unroll
;                 for (int n = 0; n < 2; ++n)
; #pragma unroll
;                     for (int j = 0; j < 4; ++j) { const float a = acc[ai][0][m][n][j] * rs, b = acc[ai][1][m][n][j] * rs; y[n * 4 + j] = a * b * sigmoidf_(a); }
;                 u32x4 w; w.x = cvtpk(y[0], y[1]); w.y = cvtpk(y[2], y[3]); w.z = cvtpk(y[4], y[5]); w.w = cvtpk(y[6], y[7]);
;                 *(u32x4*)(O + (size_t)r * FF + col0) = w; }
	v_mfma_f32_16x16x32_bf16 v[60:63], v[166:169], v[184:187], v[60:63]
	v_mfma_f32_16x16x32_bf16 v[52:55], v[174:177], v[184:187], v[52:55]
	v_mfma_f32_16x16x32_bf16 v[44:47], v[166:169], v[192:195], v[44:47]
	v_mfma_f32_16x16x32_bf16 v[36:39], v[174:177], v[192:195], v[36:39]
	v_mfma_f32_16x16x32_bf16 v[28:31], v[166:169], v[200:203], v[28:31]
	v_mfma_f32_16x16x32_bf16 v[20:23], v[174:177], v[200:203], v[20:23]
	v_mfma_f32_16x16x32_bf16 v[12:15], v[166:169], v[208:211], v[12:15]
	v_mfma_f32_16x16x32_bf16 v[4:7], v[174:177], v[208:211], v[4:7]
	v_mfma_f32_16x16x32_bf16 v[60:63], v[170:173], v[188:191], v[60:63]
	v_mfma_f32_16x16x32_bf16 v[52:55], v[180:183], v[188:191], v[52:55]
	v_mfma_f32_16x16x32_bf16 v[44:47], v[170:173], v[196:199], v[44:47]
	v_mfma_f32_16x16x32_bf16 v[36:39], v[180:183], v[196:199], v[36:39]
	v_mfma_f32_16x16x32_bf16 v[28:31], v[170:173], v[204:207], v[28:31]
	v_mfma_f32_16x16x32_bf16 v[20:23], v[180:183], v[204:207], v[20:23]
	v_mfma_f32_16x16x32_bf16 v[12:15], v[170:173], v[212:215], v[12:15]
	v_mfma_f32_16x16x32_bf16 v[4:7], v[180:183], v[212:215], v[4:7]
	s_setprio 0
	s_barrier
	s_add_u32 s18, s18, 0x80080
	s_addc_u32 s19, s19, 0
	s_add_i32 s20, s20, s31
	v_lshl_add_u64 v[162:163], s[18:19], 0, v[132:133]
	s_mov_b32 m0, s20
	s_nop 0
	global_load_lds_dwordx4 v[162:163], off
	v_lshl_add_u64 v[162:163], s[18:19], 0, v[128:129]
	s_add_i32 m0, s20, 0x2000
	s_nop 0
	global_load_lds_dwordx4 v[162:163], off
	s_waitcnt vmcnt(6)
	s_barrier
	s_setprio 1
	v_mfma_f32_16x16x32_bf16 v[56:59], v[216:219], v[184:187], v[56:59]
	v_mfma_f32_16x16x32_bf16 v[48:51], v[224:227], v[184:187], v[48:51]
	v_mfma_f32_16x16x32_bf16 v[40:43], v[216:219], v[192:195], v[40:43]
	v_mfma_f32_16x16x32_bf16 v[32:35], v[224:227], v[192:195], v[32:35]
	v_mfma_f32_16x16x32_bf16 v[24:27], v[216:219], v[200:203], v[24:27]
	v_mfma_f32_16x16x32_bf16 v[16:19], v[224:227], v[200:203], v[16:19]
	v_mfma_f32_16x16x32_bf16 v[8:11], v[216:219], v[208:211], v[8:11]
	v_mfma_f32_16x16x32_bf16 v[0:3], v[224:227], v[208:211], v[0:3]
	v_mfma_f32_16x16x32_bf16 v[56:59], v[220:223], v[188:191], v[56:59]
	v_mfma_f32_16x16x32_bf16 v[48:51], v[228:231], v[188:191], v[48:51]
	v_mfma_f32_16x16x32_bf16 v[40:43], v[220:223], v[196:199], v[40:43]
	v_mfma_f32_16x16x32_bf16 v[32:35], v[228:231], v[196:199], v[32:35]
	v_mfma_f32_16x16x32_bf16 v[24:27], v[220:223], v[204:207], v[24:27]
	v_mfma_f32_16x16x32_bf16 v[16:19], v[228:231], v[204:207], v[16:19]
	v_mfma_f32_16x16x32_bf16 v[8:11], v[220:223], v[212:215], v[8:11]
	v_mfma_f32_16x16x32_bf16 v[0:3], v[228:231], v[212:215], v[0:3]
	s_setprio 0
	s_add_i32 s65, s65, 2
	s_add_u32 s16, s16, 0x100
	s_addc_u32 s17, s17, 0
	s_add_u32 s63, s63, 0x100
	s_addc_u32 s64, s64, 0
	s_cmp_gt_u32 s65, 29
	s_barrier
	s_cbranch_scc0 .LBB0_1306
	s_waitcnt vmcnt(0)
	v_fmamk_f32 v160, v160, 0x3a000000, v153
	v_rsq_f32_e32 v160, v160
	v_lshl_or_b32 v166, s15, 7, v148
	v_ashrrev_i32_e32 v167, 31, v166
	s_and_b64 vcc, vcc, exec
	v_pk_mul_f32 v[162:163], v[160:161], v[124:125] op_sel_hi:[0,1]
	v_mul_f32_e32 v124, 0xbfb8aa3b, v162
	v_mul_f32_e32 v125, 0xbfb8aa3b, v163
	v_exp_f32_e32 v161, v124
	v_exp_f32_e32 v125, v125
	v_lshl_add_u32 v124, s14, 8, v146
	v_add_f32_e32 v161, 1.0, v161
	v_add_f32_e32 v125, 1.0, v125
	v_rcp_f32_e32 v168, v161
	v_rcp_f32_e32 v169, v125
	v_pk_mul_f32 v[120:121], v[160:161], v[120:121] op_sel_hi:[0,1]
	v_pk_mul_f32 v[120:121], v[162:163], v[120:121]
	v_pk_mul_f32 v[126:127], v[160:161], v[126:127] op_sel_hi:[0,1]
	v_pk_mul_f32 v[120:121], v[168:169], v[120:121]
	v_mul_f32_e32 v125, 0xbfb8aa3b, v126
	v_cvt_pk_bf16_f32 v120, v120, v121
	v_mul_f32_e32 v121, 0xbfb8aa3b, v127
	v_exp_f32_e32 v125, v125
	v_exp_f32_e32 v121, v121
	v_pk_mul_f32 v[122:123], v[160:161], v[122:123] op_sel_hi:[0,1]
	v_pk_mul_f32 v[116:117], v[160:161], v[116:117] op_sel_hi:[0,1]
	v_add_f32_e32 v125, 1.0, v125
	v_add_f32_e32 v121, 1.0, v121
	v_rcp_f32_e32 v162, v125
	v_rcp_f32_e32 v163, v121
	v_pk_mul_f32 v[122:123], v[126:127], v[122:123]
	v_mul_f32_e32 v121, 0xbfb8aa3b, v116
	v_exp_f32_e32 v125, v121
	v_pk_mul_f32 v[122:123], v[162:163], v[122:123]
	v_pk_mul_f32 v[112:113], v[160:161], v[112:113] op_sel_hi:[0,1]
	v_cvt_pk_bf16_f32 v121, v122, v123
	v_mul_f32_e32 v123, 0xbfb8aa3b, v117
	v_exp_f32_e32 v123, v123
	v_add_f32_e32 v122, 1.0, v125
	v_pk_mul_f32 v[112:113], v[116:117], v[112:113]
	v_rcp_f32_e32 v122, v122
	v_add_f32_e32 v116, 1.0, v123
	v_rcp_f32_e32 v123, v116
	v_pk_mul_f32 v[116:117], v[160:161], v[118:119] op_sel_hi:[0,1]
	v_mul_f32_e32 v118, 0xbfb8aa3b, v116
	v_mul_f32_e32 v119, 0xbfb8aa3b, v117
	v_exp_f32_e32 v118, v118
	v_exp_f32_e32 v119, v119
	v_pk_mul_f32 v[112:113], v[122:123], v[112:113]
	v_add_f32_e32 v118, 1.0, v118
	v_cvt_pk_bf16_f32 v122, v112, v113
	v_pk_mul_f32 v[112:113], v[160:161], v[114:115] op_sel_hi:[0,1]
	v_fmamk_f32 v114, v159, 0x3a000000, v153
	v_pk_mul_f32 v[112:113], v[116:117], v[112:113]
	v_rsq_f32_e32 v116, v114
	v_add_f32_e32 v119, 1.0, v119
	v_rcp_f32_e32 v118, v118
	v_rcp_f32_e32 v119, v119
	v_pk_mul_f32 v[108:109], v[116:117], v[108:109] op_sel_hi:[0,1]
	v_mul_f32_e32 v117, 0xbfb8aa3b, v108
	v_exp_f32_e32 v117, v117
	v_mul_f32_e32 v125, 0xbfb8aa3b, v109
	v_pk_mul_f32 v[112:113], v[118:119], v[112:113]
	v_exp_f32_e32 v125, v125
	v_cvt_pk_bf16_f32 v123, v112, v113
	v_mov_b64_e32 v[112:113], s[0:1]
	v_mad_i64_i32 v[118:119], s[14:15], v124, s60, v[112:113]
	v_lshlrev_b64 v[114:115], 1, v[166:167]
	v_lshl_add_u64 v[118:119], v[118:119], 0, v[114:115]
	v_add_f32_e32 v117, 1.0, v117
	global_store_dwordx4 v[118:119], v[120:123], off
	v_rcp_f32_e32 v118, v117
	v_add_f32_e32 v117, 1.0, v125
	v_rcp_f32_e32 v119, v117
; __device__ __forceinline__ float sigmoidf_(float x) { return __builtin_amdgcn_rcpf(1.0f + fexp(-x)); }
;     __device__ __forceinline__ void operator()(const f32x4 (&acc)[2][2][4][2], const Unit& u, int wr, int wc, int fr, int fq, const Pre& P) const {
;         const int row0 = ROW_X + u.pm * BM + wr * 64 + fr, col0 = u.pn * HALF + wc * 32 + 8 * fq;
; #pragma unroll
;         for (int ai = 0; ai < 2; ++ai)
; #pragma unroll
;             for (int m = 0; m < 4; ++m) { const int r = row0 + ai * HALF + m * 16; const float rs = __builtin_amdgcn_rsqf(P.rs[ai * 4 + m] * (1.0f / DM) + RMS_EPS);
;                 float y[8];
; #pragma unroll
;                 for (int n = 0; n < 2; ++n)
; #pragma unroll
;                     for (int j = 0; j < 4; ++j) { const float a = acc[ai][0][m][n][j] * rs, b = acc[ai][1][m][n][j] * rs; y[n * 4 + j] = a * b * sigmoidf_(a); }
;                 u32x4 w; w.x = cvtpk(y[0], y[1]); w.y = cvtpk(y[2], y[3]); w.z = cvtpk(y[4], y[5]); w.w = cvtpk(y[6], y[7]);
;                 *(u32x4*)(O + (size_t)r * FF + col0) = w; }
	v_or_b32_e32 v117, 16, v124
	v_pk_mul_f32 v[104:105], v[116:117], v[104:105] op_sel_hi:[0,1]
	v_pk_mul_f32 v[104:105], v[108:109], v[104:105]
	v_pk_mul_f32 v[108:109], v[116:117], v[110:111] op_sel_hi:[0,1]
	v_pk_mul_f32 v[104:105], v[118:119], v[104:105]
	v_mul_f32_e32 v110, 0xbfb8aa3b, v108
	v_cvt_pk_bf16_f32 v104, v104, v105
	v_mul_f32_e32 v105, 0xbfb8aa3b, v109
	v_exp_f32_e32 v110, v110
	v_exp_f32_e32 v105, v105
	v_pk_mul_f32 v[106:107], v[116:117], v[106:107] op_sel_hi:[0,1]
	v_pk_mul_f32 v[100:101], v[116:117], v[100:101] op_sel_hi:[0,1]
	v_add_f32_e32 v110, 1.0, v110
	v_add_f32_e32 v105, 1.0, v105
	v_rcp_f32_e32 v110, v110
	v_rcp_f32_e32 v111, v105
	v_pk_mul_f32 v[106:107], v[108:109], v[106:107]
	v_mul_f32_e32 v105, 0xbfb8aa3b, v100
	v_exp_f32_e32 v118, v105
	v_pk_mul_f32 v[106:107], v[110:111], v[106:107]
	v_pk_mul_f32 v[96:97], v[116:117], v[96:97] op_sel_hi:[0,1]
	v_cvt_pk_bf16_f32 v105, v106, v107
	v_mul_f32_e32 v107, 0xbfb8aa3b, v101
	v_exp_f32_e32 v107, v107
	v_pk_mul_f32 v[96:97], v[100:101], v[96:97]
	v_add_f32_e32 v106, 1.0, v118
	v_rcp_f32_e32 v106, v106
	v_add_f32_e32 v100, 1.0, v107
	v_rcp_f32_e32 v107, v100
	v_pk_mul_f32 v[100:101], v[116:117], v[102:103] op_sel_hi:[0,1]
	v_mul_f32_e32 v102, 0xbfb8aa3b, v100
	v_mul_f32_e32 v103, 0xbfb8aa3b, v101
	v_exp_f32_e32 v102, v102
	v_exp_f32_e32 v103, v103
	v_pk_mul_f32 v[96:97], v[106:107], v[96:97]
	v_add_f32_e32 v102, 1.0, v102
	v_add_f32_e32 v103, 1.0, v103
	v_rcp_f32_e32 v102, v102
	v_rcp_f32_e32 v103, v103
	v_cvt_pk_bf16_f32 v106, v96, v97
	v_pk_mul_f32 v[96:97], v[116:117], v[98:99] op_sel_hi:[0,1]
	v_pk_mul_f32 v[96:97], v[100:101], v[96:97]
	v_mad_i64_i32 v[98:99], s[14:15], v117, s60, v[112:113]
	v_pk_mul_f32 v[96:97], v[102:103], v[96:97]
	v_lshl_add_u64 v[98:99], v[98:99], 0, v[114:115]
	v_cvt_pk_bf16_f32 v107, v96, v97
	v_fmamk_f32 v96, v158, 0x3a000000, v153
	v_rsq_f32_e32 v96, v96
	global_store_dwordx4 v[98:99], v[104:107], off
	v_pk_mul_f32 v[92:93], v[96:97], v[92:93] op_sel_hi:[0,1]
	v_mul_f32_e32 v97, 0xbfb8aa3b, v92
	v_exp_f32_e32 v97, v97
	v_mul_f32_e32 v100, 0xbfb8aa3b, v93
	v_exp_f32_e32 v100, v100
	v_add_f32_e32 v97, 1.0, v97
	v_rcp_f32_e32 v98, v97
	v_add_f32_e32 v97, 1.0, v100
	v_rcp_f32_e32 v99, v97
	v_or_b32_e32 v97, 32, v124
	v_pk_mul_f32 v[88:89], v[96:97], v[88:89] op_sel_hi:[0,1]
	v_pk_mul_f32 v[88:89], v[92:93], v[88:89]
	v_pk_mul_f32 v[92:93], v[96:97], v[94:95] op_sel_hi:[0,1]
	v_pk_mul_f32 v[88:89], v[98:99], v[88:89]
	v_mul_f32_e32 v94, 0xbfb8aa3b, v92
	v_cvt_pk_bf16_f32 v88, v88, v89
	v_mul_f32_e32 v89, 0xbfb8aa3b, v93
	v_exp_f32_e32 v94, v94
	v_exp_f32_e32 v89, v89
	v_pk_mul_f32 v[90:91], v[96:97], v[90:91] op_sel_hi:[0,1]
	v_pk_mul_f32 v[84:85], v[96:97], v[84:85] op_sel_hi:[0,1]
	v_add_f32_e32 v94, 1.0, v94
	v_add_f32_e32 v89, 1.0, v89
	v_rcp_f32_e32 v94, v94
	v_rcp_f32_e32 v95, v89
	v_pk_mul_f32 v[90:91], v[92:93], v[90:91]
	v_mul_f32_e32 v89, 0xbfb8aa3b, v84
	v_exp_f32_e32 v98, v89
	v_pk_mul_f32 v[90:91], v[94:95], v[90:91]
	v_pk_mul_f32 v[80:81], v[96:97], v[80:81] op_sel_hi:[0,1]
	v_cvt_pk_bf16_f32 v89, v90, v91
	v_mul_f32_e32 v91, 0xbfb8aa3b, v85
	v_exp_f32_e32 v91, v91
	v_pk_mul_f32 v[80:81], v[84:85], v[80:81]
	v_add_f32_e32 v90, 1.0, v98
	v_rcp_f32_e32 v90, v90
	v_add_f32_e32 v84, 1.0, v91
	v_rcp_f32_e32 v91, v84
	v_pk_mul_f32 v[84:85], v[96:97], v[86:87] op_sel_hi:[0,1]
	v_mul_f32_e32 v86, 0xbfb8aa3b, v84
	v_mul_f32_e32 v87, 0xbfb8aa3b, v85
	v_exp_f32_e32 v86, v86
	v_exp_f32_e32 v87, v87
	v_pk_mul_f32 v[80:81], v[90:91], v[80:81]
	v_add_f32_e32 v86, 1.0, v86
	v_add_f32_e32 v87, 1.0, v87
	v_rcp_f32_e32 v86, v86
	v_rcp_f32_e32 v87, v87
	v_cvt_pk_bf16_f32 v90, v80, v81
	v_pk_mul_f32 v[80:81], v[96:97], v[82:83] op_sel_hi:[0,1]
	v_pk_mul_f32 v[80:81], v[84:85], v[80:81]
	v_mad_i64_i32 v[82:83], s[14:15], v97, s60, v[112:113]
	v_pk_mul_f32 v[80:81], v[86:87], v[80:81]
	v_lshl_add_u64 v[82:83], v[82:83], 0, v[114:115]
	v_cvt_pk_bf16_f32 v91, v80, v81
	v_fmamk_f32 v80, v157, 0x3a000000, v153
	v_rsq_f32_e32 v80, v80
	global_store_dwordx4 v[82:83], v[88:91], off
	v_pk_mul_f32 v[76:77], v[80:81], v[76:77] op_sel_hi:[0,1]
	v_mul_f32_e32 v81, 0xbfb8aa3b, v76
	v_exp_f32_e32 v81, v81
	v_mul_f32_e32 v84, 0xbfb8aa3b, v77
	v_exp_f32_e32 v84, v84
	v_add_f32_e32 v81, 1.0, v81
	v_rcp_f32_e32 v82, v81
	v_add_f32_e32 v81, 1.0, v84
	v_rcp_f32_e32 v83, v81
	v_or_b32_e32 v81, 48, v124
	v_pk_mul_f32 v[72:73], v[80:81], v[72:73] op_sel_hi:[0,1]
	v_pk_mul_f32 v[72:73], v[76:77], v[72:73]
	v_pk_mul_f32 v[76:77], v[80:81], v[78:79] op_sel_hi:[0,1]
	v_pk_mul_f32 v[72:73], v[82:83], v[72:73]
	v_mul_f32_e32 v78, 0xbfb8aa3b, v76
	v_cvt_pk_bf16_f32 v72, v72, v73
	v_mul_f32_e32 v73, 0xbfb8aa3b, v77
	v_exp_f32_e32 v78, v78
	v_exp_f32_e32 v73, v73
	v_pk_mul_f32 v[74:75], v[80:81], v[74:75] op_sel_hi:[0,1]
	v_pk_mul_f32 v[68:69], v[80:81], v[68:69] op_sel_hi:[0,1]
	v_add_f32_e32 v78, 1.0, v78
	v_add_f32_e32 v73, 1.0, v73
	v_rcp_f32_e32 v78, v78
	v_rcp_f32_e32 v79, v73
	v_pk_mul_f32 v[74:75], v[76:77], v[74:75]
	v_mul_f32_e32 v73, 0xbfb8aa3b, v68
	v_exp_f32_e32 v82, v73
	v_pk_mul_f32 v[74:75], v[78:79], v[74:75]
	v_pk_mul_f32 v[64:65], v[80:81], v[64:65] op_sel_hi:[0,1]
	v_cvt_pk_bf16_f32 v73, v74, v75
	v_mul_f32_e32 v75, 0xbfb8aa3b, v69
	v_exp_f32_e32 v75, v75
	v_pk_mul_f32 v[64:65], v[68:69], v[64:65]
	v_add_f32_e32 v74, 1.0, v82
	v_rcp_f32_e32 v74, v74
	v_add_f32_e32 v68, 1.0, v75
	v_rcp_f32_e32 v75, v68
	v_pk_mul_f32 v[68:69], v[80:81], v[70:71] op_sel_hi:[0,1]
	v_mul_f32_e32 v70, 0xbfb8aa3b, v68
	v_mul_f32_e32 v71, 0xbfb8aa3b, v69
	v_exp_f32_e32 v70, v70
	v_exp_f32_e32 v71, v71
	v_pk_mul_f32 v[64:65], v[74:75], v[64:65]
	v_add_f32_e32 v70, 1.0, v70
; __device__ __forceinline__ float sigmoidf_(float x) { return __builtin_amdgcn_rcpf(1.0f + fexp(-x)); }
;     __device__ __forceinline__ void operator()(const f32x4 (&acc)[2][2][4][2], const Unit& u, int wr, int wc, int fr, int fq, const Pre& P) const {
;     ...
; #pragma unroll
;         for (int ai = 0; ai < 2; ++ai)
; #pragma unroll
;             for (int m = 0; m < 4; ++m) { const int r = row0 + ai * HALF + m * 16; const float rs = __builtin_amdgcn_rsqf(P.rs[ai * 4 + m] * (1.0f / DM) + RMS_EPS);
;                 float y[8];
; #pragma unroll
;                 for (int n = 0; n < 2; ++n)
; #pragma unroll
;                     for (int j = 0; j < 4; ++j) { const float a = acc[ai][0][m][n][j] * rs, b = acc[ai][1][m][n][j] * rs; y[n * 4 + j] = a * b * sigmoidf_(a); }
;                 u32x4 w; w.x = cvtpk(y[0], y[1]); w.y = cvtpk(y[2], y[3]); w.z = cvtpk(y[4], y[5]); w.w = cvtpk(y[6], y[7]);
;                 *(u32x4*)(O + (size_t)r * FF + col0) = w; }
	v_add_f32_e32 v71, 1.0, v71
	v_rcp_f32_e32 v70, v70
	v_rcp_f32_e32 v71, v71
	v_cvt_pk_bf16_f32 v74, v64, v65
	v_pk_mul_f32 v[64:65], v[80:81], v[66:67] op_sel_hi:[0,1]
	v_pk_mul_f32 v[64:65], v[68:69], v[64:65]
	v_mad_i64_i32 v[66:67], s[14:15], v81, s60, v[112:113]
	v_pk_mul_f32 v[64:65], v[70:71], v[64:65]
	v_lshl_add_u64 v[66:67], v[66:67], 0, v[114:115]
	v_cvt_pk_bf16_f32 v75, v64, v65
	v_fmamk_f32 v64, v156, 0x3a000000, v153
	v_rsq_f32_e32 v64, v64
	global_store_dwordx4 v[66:67], v[72:75], off
	v_pk_mul_f32 v[60:61], v[64:65], v[60:61] op_sel_hi:[0,1]
	v_mul_f32_e32 v65, 0xbfb8aa3b, v60
	v_exp_f32_e32 v65, v65
	v_mul_f32_e32 v68, 0xbfb8aa3b, v61
	v_exp_f32_e32 v68, v68
	v_add_f32_e32 v65, 1.0, v65
	v_rcp_f32_e32 v66, v65
	v_add_f32_e32 v65, 1.0, v68
	v_rcp_f32_e32 v67, v65
	v_add_u32_e32 v65, 0x80, v124
	v_pk_mul_f32 v[56:57], v[64:65], v[56:57] op_sel_hi:[0,1]
	v_pk_mul_f32 v[56:57], v[60:61], v[56:57]
	v_pk_mul_f32 v[60:61], v[64:65], v[62:63] op_sel_hi:[0,1]
	v_pk_mul_f32 v[56:57], v[66:67], v[56:57]
	v_mul_f32_e32 v62, 0xbfb8aa3b, v60
	v_cvt_pk_bf16_f32 v56, v56, v57
	v_mul_f32_e32 v57, 0xbfb8aa3b, v61
	v_exp_f32_e32 v62, v62
	v_exp_f32_e32 v57, v57
	v_pk_mul_f32 v[58:59], v[64:65], v[58:59] op_sel_hi:[0,1]
	v_pk_mul_f32 v[52:53], v[64:65], v[52:53] op_sel_hi:[0,1]
	v_add_f32_e32 v62, 1.0, v62
	v_add_f32_e32 v57, 1.0, v57
	v_rcp_f32_e32 v62, v62
	v_rcp_f32_e32 v63, v57
	v_pk_mul_f32 v[58:59], v[60:61], v[58:59]
	v_mul_f32_e32 v57, 0xbfb8aa3b, v52
	v_exp_f32_e32 v66, v57
	v_pk_mul_f32 v[58:59], v[62:63], v[58:59]
	v_pk_mul_f32 v[48:49], v[64:65], v[48:49] op_sel_hi:[0,1]
	v_cvt_pk_bf16_f32 v57, v58, v59
	v_mul_f32_e32 v59, 0xbfb8aa3b, v53
	v_exp_f32_e32 v59, v59
	v_pk_mul_f32 v[48:49], v[52:53], v[48:49]
	v_add_f32_e32 v58, 1.0, v66
	v_rcp_f32_e32 v58, v58
	v_add_f32_e32 v52, 1.0, v59
	v_rcp_f32_e32 v59, v52
	v_pk_mul_f32 v[52:53], v[64:65], v[54:55] op_sel_hi:[0,1]
	v_mul_f32_e32 v54, 0xbfb8aa3b, v52
	v_mul_f32_e32 v55, 0xbfb8aa3b, v53
	v_exp_f32_e32 v54, v54
	v_exp_f32_e32 v55, v55
	v_pk_mul_f32 v[48:49], v[58:59], v[48:49]
	v_add_f32_e32 v54, 1.0, v54
	v_add_f32_e32 v55, 1.0, v55
	v_rcp_f32_e32 v54, v54
	v_rcp_f32_e32 v55, v55
	v_cvt_pk_bf16_f32 v58, v48, v49
	v_pk_mul_f32 v[48:49], v[64:65], v[50:51] op_sel_hi:[0,1]
	v_pk_mul_f32 v[48:49], v[52:53], v[48:49]
	v_mad_i64_i32 v[50:51], s[14:15], v65, s60, v[112:113]
	v_pk_mul_f32 v[48:49], v[54:55], v[48:49]
	v_lshl_add_u64 v[50:51], v[50:51], 0, v[114:115]
	v_cvt_pk_bf16_f32 v59, v48, v49
	v_fmamk_f32 v48, v155, 0x3a000000, v153
	v_rsq_f32_e32 v48, v48
	global_store_dwordx4 v[50:51], v[56:59], off
	v_pk_mul_f32 v[44:45], v[48:49], v[44:45] op_sel_hi:[0,1]
	v_mul_f32_e32 v49, 0xbfb8aa3b, v44
	v_exp_f32_e32 v49, v49
	v_mul_f32_e32 v52, 0xbfb8aa3b, v45
	v_exp_f32_e32 v52, v52
	v_add_f32_e32 v49, 1.0, v49
	v_rcp_f32_e32 v50, v49
	v_add_f32_e32 v49, 1.0, v52
	v_rcp_f32_e32 v51, v49
	v_add_u32_e32 v49, 0x90, v124
	v_pk_mul_f32 v[40:41], v[48:49], v[40:41] op_sel_hi:[0,1]
	v_pk_mul_f32 v[40:41], v[44:45], v[40:41]
	v_pk_mul_f32 v[44:45], v[48:49], v[46:47] op_sel_hi:[0,1]
	v_pk_mul_f32 v[40:41], v[50:51], v[40:41]
	v_mul_f32_e32 v46, 0xbfb8aa3b, v44
	v_cvt_pk_bf16_f32 v40, v40, v41
	v_mul_f32_e32 v41, 0xbfb8aa3b, v45
	v_exp_f32_e32 v46, v46
	v_exp_f32_e32 v41, v41
	v_pk_mul_f32 v[42:43], v[48:49], v[42:43] op_sel_hi:[0,1]
	v_pk_mul_f32 v[36:37], v[48:49], v[36:37] op_sel_hi:[0,1]
	v_add_f32_e32 v46, 1.0, v46
	v_add_f32_e32 v41, 1.0, v41
	v_rcp_f32_e32 v46, v46
	v_rcp_f32_e32 v47, v41
	v_pk_mul_f32 v[42:43], v[44:45], v[42:43]
	v_mul_f32_e32 v41, 0xbfb8aa3b, v36
	v_exp_f32_e32 v50, v41
	v_pk_mul_f32 v[42:43], v[46:47], v[42:43]
	v_pk_mul_f32 v[32:33], v[48:49], v[32:33] op_sel_hi:[0,1]
	v_cvt_pk_bf16_f32 v41, v42, v43
	v_mul_f32_e32 v43, 0xbfb8aa3b, v37
	v_exp_f32_e32 v43, v43
	v_pk_mul_f32 v[32:33], v[36:37], v[32:33]
	v_add_f32_e32 v42, 1.0, v50
	v_rcp_f32_e32 v42, v42
	v_add_f32_e32 v36, 1.0, v43
	v_rcp_f32_e32 v43, v36
	v_pk_mul_f32 v[36:37], v[48:49], v[38:39] op_sel_hi:[0,1]
	v_mul_f32_e32 v38, 0xbfb8aa3b, v36
	v_mul_f32_e32 v39, 0xbfb8aa3b, v37
	v_exp_f32_e32 v38, v38
	v_exp_f32_e32 v39, v39
	v_pk_mul_f32 v[32:33], v[42:43], v[32:33]
	v_add_f32_e32 v38, 1.0, v38
	v_add_f32_e32 v39, 1.0, v39
	v_rcp_f32_e32 v38, v38
	v_rcp_f32_e32 v39, v39
	v_cvt_pk_bf16_f32 v42, v32, v33
	v_pk_mul_f32 v[32:33], v[48:49], v[34:35] op_sel_hi:[0,1]
	v_pk_mul_f32 v[32:33], v[36:37], v[32:33]
	v_mad_i64_i32 v[34:35], s[14:15], v49, s60, v[112:113]
	v_pk_mul_f32 v[32:33], v[38:39], v[32:33]
	v_lshl_add_u64 v[34:35], v[34:35], 0, v[114:115]
	v_cvt_pk_bf16_f32 v43, v32, v33
	v_fmamk_f32 v32, v154, 0x3a000000, v153
	v_rsq_f32_e32 v32, v32
	global_store_dwordx4 v[34:35], v[40:43], off
	v_pk_mul_f32 v[28:29], v[32:33], v[28:29] op_sel_hi:[0,1]
	v_mul_f32_e32 v33, 0xbfb8aa3b, v28
	v_exp_f32_e32 v33, v33
	v_mul_f32_e32 v36, 0xbfb8aa3b, v29
; __device__ __forceinline__ float sigmoidf_(float x) { return __builtin_amdgcn_rcpf(1.0f + fexp(-x)); }
; __device__ __forceinline__ PreRs load_rs(const float* ssq, int pm, int wr, int fr) { PreRs p;
; #pragma unroll
;     for (int ai = 0; ai < 2; ++ai)
; #pragma unroll
;         for (int m = 0; m < 4; ++m) p.rs[ai * 4 + m] = ssq[ROW_X + pm * BM + ai * HALF + wr * 64 + m * 16 + fr];
;     return p; }
;     __device__ __forceinline__ void operator()(const f32x4 (&acc)[2][2][4][2], const Unit& u, int wr, int wc, int fr, int fq, const Pre& P) const {
;     ...
; #pragma unroll
;         for (int ai = 0; ai < 2; ++ai)
; #pragma unroll
;             for (int m = 0; m < 4; ++m) { const int r = row0 + ai * HALF + m * 16; const float rs = __builtin_amdgcn_rsqf(P.rs[ai * 4 + m] * (1.0f / DM) + RMS_EPS);
;                 float y[8];
; #pragma unroll
;                 for (int n = 0; n < 2; ++n)
; #pragma unroll
;                     for (int j = 0; j < 4; ++j) { const float a = acc[ai][0][m][n][j] * rs, b = acc[ai][1][m][n][j] * rs; y[n * 4 + j] = a * b * sigmoidf_(a); }
;                 u32x4 w; w.x = cvtpk(y[0], y[1]); w.y = cvtpk(y[2], y[3]); w.z = cvtpk(y[4], y[5]); w.w = cvtpk(y[6], y[7]);
;                 *(u32x4*)(O + (size_t)r * FF + col0) = w; }
	v_exp_f32_e32 v36, v36
	v_add_f32_e32 v33, 1.0, v33
	v_rcp_f32_e32 v34, v33
	v_add_f32_e32 v33, 1.0, v36
	v_rcp_f32_e32 v35, v33
	v_add_u32_e32 v33, 0xa0, v124
	v_pk_mul_f32 v[24:25], v[32:33], v[24:25] op_sel_hi:[0,1]
	v_pk_mul_f32 v[24:25], v[28:29], v[24:25]
	v_pk_mul_f32 v[28:29], v[32:33], v[30:31] op_sel_hi:[0,1]
	v_pk_mul_f32 v[24:25], v[34:35], v[24:25]
	v_mul_f32_e32 v30, 0xbfb8aa3b, v28
	v_cvt_pk_bf16_f32 v24, v24, v25
	v_mul_f32_e32 v25, 0xbfb8aa3b, v29
	v_exp_f32_e32 v30, v30
	v_exp_f32_e32 v25, v25
	v_pk_mul_f32 v[26:27], v[32:33], v[26:27] op_sel_hi:[0,1]
	v_pk_mul_f32 v[20:21], v[32:33], v[20:21] op_sel_hi:[0,1]
	v_add_f32_e32 v30, 1.0, v30
	v_add_f32_e32 v25, 1.0, v25
	v_rcp_f32_e32 v30, v30
	v_rcp_f32_e32 v31, v25
	v_pk_mul_f32 v[26:27], v[28:29], v[26:27]
	v_mul_f32_e32 v25, 0xbfb8aa3b, v20
	v_exp_f32_e32 v34, v25
	v_pk_mul_f32 v[26:27], v[30:31], v[26:27]
	v_pk_mul_f32 v[16:17], v[32:33], v[16:17] op_sel_hi:[0,1]
	v_cvt_pk_bf16_f32 v25, v26, v27
	v_mul_f32_e32 v27, 0xbfb8aa3b, v21
	v_exp_f32_e32 v27, v27
	v_pk_mul_f32 v[16:17], v[20:21], v[16:17]
	v_add_f32_e32 v26, 1.0, v34
	v_rcp_f32_e32 v26, v26
	v_add_f32_e32 v20, 1.0, v27
	v_rcp_f32_e32 v27, v20
	v_pk_mul_f32 v[20:21], v[32:33], v[22:23] op_sel_hi:[0,1]
	v_mul_f32_e32 v22, 0xbfb8aa3b, v20
	v_mul_f32_e32 v23, 0xbfb8aa3b, v21
	v_exp_f32_e32 v22, v22
	v_exp_f32_e32 v23, v23
	v_pk_mul_f32 v[16:17], v[26:27], v[16:17]
	v_add_f32_e32 v22, 1.0, v22
	v_add_f32_e32 v23, 1.0, v23
	v_rcp_f32_e32 v22, v22
	v_rcp_f32_e32 v23, v23
	v_cvt_pk_bf16_f32 v26, v16, v17
	v_pk_mul_f32 v[16:17], v[32:33], v[18:19] op_sel_hi:[0,1]
	v_pk_mul_f32 v[16:17], v[20:21], v[16:17]
	v_mad_i64_i32 v[18:19], s[14:15], v33, s60, v[112:113]
	v_pk_mul_f32 v[16:17], v[22:23], v[16:17]
	v_lshl_add_u64 v[18:19], v[18:19], 0, v[114:115]
	v_cvt_pk_bf16_f32 v27, v16, v17
	v_fmamk_f32 v16, v151, 0x3a000000, v153
	v_rsq_f32_e32 v16, v16
	global_store_dwordx4 v[18:19], v[24:27], off
	v_pk_mul_f32 v[12:13], v[16:17], v[12:13] op_sel_hi:[0,1]
	v_mul_f32_e32 v17, 0xbfb8aa3b, v12
	v_exp_f32_e32 v17, v17
	v_mul_f32_e32 v20, 0xbfb8aa3b, v13
	v_exp_f32_e32 v20, v20
	v_add_f32_e32 v17, 1.0, v17
	v_rcp_f32_e32 v18, v17
	v_add_f32_e32 v17, 1.0, v20
	v_rcp_f32_e32 v19, v17
	v_add_u32_e32 v17, 0xb0, v124
	v_pk_mul_f32 v[8:9], v[16:17], v[8:9] op_sel_hi:[0,1]
	v_pk_mul_f32 v[8:9], v[12:13], v[8:9]
	v_pk_mul_f32 v[12:13], v[16:17], v[14:15] op_sel_hi:[0,1]
	v_pk_mul_f32 v[8:9], v[18:19], v[8:9]
	v_mul_f32_e32 v14, 0xbfb8aa3b, v12
	v_cvt_pk_bf16_f32 v8, v8, v9
	v_mul_f32_e32 v9, 0xbfb8aa3b, v13
	v_exp_f32_e32 v14, v14
	v_exp_f32_e32 v9, v9
	v_pk_mul_f32 v[10:11], v[16:17], v[10:11] op_sel_hi:[0,1]
	v_pk_mul_f32 v[4:5], v[16:17], v[4:5] op_sel_hi:[0,1]
	v_add_f32_e32 v14, 1.0, v14
	v_add_f32_e32 v9, 1.0, v9
	v_rcp_f32_e32 v14, v14
	v_rcp_f32_e32 v15, v9
	v_pk_mul_f32 v[10:11], v[12:13], v[10:11]
	v_mul_f32_e32 v9, 0xbfb8aa3b, v4
	v_exp_f32_e32 v18, v9
	v_pk_mul_f32 v[10:11], v[14:15], v[10:11]
	v_pk_mul_f32 v[0:1], v[16:17], v[0:1] op_sel_hi:[0,1]
	v_cvt_pk_bf16_f32 v9, v10, v11
	v_mul_f32_e32 v11, 0xbfb8aa3b, v5
	v_exp_f32_e32 v11, v11
	v_pk_mul_f32 v[0:1], v[4:5], v[0:1]
	v_add_f32_e32 v10, 1.0, v18
	v_rcp_f32_e32 v10, v10
	v_add_f32_e32 v4, 1.0, v11
	v_rcp_f32_e32 v11, v4
	v_pk_mul_f32 v[4:5], v[16:17], v[6:7] op_sel_hi:[0,1]
	v_mul_f32_e32 v6, 0xbfb8aa3b, v4
	v_mul_f32_e32 v7, 0xbfb8aa3b, v5
	v_exp_f32_e32 v6, v6
	v_exp_f32_e32 v7, v7
	v_pk_mul_f32 v[0:1], v[10:11], v[0:1]
	v_add_f32_e32 v6, 1.0, v6
	v_add_f32_e32 v7, 1.0, v7
	v_rcp_f32_e32 v6, v6
	v_rcp_f32_e32 v7, v7
	v_cvt_pk_bf16_f32 v10, v0, v1
	v_pk_mul_f32 v[0:1], v[16:17], v[2:3] op_sel_hi:[0,1]
	v_pk_mul_f32 v[0:1], v[4:5], v[0:1]
	s_nop 0
	v_pk_mul_f32 v[0:1], v[6:7], v[0:1]
	s_nop 0
	v_cvt_pk_bf16_f32 v11, v0, v1
	v_mad_i64_i32 v[0:1], s[14:15], v17, s60, v[112:113]
	v_lshl_add_u64 v[0:1], v[0:1], 0, v[114:115]
	s_mov_b64 s[14:15], -1
	global_store_dwordx4 v[0:1], v[8:11], off
	s_cbranch_vccz .LBB0_1302
	v_lshl_add_u32 v0, s8, 8, v146
	v_ashrrev_i32_e32 v1, 31, v0
	v_lshl_add_u64 v[2:3], v[0:1], 2, s[2:3]
	v_add_u32_e32 v4, 0x80, v0
	v_add_u32_e32 v6, 0x90, v0
	v_add_u32_e32 v8, 0xa0, v0
	v_add_u32_e32 v0, 0xb0, v0
	v_ashrrev_i32_e32 v5, 31, v4
	v_ashrrev_i32_e32 v7, 31, v6
	v_ashrrev_i32_e32 v9, 31, v8
	v_ashrrev_i32_e32 v1, 31, v0
	v_lshl_add_u64 v[4:5], v[4:5], 2, s[2:3]
	v_lshl_add_u64 v[6:7], v[6:7], 2, s[2:3]
	v_lshl_add_u64 v[8:9], v[8:9], 2, s[2:3]
	v_lshl_add_u64 v[0:1], v[0:1], 2, s[2:3]
	global_load_dword v160, v[2:3], off
	global_load_dword v159, v[2:3], off offset:64
	global_load_dword v158, v[2:3], off offset:128
	global_load_dword v157, v[2:3], off offset:192
	global_load_dword v156, v[4:5], off
	global_load_dword v155, v[6:7], off
	global_load_dword v154, v[8:9], off
	global_load_dword v151, v[0:1], off
	s_mov_b64 s[14:15], 0
	s_branch .LBB0_1302

; #define PG8_STAGE(bufoff, gbase, voff) do { _Pragma("unroll") for (int _i = 0; _i < 2; ++_i) \
;         __builtin_amdgcn_global_load_lds((const unsigned*)((const char*)(gbase) + (voff)[_i]), (LAS unsigned*)(lds + (bufoff) + ldsw + _i * 8192), 16, 0, 0); } while (0)
; #define PG8_LDA(dst, b, h) do { _Pragma("unroll") for (int m = 0; m < 4; ++m) _Pragma("unroll") for (int k = 0; k < 2; ++k) dst[m][k] = *(const LAS bf16x8*)(lds + PG8_SA(b, h) + aoff + m * 2048 + k * 1024); } while (0)
; #define PG8_LDB(dst, b, h) do { _Pragma("unroll") for (int n = 0; n < 2; ++n) _Pragma("unroll") for (int k = 0; k < 2; ++k) dst[n][k] = *(const LAS bf16x8*)(lds + PG8_SB(b, h) + boff + n * 2048 + k * 1024); } while (0)
; #define PG8_MMA(ai, bj, At, Bt) do { __builtin_amdgcn_s_setprio(1); _Pragma("unroll") for (int m = 0; m < 4; ++m) _Pragma("unroll") for (int n = 0; n < 2; ++n) _Pragma("unroll") for (int k = 0; k < 2; ++k) \
;         acc[ai][bj][m][n] = __builtin_amdgcn_mfma_f32_16x16x32_bf16(Bt[n][k], At[m][k], acc[ai][bj][m][n], 0, 0, 0); __builtin_amdgcn_s_setprio(0); } while (0)
; #define PG8_WAIT_L(n) asm volatile("s_waitcnt lgkmcnt(" #n ")" ::: "memory")
; #define PG8_BAR __builtin_amdgcn_s_barrier()
; #define PG8_SCHED __builtin_amdgcn_sched_barrier(0)
; template <class Epi>
; __device__ __forceinline__ void gemm_phase(LAS unsigned char* lds, const Gemm g, const StaticOrder& S, const Epi& E) {
;     ...
;         for (int t = 0; t < nt; t += 2) {
;             const bool last = (t == nt - 2);
;             const char* a1 = cA + (size_t)(t + 1) * kstep;
;             const char* a2 = last ? nA : cA + (size_t)(t + 2) * kstep; const char* b2 = last ? nB : cB + (size_t)(t + 2) * kstep;
;             const char* a3 = a2 + kstep; const char* b3 = b2 + kstep;
;             PG8_LDB(B0, 0, 0); PG8_SCHED; PG8_LDA(At, 0, 0); PG8_STAGE(PG8_SA(1, 1), a1 + hstep, voffA);
;             PG8_WAIT_L(8); PG8_BAR; PG8_WAIT_L(0); PG8_MMA(0, 0, At, B0); PG8_BAR; PG8_SCHED;
.LBB0_1411:
	ds_read_b128 v[128:131], v162
	ds_read_b128 v[132:135], v162 offset:1024
	ds_read_b128 v[154:157], v162 offset:2048
	ds_read_b128 v[168:171], v162 offset:3072
	s_add_u32 s16, s14, 0xffea8080
	s_addc_u32 s17, s15, -1
	s_cmpk_eq_i32 s63, 0x52
	s_cselect_b32 s19, s1, s17
	s_cselect_b32 s18, s0, s16
	s_cselect_b32 s17, s7, s62
	s_cselect_b32 s16, s6, s61
	v_lshl_add_u64 v[158:159], s[14:15], 0, v[146:147]
	s_add_i32 m0, s30, 0xc000
	ds_read_b128 v[172:175], v163
	ds_read_b128 v[180:183], v163 offset:1024
	ds_read_b128 v[184:187], v163 offset:2048
	ds_read_b128 v[188:191], v163 offset:3072
	ds_read_b128 v[192:195], v163 offset:4096
	ds_read_b128 v[196:199], v163 offset:5120
	ds_read_b128 v[200:203], v163 offset:6144
	ds_read_b128 v[204:207], v163 offset:7168
	global_load_lds_dwordx4 v[158:159], off
	v_lshl_add_u64 v[158:159], s[14:15], 0, v[148:149]
	s_add_i32 m0, s30, 0xe000
	s_nop 0
	global_load_lds_dwordx4 v[158:159], off
	s_waitcnt lgkmcnt(8)
	s_barrier
	s_waitcnt lgkmcnt(0)
	s_setprio 1

; #define PG8_STAGE(bufoff, gbase, voff) do { _Pragma("unroll") for (int _i = 0; _i < 2; ++_i) \
;         __builtin_amdgcn_global_load_lds((const unsigned*)((const char*)(gbase) + (voff)[_i]), (LAS unsigned*)(lds + (bufoff) + ldsw + _i * 8192), 16, 0, 0); } while (0)
; #define PG8_LDB(dst, b, h) do { _Pragma("unroll") for (int n = 0; n < 2; ++n) _Pragma("unroll") for (int k = 0; k < 2; ++k) dst[n][k] = *(const LAS bf16x8*)(lds + PG8_SB(b, h) + boff + n * 2048 + k * 1024); } while (0)
; #define PG8_MMA(ai, bj, At, Bt) do { __builtin_amdgcn_s_setprio(1); _Pragma("unroll") for (int m = 0; m < 4; ++m) _Pragma("unroll") for (int n = 0; n < 2; ++n) _Pragma("unroll") for (int k = 0; k < 2; ++k) \
;         acc[ai][bj][m][n] = __builtin_amdgcn_mfma_f32_16x16x32_bf16(Bt[n][k], At[m][k], acc[ai][bj][m][n], 0, 0, 0); __builtin_amdgcn_s_setprio(0); } while (0)
; #define PG8_WAIT_L(n) asm volatile("s_waitcnt lgkmcnt(" #n ")" ::: "memory")
; #define PG8_BAR __builtin_amdgcn_s_barrier()
; #define PG8_SCHED __builtin_amdgcn_sched_barrier(0)
; template <class Epi>
; __device__ __forceinline__ void gemm_phase(LAS unsigned char* lds, const Gemm g, const StaticOrder& S, const Epi& E) {
;     ...
;             PG8_WAIT_L(8); PG8_BAR; PG8_WAIT_L(0); PG8_MMA(0, 0, At, B0); PG8_BAR; PG8_SCHED;
;             PG8_LDB(B1, 0, 1); PG8_STAGE(PG8_SB(0, 0), b2, voffB);
;             PG8_BAR; PG8_WAIT_L(0); PG8_MMA(0, 1, At, B1); PG8_BAR;
	v_mfma_f32_16x16x32_bf16 v[124:127], v[128:131], v[172:175], v[124:127]
	v_mfma_f32_16x16x32_bf16 v[120:123], v[154:157], v[172:175], v[120:123]
	v_mfma_f32_16x16x32_bf16 v[108:111], v[128:131], v[184:187], v[108:111]
	v_mfma_f32_16x16x32_bf16 v[104:107], v[154:157], v[184:187], v[104:107]
	v_mfma_f32_16x16x32_bf16 v[92:95], v[128:131], v[192:195], v[92:95]
	v_mfma_f32_16x16x32_bf16 v[88:91], v[154:157], v[192:195], v[88:91]
	v_mfma_f32_16x16x32_bf16 v[76:79], v[128:131], v[200:203], v[76:79]
	v_mfma_f32_16x16x32_bf16 v[72:75], v[154:157], v[200:203], v[72:75]
	v_mfma_f32_16x16x32_bf16 v[124:127], v[132:135], v[180:183], v[124:127]
	v_mfma_f32_16x16x32_bf16 v[120:123], v[168:171], v[180:183], v[120:123]
	v_mfma_f32_16x16x32_bf16 v[108:111], v[132:135], v[188:191], v[108:111]
	v_mfma_f32_16x16x32_bf16 v[104:107], v[168:171], v[188:191], v[104:107]
	v_mfma_f32_16x16x32_bf16 v[92:95], v[132:135], v[196:199], v[92:95]
	v_mfma_f32_16x16x32_bf16 v[88:91], v[168:171], v[196:199], v[88:91]
	v_mfma_f32_16x16x32_bf16 v[76:79], v[132:135], v[204:207], v[76:79]
	v_mfma_f32_16x16x32_bf16 v[72:75], v[168:171], v[204:207], v[72:75]
	s_setprio 0
	s_barrier
	s_add_i32 s64, s43, s21
	v_lshl_add_u64 v[158:159], s[16:17], 0, v[140:141]
	s_mov_b32 m0, s64
	ds_read_b128 v[208:211], v165
	ds_read_b128 v[212:215], v165 offset:1024
	ds_read_b128 v[216:219], v165 offset:2048
	ds_read_b128 v[220:223], v165 offset:3072
	global_load_lds_dwordx4 v[158:159], off
	v_lshl_add_u64 v[176:177], s[16:17], 0, v[144:145]
	s_add_i32 m0, s64, 0x2000
	s_nop 0
	global_load_lds_dwordx4 v[176:177], off
	s_barrier
	s_waitcnt lgkmcnt(0)
	s_setprio 1

; #define PG8_STAGE(bufoff, gbase, voff) do { _Pragma("unroll") for (int _i = 0; _i < 2; ++_i) \
;         __builtin_amdgcn_global_load_lds((const unsigned*)((const char*)(gbase) + (voff)[_i]), (LAS unsigned*)(lds + (bufoff) + ldsw + _i * 8192), 16, 0, 0); } while (0)
; #define PG8_LDA(dst, b, h) do { _Pragma("unroll") for (int m = 0; m < 4; ++m) _Pragma("unroll") for (int k = 0; k < 2; ++k) dst[m][k] = *(const LAS bf16x8*)(lds + PG8_SA(b, h) + aoff + m * 2048 + k * 1024); } while (0)
; #define PG8_MMA(ai, bj, At, Bt) do { __builtin_amdgcn_s_setprio(1); _Pragma("unroll") for (int m = 0; m < 4; ++m) _Pragma("unroll") for (int n = 0; n < 2; ++n) _Pragma("unroll") for (int k = 0; k < 2; ++k) \
;         acc[ai][bj][m][n] = __builtin_amdgcn_mfma_f32_16x16x32_bf16(Bt[n][k], At[m][k], acc[ai][bj][m][n], 0, 0, 0); __builtin_amdgcn_s_setprio(0); } while (0)
; #define PG8_WAIT_L(n) asm volatile("s_waitcnt lgkmcnt(" #n ")" ::: "memory")
; #define PG8_BAR __builtin_amdgcn_s_barrier()
; #define PG8_SCHED __builtin_amdgcn_sched_barrier(0)
; template <class Epi>
; __device__ __forceinline__ void gemm_phase(LAS unsigned char* lds, const Gemm g, const StaticOrder& S, const Epi& E) {
;     ...
;             PG8_BAR; PG8_WAIT_L(0); PG8_MMA(0, 1, At, B1); PG8_BAR;
;             PG8_LDA(At, 0, 1); PG8_STAGE(PG8_SA(0, 0), a2, voffA);
;             PG8_BAR; PG8_WAIT_L(0); PG8_MMA(1, 0, At, B0); PG8_BAR; PG8_SCHED;
	v_mfma_f32_16x16x32_bf16 v[116:119], v[208:211], v[172:175], v[116:119]
	v_mfma_f32_16x16x32_bf16 v[112:115], v[216:219], v[172:175], v[112:115]
	v_mfma_f32_16x16x32_bf16 v[100:103], v[208:211], v[184:187], v[100:103]
	v_mfma_f32_16x16x32_bf16 v[96:99], v[216:219], v[184:187], v[96:99]
	v_mfma_f32_16x16x32_bf16 v[84:87], v[208:211], v[192:195], v[84:87]
	v_mfma_f32_16x16x32_bf16 v[80:83], v[216:219], v[192:195], v[80:83]
	v_mfma_f32_16x16x32_bf16 v[68:71], v[208:211], v[200:203], v[68:71]
	v_mfma_f32_16x16x32_bf16 v[64:67], v[216:219], v[200:203], v[64:67]
	v_mfma_f32_16x16x32_bf16 v[116:119], v[212:215], v[180:183], v[116:119]
	v_mfma_f32_16x16x32_bf16 v[112:115], v[220:223], v[180:183], v[112:115]
	v_mfma_f32_16x16x32_bf16 v[100:103], v[212:215], v[188:191], v[100:103]
	v_mfma_f32_16x16x32_bf16 v[96:99], v[220:223], v[188:191], v[96:99]
	v_mfma_f32_16x16x32_bf16 v[84:87], v[212:215], v[196:199], v[84:87]
	v_mfma_f32_16x16x32_bf16 v[80:83], v[220:223], v[196:199], v[80:83]
	v_mfma_f32_16x16x32_bf16 v[68:71], v[212:215], v[204:207], v[68:71]
	v_mfma_f32_16x16x32_bf16 v[64:67], v[220:223], v[204:207], v[64:67]
	s_setprio 0
	s_mov_b32 m0, s30
	v_lshl_add_u64 v[224:225], s[18:19], 0, v[138:139]
	s_barrier
	ds_read_b128 v[172:175], v163 offset:16384
	ds_read_b128 v[180:183], v163 offset:17408
	ds_read_b128 v[184:187], v163 offset:18432
	ds_read_b128 v[188:191], v163 offset:19456
	ds_read_b128 v[192:195], v163 offset:20480
	ds_read_b128 v[196:199], v163 offset:21504
	ds_read_b128 v[200:203], v163 offset:22528
	ds_read_b128 v[204:207], v163 offset:23552
	global_load_lds_dwordx4 v[224:225], off
	v_lshl_add_u64 v[226:227], s[18:19], 0, v[142:143]
	s_mov_b32 m0, s31
	s_nop 0
	global_load_lds_dwordx4 v[226:227], off
	s_barrier
	s_waitcnt lgkmcnt(0)
	s_setprio 1

; #define PG8_STAGE(bufoff, gbase, voff) do { _Pragma("unroll") for (int _i = 0; _i < 2; ++_i) \
;         __builtin_amdgcn_global_load_lds((const unsigned*)((const char*)(gbase) + (voff)[_i]), (LAS unsigned*)(lds + (bufoff) + ldsw + _i * 8192), 16, 0, 0); } while (0)
; #define PG8_LDA(dst, b, h) do { _Pragma("unroll") for (int m = 0; m < 4; ++m) _Pragma("unroll") for (int k = 0; k < 2; ++k) dst[m][k] = *(const LAS bf16x8*)(lds + PG8_SA(b, h) + aoff + m * 2048 + k * 1024); } while (0)
; #define PG8_LDB(dst, b, h) do { _Pragma("unroll") for (int n = 0; n < 2; ++n) _Pragma("unroll") for (int k = 0; k < 2; ++k) dst[n][k] = *(const LAS bf16x8*)(lds + PG8_SB(b, h) + boff + n * 2048 + k * 1024); } while (0)
; #define PG8_MMA(ai, bj, At, Bt) do { __builtin_amdgcn_s_setprio(1); _Pragma("unroll") for (int m = 0; m < 4; ++m) _Pragma("unroll") for (int n = 0; n < 2; ++n) _Pragma("unroll") for (int k = 0; k < 2; ++k) \
;         acc[ai][bj][m][n] = __builtin_amdgcn_mfma_f32_16x16x32_bf16(Bt[n][k], At[m][k], acc[ai][bj][m][n], 0, 0, 0); __builtin_amdgcn_s_setprio(0); } while (0)
; #define PG8_WAIT_V(n) asm volatile("s_waitcnt vmcnt(" #n ")" ::: "memory")
; #define PG8_WAIT_L(n) asm volatile("s_waitcnt lgkmcnt(" #n ")" ::: "memory")
; #define PG8_BAR __builtin_amdgcn_s_barrier()
; #define PG8_SCHED __builtin_amdgcn_sched_barrier(0)
; template <class Epi>
; __device__ __forceinline__ void gemm_phase(LAS unsigned char* lds, const Gemm g, const StaticOrder& S, const Epi& E) {
;     ...
;             PG8_BAR; PG8_WAIT_L(0); PG8_MMA(1, 0, At, B0); PG8_BAR; PG8_SCHED;
;             PG8_STAGE(PG8_SB(0, 1), b2 + hstep, voffB);
;             PG8_WAIT_V(6); PG8_BAR; PG8_MMA(1, 1, At, B1); PG8_BAR;
;             PG8_LDB(B0, 1, 0); PG8_SCHED; PG8_LDA(At, 1, 0); PG8_STAGE(PG8_SA(0, 1), a2 + hstep, voffA);
;             PG8_WAIT_L(8); PG8_BAR; PG8_WAIT_L(0); PG8_MMA(0, 0, At, B0); PG8_BAR; PG8_SCHED;
	v_mfma_f32_16x16x32_bf16 v[60:63], v[128:131], v[172:175], v[60:63]
	v_mfma_f32_16x16x32_bf16 v[56:59], v[154:157], v[172:175], v[56:59]
	v_mfma_f32_16x16x32_bf16 v[44:47], v[128:131], v[184:187], v[44:47]
	v_mfma_f32_16x16x32_bf16 v[40:43], v[154:157], v[184:187], v[40:43]
	v_mfma_f32_16x16x32_bf16 v[28:31], v[128:131], v[192:195], v[28:31]
	v_mfma_f32_16x16x32_bf16 v[24:27], v[154:157], v[192:195], v[24:27]
	v_mfma_f32_16x16x32_bf16 v[12:15], v[128:131], v[200:203], v[12:15]
	v_mfma_f32_16x16x32_bf16 v[8:11], v[154:157], v[200:203], v[8:11]
	v_mfma_f32_16x16x32_bf16 v[60:63], v[132:135], v[180:183], v[60:63]
	v_mfma_f32_16x16x32_bf16 v[56:59], v[168:171], v[180:183], v[56:59]
	v_mfma_f32_16x16x32_bf16 v[44:47], v[132:135], v[188:191], v[44:47]
	v_mfma_f32_16x16x32_bf16 v[40:43], v[168:171], v[188:191], v[40:43]
	v_mfma_f32_16x16x32_bf16 v[28:31], v[132:135], v[196:199], v[28:31]
	v_mfma_f32_16x16x32_bf16 v[24:27], v[168:171], v[196:199], v[24:27]
	v_mfma_f32_16x16x32_bf16 v[12:15], v[132:135], v[204:207], v[12:15]
	v_mfma_f32_16x16x32_bf16 v[8:11], v[168:171], v[204:207], v[8:11]
	s_setprio 0
	s_barrier
	s_add_u32 s64, s16, 0x158000
	s_addc_u32 s65, s17, 0
	s_add_i32 s66, s56, s21
	v_lshl_add_u64 v[128:129], s[64:65], 0, v[140:141]
	s_mov_b32 m0, s66
	s_nop 0
	global_load_lds_dwordx4 v[128:129], off
	v_lshl_add_u64 v[128:129], s[64:65], 0, v[144:145]
	s_add_i32 m0, s66, 0x2000
	s_nop 0
	global_load_lds_dwordx4 v[128:129], off
	s_waitcnt vmcnt(6)
	s_barrier
	s_setprio 1
	v_mfma_f32_16x16x32_bf16 v[52:55], v[208:211], v[172:175], v[52:55]
	v_mfma_f32_16x16x32_bf16 v[48:51], v[216:219], v[172:175], v[48:51]
	v_mfma_f32_16x16x32_bf16 v[36:39], v[208:211], v[184:187], v[36:39]
	v_mfma_f32_16x16x32_bf16 v[32:35], v[216:219], v[184:187], v[32:35]
	v_mfma_f32_16x16x32_bf16 v[20:23], v[208:211], v[192:195], v[20:23]
	v_mfma_f32_16x16x32_bf16 v[16:19], v[216:219], v[192:195], v[16:19]
	v_mfma_f32_16x16x32_bf16 v[4:7], v[208:211], v[200:203], v[4:7]
	v_mfma_f32_16x16x32_bf16 v[0:3], v[216:219], v[200:203], v[0:3]
	v_mfma_f32_16x16x32_bf16 v[52:55], v[212:215], v[180:183], v[52:55]
	v_mfma_f32_16x16x32_bf16 v[48:51], v[220:223], v[180:183], v[48:51]
	v_mfma_f32_16x16x32_bf16 v[36:39], v[212:215], v[188:191], v[36:39]
	v_mfma_f32_16x16x32_bf16 v[32:35], v[220:223], v[188:191], v[32:35]
	v_mfma_f32_16x16x32_bf16 v[20:23], v[212:215], v[196:199], v[20:23]
	v_mfma_f32_16x16x32_bf16 v[16:19], v[220:223], v[196:199], v[16:19]
	v_mfma_f32_16x16x32_bf16 v[4:7], v[212:215], v[204:207], v[4:7]
	v_mfma_f32_16x16x32_bf16 v[0:3], v[220:223], v[204:207], v[0:3]
	s_setprio 0
	s_add_i32 s64, 0, 0x18000
	v_add_u32_e32 v167, s64, v137
	s_barrier
	ds_read_b128 v[128:131], v167
	ds_read_b128 v[132:135], v167 offset:1024
	ds_read_b128 v[154:157], v167 offset:2048
	ds_read_b128 v[168:171], v167 offset:3072
	s_add_u32 s18, s18, 0x158000
	s_addc_u32 s19, s19, 0
	s_mov_b32 m0, s33
	v_lshl_add_u64 v[208:209], s[18:19], 0, v[138:139]
	ds_read_b128 v[172:175], v163 offset:32768
	ds_read_b128 v[180:183], v163 offset:33792
	ds_read_b128 v[184:187], v163 offset:34816
	ds_read_b128 v[188:191], v163 offset:35840
	ds_read_b128 v[192:195], v163 offset:36864
	ds_read_b128 v[196:199], v163 offset:37888
	ds_read_b128 v[200:203], v163 offset:38912
	ds_read_b128 v[204:207], v163 offset:39936
	global_load_lds_dwordx4 v[208:209], off
	v_lshl_add_u64 v[208:209], s[18:19], 0, v[142:143]
	s_mov_b32 m0, s34
	s_nop 0
	global_load_lds_dwordx4 v[208:209], off
	s_waitcnt lgkmcnt(8)
	s_barrier
	s_waitcnt lgkmcnt(0)
	s_setprio 1

; #define PG8_STAGE(bufoff, gbase, voff) do { _Pragma("unroll") for (int _i = 0; _i < 2; ++_i) \
;         __builtin_amdgcn_global_load_lds((const unsigned*)((const char*)(gbase) + (voff)[_i]), (LAS unsigned*)(lds + (bufoff) + ldsw + _i * 8192), 16, 0, 0); } while (0)
; #define PG8_LDB(dst, b, h) do { _Pragma("unroll") for (int n = 0; n < 2; ++n) _Pragma("unroll") for (int k = 0; k < 2; ++k) dst[n][k] = *(const LAS bf16x8*)(lds + PG8_SB(b, h) + boff + n * 2048 + k * 1024); } while (0)
; #define PG8_MMA(ai, bj, At, Bt) do { __builtin_amdgcn_s_setprio(1); _Pragma("unroll") for (int m = 0; m < 4; ++m) _Pragma("unroll") for (int n = 0; n < 2; ++n) _Pragma("unroll") for (int k = 0; k < 2; ++k) \
;         acc[ai][bj][m][n] = __builtin_amdgcn_mfma_f32_16x16x32_bf16(Bt[n][k], At[m][k], acc[ai][bj][m][n], 0, 0, 0); __builtin_amdgcn_s_setprio(0); } while (0)
; #define PG8_WAIT_L(n) asm volatile("s_waitcnt lgkmcnt(" #n ")" ::: "memory")
; #define PG8_BAR __builtin_amdgcn_s_barrier()
; #define PG8_SCHED __builtin_amdgcn_sched_barrier(0)
; template <class Epi>
; __device__ __forceinline__ void gemm_phase(LAS unsigned char* lds, const Gemm g, const StaticOrder& S, const Epi& E) {
;     ...
;             PG8_WAIT_L(8); PG8_BAR; PG8_WAIT_L(0); PG8_MMA(0, 0, At, B0); PG8_BAR; PG8_SCHED;
;             PG8_LDB(B1, 1, 1); PG8_STAGE(PG8_SB(1, 0), b3, voffB);
;             PG8_BAR; PG8_WAIT_L(0); PG8_MMA(0, 1, At, B1); PG8_BAR;
	v_mfma_f32_16x16x32_bf16 v[124:127], v[128:131], v[172:175], v[124:127]
	v_mfma_f32_16x16x32_bf16 v[120:123], v[154:157], v[172:175], v[120:123]
	v_mfma_f32_16x16x32_bf16 v[108:111], v[128:131], v[184:187], v[108:111]
	v_mfma_f32_16x16x32_bf16 v[104:107], v[154:157], v[184:187], v[104:107]
	v_mfma_f32_16x16x32_bf16 v[92:95], v[128:131], v[192:195], v[92:95]
	v_mfma_f32_16x16x32_bf16 v[88:91], v[154:157], v[192:195], v[88:91]
	v_mfma_f32_16x16x32_bf16 v[76:79], v[128:131], v[200:203], v[76:79]
	v_mfma_f32_16x16x32_bf16 v[72:75], v[154:157], v[200:203], v[72:75]
	v_mfma_f32_16x16x32_bf16 v[124:127], v[132:135], v[180:183], v[124:127]
	v_mfma_f32_16x16x32_bf16 v[120:123], v[168:171], v[180:183], v[120:123]
	v_mfma_f32_16x16x32_bf16 v[108:111], v[132:135], v[188:191], v[108:111]
	v_mfma_f32_16x16x32_bf16 v[104:107], v[168:171], v[188:191], v[104:107]
	v_mfma_f32_16x16x32_bf16 v[92:95], v[132:135], v[196:199], v[92:95]
	v_mfma_f32_16x16x32_bf16 v[88:91], v[168:171], v[196:199], v[88:91]
	v_mfma_f32_16x16x32_bf16 v[76:79], v[132:135], v[204:207], v[76:79]
	v_mfma_f32_16x16x32_bf16 v[72:75], v[168:171], v[204:207], v[72:75]
	s_setprio 0
	s_barrier
	s_add_i32 s18, 0, 0x1c000
	s_add_i32 s19, s64, s21
	v_add_u32_e32 v167, s18, v137
	v_lshl_add_u64 v[158:159], v[158:159], 0, s[12:13]
	s_mov_b32 m0, s19
	ds_read_b128 v[208:211], v167
	ds_read_b128 v[212:215], v167 offset:1024
	ds_read_b128 v[216:219], v167 offset:2048
	ds_read_b128 v[220:223], v167 offset:3072
	global_load_lds_dwordx4 v[158:159], off
	v_lshl_add_u64 v[158:159], v[176:177], 0, s[12:13]
	s_add_i32 m0, s19, 0x2000
	s_nop 0
	global_load_lds_dwordx4 v[158:159], off
	s_barrier
	s_waitcnt lgkmcnt(0)
	s_setprio 1

; #define PG8_STAGE(bufoff, gbase, voff) do { _Pragma("unroll") for (int _i = 0; _i < 2; ++_i) \
;         __builtin_amdgcn_global_load_lds((const unsigned*)((const char*)(gbase) + (voff)[_i]), (LAS unsigned*)(lds + (bufoff) + ldsw + _i * 8192), 16, 0, 0); } while (0)
; #define PG8_LDA(dst, b, h) do { _Pragma("unroll") for (int m = 0; m < 4; ++m) _Pragma("unroll") for (int k = 0; k < 2; ++k) dst[m][k] = *(const LAS bf16x8*)(lds + PG8_SA(b, h) + aoff + m * 2048 + k * 1024); } while (0)
; #define PG8_MMA(ai, bj, At, Bt) do { __builtin_amdgcn_s_setprio(1); _Pragma("unroll") for (int m = 0; m < 4; ++m) _Pragma("unroll") for (int n = 0; n < 2; ++n) _Pragma("unroll") for (int k = 0; k < 2; ++k) \
;         acc[ai][bj][m][n] = __builtin_amdgcn_mfma_f32_16x16x32_bf16(Bt[n][k], At[m][k], acc[ai][bj][m][n], 0, 0, 0); __builtin_amdgcn_s_setprio(0); } while (0)
; #define PG8_WAIT_L(n) asm volatile("s_waitcnt lgkmcnt(" #n ")" ::: "memory")
; #define PG8_BAR __builtin_amdgcn_s_barrier()
; #define PG8_SCHED __builtin_amdgcn_sched_barrier(0)
; template <class Epi>
; __device__ __forceinline__ void gemm_phase(LAS unsigned char* lds, const Gemm g, const StaticOrder& S, const Epi& E) {
;     ...
;             PG8_BAR; PG8_WAIT_L(0); PG8_MMA(0, 1, At, B1); PG8_BAR;
;             PG8_LDA(At, 1, 1); PG8_STAGE(PG8_SA(1, 0), a3, voffA);
;             PG8_BAR; PG8_WAIT_L(0); PG8_MMA(1, 0, At, B0); PG8_BAR; PG8_SCHED;
	v_mfma_f32_16x16x32_bf16 v[116:119], v[208:211], v[172:175], v[116:119]
	v_mfma_f32_16x16x32_bf16 v[112:115], v[216:219], v[172:175], v[112:115]
	v_mfma_f32_16x16x32_bf16 v[100:103], v[208:211], v[184:187], v[100:103]
	v_mfma_f32_16x16x32_bf16 v[96:99], v[216:219], v[184:187], v[96:99]
	v_mfma_f32_16x16x32_bf16 v[84:87], v[208:211], v[192:195], v[84:87]
	v_mfma_f32_16x16x32_bf16 v[80:83], v[216:219], v[192:195], v[80:83]
	v_mfma_f32_16x16x32_bf16 v[68:71], v[208:211], v[200:203], v[68:71]
	v_mfma_f32_16x16x32_bf16 v[64:67], v[216:219], v[200:203], v[64:67]
	v_mfma_f32_16x16x32_bf16 v[116:119], v[212:215], v[180:183], v[116:119]
	v_mfma_f32_16x16x32_bf16 v[112:115], v[220:223], v[180:183], v[112:115]
	v_mfma_f32_16x16x32_bf16 v[100:103], v[212:215], v[188:191], v[100:103]
	v_mfma_f32_16x16x32_bf16 v[96:99], v[220:223], v[188:191], v[96:99]
	v_mfma_f32_16x16x32_bf16 v[84:87], v[212:215], v[196:199], v[84:87]
	v_mfma_f32_16x16x32_bf16 v[80:83], v[220:223], v[196:199], v[80:83]
	v_mfma_f32_16x16x32_bf16 v[68:71], v[212:215], v[204:207], v[68:71]
	v_mfma_f32_16x16x32_bf16 v[64:67], v[220:223], v[204:207], v[64:67]
	s_setprio 0
	s_mov_b32 m0, s36
	v_lshl_add_u64 v[158:159], v[224:225], 0, s[12:13]
	s_barrier
	ds_read_b128 v[172:175], v163 offset:49152
	ds_read_b128 v[180:183], v163 offset:50176
	ds_read_b128 v[184:187], v163 offset:51200
	ds_read_b128 v[188:191], v163 offset:52224
	ds_read_b128 v[192:195], v163 offset:53248
	ds_read_b128 v[196:199], v163 offset:54272
	ds_read_b128 v[200:203], v163 offset:55296
	ds_read_b128 v[204:207], v163 offset:56320
	global_load_lds_dwordx4 v[158:159], off
	v_lshl_add_u64 v[158:159], v[226:227], 0, s[12:13]
	s_mov_b32 m0, s37
	s_nop 0
	global_load_lds_dwordx4 v[158:159], off
	s_barrier
	s_waitcnt lgkmcnt(0)
	s_setprio 1

; #define PG8_STAGE(bufoff, gbase, voff) do { _Pragma("unroll") for (int _i = 0; _i < 2; ++_i) \
;         __builtin_amdgcn_global_load_lds((const unsigned*)((const char*)(gbase) + (voff)[_i]), (LAS unsigned*)(lds + (bufoff) + ldsw + _i * 8192), 16, 0, 0); } while (0)
; #define PG8_MMA(ai, bj, At, Bt) do { __builtin_amdgcn_s_setprio(1); _Pragma("unroll") for (int m = 0; m < 4; ++m) _Pragma("unroll") for (int n = 0; n < 2; ++n) _Pragma("unroll") for (int k = 0; k < 2; ++k) \
;         acc[ai][bj][m][n] = __builtin_amdgcn_mfma_f32_16x16x32_bf16(Bt[n][k], At[m][k], acc[ai][bj][m][n], 0, 0, 0); __builtin_amdgcn_s_setprio(0); } while (0)
; #define PG8_WAIT_V(n) asm volatile("s_waitcnt vmcnt(" #n ")" ::: "memory")
; #define PG8_WAIT_L(n) asm volatile("s_waitcnt lgkmcnt(" #n ")" ::: "memory")
; #define PG8_BAR __builtin_amdgcn_s_barrier()
; #define PG8_SCHED __builtin_amdgcn_sched_barrier(0)
; template <class Epi>
; __device__ __forceinline__ void gemm_phase(LAS unsigned char* lds, const Gemm g, const StaticOrder& S, const Epi& E) {
;     ...
;             PG8_BAR; PG8_WAIT_L(0); PG8_MMA(1, 0, At, B0); PG8_BAR; PG8_SCHED;
;             PG8_STAGE(PG8_SB(1, 1), b3 + hstep, voffB);
;             PG8_WAIT_V(6); PG8_BAR; PG8_MMA(1, 1, At, B1); PG8_BAR;
;         }
	v_mfma_f32_16x16x32_bf16 v[60:63], v[128:131], v[172:175], v[60:63]
	v_mfma_f32_16x16x32_bf16 v[56:59], v[154:157], v[172:175], v[56:59]
	v_mfma_f32_16x16x32_bf16 v[44:47], v[128:131], v[184:187], v[44:47]
	v_mfma_f32_16x16x32_bf16 v[40:43], v[154:157], v[184:187], v[40:43]
	v_mfma_f32_16x16x32_bf16 v[28:31], v[128:131], v[192:195], v[28:31]
	v_mfma_f32_16x16x32_bf16 v[24:27], v[154:157], v[192:195], v[24:27]
	v_mfma_f32_16x16x32_bf16 v[12:15], v[128:131], v[200:203], v[12:15]
	v_mfma_f32_16x16x32_bf16 v[8:11], v[154:157], v[200:203], v[8:11]
	v_mfma_f32_16x16x32_bf16 v[60:63], v[132:135], v[180:183], v[60:63]
	v_mfma_f32_16x16x32_bf16 v[56:59], v[168:171], v[180:183], v[56:59]
	v_mfma_f32_16x16x32_bf16 v[44:47], v[132:135], v[188:191], v[44:47]
	v_mfma_f32_16x16x32_bf16 v[40:43], v[168:171], v[188:191], v[40:43]
	v_mfma_f32_16x16x32_bf16 v[28:31], v[132:135], v[196:199], v[28:31]
	v_mfma_f32_16x16x32_bf16 v[24:27], v[168:171], v[196:199], v[24:27]
	v_mfma_f32_16x16x32_bf16 v[12:15], v[132:135], v[204:207], v[12:15]
	v_mfma_f32_16x16x32_bf16 v[8:11], v[168:171], v[204:207], v[8:11]
	s_setprio 0
	s_barrier
	s_add_u32 s16, s16, 0x158080
	s_addc_u32 s17, s17, 0
	s_add_i32 s18, s18, s21
	v_lshl_add_u64 v[128:129], s[16:17], 0, v[140:141]
	s_mov_b32 m0, s18
	s_nop 0
	global_load_lds_dwordx4 v[128:129], off
	v_lshl_add_u64 v[128:129], s[16:17], 0, v[144:145]
	s_add_i32 m0, s18, 0x2000
	s_nop 0
	global_load_lds_dwordx4 v[128:129], off
	s_waitcnt vmcnt(6)
	s_barrier
	s_setprio 1
	v_mfma_f32_16x16x32_bf16 v[52:55], v[208:211], v[172:175], v[52:55]
	v_mfma_f32_16x16x32_bf16 v[48:51], v[216:219], v[172:175], v[48:51]
	v_mfma_f32_16x16x32_bf16 v[36:39], v[208:211], v[184:187], v[36:39]
	v_mfma_f32_16x16x32_bf16 v[32:35], v[216:219], v[184:187], v[32:35]
	v_mfma_f32_16x16x32_bf16 v[20:23], v[208:211], v[192:195], v[20:23]
	v_mfma_f32_16x16x32_bf16 v[16:19], v[216:219], v[192:195], v[16:19]
	v_mfma_f32_16x16x32_bf16 v[4:7], v[208:211], v[200:203], v[4:7]
	v_mfma_f32_16x16x32_bf16 v[0:3], v[216:219], v[200:203], v[0:3]
	v_mfma_f32_16x16x32_bf16 v[52:55], v[212:215], v[180:183], v[52:55]
	v_mfma_f32_16x16x32_bf16 v[48:51], v[220:223], v[180:183], v[48:51]
	v_mfma_f32_16x16x32_bf16 v[36:39], v[212:215], v[188:191], v[36:39]
	v_mfma_f32_16x16x32_bf16 v[32:35], v[220:223], v[188:191], v[32:35]
	v_mfma_f32_16x16x32_bf16 v[20:23], v[212:215], v[196:199], v[20:23]
	v_mfma_f32_16x16x32_bf16 v[16:19], v[220:223], v[196:199], v[16:19]
	v_mfma_f32_16x16x32_bf16 v[4:7], v[212:215], v[204:207], v[4:7]
	v_mfma_f32_16x16x32_bf16 v[0:3], v[220:223], v[204:207], v[0:3]
	s_setprio 0
	s_add_i32 s63, s63, 2
	s_add_u32 s14, s14, 0x100
	s_addc_u32 s15, s15, 0
	s_add_u32 s61, s61, 0x100
	s_addc_u32 s62, s62, 0
	s_cmpk_gt_u32 s63, 0x53
	s_barrier
	s_cbranch_scc0 .LBB0_1411
; __device__ __forceinline__ float bflo(unsigned w) { return __uint_as_float(w << 16); }
; __device__ __forceinline__ float bfhi(unsigned w) { return __uint_as_float(w & 0xffff0000u); }
; #define ER_LOAD(g_, set_) do { const size_t off_ = (size_t)(row0 + ((g_) >> 2) * HALF + ((g_) & 3) * 16) * DM + col0; \
;         hv[set_][0] = *(const u32x4*)(HB + off_); hv[set_][1] = *(const u32x4*)(HB + off_ + HALF); } while (0)
;     __device__ __forceinline__ void operator()(const f32x4 (&acc)[2][2][4][2], const Unit& u, int wr, int wc, int fr, int fq, const Pre&) const {
;         const int row0 = ROW_X + u.pm * BM + wr * 64 + fr, col0 = u.pn * BM + wc * 32 + 8 * fq;
;         u32x4 hv[2][2]; float sprev = 0.f;
;     ...
;         ER_LOAD(0, 0);
; #pragma unroll
;         for (int g = 0; g < 8; ++g) { const int ai = g >> 2, m = g & 3; const int r = row0 + ai * HALF + m * 16; const size_t off = (size_t)r * DM + col0; float s = 0.f;
;             if (g + 1 < 8) ER_LOAD(g + 1, (g + 1) & 1);
; #pragma unroll
;             for (int bj = 0; bj < 2; ++bj) { const u32x4 w = hv[g & 1][bj];
;                 const f32x4 h0 = {bflo(w.x), bfhi(w.x), bflo(w.y), bfhi(w.y)}, h1 = {bflo(w.z), bfhi(w.z), bflo(w.w), bfhi(w.w)};
;                 const f32x4 o0 = h0 + acc[ai][bj][m][0] * alpha, o1 = h1 + acc[ai][bj][m][1] * alpha;
;                 if (FINAL) { float* op = OUT + (size_t)(r - ROW_X) * DM + col0 + bj * HALF; *(f32x4*)op = o0; *(f32x4*)(op + 4) = o1; }
;                 else { u32x4 q; q.x = cvtpk(o0[0], o0[1]); q.y = cvtpk(o0[2], o0[3]); q.z = cvtpk(o1[0], o1[1]); q.w = cvtpk(o1[2], o1[3]); *(u32x4*)(HB + off + bj * HALF) = q;
;                        s += ((o0[0] * o0[0] + o0[1] * o0[1]) + (o0[2] * o0[2] + o0[3] * o0[3])) + ((o1[0] * o1[0] + o1[1] * o1[1]) + (o1[2] * o1[2] + o1[3] * o1[3])); } }
;             if (!FINAL) { if (g > 0) { float t = sprev; t += __shfl_xor(t, 16); t += __shfl_xor(t, 32);
;                     if (fq == 0) __hip_atomic_fetch_add(ssq_out + row0 + ((g - 1) >> 2) * HALF + ((g - 1) & 3) * 16, t, __ATOMIC_RELAXED, __HIP_MEMORY_SCOPE_AGENT); }
	v_lshl_add_u32 v156, s59, 8, v160
	v_lshl_or_b32 v154, s60, 8, v161
	v_ashrrev_i32_e32 v157, 31, v156
	v_ashrrev_i32_e32 v155, 31, v154
	v_lshlrev_b64 v[128:129], 12, v[156:157]
	v_lshl_add_u64 v[128:129], s[8:9], 0, v[128:129]
	v_lshlrev_b64 v[130:131], 1, v[154:155]
	v_lshl_add_u64 v[176:177], v[128:129], 0, v[130:131]
	v_or_b32_e32 v128, 16, v156
	v_ashrrev_i32_e32 v129, 31, v128
	global_load_dwordx4 v[168:171], v[176:177], off
	global_load_dwordx4 v[172:175], v[176:177], off offset:256
	v_lshlrev_b64 v[128:129], 12, v[128:129]
	v_lshl_add_u64 v[128:129], s[8:9], 0, v[128:129]
	v_lshl_add_u64 v[188:189], v[128:129], 0, v[130:131]
	global_load_dwordx4 v[180:183], v[188:189], off
	global_load_dwordx4 v[184:187], v[188:189], off offset:256
	v_or_b32_e32 v128, 32, v156
	v_ashrrev_i32_e32 v129, 31, v128
	v_lshlrev_b64 v[128:129], 12, v[128:129]
	v_lshl_add_u64 v[128:129], s[8:9], 0, v[128:129]
	v_lshl_add_u64 v[158:159], v[128:129], 0, v[130:131]
	global_load_dwordx4 v[132:135], v[158:159], off
	global_load_dwordx4 v[128:131], v[158:159], off offset:256
	s_waitcnt vmcnt(0)
	v_lshlrev_b32_e32 v190, 16, v168
	v_and_b32_e32 v191, 0xffff0000, v168
	v_lshlrev_b32_e32 v168, 16, v169
	v_and_b32_e32 v169, 0xffff0000, v169
	v_lshlrev_b32_e32 v192, 16, v170
	v_and_b32_e32 v193, 0xffff0000, v170
	v_lshlrev_b32_e32 v170, 16, v171
	v_and_b32_e32 v171, 0xffff0000, v171
	v_lshlrev_b32_e32 v194, 16, v172
	v_and_b32_e32 v195, 0xffff0000, v172
	v_lshlrev_b32_e32 v172, 16, v173
	v_and_b32_e32 v173, 0xffff0000, v173
	v_lshlrev_b32_e32 v196, 16, v174
	v_and_b32_e32 v197, 0xffff0000, v174
	v_lshlrev_b32_e32 v174, 16, v175
	v_and_b32_e32 v175, 0xffff0000, v175
	v_pk_fma_f32 v[126:127], v[126:127], 0.5, v[168:169] op_sel_hi:[1,0,1]
	v_pk_fma_f32 v[124:125], v[124:125], 0.5, v[190:191] op_sel_hi:[1,0,1]
	v_pk_fma_f32 v[122:123], v[122:123], 0.5, v[170:171] op_sel_hi:[1,0,1]
	v_pk_fma_f32 v[168:169], v[120:121], 0.5, v[192:193] op_sel_hi:[1,0,1]
	v_pk_fma_f32 v[170:171], v[118:119], 0.5, v[172:173] op_sel_hi:[1,0,1]
	v_pk_fma_f32 v[172:173], v[116:117], 0.5, v[194:195] op_sel_hi:[1,0,1]
	v_pk_fma_f32 v[174:175], v[114:115], 0.5, v[174:175] op_sel_hi:[1,0,1]
	v_pk_fma_f32 v[190:191], v[112:113], 0.5, v[196:197] op_sel_hi:[1,0,1]
	v_cvt_pk_bf16_f32 v114, v124, v125
	v_cvt_pk_bf16_f32 v115, v126, v127
	v_cvt_pk_bf16_f32 v116, v168, v169
	v_cvt_pk_bf16_f32 v117, v122, v123
	v_mul_f32_e32 v125, v125, v125
	v_mul_f32_e32 v127, v127, v127
	v_mul_f32_e32 v167, v169, v169
	v_mul_f32_e32 v123, v123, v123
	v_cvt_pk_bf16_f32 v118, v172, v173
	v_cvt_pk_bf16_f32 v119, v170, v171
	v_cvt_pk_bf16_f32 v121, v174, v175
	v_mul_f32_e32 v169, v173, v173
	v_mul_f32_e32 v171, v171, v171
	v_mul_f32_e32 v173, v191, v191
	v_mul_f32_e32 v175, v175, v175
	v_lshlrev_b32_e32 v112, 16, v180
	v_and_b32_e32 v113, 0xffff0000, v180
	v_lshlrev_b32_e32 v192, 16, v182
	v_and_b32_e32 v193, 0xffff0000, v182
	v_lshlrev_b32_e32 v182, 16, v183
	v_and_b32_e32 v183, 0xffff0000, v183
	v_fmac_f32_e32 v125, v124, v124
	v_fmac_f32_e32 v127, v126, v126
	v_fmac_f32_e32 v167, v168, v168
	v_fmac_f32_e32 v123, v122, v122
	v_fmac_f32_e32 v169, v172, v172
	v_fmac_f32_e32 v171, v170, v170
	v_fmac_f32_e32 v173, v190, v190
	v_fmac_f32_e32 v175, v174, v174
	v_lshlrev_b32_e32 v180, 16, v181
	v_and_b32_e32 v181, 0xffff0000, v181
	v_pk_fma_f32 v[112:113], v[108:109], 0.5, v[112:113] op_sel_hi:[1,0,1]
	v_pk_fma_f32 v[108:109], v[106:107], 0.5, v[182:183] op_sel_hi:[1,0,1]
	global_store_dwordx4 v[176:177], v[114:117], off
	v_add_f32_e32 v106, v125, v127
	v_add_f32_e32 v107, v167, v123
	v_add_f32_e32 v114, v169, v171
	v_add_f32_e32 v115, v173, v175
	v_pk_fma_f32 v[110:111], v[110:111], 0.5, v[180:181] op_sel_hi:[1,0,1]
	v_add_f32_e32 v106, v106, v107
	v_add_f32_e32 v107, v114, v115
	v_pk_fma_f32 v[114:115], v[104:105], 0.5, v[192:193] op_sel_hi:[1,0,1]
	v_add_f32_e32 v125, v106, v107
	v_cvt_pk_bf16_f32 v104, v112, v113
	v_cvt_pk_bf16_f32 v105, v110, v111
	v_cvt_pk_bf16_f32 v106, v114, v115
	v_cvt_pk_bf16_f32 v107, v108, v109
	v_cvt_pk_bf16_f32 v120, v190, v191
	global_store_dwordx4 v[188:189], v[104:107], off
	global_store_dwordx4 v[176:177], v[118:121], off offset:256
	v_lshlrev_b32_e32 v122, 16, v186
	v_lshlrev_b32_e32 v104, 16, v184
	v_and_b32_e32 v105, 0xffff0000, v184
	v_pk_fma_f32 v[118:119], v[100:101], 0.5, v[104:105] op_sel_hi:[1,0,1]
	v_and_b32_e32 v101, 64, v166
	v_xor_b32_e32 v100, 16, v166
	v_add_u32_e32 v101, 64, v101
	v_cmp_lt_i32_e32 vcc, v100, v101
	v_and_b32_e32 v123, 0xffff0000, v186
	v_pk_fma_f32 v[122:123], v[96:97], 0.5, v[122:123] op_sel_hi:[1,0,1]
	v_cndmask_b32_e32 v100, v166, v100, vcc
	v_lshlrev_b32_e32 v124, 2, v100
	ds_bpermute_b32 v100, v124, v125
	v_xor_b32_e32 v97, 32, v166
	v_cmp_lt_i32_e32 vcc, v97, v101
	v_lshlrev_b32_e32 v106, 16, v185
	v_and_b32_e32 v107, 0xffff0000, v185
	v_cndmask_b32_e32 v97, v166, v97, vcc
	s_waitcnt lgkmcnt(0)
	v_add_f32_e32 v96, v125, v100
	v_lshlrev_b32_e32 v125, 2, v97
	ds_bpermute_b32 v97, v125, v96
	v_lshlrev_b32_e32 v120, 16, v187
	v_and_b32_e32 v121, 0xffff0000, v187
	v_pk_fma_f32 v[116:117], v[102:103], 0.5, v[106:107] op_sel_hi:[1,0,1]
	v_pk_fma_f32 v[120:121], v[98:99], 0.5, v[120:121] op_sel_hi:[1,0,1]
	v_cvt_pk_bf16_f32 v98, v118, v119
	v_cvt_pk_bf16_f32 v99, v116, v117
	v_cvt_pk_bf16_f32 v100, v122, v123
	v_cvt_pk_bf16_f32 v101, v120, v121
	v_lshl_add_u64 v[104:105], v[156:157], 2, s[10:11]
	global_store_dwordx4 v[188:189], v[98:101], off offset:256
	s_and_saveexec_b64 s[14:15], s[2:3]
	s_cbranch_execz .LBB0_1414
	s_waitcnt lgkmcnt(0)
	v_add_f32_e32 v96, v96, v97
	global_atomic_add_f32 v[104:105], v96, off

; #define PG8_STAGE(bufoff, gbase, voff) do { _Pragma("unroll") for (int _i = 0; _i < 2; ++_i) \
;         __builtin_amdgcn_global_load_lds((const unsigned*)((const char*)(gbase) + (voff)[_i]), (LAS unsigned*)(lds + (bufoff) + ldsw + _i * 8192), 16, 0, 0); } while (0)
; #define PG8_LDA(dst, b, h) do { _Pragma("unroll") for (int m = 0; m < 4; ++m) _Pragma("unroll") for (int k = 0; k < 2; ++k) dst[m][k] = *(const LAS bf16x8*)(lds + PG8_SA(b, h) + aoff + m * 2048 + k * 1024); } while (0)
; #define PG8_LDB(dst, b, h) do { _Pragma("unroll") for (int n = 0; n < 2; ++n) _Pragma("unroll") for (int k = 0; k < 2; ++k) dst[n][k] = *(const LAS bf16x8*)(lds + PG8_SB(b, h) + boff + n * 2048 + k * 1024); } while (0)
; #define PG8_MMA(ai, bj, At, Bt) do { __builtin_amdgcn_s_setprio(1); _Pragma("unroll") for (int m = 0; m < 4; ++m) _Pragma("unroll") for (int n = 0; n < 2; ++n) _Pragma("unroll") for (int k = 0; k < 2; ++k) \
;         acc[ai][bj][m][n] = __builtin_amdgcn_mfma_f32_16x16x32_bf16(Bt[n][k], At[m][k], acc[ai][bj][m][n], 0, 0, 0); __builtin_amdgcn_s_setprio(0); } while (0)
; #define PG8_WAIT_L(n) asm volatile("s_waitcnt lgkmcnt(" #n ")" ::: "memory")
; #define PG8_BAR __builtin_amdgcn_s_barrier()
; #define PG8_SCHED __builtin_amdgcn_sched_barrier(0)
; template <class Epi>
; __device__ __forceinline__ void gemm_phase(LAS unsigned char* lds, const Gemm g, const StaticOrder& S, const Epi& E) {
;     ...
;         for (int t = 0; t < nt; t += 2) {
;             const bool last = (t == nt - 2);
;             const char* a1 = cA + (size_t)(t + 1) * kstep;
;             const char* a2 = last ? nA : cA + (size_t)(t + 2) * kstep; const char* b2 = last ? nB : cB + (size_t)(t + 2) * kstep;
;             const char* a3 = a2 + kstep; const char* b3 = b2 + kstep;
;             PG8_LDB(B0, 0, 0); PG8_SCHED; PG8_LDA(At, 0, 0); PG8_STAGE(PG8_SA(1, 1), a1 + hstep, voffA);
;             PG8_WAIT_L(8); PG8_BAR; PG8_WAIT_L(0); PG8_MMA(0, 0, At, B0); PG8_BAR; PG8_SCHED;
.LBB0_1796:
	ds_read_b128 v[172:175], v157
	ds_read_b128 v[180:183], v157 offset:1024
	ds_read_b128 v[184:187], v157 offset:2048
	ds_read_b128 v[188:191], v157 offset:3072
	s_add_u32 s8, s6, 0xfff80080
	s_addc_u32 s9, s7, -1
	s_cmp_eq_u32 s37, 28
	s_cselect_b32 s11, s1, s9
	s_cselect_b32 s10, s5, s8
	s_cselect_b32 s9, s12, s35
	s_cselect_b32 s8, s13, s33
	v_lshl_add_u64 v[152:153], s[6:7], 0, v[142:143]
	s_add_i32 m0, s62, 0xc000
	ds_read_b128 v[192:195], v158
	ds_read_b128 v[196:199], v158 offset:1024
	ds_read_b128 v[200:203], v158 offset:2048
	ds_read_b128 v[204:207], v158 offset:3072
	ds_read_b128 v[208:211], v158 offset:4096
	ds_read_b128 v[212:215], v158 offset:5120
	ds_read_b128 v[216:219], v158 offset:6144
	ds_read_b128 v[220:223], v158 offset:7168
	global_load_lds_dwordx4 v[152:153], off
	v_lshl_add_u64 v[152:153], s[6:7], 0, v[144:145]
	s_add_i32 m0, s62, 0xe000
	s_nop 0
	global_load_lds_dwordx4 v[152:153], off
	s_waitcnt lgkmcnt(8)
	s_barrier
	s_waitcnt lgkmcnt(0)
	s_setprio 1

; #define PG8_STAGE(bufoff, gbase, voff) do { _Pragma("unroll") for (int _i = 0; _i < 2; ++_i) \
;         __builtin_amdgcn_global_load_lds((const unsigned*)((const char*)(gbase) + (voff)[_i]), (LAS unsigned*)(lds + (bufoff) + ldsw + _i * 8192), 16, 0, 0); } while (0)
; #define PG8_LDB(dst, b, h) do { _Pragma("unroll") for (int n = 0; n < 2; ++n) _Pragma("unroll") for (int k = 0; k < 2; ++k) dst[n][k] = *(const LAS bf16x8*)(lds + PG8_SB(b, h) + boff + n * 2048 + k * 1024); } while (0)
; #define PG8_MMA(ai, bj, At, Bt) do { __builtin_amdgcn_s_setprio(1); _Pragma("unroll") for (int m = 0; m < 4; ++m) _Pragma("unroll") for (int n = 0; n < 2; ++n) _Pragma("unroll") for (int k = 0; k < 2; ++k) \
;         acc[ai][bj][m][n] = __builtin_amdgcn_mfma_f32_16x16x32_bf16(Bt[n][k], At[m][k], acc[ai][bj][m][n], 0, 0, 0); __builtin_amdgcn_s_setprio(0); } while (0)
; #define PG8_WAIT_L(n) asm volatile("s_waitcnt lgkmcnt(" #n ")" ::: "memory")
; #define PG8_BAR __builtin_amdgcn_s_barrier()
; #define PG8_SCHED __builtin_amdgcn_sched_barrier(0)
; template <class Epi>
; __device__ __forceinline__ void gemm_phase(LAS unsigned char* lds, const Gemm g, const StaticOrder& S, const Epi& E) {
;     ...
;             PG8_WAIT_L(8); PG8_BAR; PG8_WAIT_L(0); PG8_MMA(0, 0, At, B0); PG8_BAR; PG8_SCHED;
;             PG8_LDB(B1, 0, 1); PG8_STAGE(PG8_SB(0, 0), b2, voffB);
;             PG8_BAR; PG8_WAIT_L(0); PG8_MMA(0, 1, At, B1); PG8_BAR;
	v_mfma_f32_16x16x32_bf16 v[116:119], v[172:175], v[192:195], v[116:119]
	v_mfma_f32_16x16x32_bf16 v[112:115], v[184:187], v[192:195], v[112:115]
	v_mfma_f32_16x16x32_bf16 v[100:103], v[172:175], v[200:203], v[100:103]
	v_mfma_f32_16x16x32_bf16 v[96:99], v[184:187], v[200:203], v[96:99]
	v_mfma_f32_16x16x32_bf16 v[84:87], v[172:175], v[208:211], v[84:87]
	v_mfma_f32_16x16x32_bf16 v[80:83], v[184:187], v[208:211], v[80:83]
	v_mfma_f32_16x16x32_bf16 v[68:71], v[172:175], v[216:219], v[68:71]
	v_mfma_f32_16x16x32_bf16 v[64:67], v[184:187], v[216:219], v[64:67]
	v_mfma_f32_16x16x32_bf16 v[116:119], v[180:183], v[196:199], v[116:119]
	v_mfma_f32_16x16x32_bf16 v[112:115], v[188:191], v[196:199], v[112:115]
	v_mfma_f32_16x16x32_bf16 v[100:103], v[180:183], v[204:207], v[100:103]
	v_mfma_f32_16x16x32_bf16 v[96:99], v[188:191], v[204:207], v[96:99]
	v_mfma_f32_16x16x32_bf16 v[84:87], v[180:183], v[212:215], v[84:87]
	v_mfma_f32_16x16x32_bf16 v[80:83], v[188:191], v[212:215], v[80:83]
	v_mfma_f32_16x16x32_bf16 v[68:71], v[180:183], v[220:223], v[68:71]
	v_mfma_f32_16x16x32_bf16 v[64:67], v[188:191], v[220:223], v[64:67]
	s_setprio 0
	s_barrier
	s_add_i32 s42, s72, s57
	v_lshl_add_u64 v[152:153], s[8:9], 0, v[130:131]
	s_mov_b32 m0, s42
	ds_read_b128 v[224:227], v159
	ds_read_b128 v[228:231], v159 offset:1024
	ds_read_b128 v[232:235], v159 offset:2048
	ds_read_b128 v[236:239], v159 offset:3072
	global_load_lds_dwordx4 v[152:153], off
	v_lshl_add_u64 v[176:177], s[8:9], 0, v[134:135]
	s_add_i32 m0, s42, 0x2000
	s_nop 0
	global_load_lds_dwordx4 v[176:177], off
	s_barrier
	s_waitcnt lgkmcnt(0)
	s_setprio 1

; #define PG8_STAGE(bufoff, gbase, voff) do { _Pragma("unroll") for (int _i = 0; _i < 2; ++_i) \
;         __builtin_amdgcn_global_load_lds((const unsigned*)((const char*)(gbase) + (voff)[_i]), (LAS unsigned*)(lds + (bufoff) + ldsw + _i * 8192), 16, 0, 0); } while (0)
; #define PG8_LDA(dst, b, h) do { _Pragma("unroll") for (int m = 0; m < 4; ++m) _Pragma("unroll") for (int k = 0; k < 2; ++k) dst[m][k] = *(const LAS bf16x8*)(lds + PG8_SA(b, h) + aoff + m * 2048 + k * 1024); } while (0)
; #define PG8_MMA(ai, bj, At, Bt) do { __builtin_amdgcn_s_setprio(1); _Pragma("unroll") for (int m = 0; m < 4; ++m) _Pragma("unroll") for (int n = 0; n < 2; ++n) _Pragma("unroll") for (int k = 0; k < 2; ++k) \
;         acc[ai][bj][m][n] = __builtin_amdgcn_mfma_f32_16x16x32_bf16(Bt[n][k], At[m][k], acc[ai][bj][m][n], 0, 0, 0); __builtin_amdgcn_s_setprio(0); } while (0)
; #define PG8_WAIT_L(n) asm volatile("s_waitcnt lgkmcnt(" #n ")" ::: "memory")
; #define PG8_BAR __builtin_amdgcn_s_barrier()
; #define PG8_SCHED __builtin_amdgcn_sched_barrier(0)
; template <class Epi>
; __device__ __forceinline__ void gemm_phase(LAS unsigned char* lds, const Gemm g, const StaticOrder& S, const Epi& E) {
;     ...
;             PG8_BAR; PG8_WAIT_L(0); PG8_MMA(0, 1, At, B1); PG8_BAR;
;             PG8_LDA(At, 0, 1); PG8_STAGE(PG8_SA(0, 0), a2, voffA);
;             PG8_BAR; PG8_WAIT_L(0); PG8_MMA(1, 0, At, B0); PG8_BAR; PG8_SCHED;
	v_mfma_f32_16x16x32_bf16 v[124:127], v[224:227], v[192:195], v[124:127]
	v_mfma_f32_16x16x32_bf16 v[120:123], v[232:235], v[192:195], v[120:123]
	v_mfma_f32_16x16x32_bf16 v[108:111], v[224:227], v[200:203], v[108:111]
	v_mfma_f32_16x16x32_bf16 v[104:107], v[232:235], v[200:203], v[104:107]
	v_mfma_f32_16x16x32_bf16 v[92:95], v[224:227], v[208:211], v[92:95]
	v_mfma_f32_16x16x32_bf16 v[88:91], v[232:235], v[208:211], v[88:91]
	v_mfma_f32_16x16x32_bf16 v[76:79], v[224:227], v[216:219], v[76:79]
	v_mfma_f32_16x16x32_bf16 v[72:75], v[232:235], v[216:219], v[72:75]
	v_mfma_f32_16x16x32_bf16 v[124:127], v[228:231], v[196:199], v[124:127]
	v_mfma_f32_16x16x32_bf16 v[120:123], v[236:239], v[196:199], v[120:123]
	v_mfma_f32_16x16x32_bf16 v[108:111], v[228:231], v[204:207], v[108:111]
	v_mfma_f32_16x16x32_bf16 v[104:107], v[236:239], v[204:207], v[104:107]
	v_mfma_f32_16x16x32_bf16 v[92:95], v[228:231], v[212:215], v[92:95]
	v_mfma_f32_16x16x32_bf16 v[88:91], v[236:239], v[212:215], v[88:91]
	v_mfma_f32_16x16x32_bf16 v[76:79], v[228:231], v[220:223], v[76:79]
	v_mfma_f32_16x16x32_bf16 v[72:75], v[236:239], v[220:223], v[72:75]
	s_setprio 0
	s_mov_b32 m0, s62
	v_lshl_add_u64 v[240:241], s[10:11], 0, v[128:129]
	s_barrier
	ds_read_b128 v[192:195], v158 offset:16384
	ds_read_b128 v[196:199], v158 offset:17408
	ds_read_b128 v[200:203], v158 offset:18432
	ds_read_b128 v[204:207], v158 offset:19456
	ds_read_b128 v[208:211], v158 offset:20480
	ds_read_b128 v[212:215], v158 offset:21504
	ds_read_b128 v[216:219], v158 offset:22528
	ds_read_b128 v[220:223], v158 offset:23552
	global_load_lds_dwordx4 v[240:241], off
	v_lshl_add_u64 v[242:243], s[10:11], 0, v[132:133]
	s_mov_b32 m0, s63
	s_nop 0
	global_load_lds_dwordx4 v[242:243], off
	s_barrier
	s_waitcnt lgkmcnt(0)
	s_setprio 1

; #define PG8_STAGE(bufoff, gbase, voff) do { _Pragma("unroll") for (int _i = 0; _i < 2; ++_i) \
;         __builtin_amdgcn_global_load_lds((const unsigned*)((const char*)(gbase) + (voff)[_i]), (LAS unsigned*)(lds + (bufoff) + ldsw + _i * 8192), 16, 0, 0); } while (0)
; #define PG8_LDA(dst, b, h) do { _Pragma("unroll") for (int m = 0; m < 4; ++m) _Pragma("unroll") for (int k = 0; k < 2; ++k) dst[m][k] = *(const LAS bf16x8*)(lds + PG8_SA(b, h) + aoff + m * 2048 + k * 1024); } while (0)
; #define PG8_LDB(dst, b, h) do { _Pragma("unroll") for (int n = 0; n < 2; ++n) _Pragma("unroll") for (int k = 0; k < 2; ++k) dst[n][k] = *(const LAS bf16x8*)(lds + PG8_SB(b, h) + boff + n * 2048 + k * 1024); } while (0)
; #define PG8_MMA(ai, bj, At, Bt) do { __builtin_amdgcn_s_setprio(1); _Pragma("unroll") for (int m = 0; m < 4; ++m) _Pragma("unroll") for (int n = 0; n < 2; ++n) _Pragma("unroll") for (int k = 0; k < 2; ++k) \
;         acc[ai][bj][m][n] = __builtin_amdgcn_mfma_f32_16x16x32_bf16(Bt[n][k], At[m][k], acc[ai][bj][m][n], 0, 0, 0); __builtin_amdgcn_s_setprio(0); } while (0)
; #define PG8_WAIT_V(n) asm volatile("s_waitcnt vmcnt(" #n ")" ::: "memory")
; #define PG8_WAIT_L(n) asm volatile("s_waitcnt lgkmcnt(" #n ")" ::: "memory")
; #define PG8_BAR __builtin_amdgcn_s_barrier()
; #define PG8_SCHED __builtin_amdgcn_sched_barrier(0)
; template <class Epi>
; __device__ __forceinline__ void gemm_phase(LAS unsigned char* lds, const Gemm g, const StaticOrder& S, const Epi& E) {
;     ...
;             PG8_BAR; PG8_WAIT_L(0); PG8_MMA(1, 0, At, B0); PG8_BAR; PG8_SCHED;
;             PG8_STAGE(PG8_SB(0, 1), b2 + hstep, voffB);
;             PG8_WAIT_V(6); PG8_BAR; PG8_MMA(1, 1, At, B1); PG8_BAR;
;             PG8_LDB(B0, 1, 0); PG8_SCHED; PG8_LDA(At, 1, 0); PG8_STAGE(PG8_SA(0, 1), a2 + hstep, voffA);
;             PG8_WAIT_L(8); PG8_BAR; PG8_WAIT_L(0); PG8_MMA(0, 0, At, B0); PG8_BAR; PG8_SCHED;
	v_mfma_f32_16x16x32_bf16 v[52:55], v[172:175], v[192:195], v[52:55]
	v_mfma_f32_16x16x32_bf16 v[48:51], v[184:187], v[192:195], v[48:51]
	v_mfma_f32_16x16x32_bf16 v[36:39], v[172:175], v[200:203], v[36:39]
	v_mfma_f32_16x16x32_bf16 v[32:35], v[184:187], v[200:203], v[32:35]
	v_mfma_f32_16x16x32_bf16 v[20:23], v[172:175], v[208:211], v[20:23]
	v_mfma_f32_16x16x32_bf16 v[16:19], v[184:187], v[208:211], v[16:19]
	v_mfma_f32_16x16x32_bf16 v[4:7], v[172:175], v[216:219], v[4:7]
	v_mfma_f32_16x16x32_bf16 v[0:3], v[184:187], v[216:219], v[0:3]
	v_mfma_f32_16x16x32_bf16 v[52:55], v[180:183], v[196:199], v[52:55]
	v_mfma_f32_16x16x32_bf16 v[48:51], v[188:191], v[196:199], v[48:51]
	v_mfma_f32_16x16x32_bf16 v[36:39], v[180:183], v[204:207], v[36:39]
	v_mfma_f32_16x16x32_bf16 v[32:35], v[188:191], v[204:207], v[32:35]
	v_mfma_f32_16x16x32_bf16 v[20:23], v[180:183], v[212:215], v[20:23]
	v_mfma_f32_16x16x32_bf16 v[16:19], v[188:191], v[212:215], v[16:19]
	v_mfma_f32_16x16x32_bf16 v[4:7], v[180:183], v[220:223], v[4:7]
	v_mfma_f32_16x16x32_bf16 v[0:3], v[188:191], v[220:223], v[0:3]
	s_setprio 0
	s_barrier
	s_add_u32 s42, s8, 0x80000
	s_addc_u32 s43, s9, 0
	s_add_i32 s78, s73, s57
	v_lshl_add_u64 v[172:173], s[42:43], 0, v[130:131]
	s_mov_b32 m0, s78
	s_nop 0
	global_load_lds_dwordx4 v[172:173], off
	v_lshl_add_u64 v[172:173], s[42:43], 0, v[134:135]
	s_add_i32 m0, s78, 0x2000
	s_nop 0
	global_load_lds_dwordx4 v[172:173], off
	s_waitcnt vmcnt(6)
	s_barrier
	s_setprio 1
	v_mfma_f32_16x16x32_bf16 v[60:63], v[224:227], v[192:195], v[60:63]
	v_mfma_f32_16x16x32_bf16 v[56:59], v[232:235], v[192:195], v[56:59]
	v_mfma_f32_16x16x32_bf16 v[44:47], v[224:227], v[200:203], v[44:47]
	v_mfma_f32_16x16x32_bf16 v[40:43], v[232:235], v[200:203], v[40:43]
	v_mfma_f32_16x16x32_bf16 v[28:31], v[224:227], v[208:211], v[28:31]
	v_mfma_f32_16x16x32_bf16 v[24:27], v[232:235], v[208:211], v[24:27]
	v_mfma_f32_16x16x32_bf16 v[12:15], v[224:227], v[216:219], v[12:15]
	v_mfma_f32_16x16x32_bf16 v[8:11], v[232:235], v[216:219], v[8:11]
	v_mfma_f32_16x16x32_bf16 v[60:63], v[228:231], v[196:199], v[60:63]
	v_mfma_f32_16x16x32_bf16 v[56:59], v[236:239], v[196:199], v[56:59]
	v_mfma_f32_16x16x32_bf16 v[44:47], v[228:231], v[204:207], v[44:47]
	v_mfma_f32_16x16x32_bf16 v[40:43], v[236:239], v[204:207], v[40:43]
	v_mfma_f32_16x16x32_bf16 v[28:31], v[228:231], v[212:215], v[28:31]
	v_mfma_f32_16x16x32_bf16 v[24:27], v[236:239], v[212:215], v[24:27]
	v_mfma_f32_16x16x32_bf16 v[12:15], v[228:231], v[220:223], v[12:15]
	v_mfma_f32_16x16x32_bf16 v[8:11], v[236:239], v[220:223], v[8:11]
	s_setprio 0
	s_add_i32 s42, 0, 0x18000
	v_add_u32_e32 v136, s42, v155
	s_barrier
	ds_read_b128 v[172:175], v136
	ds_read_b128 v[180:183], v136 offset:1024
	ds_read_b128 v[184:187], v136 offset:2048
	ds_read_b128 v[188:191], v136 offset:3072
	s_add_u32 s10, s10, 0x80000
	s_addc_u32 s11, s11, 0
	s_mov_b32 m0, s64
	v_lshl_add_u64 v[224:225], s[10:11], 0, v[128:129]
	ds_read_b128 v[192:195], v158 offset:32768
	ds_read_b128 v[196:199], v158 offset:33792
	ds_read_b128 v[200:203], v158 offset:34816
	ds_read_b128 v[204:207], v158 offset:35840
	ds_read_b128 v[208:211], v158 offset:36864
	ds_read_b128 v[212:215], v158 offset:37888
	ds_read_b128 v[216:219], v158 offset:38912
	ds_read_b128 v[220:223], v158 offset:39936
	global_load_lds_dwordx4 v[224:225], off
	v_lshl_add_u64 v[224:225], s[10:11], 0, v[132:133]
	s_mov_b32 m0, s65
	s_nop 0
	global_load_lds_dwordx4 v[224:225], off
	s_waitcnt lgkmcnt(8)
	s_barrier
	s_waitcnt lgkmcnt(0)
	s_setprio 1

; #define PG8_STAGE(bufoff, gbase, voff) do { _Pragma("unroll") for (int _i = 0; _i < 2; ++_i) \
;         __builtin_amdgcn_global_load_lds((const unsigned*)((const char*)(gbase) + (voff)[_i]), (LAS unsigned*)(lds + (bufoff) + ldsw + _i * 8192), 16, 0, 0); } while (0)
; #define PG8_LDB(dst, b, h) do { _Pragma("unroll") for (int n = 0; n < 2; ++n) _Pragma("unroll") for (int k = 0; k < 2; ++k) dst[n][k] = *(const LAS bf16x8*)(lds + PG8_SB(b, h) + boff + n * 2048 + k * 1024); } while (0)
; #define PG8_MMA(ai, bj, At, Bt) do { __builtin_amdgcn_s_setprio(1); _Pragma("unroll") for (int m = 0; m < 4; ++m) _Pragma("unroll") for (int n = 0; n < 2; ++n) _Pragma("unroll") for (int k = 0; k < 2; ++k) \
;         acc[ai][bj][m][n] = __builtin_amdgcn_mfma_f32_16x16x32_bf16(Bt[n][k], At[m][k], acc[ai][bj][m][n], 0, 0, 0); __builtin_amdgcn_s_setprio(0); } while (0)
; #define PG8_WAIT_L(n) asm volatile("s_waitcnt lgkmcnt(" #n ")" ::: "memory")
; #define PG8_BAR __builtin_amdgcn_s_barrier()
; #define PG8_SCHED __builtin_amdgcn_sched_barrier(0)
; template <class Epi>
; __device__ __forceinline__ void gemm_phase(LAS unsigned char* lds, const Gemm g, const StaticOrder& S, const Epi& E) {
;     ...
;             PG8_WAIT_L(8); PG8_BAR; PG8_WAIT_L(0); PG8_MMA(0, 0, At, B0); PG8_BAR; PG8_SCHED;
;             PG8_LDB(B1, 1, 1); PG8_STAGE(PG8_SB(1, 0), b3, voffB);
;             PG8_BAR; PG8_WAIT_L(0); PG8_MMA(0, 1, At, B1); PG8_BAR;
	v_mfma_f32_16x16x32_bf16 v[116:119], v[172:175], v[192:195], v[116:119]
	v_mfma_f32_16x16x32_bf16 v[112:115], v[184:187], v[192:195], v[112:115]
	v_mfma_f32_16x16x32_bf16 v[100:103], v[172:175], v[200:203], v[100:103]
	v_mfma_f32_16x16x32_bf16 v[96:99], v[184:187], v[200:203], v[96:99]
	v_mfma_f32_16x16x32_bf16 v[84:87], v[172:175], v[208:211], v[84:87]
	v_mfma_f32_16x16x32_bf16 v[80:83], v[184:187], v[208:211], v[80:83]
	v_mfma_f32_16x16x32_bf16 v[68:71], v[172:175], v[216:219], v[68:71]
	v_mfma_f32_16x16x32_bf16 v[64:67], v[184:187], v[216:219], v[64:67]
	v_mfma_f32_16x16x32_bf16 v[116:119], v[180:183], v[196:199], v[116:119]
	v_mfma_f32_16x16x32_bf16 v[112:115], v[188:191], v[196:199], v[112:115]
	v_mfma_f32_16x16x32_bf16 v[100:103], v[180:183], v[204:207], v[100:103]
	v_mfma_f32_16x16x32_bf16 v[96:99], v[188:191], v[204:207], v[96:99]
	v_mfma_f32_16x16x32_bf16 v[84:87], v[180:183], v[212:215], v[84:87]
	v_mfma_f32_16x16x32_bf16 v[80:83], v[188:191], v[212:215], v[80:83]
	v_mfma_f32_16x16x32_bf16 v[68:71], v[180:183], v[220:223], v[68:71]
	v_mfma_f32_16x16x32_bf16 v[64:67], v[188:191], v[220:223], v[64:67]
	s_setprio 0
	s_barrier
	s_add_i32 s10, 0, 0x1c000
	s_add_i32 s11, s42, s57
	v_add_u32_e32 v136, s10, v155
	v_lshl_add_u64 v[152:153], v[152:153], 0, s[24:25]
	s_mov_b32 m0, s11
	ds_read_b128 v[224:227], v136
	ds_read_b128 v[228:231], v136 offset:1024
	ds_read_b128 v[232:235], v136 offset:2048
	ds_read_b128 v[236:239], v136 offset:3072
	global_load_lds_dwordx4 v[152:153], off
	v_lshl_add_u64 v[152:153], v[176:177], 0, s[24:25]
	s_add_i32 m0, s11, 0x2000
	s_nop 0
	global_load_lds_dwordx4 v[152:153], off
	s_barrier
	s_waitcnt lgkmcnt(0)
	s_setprio 1

; #define PG8_STAGE(bufoff, gbase, voff) do { _Pragma("unroll") for (int _i = 0; _i < 2; ++_i) \
;         __builtin_amdgcn_global_load_lds((const unsigned*)((const char*)(gbase) + (voff)[_i]), (LAS unsigned*)(lds + (bufoff) + ldsw + _i * 8192), 16, 0, 0); } while (0)
; #define PG8_LDA(dst, b, h) do { _Pragma("unroll") for (int m = 0; m < 4; ++m) _Pragma("unroll") for (int k = 0; k < 2; ++k) dst[m][k] = *(const LAS bf16x8*)(lds + PG8_SA(b, h) + aoff + m * 2048 + k * 1024); } while (0)
; #define PG8_MMA(ai, bj, At, Bt) do { __builtin_amdgcn_s_setprio(1); _Pragma("unroll") for (int m = 0; m < 4; ++m) _Pragma("unroll") for (int n = 0; n < 2; ++n) _Pragma("unroll") for (int k = 0; k < 2; ++k) \
;         acc[ai][bj][m][n] = __builtin_amdgcn_mfma_f32_16x16x32_bf16(Bt[n][k], At[m][k], acc[ai][bj][m][n], 0, 0, 0); __builtin_amdgcn_s_setprio(0); } while (0)
; #define PG8_WAIT_L(n) asm volatile("s_waitcnt lgkmcnt(" #n ")" ::: "memory")
; #define PG8_BAR __builtin_amdgcn_s_barrier()
; #define PG8_SCHED __builtin_amdgcn_sched_barrier(0)
; template <class Epi>
; __device__ __forceinline__ void gemm_phase(LAS unsigned char* lds, const Gemm g, const StaticOrder& S, const Epi& E) {
;     ...
;             PG8_BAR; PG8_WAIT_L(0); PG8_MMA(0, 1, At, B1); PG8_BAR;
;             PG8_LDA(At, 1, 1); PG8_STAGE(PG8_SA(1, 0), a3, voffA);
;             PG8_BAR; PG8_WAIT_L(0); PG8_MMA(1, 0, At, B0); PG8_BAR; PG8_SCHED;
	v_mfma_f32_16x16x32_bf16 v[124:127], v[224:227], v[192:195], v[124:127]
	v_mfma_f32_16x16x32_bf16 v[120:123], v[232:235], v[192:195], v[120:123]
	v_mfma_f32_16x16x32_bf16 v[108:111], v[224:227], v[200:203], v[108:111]
	v_mfma_f32_16x16x32_bf16 v[104:107], v[232:235], v[200:203], v[104:107]
	v_mfma_f32_16x16x32_bf16 v[92:95], v[224:227], v[208:211], v[92:95]
	v_mfma_f32_16x16x32_bf16 v[88:91], v[232:235], v[208:211], v[88:91]
	v_mfma_f32_16x16x32_bf16 v[76:79], v[224:227], v[216:219], v[76:79]
	v_mfma_f32_16x16x32_bf16 v[72:75], v[232:235], v[216:219], v[72:75]
	v_mfma_f32_16x16x32_bf16 v[124:127], v[228:231], v[196:199], v[124:127]
	v_mfma_f32_16x16x32_bf16 v[120:123], v[236:239], v[196:199], v[120:123]
	v_mfma_f32_16x16x32_bf16 v[108:111], v[228:231], v[204:207], v[108:111]
	v_mfma_f32_16x16x32_bf16 v[104:107], v[236:239], v[204:207], v[104:107]
	v_mfma_f32_16x16x32_bf16 v[92:95], v[228:231], v[212:215], v[92:95]
	v_mfma_f32_16x16x32_bf16 v[88:91], v[236:239], v[212:215], v[88:91]
	v_mfma_f32_16x16x32_bf16 v[76:79], v[228:231], v[220:223], v[76:79]
	v_mfma_f32_16x16x32_bf16 v[72:75], v[236:239], v[220:223], v[72:75]
	s_setprio 0
	s_mov_b32 m0, s67
	v_lshl_add_u64 v[152:153], v[240:241], 0, s[24:25]
	s_barrier
	ds_read_b128 v[192:195], v158 offset:49152
	ds_read_b128 v[196:199], v158 offset:50176
	ds_read_b128 v[200:203], v158 offset:51200
	ds_read_b128 v[204:207], v158 offset:52224
	ds_read_b128 v[208:211], v158 offset:53248
	ds_read_b128 v[212:215], v158 offset:54272
	ds_read_b128 v[216:219], v158 offset:55296
	ds_read_b128 v[220:223], v158 offset:56320
	global_load_lds_dwordx4 v[152:153], off
	v_lshl_add_u64 v[152:153], v[242:243], 0, s[24:25]
	s_mov_b32 m0, s68
	s_nop 0
	global_load_lds_dwordx4 v[152:153], off
	s_barrier
	s_waitcnt lgkmcnt(0)
	s_setprio 1

; #define PG8_STAGE(bufoff, gbase, voff) do { _Pragma("unroll") for (int _i = 0; _i < 2; ++_i) \
;         __builtin_amdgcn_global_load_lds((const unsigned*)((const char*)(gbase) + (voff)[_i]), (LAS unsigned*)(lds + (bufoff) + ldsw + _i * 8192), 16, 0, 0); } while (0)
; #define PG8_MMA(ai, bj, At, Bt) do { __builtin_amdgcn_s_setprio(1); _Pragma("unroll") for (int m = 0; m < 4; ++m) _Pragma("unroll") for (int n = 0; n < 2; ++n) _Pragma("unroll") for (int k = 0; k < 2; ++k) \
;         acc[ai][bj][m][n] = __builtin_amdgcn_mfma_f32_16x16x32_bf16(Bt[n][k], At[m][k], acc[ai][bj][m][n], 0, 0, 0); __builtin_amdgcn_s_setprio(0); } while (0)
; #define PG8_WAIT_V(n) asm volatile("s_waitcnt vmcnt(" #n ")" ::: "memory")
; #define PG8_WAIT_L(n) asm volatile("s_waitcnt lgkmcnt(" #n ")" ::: "memory")
; #define PG8_BAR __builtin_amdgcn_s_barrier()
; #define PG8_SCHED __builtin_amdgcn_sched_barrier(0)
; template <class Epi>
; __device__ __forceinline__ void gemm_phase(LAS unsigned char* lds, const Gemm g, const StaticOrder& S, const Epi& E) {
;     ...
;             PG8_BAR; PG8_WAIT_L(0); PG8_MMA(1, 0, At, B0); PG8_BAR; PG8_SCHED;
;             PG8_STAGE(PG8_SB(1, 1), b3 + hstep, voffB);
;             PG8_WAIT_V(6); PG8_BAR; PG8_MMA(1, 1, At, B1); PG8_BAR;
;         }
;     __device__ __forceinline__ void operator()(const f32x4 (&acc)[2][2][4][2], const Unit& u, int wr, int wc, int fr, int fq, const Pre& P) const {
;         const int sec = u.pn >> 3, row0 = ROW_X + u.pm * BM + wr * 64 + fr, colb = (u.pn & 7) * BM + wc * 32 + 8 * fq;
; #pragma unroll
;         for (int ai = 0; ai < 2; ++ai)
; #pragma unroll
;             for (int m = 0; m < 4; ++m) { const int r = row0 + ai * HALF + m * 16; const float rs = __builtin_amdgcn_rsqf(P.rs[ai * 4 + m] * (1.0f / DM) + RMS_EPS);
;                 if (sec == 4) {
	v_mfma_f32_16x16x32_bf16 v[52:55], v[172:175], v[192:195], v[52:55]
	v_mfma_f32_16x16x32_bf16 v[48:51], v[184:187], v[192:195], v[48:51]
	v_mfma_f32_16x16x32_bf16 v[36:39], v[172:175], v[200:203], v[36:39]
	v_mfma_f32_16x16x32_bf16 v[32:35], v[184:187], v[200:203], v[32:35]
	v_mfma_f32_16x16x32_bf16 v[20:23], v[172:175], v[208:211], v[20:23]
	v_mfma_f32_16x16x32_bf16 v[16:19], v[184:187], v[208:211], v[16:19]
	v_mfma_f32_16x16x32_bf16 v[4:7], v[172:175], v[216:219], v[4:7]
	v_mfma_f32_16x16x32_bf16 v[0:3], v[184:187], v[216:219], v[0:3]
	v_mfma_f32_16x16x32_bf16 v[52:55], v[180:183], v[196:199], v[52:55]
	v_mfma_f32_16x16x32_bf16 v[48:51], v[188:191], v[196:199], v[48:51]
	v_mfma_f32_16x16x32_bf16 v[36:39], v[180:183], v[204:207], v[36:39]
	v_mfma_f32_16x16x32_bf16 v[32:35], v[188:191], v[204:207], v[32:35]
	v_mfma_f32_16x16x32_bf16 v[20:23], v[180:183], v[212:215], v[20:23]
	v_mfma_f32_16x16x32_bf16 v[16:19], v[188:191], v[212:215], v[16:19]
	v_mfma_f32_16x16x32_bf16 v[4:7], v[180:183], v[220:223], v[4:7]
	v_mfma_f32_16x16x32_bf16 v[0:3], v[188:191], v[220:223], v[0:3]
	s_setprio 0
	s_barrier
	s_add_u32 s8, s8, 0x80080
	s_addc_u32 s9, s9, 0
	s_add_i32 s10, s10, s57
	v_lshl_add_u64 v[152:153], s[8:9], 0, v[130:131]
	s_mov_b32 m0, s10
	s_nop 0
	global_load_lds_dwordx4 v[152:153], off
	v_lshl_add_u64 v[152:153], s[8:9], 0, v[134:135]
	s_add_i32 m0, s10, 0x2000
	s_nop 0
	global_load_lds_dwordx4 v[152:153], off
	s_waitcnt vmcnt(6)
	s_barrier
	s_setprio 1
	v_mfma_f32_16x16x32_bf16 v[60:63], v[224:227], v[192:195], v[60:63]
	v_mfma_f32_16x16x32_bf16 v[56:59], v[232:235], v[192:195], v[56:59]
	v_mfma_f32_16x16x32_bf16 v[44:47], v[224:227], v[200:203], v[44:47]
	v_mfma_f32_16x16x32_bf16 v[40:43], v[232:235], v[200:203], v[40:43]
	v_mfma_f32_16x16x32_bf16 v[28:31], v[224:227], v[208:211], v[28:31]
	v_mfma_f32_16x16x32_bf16 v[24:27], v[232:235], v[208:211], v[24:27]
	v_mfma_f32_16x16x32_bf16 v[12:15], v[224:227], v[216:219], v[12:15]
	v_mfma_f32_16x16x32_bf16 v[8:11], v[232:235], v[216:219], v[8:11]
	v_mfma_f32_16x16x32_bf16 v[60:63], v[228:231], v[196:199], v[60:63]
	v_mfma_f32_16x16x32_bf16 v[56:59], v[236:239], v[196:199], v[56:59]
	v_mfma_f32_16x16x32_bf16 v[44:47], v[228:231], v[204:207], v[44:47]
	v_mfma_f32_16x16x32_bf16 v[40:43], v[236:239], v[204:207], v[40:43]
	v_mfma_f32_16x16x32_bf16 v[28:31], v[228:231], v[212:215], v[28:31]
	v_mfma_f32_16x16x32_bf16 v[24:27], v[236:239], v[212:215], v[24:27]
	v_mfma_f32_16x16x32_bf16 v[12:15], v[228:231], v[220:223], v[12:15]
	v_mfma_f32_16x16x32_bf16 v[8:11], v[236:239], v[220:223], v[8:11]
	s_setprio 0
	s_add_i32 s37, s37, 2
	s_add_u32 s6, s6, 0x100
	s_addc_u32 s7, s7, 0
	s_add_u32 s33, s33, 0x100
	s_addc_u32 s35, s35, 0
	s_cmp_gt_u32 s37, 29
	s_barrier
	s_cbranch_scc0 .LBB0_1796
	s_lshl_b32 s1, s0, 8
	s_ashr_i32 s35, s0, 3
	s_and_b32 s1, s1, 0x700
	s_waitcnt vmcnt(0)
	v_fmamk_f32 v136, v151, 0x3a000000, v160
	s_cmp_lg_u32 s35, 4
	v_rsq_f32_e32 v171, v136
	s_cselect_b64 s[10:11], -1, 0
	s_cmp_eq_u32 s35, 3
	v_lshl_add_u32 v150, s4, 8, v154
	s_cselect_b64 s[4:5], -1, 0
	s_cmp_gt_u32 s0, 7
	v_or_b32_e32 v165, s1, v156
	s_cselect_b64 s[12:13], -1, 0
	s_cmp_eq_u32 s35, 4
	s_mov_b64 s[0:1], -1
	s_cbranch_scc1 .LBB0_1817
	s_and_b64 vcc, exec, s[12:13]
	s_mov_b64 s[0:1], s[14:15]
	s_cbranch_vccz .LBB0_1807
	s_cmp_lt_i32 s35, 2
	s_cbranch_scc1 .LBB0_1803
	s_cmp_eq_u32 s35, 2
	s_mov_b64 s[6:7], -1
	s_cbranch_scc0 .LBB0_1802
	s_mov_b64 s[6:7], 0

; #define PG8_STAGE(bufoff, gbase, voff) do { _Pragma("unroll") for (int _i = 0; _i < 2; ++_i) \
;         __builtin_amdgcn_global_load_lds((const unsigned*)((const char*)(gbase) + (voff)[_i]), (LAS unsigned*)(lds + (bufoff) + ldsw + _i * 8192), 16, 0, 0); } while (0)
; #define PG8_LDA(dst, b, h) do { _Pragma("unroll") for (int m = 0; m < 4; ++m) _Pragma("unroll") for (int k = 0; k < 2; ++k) dst[m][k] = *(const LAS bf16x8*)(lds + PG8_SA(b, h) + aoff + m * 2048 + k * 1024); } while (0)
; #define PG8_LDB(dst, b, h) do { _Pragma("unroll") for (int n = 0; n < 2; ++n) _Pragma("unroll") for (int k = 0; k < 2; ++k) dst[n][k] = *(const LAS bf16x8*)(lds + PG8_SB(b, h) + boff + n * 2048 + k * 1024); } while (0)
; #define PG8_MMA(ai, bj, At, Bt) do { __builtin_amdgcn_s_setprio(1); _Pragma("unroll") for (int m = 0; m < 4; ++m) _Pragma("unroll") for (int n = 0; n < 2; ++n) _Pragma("unroll") for (int k = 0; k < 2; ++k) \
;         acc[ai][bj][m][n] = __builtin_amdgcn_mfma_f32_16x16x32_bf16(Bt[n][k], At[m][k], acc[ai][bj][m][n], 0, 0, 0); __builtin_amdgcn_s_setprio(0); } while (0)
; #define PG8_WAIT_L(n) asm volatile("s_waitcnt lgkmcnt(" #n ")" ::: "memory")
; #define PG8_BAR __builtin_amdgcn_s_barrier()
; #define PG8_SCHED __builtin_amdgcn_sched_barrier(0)
; template <class Epi>
; __device__ __forceinline__ void gemm_phase(LAS unsigned char* lds, const Gemm g, const StaticOrder& S, const Epi& E) {
;     ...
;         for (int t = 0; t < nt; t += 2) {
;             const bool last = (t == nt - 2);
;             const char* a1 = cA + (size_t)(t + 1) * kstep;
;             const char* a2 = last ? nA : cA + (size_t)(t + 2) * kstep; const char* b2 = last ? nB : cB + (size_t)(t + 2) * kstep;
;             const char* a3 = a2 + kstep; const char* b3 = b2 + kstep;
;             PG8_LDB(B0, 0, 0); PG8_SCHED; PG8_LDA(At, 0, 0); PG8_STAGE(PG8_SA(1, 1), a1 + hstep, voffA);
;             PG8_WAIT_L(8); PG8_BAR; PG8_WAIT_L(0); PG8_MMA(0, 0, At, B0); PG8_BAR; PG8_SCHED;
.LBB0_2460:
	ds_read_b128 v[128:131], v161
	ds_read_b128 v[132:135], v161 offset:1024
	ds_read_b128 v[152:155], v161 offset:2048
	ds_read_b128 v[166:169], v161 offset:3072
	s_add_u32 s24, s22, 0xfff80080
	s_addc_u32 s25, s23, -1
	s_cmp_eq_u32 s61, 28
	s_cselect_b32 s31, s13, s25
	s_cselect_b32 s30, s19, s24
	s_cselect_b32 s25, s11, s60
	s_cselect_b32 s24, s58, s59
	v_lshl_add_u64 v[156:157], s[22:23], 0, v[144:145]
	s_add_i32 m0, s21, 0xc000
	ds_read_b128 v[170:173], v162
	ds_read_b128 v[174:177], v162 offset:1024
	ds_read_b128 v[180:183], v162 offset:2048
	ds_read_b128 v[184:187], v162 offset:3072
	ds_read_b128 v[188:191], v162 offset:4096
	ds_read_b128 v[192:195], v162 offset:5120
	ds_read_b128 v[196:199], v162 offset:6144
	ds_read_b128 v[200:203], v162 offset:7168
	global_load_lds_dwordx4 v[156:157], off
	v_lshl_add_u64 v[156:157], s[22:23], 0, v[146:147]
	s_add_i32 m0, s21, 0xe000
	s_nop 0
	global_load_lds_dwordx4 v[156:157], off
	s_waitcnt lgkmcnt(8)
	s_barrier
	s_waitcnt lgkmcnt(0)
	s_setprio 1

; #define PG8_STAGE(bufoff, gbase, voff) do { _Pragma("unroll") for (int _i = 0; _i < 2; ++_i) \
;         __builtin_amdgcn_global_load_lds((const unsigned*)((const char*)(gbase) + (voff)[_i]), (LAS unsigned*)(lds + (bufoff) + ldsw + _i * 8192), 16, 0, 0); } while (0)
; #define PG8_LDB(dst, b, h) do { _Pragma("unroll") for (int n = 0; n < 2; ++n) _Pragma("unroll") for (int k = 0; k < 2; ++k) dst[n][k] = *(const LAS bf16x8*)(lds + PG8_SB(b, h) + boff + n * 2048 + k * 1024); } while (0)
; #define PG8_MMA(ai, bj, At, Bt) do { __builtin_amdgcn_s_setprio(1); _Pragma("unroll") for (int m = 0; m < 4; ++m) _Pragma("unroll") for (int n = 0; n < 2; ++n) _Pragma("unroll") for (int k = 0; k < 2; ++k) \
;         acc[ai][bj][m][n] = __builtin_amdgcn_mfma_f32_16x16x32_bf16(Bt[n][k], At[m][k], acc[ai][bj][m][n], 0, 0, 0); __builtin_amdgcn_s_setprio(0); } while (0)
; #define PG8_WAIT_L(n) asm volatile("s_waitcnt lgkmcnt(" #n ")" ::: "memory")
; #define PG8_BAR __builtin_amdgcn_s_barrier()
; #define PG8_SCHED __builtin_amdgcn_sched_barrier(0)
; template <class Epi>
; __device__ __forceinline__ void gemm_phase(LAS unsigned char* lds, const Gemm g, const StaticOrder& S, const Epi& E) {
;     ...
;             PG8_WAIT_L(8); PG8_BAR; PG8_WAIT_L(0); PG8_MMA(0, 0, At, B0); PG8_BAR; PG8_SCHED;
;             PG8_LDB(B1, 0, 1); PG8_STAGE(PG8_SB(0, 0), b2, voffB);
;             PG8_BAR; PG8_WAIT_L(0); PG8_MMA(0, 1, At, B1); PG8_BAR;
	v_mfma_f32_16x16x32_bf16 v[124:127], v[128:131], v[170:173], v[124:127]
	v_mfma_f32_16x16x32_bf16 v[120:123], v[152:155], v[170:173], v[120:123]
	v_mfma_f32_16x16x32_bf16 v[108:111], v[128:131], v[180:183], v[108:111]
	v_mfma_f32_16x16x32_bf16 v[104:107], v[152:155], v[180:183], v[104:107]
	v_mfma_f32_16x16x32_bf16 v[92:95], v[128:131], v[188:191], v[92:95]
	v_mfma_f32_16x16x32_bf16 v[88:91], v[152:155], v[188:191], v[88:91]
	v_mfma_f32_16x16x32_bf16 v[76:79], v[128:131], v[196:199], v[76:79]
	v_mfma_f32_16x16x32_bf16 v[72:75], v[152:155], v[196:199], v[72:75]
	v_mfma_f32_16x16x32_bf16 v[124:127], v[132:135], v[174:177], v[124:127]
	v_mfma_f32_16x16x32_bf16 v[120:123], v[166:169], v[174:177], v[120:123]
	v_mfma_f32_16x16x32_bf16 v[108:111], v[132:135], v[184:187], v[108:111]
	v_mfma_f32_16x16x32_bf16 v[104:107], v[166:169], v[184:187], v[104:107]
	v_mfma_f32_16x16x32_bf16 v[92:95], v[132:135], v[192:195], v[92:95]
	v_mfma_f32_16x16x32_bf16 v[88:91], v[166:169], v[192:195], v[88:91]
	v_mfma_f32_16x16x32_bf16 v[76:79], v[132:135], v[200:203], v[76:79]
	v_mfma_f32_16x16x32_bf16 v[72:75], v[166:169], v[200:203], v[72:75]
	s_setprio 0
	s_barrier
	s_add_i32 s62, s56, s38
	v_lshl_add_u64 v[156:157], s[24:25], 0, v[138:139]
	s_mov_b32 m0, s62
	ds_read_b128 v[204:207], v163
	ds_read_b128 v[208:211], v163 offset:1024
	ds_read_b128 v[212:215], v163 offset:2048
	ds_read_b128 v[216:219], v163 offset:3072
	global_load_lds_dwordx4 v[156:157], off
	v_lshl_add_u64 v[220:221], s[24:25], 0, v[142:143]
	s_add_i32 m0, s62, 0x2000
	s_nop 0
	global_load_lds_dwordx4 v[220:221], off
	s_barrier
	s_waitcnt lgkmcnt(0)
	s_setprio 1

; #define PG8_STAGE(bufoff, gbase, voff) do { _Pragma("unroll") for (int _i = 0; _i < 2; ++_i) \
;         __builtin_amdgcn_global_load_lds((const unsigned*)((const char*)(gbase) + (voff)[_i]), (LAS unsigned*)(lds + (bufoff) + ldsw + _i * 8192), 16, 0, 0); } while (0)
; #define PG8_LDA(dst, b, h) do { _Pragma("unroll") for (int m = 0; m < 4; ++m) _Pragma("unroll") for (int k = 0; k < 2; ++k) dst[m][k] = *(const LAS bf16x8*)(lds + PG8_SA(b, h) + aoff + m * 2048 + k * 1024); } while (0)
; #define PG8_MMA(ai, bj, At, Bt) do { __builtin_amdgcn_s_setprio(1); _Pragma("unroll") for (int m = 0; m < 4; ++m) _Pragma("unroll") for (int n = 0; n < 2; ++n) _Pragma("unroll") for (int k = 0; k < 2; ++k) \
;         acc[ai][bj][m][n] = __builtin_amdgcn_mfma_f32_16x16x32_bf16(Bt[n][k], At[m][k], acc[ai][bj][m][n], 0, 0, 0); __builtin_amdgcn_s_setprio(0); } while (0)
; #define PG8_WAIT_L(n) asm volatile("s_waitcnt lgkmcnt(" #n ")" ::: "memory")
; #define PG8_BAR __builtin_amdgcn_s_barrier()
; #define PG8_SCHED __builtin_amdgcn_sched_barrier(0)
; template <class Epi>
; __device__ __forceinline__ void gemm_phase(LAS unsigned char* lds, const Gemm g, const StaticOrder& S, const Epi& E) {
;     ...
;             PG8_BAR; PG8_WAIT_L(0); PG8_MMA(0, 1, At, B1); PG8_BAR;
;             PG8_LDA(At, 0, 1); PG8_STAGE(PG8_SA(0, 0), a2, voffA);
;             PG8_BAR; PG8_WAIT_L(0); PG8_MMA(1, 0, At, B0); PG8_BAR; PG8_SCHED;
	v_mfma_f32_16x16x32_bf16 v[116:119], v[204:207], v[170:173], v[116:119]
	v_mfma_f32_16x16x32_bf16 v[112:115], v[212:215], v[170:173], v[112:115]
	v_mfma_f32_16x16x32_bf16 v[100:103], v[204:207], v[180:183], v[100:103]
	v_mfma_f32_16x16x32_bf16 v[96:99], v[212:215], v[180:183], v[96:99]
	v_mfma_f32_16x16x32_bf16 v[84:87], v[204:207], v[188:191], v[84:87]
	v_mfma_f32_16x16x32_bf16 v[80:83], v[212:215], v[188:191], v[80:83]
	v_mfma_f32_16x16x32_bf16 v[68:71], v[204:207], v[196:199], v[68:71]
	v_mfma_f32_16x16x32_bf16 v[64:67], v[212:215], v[196:199], v[64:67]
	v_mfma_f32_16x16x32_bf16 v[116:119], v[208:211], v[174:177], v[116:119]
	v_mfma_f32_16x16x32_bf16 v[112:115], v[216:219], v[174:177], v[112:115]
	v_mfma_f32_16x16x32_bf16 v[100:103], v[208:211], v[184:187], v[100:103]
	v_mfma_f32_16x16x32_bf16 v[96:99], v[216:219], v[184:187], v[96:99]
	v_mfma_f32_16x16x32_bf16 v[84:87], v[208:211], v[192:195], v[84:87]
	v_mfma_f32_16x16x32_bf16 v[80:83], v[216:219], v[192:195], v[80:83]
	v_mfma_f32_16x16x32_bf16 v[68:71], v[208:211], v[200:203], v[68:71]
	v_mfma_f32_16x16x32_bf16 v[64:67], v[216:219], v[200:203], v[64:67]
	s_setprio 0
	s_mov_b32 m0, s21
	v_lshl_add_u64 v[222:223], s[30:31], 0, v[136:137]
	s_barrier
	ds_read_b128 v[170:173], v162 offset:16384
	ds_read_b128 v[174:177], v162 offset:17408
	ds_read_b128 v[180:183], v162 offset:18432
	ds_read_b128 v[184:187], v162 offset:19456
	ds_read_b128 v[188:191], v162 offset:20480
	ds_read_b128 v[192:195], v162 offset:21504
	ds_read_b128 v[196:199], v162 offset:22528
	ds_read_b128 v[200:203], v162 offset:23552
	global_load_lds_dwordx4 v[222:223], off
	v_lshl_add_u64 v[224:225], s[30:31], 0, v[140:141]
	s_mov_b32 m0, s39
	s_nop 0
	global_load_lds_dwordx4 v[224:225], off
	s_barrier
	s_waitcnt lgkmcnt(0)
	s_setprio 1

; #define PG8_STAGE(bufoff, gbase, voff) do { _Pragma("unroll") for (int _i = 0; _i < 2; ++_i) \
;         __builtin_amdgcn_global_load_lds((const unsigned*)((const char*)(gbase) + (voff)[_i]), (LAS unsigned*)(lds + (bufoff) + ldsw + _i * 8192), 16, 0, 0); } while (0)
; #define PG8_LDA(dst, b, h) do { _Pragma("unroll") for (int m = 0; m < 4; ++m) _Pragma("unroll") for (int k = 0; k < 2; ++k) dst[m][k] = *(const LAS bf16x8*)(lds + PG8_SA(b, h) + aoff + m * 2048 + k * 1024); } while (0)
; #define PG8_LDB(dst, b, h) do { _Pragma("unroll") for (int n = 0; n < 2; ++n) _Pragma("unroll") for (int k = 0; k < 2; ++k) dst[n][k] = *(const LAS bf16x8*)(lds + PG8_SB(b, h) + boff + n * 2048 + k * 1024); } while (0)
; #define PG8_MMA(ai, bj, At, Bt) do { __builtin_amdgcn_s_setprio(1); _Pragma("unroll") for (int m = 0; m < 4; ++m) _Pragma("unroll") for (int n = 0; n < 2; ++n) _Pragma("unroll") for (int k = 0; k < 2; ++k) \
;         acc[ai][bj][m][n] = __builtin_amdgcn_mfma_f32_16x16x32_bf16(Bt[n][k], At[m][k], acc[ai][bj][m][n], 0, 0, 0); __builtin_amdgcn_s_setprio(0); } while (0)
; #define PG8_WAIT_V(n) asm volatile("s_waitcnt vmcnt(" #n ")" ::: "memory")
; #define PG8_WAIT_L(n) asm volatile("s_waitcnt lgkmcnt(" #n ")" ::: "memory")
; #define PG8_BAR __builtin_amdgcn_s_barrier()
; #define PG8_SCHED __builtin_amdgcn_sched_barrier(0)
; template <class Epi>
; __device__ __forceinline__ void gemm_phase(LAS unsigned char* lds, const Gemm g, const StaticOrder& S, const Epi& E) {
;     ...
;             PG8_BAR; PG8_WAIT_L(0); PG8_MMA(1, 0, At, B0); PG8_BAR; PG8_SCHED;
;             PG8_STAGE(PG8_SB(0, 1), b2 + hstep, voffB);
;             PG8_WAIT_V(6); PG8_BAR; PG8_MMA(1, 1, At, B1); PG8_BAR;
;             PG8_LDB(B0, 1, 0); PG8_SCHED; PG8_LDA(At, 1, 0); PG8_STAGE(PG8_SA(0, 1), a2 + hstep, voffA);
;             PG8_WAIT_L(8); PG8_BAR; PG8_WAIT_L(0); PG8_MMA(0, 0, At, B0); PG8_BAR; PG8_SCHED;
	v_mfma_f32_16x16x32_bf16 v[60:63], v[128:131], v[170:173], v[60:63]
	v_mfma_f32_16x16x32_bf16 v[56:59], v[152:155], v[170:173], v[56:59]
	v_mfma_f32_16x16x32_bf16 v[44:47], v[128:131], v[180:183], v[44:47]
	v_mfma_f32_16x16x32_bf16 v[40:43], v[152:155], v[180:183], v[40:43]
	v_mfma_f32_16x16x32_bf16 v[28:31], v[128:131], v[188:191], v[28:31]
	v_mfma_f32_16x16x32_bf16 v[24:27], v[152:155], v[188:191], v[24:27]
	v_mfma_f32_16x16x32_bf16 v[12:15], v[128:131], v[196:199], v[12:15]
	v_mfma_f32_16x16x32_bf16 v[8:11], v[152:155], v[196:199], v[8:11]
	v_mfma_f32_16x16x32_bf16 v[60:63], v[132:135], v[174:177], v[60:63]
	v_mfma_f32_16x16x32_bf16 v[56:59], v[166:169], v[174:177], v[56:59]
	v_mfma_f32_16x16x32_bf16 v[44:47], v[132:135], v[184:187], v[44:47]
	v_mfma_f32_16x16x32_bf16 v[40:43], v[166:169], v[184:187], v[40:43]
	v_mfma_f32_16x16x32_bf16 v[28:31], v[132:135], v[192:195], v[28:31]
	v_mfma_f32_16x16x32_bf16 v[24:27], v[166:169], v[192:195], v[24:27]
	v_mfma_f32_16x16x32_bf16 v[12:15], v[132:135], v[200:203], v[12:15]
	v_mfma_f32_16x16x32_bf16 v[8:11], v[166:169], v[200:203], v[8:11]
	s_setprio 0
	s_barrier
	s_add_u32 s62, s24, 0x80000
	s_addc_u32 s63, s25, 0
	s_add_i32 s64, s57, s38
	v_lshl_add_u64 v[128:129], s[62:63], 0, v[138:139]
	s_mov_b32 m0, s64
	s_nop 0
	global_load_lds_dwordx4 v[128:129], off
	v_lshl_add_u64 v[128:129], s[62:63], 0, v[142:143]
	s_add_i32 m0, s64, 0x2000
	s_nop 0
	global_load_lds_dwordx4 v[128:129], off
	s_waitcnt vmcnt(6)
	s_barrier
	s_setprio 1
	v_mfma_f32_16x16x32_bf16 v[52:55], v[204:207], v[170:173], v[52:55]
	v_mfma_f32_16x16x32_bf16 v[48:51], v[212:215], v[170:173], v[48:51]
	v_mfma_f32_16x16x32_bf16 v[36:39], v[204:207], v[180:183], v[36:39]
	v_mfma_f32_16x16x32_bf16 v[32:35], v[212:215], v[180:183], v[32:35]
	v_mfma_f32_16x16x32_bf16 v[20:23], v[204:207], v[188:191], v[20:23]
	v_mfma_f32_16x16x32_bf16 v[16:19], v[212:215], v[188:191], v[16:19]
	v_mfma_f32_16x16x32_bf16 v[4:7], v[204:207], v[196:199], v[4:7]
	v_mfma_f32_16x16x32_bf16 v[0:3], v[212:215], v[196:199], v[0:3]
	v_mfma_f32_16x16x32_bf16 v[52:55], v[208:211], v[174:177], v[52:55]
	v_mfma_f32_16x16x32_bf16 v[48:51], v[216:219], v[174:177], v[48:51]
	v_mfma_f32_16x16x32_bf16 v[36:39], v[208:211], v[184:187], v[36:39]
	v_mfma_f32_16x16x32_bf16 v[32:35], v[216:219], v[184:187], v[32:35]
	v_mfma_f32_16x16x32_bf16 v[20:23], v[208:211], v[192:195], v[20:23]
	v_mfma_f32_16x16x32_bf16 v[16:19], v[216:219], v[192:195], v[16:19]
	v_mfma_f32_16x16x32_bf16 v[4:7], v[208:211], v[200:203], v[4:7]
	v_mfma_f32_16x16x32_bf16 v[0:3], v[216:219], v[200:203], v[0:3]
	s_setprio 0
	s_add_i32 s62, 0, 0x18000
	v_add_u32_e32 v165, s62, v158
	s_barrier
	ds_read_b128 v[128:131], v165
	ds_read_b128 v[132:135], v165 offset:1024
	ds_read_b128 v[152:155], v165 offset:2048
	ds_read_b128 v[166:169], v165 offset:3072
	s_add_u32 s30, s30, 0x80000
	s_addc_u32 s31, s31, 0
	s_mov_b32 m0, s40
	v_lshl_add_u64 v[204:205], s[30:31], 0, v[136:137]
	ds_read_b128 v[170:173], v162 offset:32768
	ds_read_b128 v[174:177], v162 offset:33792
	ds_read_b128 v[180:183], v162 offset:34816
	ds_read_b128 v[184:187], v162 offset:35840
	ds_read_b128 v[188:191], v162 offset:36864
	ds_read_b128 v[192:195], v162 offset:37888
	ds_read_b128 v[196:199], v162 offset:38912
	ds_read_b128 v[200:203], v162 offset:39936
	global_load_lds_dwordx4 v[204:205], off
	v_lshl_add_u64 v[204:205], s[30:31], 0, v[140:141]
	s_mov_b32 m0, s41
	s_nop 0
	global_load_lds_dwordx4 v[204:205], off
	s_waitcnt lgkmcnt(8)
	s_barrier
	s_waitcnt lgkmcnt(0)
	s_setprio 1

; #define PG8_STAGE(bufoff, gbase, voff) do { _Pragma("unroll") for (int _i = 0; _i < 2; ++_i) \
;         __builtin_amdgcn_global_load_lds((const unsigned*)((const char*)(gbase) + (voff)[_i]), (LAS unsigned*)(lds + (bufoff) + ldsw + _i * 8192), 16, 0, 0); } while (0)
; #define PG8_LDB(dst, b, h) do { _Pragma("unroll") for (int n = 0; n < 2; ++n) _Pragma("unroll") for (int k = 0; k < 2; ++k) dst[n][k] = *(const LAS bf16x8*)(lds + PG8_SB(b, h) + boff + n * 2048 + k * 1024); } while (0)
; #define PG8_MMA(ai, bj, At, Bt) do { __builtin_amdgcn_s_setprio(1); _Pragma("unroll") for (int m = 0; m < 4; ++m) _Pragma("unroll") for (int n = 0; n < 2; ++n) _Pragma("unroll") for (int k = 0; k < 2; ++k) \
;         acc[ai][bj][m][n] = __builtin_amdgcn_mfma_f32_16x16x32_bf16(Bt[n][k], At[m][k], acc[ai][bj][m][n], 0, 0, 0); __builtin_amdgcn_s_setprio(0); } while (0)
; #define PG8_WAIT_L(n) asm volatile("s_waitcnt lgkmcnt(" #n ")" ::: "memory")
; #define PG8_BAR __builtin_amdgcn_s_barrier()
; #define PG8_SCHED __builtin_amdgcn_sched_barrier(0)
; template <class Epi>
; __device__ __forceinline__ void gemm_phase(LAS unsigned char* lds, const Gemm g, const StaticOrder& S, const Epi& E) {
;     ...
;             PG8_WAIT_L(8); PG8_BAR; PG8_WAIT_L(0); PG8_MMA(0, 0, At, B0); PG8_BAR; PG8_SCHED;
;             PG8_LDB(B1, 1, 1); PG8_STAGE(PG8_SB(1, 0), b3, voffB);
;             PG8_BAR; PG8_WAIT_L(0); PG8_MMA(0, 1, At, B1); PG8_BAR;
	v_mfma_f32_16x16x32_bf16 v[124:127], v[128:131], v[170:173], v[124:127]
	v_mfma_f32_16x16x32_bf16 v[120:123], v[152:155], v[170:173], v[120:123]
	v_mfma_f32_16x16x32_bf16 v[108:111], v[128:131], v[180:183], v[108:111]
	v_mfma_f32_16x16x32_bf16 v[104:107], v[152:155], v[180:183], v[104:107]
	v_mfma_f32_16x16x32_bf16 v[92:95], v[128:131], v[188:191], v[92:95]
	v_mfma_f32_16x16x32_bf16 v[88:91], v[152:155], v[188:191], v[88:91]
	v_mfma_f32_16x16x32_bf16 v[76:79], v[128:131], v[196:199], v[76:79]
	v_mfma_f32_16x16x32_bf16 v[72:75], v[152:155], v[196:199], v[72:75]
	v_mfma_f32_16x16x32_bf16 v[124:127], v[132:135], v[174:177], v[124:127]
	v_mfma_f32_16x16x32_bf16 v[120:123], v[166:169], v[174:177], v[120:123]
	v_mfma_f32_16x16x32_bf16 v[108:111], v[132:135], v[184:187], v[108:111]
	v_mfma_f32_16x16x32_bf16 v[104:107], v[166:169], v[184:187], v[104:107]
	v_mfma_f32_16x16x32_bf16 v[92:95], v[132:135], v[192:195], v[92:95]
	v_mfma_f32_16x16x32_bf16 v[88:91], v[166:169], v[192:195], v[88:91]
	v_mfma_f32_16x16x32_bf16 v[76:79], v[132:135], v[200:203], v[76:79]
	v_mfma_f32_16x16x32_bf16 v[72:75], v[166:169], v[200:203], v[72:75]
	s_setprio 0
	s_barrier
	s_add_i32 s30, 0, 0x1c000
	s_add_i32 s31, s62, s38
	v_add_u32_e32 v165, s30, v158
	v_lshl_add_u64 v[156:157], v[156:157], 0, s[8:9]
	s_mov_b32 m0, s31
	ds_read_b128 v[204:207], v165
	ds_read_b128 v[208:211], v165 offset:1024
	ds_read_b128 v[212:215], v165 offset:2048
	ds_read_b128 v[216:219], v165 offset:3072
	global_load_lds_dwordx4 v[156:157], off
	v_lshl_add_u64 v[156:157], v[220:221], 0, s[8:9]
	s_add_i32 m0, s31, 0x2000
	s_nop 0
	global_load_lds_dwordx4 v[156:157], off
	s_barrier
	s_waitcnt lgkmcnt(0)
	s_setprio 1

; #define PG8_STAGE(bufoff, gbase, voff) do { _Pragma("unroll") for (int _i = 0; _i < 2; ++_i) \
;         __builtin_amdgcn_global_load_lds((const unsigned*)((const char*)(gbase) + (voff)[_i]), (LAS unsigned*)(lds + (bufoff) + ldsw + _i * 8192), 16, 0, 0); } while (0)
; #define PG8_LDA(dst, b, h) do { _Pragma("unroll") for (int m = 0; m < 4; ++m) _Pragma("unroll") for (int k = 0; k < 2; ++k) dst[m][k] = *(const LAS bf16x8*)(lds + PG8_SA(b, h) + aoff + m * 2048 + k * 1024); } while (0)
; #define PG8_MMA(ai, bj, At, Bt) do { __builtin_amdgcn_s_setprio(1); _Pragma("unroll") for (int m = 0; m < 4; ++m) _Pragma("unroll") for (int n = 0; n < 2; ++n) _Pragma("unroll") for (int k = 0; k < 2; ++k) \
;         acc[ai][bj][m][n] = __builtin_amdgcn_mfma_f32_16x16x32_bf16(Bt[n][k], At[m][k], acc[ai][bj][m][n], 0, 0, 0); __builtin_amdgcn_s_setprio(0); } while (0)
; #define PG8_WAIT_L(n) asm volatile("s_waitcnt lgkmcnt(" #n ")" ::: "memory")
; #define PG8_BAR __builtin_amdgcn_s_barrier()
; #define PG8_SCHED __builtin_amdgcn_sched_barrier(0)
; template <class Epi>
; __device__ __forceinline__ void gemm_phase(LAS unsigned char* lds, const Gemm g, const StaticOrder& S, const Epi& E) {
;     ...
;             PG8_BAR; PG8_WAIT_L(0); PG8_MMA(0, 1, At, B1); PG8_BAR;
;             PG8_LDA(At, 1, 1); PG8_STAGE(PG8_SA(1, 0), a3, voffA);
;             PG8_BAR; PG8_WAIT_L(0); PG8_MMA(1, 0, At, B0); PG8_BAR; PG8_SCHED;
	v_mfma_f32_16x16x32_bf16 v[116:119], v[204:207], v[170:173], v[116:119]
	v_mfma_f32_16x16x32_bf16 v[112:115], v[212:215], v[170:173], v[112:115]
	v_mfma_f32_16x16x32_bf16 v[100:103], v[204:207], v[180:183], v[100:103]
	v_mfma_f32_16x16x32_bf16 v[96:99], v[212:215], v[180:183], v[96:99]
	v_mfma_f32_16x16x32_bf16 v[84:87], v[204:207], v[188:191], v[84:87]
	v_mfma_f32_16x16x32_bf16 v[80:83], v[212:215], v[188:191], v[80:83]
	v_mfma_f32_16x16x32_bf16 v[68:71], v[204:207], v[196:199], v[68:71]
	v_mfma_f32_16x16x32_bf16 v[64:67], v[212:215], v[196:199], v[64:67]
	v_mfma_f32_16x16x32_bf16 v[116:119], v[208:211], v[174:177], v[116:119]
	v_mfma_f32_16x16x32_bf16 v[112:115], v[216:219], v[174:177], v[112:115]
	v_mfma_f32_16x16x32_bf16 v[100:103], v[208:211], v[184:187], v[100:103]
	v_mfma_f32_16x16x32_bf16 v[96:99], v[216:219], v[184:187], v[96:99]
	v_mfma_f32_16x16x32_bf16 v[84:87], v[208:211], v[192:195], v[84:87]
	v_mfma_f32_16x16x32_bf16 v[80:83], v[216:219], v[192:195], v[80:83]
	v_mfma_f32_16x16x32_bf16 v[68:71], v[208:211], v[200:203], v[68:71]
	v_mfma_f32_16x16x32_bf16 v[64:67], v[216:219], v[200:203], v[64:67]
	s_setprio 0
	s_mov_b32 m0, s43
	v_lshl_add_u64 v[156:157], v[222:223], 0, s[8:9]
	s_barrier
	ds_read_b128 v[170:173], v162 offset:49152
	ds_read_b128 v[174:177], v162 offset:50176
	ds_read_b128 v[180:183], v162 offset:51200
	ds_read_b128 v[184:187], v162 offset:52224
	ds_read_b128 v[188:191], v162 offset:53248
	ds_read_b128 v[192:195], v162 offset:54272
	ds_read_b128 v[196:199], v162 offset:55296
	ds_read_b128 v[200:203], v162 offset:56320
	global_load_lds_dwordx4 v[156:157], off
	v_lshl_add_u64 v[156:157], v[224:225], 0, s[8:9]
	s_mov_b32 m0, s44
	s_nop 0
	global_load_lds_dwordx4 v[156:157], off
	s_barrier
	s_waitcnt lgkmcnt(0)
	s_setprio 1

; #define PG8_STAGE(bufoff, gbase, voff) do { _Pragma("unroll") for (int _i = 0; _i < 2; ++_i) \
;         __builtin_amdgcn_global_load_lds((const unsigned*)((const char*)(gbase) + (voff)[_i]), (LAS unsigned*)(lds + (bufoff) + ldsw + _i * 8192), 16, 0, 0); } while (0)
; #define PG8_MMA(ai, bj, At, Bt) do { __builtin_amdgcn_s_setprio(1); _Pragma("unroll") for (int m = 0; m < 4; ++m) _Pragma("unroll") for (int n = 0; n < 2; ++n) _Pragma("unroll") for (int k = 0; k < 2; ++k) \
;         acc[ai][bj][m][n] = __builtin_amdgcn_mfma_f32_16x16x32_bf16(Bt[n][k], At[m][k], acc[ai][bj][m][n], 0, 0, 0); __builtin_amdgcn_s_setprio(0); } while (0)
; #define PG8_WAIT_V(n) asm volatile("s_waitcnt vmcnt(" #n ")" ::: "memory")
; #define PG8_WAIT_L(n) asm volatile("s_waitcnt lgkmcnt(" #n ")" ::: "memory")
; #define PG8_BAR __builtin_amdgcn_s_barrier()
; #define PG8_SCHED __builtin_amdgcn_sched_barrier(0)
; template <class Epi>
; __device__ __forceinline__ void gemm_phase(LAS unsigned char* lds, const Gemm g, const StaticOrder& S, const Epi& E) {
;     ...
;             PG8_BAR; PG8_WAIT_L(0); PG8_MMA(1, 0, At, B0); PG8_BAR; PG8_SCHED;
;             PG8_STAGE(PG8_SB(1, 1), b3 + hstep, voffB);
;             PG8_WAIT_V(6); PG8_BAR; PG8_MMA(1, 1, At, B1); PG8_BAR;
;         }
	v_mfma_f32_16x16x32_bf16 v[60:63], v[128:131], v[170:173], v[60:63]
	v_mfma_f32_16x16x32_bf16 v[56:59], v[152:155], v[170:173], v[56:59]
	v_mfma_f32_16x16x32_bf16 v[44:47], v[128:131], v[180:183], v[44:47]
	v_mfma_f32_16x16x32_bf16 v[40:43], v[152:155], v[180:183], v[40:43]
	v_mfma_f32_16x16x32_bf16 v[28:31], v[128:131], v[188:191], v[28:31]
	v_mfma_f32_16x16x32_bf16 v[24:27], v[152:155], v[188:191], v[24:27]
	v_mfma_f32_16x16x32_bf16 v[12:15], v[128:131], v[196:199], v[12:15]
	v_mfma_f32_16x16x32_bf16 v[8:11], v[152:155], v[196:199], v[8:11]
	v_mfma_f32_16x16x32_bf16 v[60:63], v[132:135], v[174:177], v[60:63]
	v_mfma_f32_16x16x32_bf16 v[56:59], v[166:169], v[174:177], v[56:59]
	v_mfma_f32_16x16x32_bf16 v[44:47], v[132:135], v[184:187], v[44:47]
	v_mfma_f32_16x16x32_bf16 v[40:43], v[166:169], v[184:187], v[40:43]
	v_mfma_f32_16x16x32_bf16 v[28:31], v[132:135], v[192:195], v[28:31]
	v_mfma_f32_16x16x32_bf16 v[24:27], v[166:169], v[192:195], v[24:27]
	v_mfma_f32_16x16x32_bf16 v[12:15], v[132:135], v[200:203], v[12:15]
	v_mfma_f32_16x16x32_bf16 v[8:11], v[166:169], v[200:203], v[8:11]
	s_setprio 0
	s_barrier
	s_add_u32 s24, s24, 0x80080
	s_addc_u32 s25, s25, 0
	s_add_i32 s30, s30, s38
	v_lshl_add_u64 v[128:129], s[24:25], 0, v[138:139]
	s_mov_b32 m0, s30
	s_nop 0
	global_load_lds_dwordx4 v[128:129], off
	v_lshl_add_u64 v[128:129], s[24:25], 0, v[142:143]
	s_add_i32 m0, s30, 0x2000
	s_nop 0
	global_load_lds_dwordx4 v[128:129], off
	s_waitcnt vmcnt(6)
	s_barrier
	s_setprio 1
	v_mfma_f32_16x16x32_bf16 v[52:55], v[204:207], v[170:173], v[52:55]
	v_mfma_f32_16x16x32_bf16 v[48:51], v[212:215], v[170:173], v[48:51]
	v_mfma_f32_16x16x32_bf16 v[36:39], v[204:207], v[180:183], v[36:39]
	v_mfma_f32_16x16x32_bf16 v[32:35], v[212:215], v[180:183], v[32:35]
	v_mfma_f32_16x16x32_bf16 v[20:23], v[204:207], v[188:191], v[20:23]
	v_mfma_f32_16x16x32_bf16 v[16:19], v[212:215], v[188:191], v[16:19]
	v_mfma_f32_16x16x32_bf16 v[4:7], v[204:207], v[196:199], v[4:7]
	v_mfma_f32_16x16x32_bf16 v[0:3], v[212:215], v[196:199], v[0:3]
	v_mfma_f32_16x16x32_bf16 v[52:55], v[208:211], v[174:177], v[52:55]
	v_mfma_f32_16x16x32_bf16 v[48:51], v[216:219], v[174:177], v[48:51]
	v_mfma_f32_16x16x32_bf16 v[36:39], v[208:211], v[184:187], v[36:39]
	v_mfma_f32_16x16x32_bf16 v[32:35], v[216:219], v[184:187], v[32:35]
	v_mfma_f32_16x16x32_bf16 v[20:23], v[208:211], v[192:195], v[20:23]
	v_mfma_f32_16x16x32_bf16 v[16:19], v[216:219], v[192:195], v[16:19]
	v_mfma_f32_16x16x32_bf16 v[4:7], v[208:211], v[200:203], v[4:7]
	v_mfma_f32_16x16x32_bf16 v[0:3], v[216:219], v[200:203], v[0:3]
	s_setprio 0
	s_add_i32 s61, s61, 2
	s_add_u32 s22, s22, 0x100
	s_addc_u32 s23, s23, 0
	s_add_u32 s59, s59, 0x100
	s_addc_u32 s60, s60, 0
	s_cmp_gt_u32 s61, 29
	s_barrier
	s_cbranch_scc0 .LBB0_2460
; __device__ __forceinline__ float bflo(unsigned w) { return __uint_as_float(w << 16); }
; __device__ __forceinline__ float bfhi(unsigned w) { return __uint_as_float(w & 0xffff0000u); }
; #define ER_LOAD(g_, set_) do { const size_t off_ = (size_t)(row0 + ((g_) >> 2) * HALF + ((g_) & 3) * 16) * DM + col0; \
;         hv[set_][0] = *(const u32x4*)(HB + off_); hv[set_][1] = *(const u32x4*)(HB + off_ + HALF); } while (0)
;     __device__ __forceinline__ void operator()(const f32x4 (&acc)[2][2][4][2], const Unit& u, int wr, int wc, int fr, int fq, const Pre&) const {
;         const int row0 = ROW_X + u.pm * BM + wr * 64 + fr, col0 = u.pn * BM + wc * 32 + 8 * fq;
;         u32x4 hv[2][2]; float sprev = 0.f;
;     ...
;         ER_LOAD(0, 0);
; #pragma unroll
;         for (int g = 0; g < 8; ++g) { const int ai = g >> 2, m = g & 3; const int r = row0 + ai * HALF + m * 16; const size_t off = (size_t)r * DM + col0; float s = 0.f;
;             if (g + 1 < 8) ER_LOAD(g + 1, (g + 1) & 1);
; #pragma unroll
;             for (int bj = 0; bj < 2; ++bj) { const u32x4 w = hv[g & 1][bj];
;                 const f32x4 h0 = {bflo(w.x), bfhi(w.x), bflo(w.y), bfhi(w.y)}, h1 = {bflo(w.z), bfhi(w.z), bflo(w.w), bfhi(w.w)};
;                 const f32x4 o0 = h0 + acc[ai][bj][m][0] * alpha, o1 = h1 + acc[ai][bj][m][1] * alpha;
;                 if (FINAL) { float* op = OUT + (size_t)(r - ROW_X) * DM + col0 + bj * HALF; *(f32x4*)op = o0; *(f32x4*)(op + 4) = o1; }
;                 else { u32x4 q; q.x = cvtpk(o0[0], o0[1]); q.y = cvtpk(o0[2], o0[3]); q.z = cvtpk(o1[0], o1[1]); q.w = cvtpk(o1[2], o1[3]); *(u32x4*)(HB + off + bj * HALF) = q;
;                        s += ((o0[0] * o0[0] + o0[1] * o0[1]) + (o0[2] * o0[2] + o0[3] * o0[3])) + ((o1[0] * o1[0] + o1[1] * o1[1]) + (o1[2] * o1[2] + o1[3] * o1[3])); } }
;             if (!FINAL) { if (g > 0) { float t = sprev; t += __shfl_xor(t, 16); t += __shfl_xor(t, 32);
;                     if (fq == 0) __hip_atomic_fetch_add(ssq_out + row0 + ((g - 1) >> 2) * HALF + ((g - 1) & 3) * 16, t, __ATOMIC_RELAXED, __HIP_MEMORY_SCOPE_AGENT); }
	v_lshl_add_u32 v154, s18, 8, v159
	v_lshl_or_b32 v152, s20, 8, v160
	v_ashrrev_i32_e32 v155, 31, v154
	v_ashrrev_i32_e32 v153, 31, v152
	v_lshlrev_b64 v[128:129], 12, v[154:155]
	v_lshl_add_u64 v[128:129], s[0:1], 0, v[128:129]
	v_lshlrev_b64 v[130:131], 1, v[152:153]
	v_lshl_add_u64 v[184:185], v[128:129], 0, v[130:131]
	v_or_b32_e32 v128, 16, v154
	v_ashrrev_i32_e32 v129, 31, v128
	global_load_dwordx4 v[166:169], v[184:185], off
	global_load_dwordx4 v[170:173], v[184:185], off offset:256
	v_lshlrev_b64 v[128:129], 12, v[128:129]
	v_lshl_add_u64 v[128:129], s[0:1], 0, v[128:129]
	v_lshl_add_u64 v[186:187], v[128:129], 0, v[130:131]
	global_load_dwordx4 v[174:177], v[186:187], off
	global_load_dwordx4 v[180:183], v[186:187], off offset:256
	v_or_b32_e32 v128, 32, v154
	v_ashrrev_i32_e32 v129, 31, v128
	v_lshlrev_b64 v[128:129], 12, v[128:129]
	v_lshl_add_u64 v[128:129], s[0:1], 0, v[128:129]
	v_lshl_add_u64 v[156:157], v[128:129], 0, v[130:131]
	global_load_dwordx4 v[132:135], v[156:157], off
	global_load_dwordx4 v[128:131], v[156:157], off offset:256
	s_waitcnt vmcnt(0)
	v_lshlrev_b32_e32 v188, 16, v166
	v_and_b32_e32 v189, 0xffff0000, v166
	v_lshlrev_b32_e32 v166, 16, v167
	v_and_b32_e32 v167, 0xffff0000, v167
	v_lshlrev_b32_e32 v190, 16, v168
	v_and_b32_e32 v191, 0xffff0000, v168
	v_lshlrev_b32_e32 v168, 16, v169
	v_and_b32_e32 v169, 0xffff0000, v169
	v_lshlrev_b32_e32 v192, 16, v170
	v_and_b32_e32 v193, 0xffff0000, v170
	v_lshlrev_b32_e32 v170, 16, v171
	v_and_b32_e32 v171, 0xffff0000, v171
	v_lshlrev_b32_e32 v194, 16, v172
	v_and_b32_e32 v195, 0xffff0000, v172
	v_lshlrev_b32_e32 v172, 16, v173
	v_and_b32_e32 v173, 0xffff0000, v173
	v_pk_add_f32 v[126:127], v[126:127], v[166:167]
	v_pk_add_f32 v[124:125], v[124:125], v[188:189]
	v_pk_add_f32 v[122:123], v[122:123], v[168:169]
	v_pk_add_f32 v[166:167], v[120:121], v[190:191]
	v_pk_add_f32 v[168:169], v[118:119], v[170:171]
	v_pk_add_f32 v[170:171], v[116:117], v[192:193]
	v_pk_add_f32 v[172:173], v[114:115], v[172:173]
	v_pk_add_f32 v[188:189], v[112:113], v[194:195]
	v_cvt_pk_bf16_f32 v114, v124, v125
	v_cvt_pk_bf16_f32 v115, v126, v127
	v_cvt_pk_bf16_f32 v116, v166, v167
	v_cvt_pk_bf16_f32 v117, v122, v123
	v_mul_f32_e32 v125, v125, v125
	v_mul_f32_e32 v127, v127, v127
	v_mul_f32_e32 v165, v167, v167
	v_mul_f32_e32 v123, v123, v123
	v_cvt_pk_bf16_f32 v118, v170, v171
	v_cvt_pk_bf16_f32 v119, v168, v169
	v_cvt_pk_bf16_f32 v121, v172, v173
	v_mul_f32_e32 v167, v171, v171
	v_mul_f32_e32 v169, v169, v169
	v_mul_f32_e32 v171, v189, v189
	v_mul_f32_e32 v173, v173, v173
	v_lshlrev_b32_e32 v112, 16, v174
	v_and_b32_e32 v113, 0xffff0000, v174
	v_lshlrev_b32_e32 v190, 16, v176
	v_and_b32_e32 v191, 0xffff0000, v176
	v_lshlrev_b32_e32 v176, 16, v177
	v_and_b32_e32 v177, 0xffff0000, v177
	v_fmac_f32_e32 v125, v124, v124
	v_fmac_f32_e32 v127, v126, v126
	v_fmac_f32_e32 v165, v166, v166
	v_fmac_f32_e32 v123, v122, v122
	v_fmac_f32_e32 v167, v170, v170
	v_fmac_f32_e32 v169, v168, v168
	v_fmac_f32_e32 v171, v188, v188
	v_fmac_f32_e32 v173, v172, v172
	v_lshlrev_b32_e32 v174, 16, v175
	v_and_b32_e32 v175, 0xffff0000, v175
	v_pk_add_f32 v[112:113], v[108:109], v[112:113]
	v_pk_add_f32 v[108:109], v[106:107], v[176:177]
	global_store_dwordx4 v[184:185], v[114:117], off
	v_add_f32_e32 v106, v125, v127
	v_add_f32_e32 v107, v165, v123
	v_add_f32_e32 v114, v167, v169
	v_add_f32_e32 v115, v171, v173
	v_pk_add_f32 v[110:111], v[110:111], v[174:175]
	v_add_f32_e32 v106, v106, v107
	v_add_f32_e32 v107, v114, v115
	v_pk_add_f32 v[114:115], v[104:105], v[190:191]
	v_add_f32_e32 v125, v106, v107
	v_cvt_pk_bf16_f32 v104, v112, v113
	v_cvt_pk_bf16_f32 v105, v110, v111
	v_cvt_pk_bf16_f32 v106, v114, v115
	v_cvt_pk_bf16_f32 v107, v108, v109
	v_cvt_pk_bf16_f32 v120, v188, v189
	global_store_dwordx4 v[186:187], v[104:107], off
	global_store_dwordx4 v[184:185], v[118:121], off offset:256
	v_lshlrev_b32_e32 v122, 16, v182
	v_lshlrev_b32_e32 v104, 16, v180
	v_and_b32_e32 v105, 0xffff0000, v180
	v_pk_add_f32 v[118:119], v[100:101], v[104:105]
	v_and_b32_e32 v101, 64, v164
	v_xor_b32_e32 v100, 16, v164
	v_add_u32_e32 v101, 64, v101
	v_cmp_lt_i32_e32 vcc, v100, v101
	v_and_b32_e32 v123, 0xffff0000, v182
	v_pk_add_f32 v[122:123], v[96:97], v[122:123]
	v_cndmask_b32_e32 v100, v164, v100, vcc
	v_lshlrev_b32_e32 v124, 2, v100
	ds_bpermute_b32 v100, v124, v125
	v_xor_b32_e32 v97, 32, v164
	v_cmp_lt_i32_e32 vcc, v97, v101
	v_lshlrev_b32_e32 v106, 16, v181
	v_and_b32_e32 v107, 0xffff0000, v181
	v_cndmask_b32_e32 v97, v164, v97, vcc
	s_waitcnt lgkmcnt(0)
	v_add_f32_e32 v96, v125, v100
	v_lshlrev_b32_e32 v125, 2, v97
	ds_bpermute_b32 v97, v125, v96
	v_lshlrev_b32_e32 v120, 16, v183
	v_and_b32_e32 v121, 0xffff0000, v183
	v_pk_add_f32 v[116:117], v[102:103], v[106:107]
	v_pk_add_f32 v[120:121], v[98:99], v[120:121]
	v_cvt_pk_bf16_f32 v98, v118, v119
	v_cvt_pk_bf16_f32 v99, v116, v117
	v_cvt_pk_bf16_f32 v100, v122, v123
	v_cvt_pk_bf16_f32 v101, v120, v121
	v_lshl_add_u64 v[104:105], v[154:155], 2, s[6:7]
	global_store_dwordx4 v[186:187], v[98:101], off offset:256
	s_and_saveexec_b64 s[18:19], s[2:3]
	s_cbranch_execz .LBB0_2463
	s_waitcnt lgkmcnt(0)
	v_add_f32_e32 v96, v96, v97
	global_atomic_add_f32 v[104:105], v96, off

; #define PG8_STAGE(bufoff, gbase, voff) do { _Pragma("unroll") for (int _i = 0; _i < 2; ++_i) \
;         __builtin_amdgcn_global_load_lds((const unsigned*)((const char*)(gbase) + (voff)[_i]), (LAS unsigned*)(lds + (bufoff) + ldsw + _i * 8192), 16, 0, 0); } while (0)
; #define PG8_LDA(dst, b, h) do { _Pragma("unroll") for (int m = 0; m < 4; ++m) _Pragma("unroll") for (int k = 0; k < 2; ++k) dst[m][k] = *(const LAS bf16x8*)(lds + PG8_SA(b, h) + aoff + m * 2048 + k * 1024); } while (0)
; #define PG8_LDB(dst, b, h) do { _Pragma("unroll") for (int n = 0; n < 2; ++n) _Pragma("unroll") for (int k = 0; k < 2; ++k) dst[n][k] = *(const LAS bf16x8*)(lds + PG8_SB(b, h) + boff + n * 2048 + k * 1024); } while (0)
; #define PG8_MMA(ai, bj, At, Bt) do { __builtin_amdgcn_s_setprio(1); _Pragma("unroll") for (int m = 0; m < 4; ++m) _Pragma("unroll") for (int n = 0; n < 2; ++n) _Pragma("unroll") for (int k = 0; k < 2; ++k) \
;         acc[ai][bj][m][n] = __builtin_amdgcn_mfma_f32_16x16x32_bf16(Bt[n][k], At[m][k], acc[ai][bj][m][n], 0, 0, 0); __builtin_amdgcn_s_setprio(0); } while (0)
; #define PG8_WAIT_L(n) asm volatile("s_waitcnt lgkmcnt(" #n ")" ::: "memory")
; #define PG8_BAR __builtin_amdgcn_s_barrier()
; #define PG8_SCHED __builtin_amdgcn_sched_barrier(0)
; template <class Epi>
; __device__ __forceinline__ void gemm_phase(LAS unsigned char* lds, const Gemm g, const StaticOrder& S, const Epi& E) {
;     ...
;         for (int t = 0; t < nt; t += 2) {
;             const bool last = (t == nt - 2);
;             const char* a1 = cA + (size_t)(t + 1) * kstep;
;             const char* a2 = last ? nA : cA + (size_t)(t + 2) * kstep; const char* b2 = last ? nB : cB + (size_t)(t + 2) * kstep;
;             const char* a3 = a2 + kstep; const char* b3 = b2 + kstep;
;             PG8_LDB(B0, 0, 0); PG8_SCHED; PG8_LDA(At, 0, 0); PG8_STAGE(PG8_SA(1, 1), a1 + hstep, voffA);
;             PG8_WAIT_L(8); PG8_BAR; PG8_WAIT_L(0); PG8_MMA(0, 0, At, B0); PG8_BAR; PG8_SCHED;
.LBB0_2546:
	ds_read_b128 v[160:163], v148
	ds_read_b128 v[164:167], v148 offset:1024
	ds_read_b128 v[168:171], v148 offset:2048
	ds_read_b128 v[172:175], v148 offset:3072
	s_add_u32 s18, s16, 0xfff80080
	s_addc_u32 s19, s17, -1
	s_cmp_eq_u32 s59, 28
	s_cselect_b32 s21, s9, s19
	s_cselect_b32 s20, s47, s18
	s_cselect_b32 s19, s7, s58
	s_cselect_b32 s18, s56, s57
	v_lshl_add_u64 v[176:177], s[16:17], 0, v[136:137]
	s_add_i32 m0, s35, 0xc000
	ds_read_b128 v[180:183], v149
	ds_read_b128 v[184:187], v149 offset:1024
	ds_read_b128 v[188:191], v149 offset:2048
	ds_read_b128 v[192:195], v149 offset:3072
	ds_read_b128 v[196:199], v149 offset:4096
	ds_read_b128 v[200:203], v149 offset:5120
	ds_read_b128 v[204:207], v149 offset:6144
	ds_read_b128 v[208:211], v149 offset:7168
	global_load_lds_dwordx4 v[176:177], off
	v_lshl_add_u64 v[176:177], s[16:17], 0, v[138:139]
	s_add_i32 m0, s35, 0xe000
	s_nop 0
	global_load_lds_dwordx4 v[176:177], off
	s_waitcnt lgkmcnt(8)
	s_barrier
	s_waitcnt lgkmcnt(0)
	s_setprio 1

; #define PG8_STAGE(bufoff, gbase, voff) do { _Pragma("unroll") for (int _i = 0; _i < 2; ++_i) \
;         __builtin_amdgcn_global_load_lds((const unsigned*)((const char*)(gbase) + (voff)[_i]), (LAS unsigned*)(lds + (bufoff) + ldsw + _i * 8192), 16, 0, 0); } while (0)
; #define PG8_LDB(dst, b, h) do { _Pragma("unroll") for (int n = 0; n < 2; ++n) _Pragma("unroll") for (int k = 0; k < 2; ++k) dst[n][k] = *(const LAS bf16x8*)(lds + PG8_SB(b, h) + boff + n * 2048 + k * 1024); } while (0)
; #define PG8_MMA(ai, bj, At, Bt) do { __builtin_amdgcn_s_setprio(1); _Pragma("unroll") for (int m = 0; m < 4; ++m) _Pragma("unroll") for (int n = 0; n < 2; ++n) _Pragma("unroll") for (int k = 0; k < 2; ++k) \
;         acc[ai][bj][m][n] = __builtin_amdgcn_mfma_f32_16x16x32_bf16(Bt[n][k], At[m][k], acc[ai][bj][m][n], 0, 0, 0); __builtin_amdgcn_s_setprio(0); } while (0)
; #define PG8_WAIT_L(n) asm volatile("s_waitcnt lgkmcnt(" #n ")" ::: "memory")
; #define PG8_BAR __builtin_amdgcn_s_barrier()
; #define PG8_SCHED __builtin_amdgcn_sched_barrier(0)
; template <class Epi>
; __device__ __forceinline__ void gemm_phase(LAS unsigned char* lds, const Gemm g, const StaticOrder& S, const Epi& E) {
;     ...
;             PG8_WAIT_L(8); PG8_BAR; PG8_WAIT_L(0); PG8_MMA(0, 0, At, B0); PG8_BAR; PG8_SCHED;
;             PG8_LDB(B1, 0, 1); PG8_STAGE(PG8_SB(0, 0), b2, voffB);
;             PG8_BAR; PG8_WAIT_L(0); PG8_MMA(0, 1, At, B1); PG8_BAR;
	v_mfma_f32_16x16x32_bf16 v[124:127], v[160:163], v[180:183], v[124:127]
	v_mfma_f32_16x16x32_bf16 v[116:119], v[168:171], v[180:183], v[116:119]
	v_mfma_f32_16x16x32_bf16 v[108:111], v[160:163], v[188:191], v[108:111]
	v_mfma_f32_16x16x32_bf16 v[100:103], v[168:171], v[188:191], v[100:103]
	v_mfma_f32_16x16x32_bf16 v[92:95], v[160:163], v[196:199], v[92:95]
	v_mfma_f32_16x16x32_bf16 v[84:87], v[168:171], v[196:199], v[84:87]
	v_mfma_f32_16x16x32_bf16 v[76:79], v[160:163], v[204:207], v[76:79]
	v_mfma_f32_16x16x32_bf16 v[68:71], v[168:171], v[204:207], v[68:71]
	v_mfma_f32_16x16x32_bf16 v[124:127], v[164:167], v[184:187], v[124:127]
	v_mfma_f32_16x16x32_bf16 v[116:119], v[172:175], v[184:187], v[116:119]
	v_mfma_f32_16x16x32_bf16 v[108:111], v[164:167], v[192:195], v[108:111]
	v_mfma_f32_16x16x32_bf16 v[100:103], v[172:175], v[192:195], v[100:103]
	v_mfma_f32_16x16x32_bf16 v[92:95], v[164:167], v[200:203], v[92:95]
	v_mfma_f32_16x16x32_bf16 v[84:87], v[172:175], v[200:203], v[84:87]
	v_mfma_f32_16x16x32_bf16 v[76:79], v[164:167], v[208:211], v[76:79]
	v_mfma_f32_16x16x32_bf16 v[68:71], v[172:175], v[208:211], v[68:71]
	s_setprio 0
	s_barrier
	s_add_i32 s60, s44, s31
	v_lshl_add_u64 v[176:177], s[18:19], 0, v[132:133]
	s_mov_b32 m0, s60
	ds_read_b128 v[212:215], v150
	ds_read_b128 v[216:219], v150 offset:1024
	ds_read_b128 v[220:223], v150 offset:2048
	ds_read_b128 v[224:227], v150 offset:3072
	global_load_lds_dwordx4 v[176:177], off
	v_lshl_add_u64 v[228:229], s[18:19], 0, v[128:129]
	s_add_i32 m0, s60, 0x2000
	s_nop 0
	global_load_lds_dwordx4 v[228:229], off
	s_barrier
	s_waitcnt lgkmcnt(0)
	s_setprio 1

; #define PG8_STAGE(bufoff, gbase, voff) do { _Pragma("unroll") for (int _i = 0; _i < 2; ++_i) \
;         __builtin_amdgcn_global_load_lds((const unsigned*)((const char*)(gbase) + (voff)[_i]), (LAS unsigned*)(lds + (bufoff) + ldsw + _i * 8192), 16, 0, 0); } while (0)
; #define PG8_LDA(dst, b, h) do { _Pragma("unroll") for (int m = 0; m < 4; ++m) _Pragma("unroll") for (int k = 0; k < 2; ++k) dst[m][k] = *(const LAS bf16x8*)(lds + PG8_SA(b, h) + aoff + m * 2048 + k * 1024); } while (0)
; #define PG8_MMA(ai, bj, At, Bt) do { __builtin_amdgcn_s_setprio(1); _Pragma("unroll") for (int m = 0; m < 4; ++m) _Pragma("unroll") for (int n = 0; n < 2; ++n) _Pragma("unroll") for (int k = 0; k < 2; ++k) \
;         acc[ai][bj][m][n] = __builtin_amdgcn_mfma_f32_16x16x32_bf16(Bt[n][k], At[m][k], acc[ai][bj][m][n], 0, 0, 0); __builtin_amdgcn_s_setprio(0); } while (0)
; #define PG8_WAIT_L(n) asm volatile("s_waitcnt lgkmcnt(" #n ")" ::: "memory")
; #define PG8_BAR __builtin_amdgcn_s_barrier()
; #define PG8_SCHED __builtin_amdgcn_sched_barrier(0)
; template <class Epi>
; __device__ __forceinline__ void gemm_phase(LAS unsigned char* lds, const Gemm g, const StaticOrder& S, const Epi& E) {
;     ...
;             PG8_BAR; PG8_WAIT_L(0); PG8_MMA(0, 1, At, B1); PG8_BAR;
;             PG8_LDA(At, 0, 1); PG8_STAGE(PG8_SA(0, 0), a2, voffA);
;             PG8_BAR; PG8_WAIT_L(0); PG8_MMA(1, 0, At, B0); PG8_BAR; PG8_SCHED;
	v_mfma_f32_16x16x32_bf16 v[120:123], v[212:215], v[180:183], v[120:123]
	v_mfma_f32_16x16x32_bf16 v[112:115], v[220:223], v[180:183], v[112:115]
	v_mfma_f32_16x16x32_bf16 v[104:107], v[212:215], v[188:191], v[104:107]
	v_mfma_f32_16x16x32_bf16 v[96:99], v[220:223], v[188:191], v[96:99]
	v_mfma_f32_16x16x32_bf16 v[88:91], v[212:215], v[196:199], v[88:91]
	v_mfma_f32_16x16x32_bf16 v[80:83], v[220:223], v[196:199], v[80:83]
	v_mfma_f32_16x16x32_bf16 v[72:75], v[212:215], v[204:207], v[72:75]
	v_mfma_f32_16x16x32_bf16 v[64:67], v[220:223], v[204:207], v[64:67]
	v_mfma_f32_16x16x32_bf16 v[120:123], v[216:219], v[184:187], v[120:123]
	v_mfma_f32_16x16x32_bf16 v[112:115], v[224:227], v[184:187], v[112:115]
	v_mfma_f32_16x16x32_bf16 v[104:107], v[216:219], v[192:195], v[104:107]
	v_mfma_f32_16x16x32_bf16 v[96:99], v[224:227], v[192:195], v[96:99]
	v_mfma_f32_16x16x32_bf16 v[88:91], v[216:219], v[200:203], v[88:91]
	v_mfma_f32_16x16x32_bf16 v[80:83], v[224:227], v[200:203], v[80:83]
	v_mfma_f32_16x16x32_bf16 v[72:75], v[216:219], v[208:211], v[72:75]
	v_mfma_f32_16x16x32_bf16 v[64:67], v[224:227], v[208:211], v[64:67]
	s_setprio 0
	s_mov_b32 m0, s35
	v_lshl_add_u64 v[230:231], s[20:21], 0, v[134:135]
	s_barrier
	ds_read_b128 v[180:183], v149 offset:16384
	ds_read_b128 v[184:187], v149 offset:17408
	ds_read_b128 v[188:191], v149 offset:18432
	ds_read_b128 v[192:195], v149 offset:19456
	ds_read_b128 v[196:199], v149 offset:20480
	ds_read_b128 v[200:203], v149 offset:21504
	ds_read_b128 v[204:207], v149 offset:22528
	ds_read_b128 v[208:211], v149 offset:23552
	global_load_lds_dwordx4 v[230:231], off
	v_lshl_add_u64 v[232:233], s[20:21], 0, v[130:131]
	s_mov_b32 m0, s36
	s_nop 0
	global_load_lds_dwordx4 v[232:233], off
	s_barrier
	s_waitcnt lgkmcnt(0)
	s_setprio 1

; #define PG8_STAGE(bufoff, gbase, voff) do { _Pragma("unroll") for (int _i = 0; _i < 2; ++_i) \
;         __builtin_amdgcn_global_load_lds((const unsigned*)((const char*)(gbase) + (voff)[_i]), (LAS unsigned*)(lds + (bufoff) + ldsw + _i * 8192), 16, 0, 0); } while (0)
; #define PG8_LDA(dst, b, h) do { _Pragma("unroll") for (int m = 0; m < 4; ++m) _Pragma("unroll") for (int k = 0; k < 2; ++k) dst[m][k] = *(const LAS bf16x8*)(lds + PG8_SA(b, h) + aoff + m * 2048 + k * 1024); } while (0)
; #define PG8_LDB(dst, b, h) do { _Pragma("unroll") for (int n = 0; n < 2; ++n) _Pragma("unroll") for (int k = 0; k < 2; ++k) dst[n][k] = *(const LAS bf16x8*)(lds + PG8_SB(b, h) + boff + n * 2048 + k * 1024); } while (0)
; #define PG8_MMA(ai, bj, At, Bt) do { __builtin_amdgcn_s_setprio(1); _Pragma("unroll") for (int m = 0; m < 4; ++m) _Pragma("unroll") for (int n = 0; n < 2; ++n) _Pragma("unroll") for (int k = 0; k < 2; ++k) \
;         acc[ai][bj][m][n] = __builtin_amdgcn_mfma_f32_16x16x32_bf16(Bt[n][k], At[m][k], acc[ai][bj][m][n], 0, 0, 0); __builtin_amdgcn_s_setprio(0); } while (0)
; #define PG8_WAIT_V(n) asm volatile("s_waitcnt vmcnt(" #n ")" ::: "memory")
; #define PG8_WAIT_L(n) asm volatile("s_waitcnt lgkmcnt(" #n ")" ::: "memory")
; #define PG8_BAR __builtin_amdgcn_s_barrier()
; #define PG8_SCHED __builtin_amdgcn_sched_barrier(0)
; template <class Epi>
; __device__ __forceinline__ void gemm_phase(LAS unsigned char* lds, const Gemm g, const StaticOrder& S, const Epi& E) {
;     ...
;             PG8_BAR; PG8_WAIT_L(0); PG8_MMA(1, 0, At, B0); PG8_BAR; PG8_SCHED;
;             PG8_STAGE(PG8_SB(0, 1), b2 + hstep, voffB);
;             PG8_WAIT_V(6); PG8_BAR; PG8_MMA(1, 1, At, B1); PG8_BAR;
;             PG8_LDB(B0, 1, 0); PG8_SCHED; PG8_LDA(At, 1, 0); PG8_STAGE(PG8_SA(0, 1), a2 + hstep, voffA);
;             PG8_WAIT_L(8); PG8_BAR; PG8_WAIT_L(0); PG8_MMA(0, 0, At, B0); PG8_BAR; PG8_SCHED;
	v_mfma_f32_16x16x32_bf16 v[60:63], v[160:163], v[180:183], v[60:63]
	v_mfma_f32_16x16x32_bf16 v[52:55], v[168:171], v[180:183], v[52:55]
	v_mfma_f32_16x16x32_bf16 v[44:47], v[160:163], v[188:191], v[44:47]
	v_mfma_f32_16x16x32_bf16 v[36:39], v[168:171], v[188:191], v[36:39]
	v_mfma_f32_16x16x32_bf16 v[28:31], v[160:163], v[196:199], v[28:31]
	v_mfma_f32_16x16x32_bf16 v[20:23], v[168:171], v[196:199], v[20:23]
	v_mfma_f32_16x16x32_bf16 v[12:15], v[160:163], v[204:207], v[12:15]
	v_mfma_f32_16x16x32_bf16 v[4:7], v[168:171], v[204:207], v[4:7]
	v_mfma_f32_16x16x32_bf16 v[60:63], v[164:167], v[184:187], v[60:63]
	v_mfma_f32_16x16x32_bf16 v[52:55], v[172:175], v[184:187], v[52:55]
	v_mfma_f32_16x16x32_bf16 v[44:47], v[164:167], v[192:195], v[44:47]
	v_mfma_f32_16x16x32_bf16 v[36:39], v[172:175], v[192:195], v[36:39]
	v_mfma_f32_16x16x32_bf16 v[28:31], v[164:167], v[200:203], v[28:31]
	v_mfma_f32_16x16x32_bf16 v[20:23], v[172:175], v[200:203], v[20:23]
	v_mfma_f32_16x16x32_bf16 v[12:15], v[164:167], v[208:211], v[12:15]
	v_mfma_f32_16x16x32_bf16 v[4:7], v[172:175], v[208:211], v[4:7]
	s_setprio 0
	s_barrier
	s_add_u32 s60, s18, 0x80000
	s_addc_u32 s61, s19, 0
	s_add_i32 s62, s45, s31
	v_lshl_add_u64 v[160:161], s[60:61], 0, v[132:133]
	s_mov_b32 m0, s62
	s_nop 0
	global_load_lds_dwordx4 v[160:161], off
	v_lshl_add_u64 v[160:161], s[60:61], 0, v[128:129]
	s_add_i32 m0, s62, 0x2000
	s_nop 0
	global_load_lds_dwordx4 v[160:161], off
	s_waitcnt vmcnt(6)
	s_barrier
	s_setprio 1
	v_mfma_f32_16x16x32_bf16 v[56:59], v[212:215], v[180:183], v[56:59]
	v_mfma_f32_16x16x32_bf16 v[48:51], v[220:223], v[180:183], v[48:51]
	v_mfma_f32_16x16x32_bf16 v[40:43], v[212:215], v[188:191], v[40:43]
	v_mfma_f32_16x16x32_bf16 v[32:35], v[220:223], v[188:191], v[32:35]
	v_mfma_f32_16x16x32_bf16 v[24:27], v[212:215], v[196:199], v[24:27]
	v_mfma_f32_16x16x32_bf16 v[16:19], v[220:223], v[196:199], v[16:19]
	v_mfma_f32_16x16x32_bf16 v[8:11], v[212:215], v[204:207], v[8:11]
	v_mfma_f32_16x16x32_bf16 v[0:3], v[220:223], v[204:207], v[0:3]
	v_mfma_f32_16x16x32_bf16 v[56:59], v[216:219], v[184:187], v[56:59]
	v_mfma_f32_16x16x32_bf16 v[48:51], v[224:227], v[184:187], v[48:51]
	v_mfma_f32_16x16x32_bf16 v[40:43], v[216:219], v[192:195], v[40:43]
	v_mfma_f32_16x16x32_bf16 v[32:35], v[224:227], v[192:195], v[32:35]
	v_mfma_f32_16x16x32_bf16 v[24:27], v[216:219], v[200:203], v[24:27]
	v_mfma_f32_16x16x32_bf16 v[16:19], v[224:227], v[200:203], v[16:19]
	v_mfma_f32_16x16x32_bf16 v[8:11], v[216:219], v[208:211], v[8:11]
	v_mfma_f32_16x16x32_bf16 v[0:3], v[224:227], v[208:211], v[0:3]
	s_setprio 0
	s_add_i32 s60, 0, 0x18000
	v_add_u32_e32 v159, s60, v145
	s_barrier
	ds_read_b128 v[160:163], v159
	ds_read_b128 v[164:167], v159 offset:1024
	ds_read_b128 v[168:171], v159 offset:2048
	ds_read_b128 v[172:175], v159 offset:3072
	s_add_u32 s20, s20, 0x80000
	s_addc_u32 s21, s21, 0
	s_mov_b32 m0, s37
	v_lshl_add_u64 v[212:213], s[20:21], 0, v[134:135]
	ds_read_b128 v[180:183], v149 offset:32768
	ds_read_b128 v[184:187], v149 offset:33792
	ds_read_b128 v[188:191], v149 offset:34816
	ds_read_b128 v[192:195], v149 offset:35840
	ds_read_b128 v[196:199], v149 offset:36864
	ds_read_b128 v[200:203], v149 offset:37888
	ds_read_b128 v[204:207], v149 offset:38912
	ds_read_b128 v[208:211], v149 offset:39936
	global_load_lds_dwordx4 v[212:213], off
	v_lshl_add_u64 v[212:213], s[20:21], 0, v[130:131]
	s_mov_b32 m0, s38
	s_nop 0
	global_load_lds_dwordx4 v[212:213], off
	s_waitcnt lgkmcnt(8)
	s_barrier
	s_waitcnt lgkmcnt(0)
	s_setprio 1

; #define PG8_STAGE(bufoff, gbase, voff) do { _Pragma("unroll") for (int _i = 0; _i < 2; ++_i) \
;         __builtin_amdgcn_global_load_lds((const unsigned*)((const char*)(gbase) + (voff)[_i]), (LAS unsigned*)(lds + (bufoff) + ldsw + _i * 8192), 16, 0, 0); } while (0)
; #define PG8_LDB(dst, b, h) do { _Pragma("unroll") for (int n = 0; n < 2; ++n) _Pragma("unroll") for (int k = 0; k < 2; ++k) dst[n][k] = *(const LAS bf16x8*)(lds + PG8_SB(b, h) + boff + n * 2048 + k * 1024); } while (0)
; #define PG8_MMA(ai, bj, At, Bt) do { __builtin_amdgcn_s_setprio(1); _Pragma("unroll") for (int m = 0; m < 4; ++m) _Pragma("unroll") for (int n = 0; n < 2; ++n) _Pragma("unroll") for (int k = 0; k < 2; ++k) \
;         acc[ai][bj][m][n] = __builtin_amdgcn_mfma_f32_16x16x32_bf16(Bt[n][k], At[m][k], acc[ai][bj][m][n], 0, 0, 0); __builtin_amdgcn_s_setprio(0); } while (0)
; #define PG8_WAIT_L(n) asm volatile("s_waitcnt lgkmcnt(" #n ")" ::: "memory")
; #define PG8_BAR __builtin_amdgcn_s_barrier()
; #define PG8_SCHED __builtin_amdgcn_sched_barrier(0)
; template <class Epi>
; __device__ __forceinline__ void gemm_phase(LAS unsigned char* lds, const Gemm g, const StaticOrder& S, const Epi& E) {
;     ...
;             PG8_WAIT_L(8); PG8_BAR; PG8_WAIT_L(0); PG8_MMA(0, 0, At, B0); PG8_BAR; PG8_SCHED;
;             PG8_LDB(B1, 1, 1); PG8_STAGE(PG8_SB(1, 0), b3, voffB);
;             PG8_BAR; PG8_WAIT_L(0); PG8_MMA(0, 1, At, B1); PG8_BAR;
	v_mfma_f32_16x16x32_bf16 v[124:127], v[160:163], v[180:183], v[124:127]
	v_mfma_f32_16x16x32_bf16 v[116:119], v[168:171], v[180:183], v[116:119]
	v_mfma_f32_16x16x32_bf16 v[108:111], v[160:163], v[188:191], v[108:111]
	v_mfma_f32_16x16x32_bf16 v[100:103], v[168:171], v[188:191], v[100:103]
	v_mfma_f32_16x16x32_bf16 v[92:95], v[160:163], v[196:199], v[92:95]
	v_mfma_f32_16x16x32_bf16 v[84:87], v[168:171], v[196:199], v[84:87]
	v_mfma_f32_16x16x32_bf16 v[76:79], v[160:163], v[204:207], v[76:79]
	v_mfma_f32_16x16x32_bf16 v[68:71], v[168:171], v[204:207], v[68:71]
	v_mfma_f32_16x16x32_bf16 v[124:127], v[164:167], v[184:187], v[124:127]
	v_mfma_f32_16x16x32_bf16 v[116:119], v[172:175], v[184:187], v[116:119]
	v_mfma_f32_16x16x32_bf16 v[108:111], v[164:167], v[192:195], v[108:111]
	v_mfma_f32_16x16x32_bf16 v[100:103], v[172:175], v[192:195], v[100:103]
	v_mfma_f32_16x16x32_bf16 v[92:95], v[164:167], v[200:203], v[92:95]
	v_mfma_f32_16x16x32_bf16 v[84:87], v[172:175], v[200:203], v[84:87]
	v_mfma_f32_16x16x32_bf16 v[76:79], v[164:167], v[208:211], v[76:79]
	v_mfma_f32_16x16x32_bf16 v[68:71], v[172:175], v[208:211], v[68:71]
	s_setprio 0
	s_barrier
	s_add_i32 s20, 0, 0x1c000
	s_add_i32 s21, s60, s31
	v_add_u32_e32 v159, s20, v145
	v_lshl_add_u64 v[176:177], v[176:177], 0, s[4:5]
	s_mov_b32 m0, s21
	ds_read_b128 v[212:215], v159
	ds_read_b128 v[216:219], v159 offset:1024
	ds_read_b128 v[220:223], v159 offset:2048
	ds_read_b128 v[224:227], v159 offset:3072
	global_load_lds_dwordx4 v[176:177], off
	v_lshl_add_u64 v[176:177], v[228:229], 0, s[4:5]
	s_add_i32 m0, s21, 0x2000
	s_nop 0
	global_load_lds_dwordx4 v[176:177], off
	s_barrier
	s_waitcnt lgkmcnt(0)
	s_setprio 1

; #define PG8_STAGE(bufoff, gbase, voff) do { _Pragma("unroll") for (int _i = 0; _i < 2; ++_i) \
;         __builtin_amdgcn_global_load_lds((const unsigned*)((const char*)(gbase) + (voff)[_i]), (LAS unsigned*)(lds + (bufoff) + ldsw + _i * 8192), 16, 0, 0); } while (0)
; #define PG8_LDA(dst, b, h) do { _Pragma("unroll") for (int m = 0; m < 4; ++m) _Pragma("unroll") for (int k = 0; k < 2; ++k) dst[m][k] = *(const LAS bf16x8*)(lds + PG8_SA(b, h) + aoff + m * 2048 + k * 1024); } while (0)
; #define PG8_MMA(ai, bj, At, Bt) do { __builtin_amdgcn_s_setprio(1); _Pragma("unroll") for (int m = 0; m < 4; ++m) _Pragma("unroll") for (int n = 0; n < 2; ++n) _Pragma("unroll") for (int k = 0; k < 2; ++k) \
;         acc[ai][bj][m][n] = __builtin_amdgcn_mfma_f32_16x16x32_bf16(Bt[n][k], At[m][k], acc[ai][bj][m][n], 0, 0, 0); __builtin_amdgcn_s_setprio(0); } while (0)
; #define PG8_WAIT_L(n) asm volatile("s_waitcnt lgkmcnt(" #n ")" ::: "memory")
; #define PG8_BAR __builtin_amdgcn_s_barrier()
; #define PG8_SCHED __builtin_amdgcn_sched_barrier(0)
; template <class Epi>
; __device__ __forceinline__ void gemm_phase(LAS unsigned char* lds, const Gemm g, const StaticOrder& S, const Epi& E) {
;     ...
;             PG8_BAR; PG8_WAIT_L(0); PG8_MMA(0, 1, At, B1); PG8_BAR;
;             PG8_LDA(At, 1, 1); PG8_STAGE(PG8_SA(1, 0), a3, voffA);
;             PG8_BAR; PG8_WAIT_L(0); PG8_MMA(1, 0, At, B0); PG8_BAR; PG8_SCHED;
	v_mfma_f32_16x16x32_bf16 v[120:123], v[212:215], v[180:183], v[120:123]
	v_mfma_f32_16x16x32_bf16 v[112:115], v[220:223], v[180:183], v[112:115]
	v_mfma_f32_16x16x32_bf16 v[104:107], v[212:215], v[188:191], v[104:107]
	v_mfma_f32_16x16x32_bf16 v[96:99], v[220:223], v[188:191], v[96:99]
	v_mfma_f32_16x16x32_bf16 v[88:91], v[212:215], v[196:199], v[88:91]
	v_mfma_f32_16x16x32_bf16 v[80:83], v[220:223], v[196:199], v[80:83]
	v_mfma_f32_16x16x32_bf16 v[72:75], v[212:215], v[204:207], v[72:75]
	v_mfma_f32_16x16x32_bf16 v[64:67], v[220:223], v[204:207], v[64:67]
	v_mfma_f32_16x16x32_bf16 v[120:123], v[216:219], v[184:187], v[120:123]
	v_mfma_f32_16x16x32_bf16 v[112:115], v[224:227], v[184:187], v[112:115]
	v_mfma_f32_16x16x32_bf16 v[104:107], v[216:219], v[192:195], v[104:107]
	v_mfma_f32_16x16x32_bf16 v[96:99], v[224:227], v[192:195], v[96:99]
	v_mfma_f32_16x16x32_bf16 v[88:91], v[216:219], v[200:203], v[88:91]
	v_mfma_f32_16x16x32_bf16 v[80:83], v[224:227], v[200:203], v[80:83]
	v_mfma_f32_16x16x32_bf16 v[72:75], v[216:219], v[208:211], v[72:75]
	v_mfma_f32_16x16x32_bf16 v[64:67], v[224:227], v[208:211], v[64:67]
	s_setprio 0
	s_mov_b32 m0, s40
	v_lshl_add_u64 v[176:177], v[230:231], 0, s[4:5]
	s_barrier
	ds_read_b128 v[180:183], v149 offset:49152
	ds_read_b128 v[184:187], v149 offset:50176
	ds_read_b128 v[188:191], v149 offset:51200
	ds_read_b128 v[192:195], v149 offset:52224
	ds_read_b128 v[196:199], v149 offset:53248
	ds_read_b128 v[200:203], v149 offset:54272
	ds_read_b128 v[204:207], v149 offset:55296
	ds_read_b128 v[208:211], v149 offset:56320
	global_load_lds_dwordx4 v[176:177], off
	v_lshl_add_u64 v[176:177], v[232:233], 0, s[4:5]
	s_mov_b32 m0, s41
	s_nop 0
	global_load_lds_dwordx4 v[176:177], off
	s_barrier
	s_waitcnt lgkmcnt(0)
	s_setprio 1

; __device__ __forceinline__ float sigmoidf_(float x) { return __builtin_amdgcn_rcpf(1.0f + fexp(-x)); }
; #define PG8_STAGE(bufoff, gbase, voff) do { _Pragma("unroll") for (int _i = 0; _i < 2; ++_i) \
;         __builtin_amdgcn_global_load_lds((const unsigned*)((const char*)(gbase) + (voff)[_i]), (LAS unsigned*)(lds + (bufoff) + ldsw + _i * 8192), 16, 0, 0); } while (0)
; #define PG8_MMA(ai, bj, At, Bt) do { __builtin_amdgcn_s_setprio(1); _Pragma("unroll") for (int m = 0; m < 4; ++m) _Pragma("unroll") for (int n = 0; n < 2; ++n) _Pragma("unroll") for (int k = 0; k < 2; ++k) \
;         acc[ai][bj][m][n] = __builtin_amdgcn_mfma_f32_16x16x32_bf16(Bt[n][k], At[m][k], acc[ai][bj][m][n], 0, 0, 0); __builtin_amdgcn_s_setprio(0); } while (0)
; #define PG8_WAIT_V(n) asm volatile("s_waitcnt vmcnt(" #n ")" ::: "memory")
; #define PG8_WAIT_L(n) asm volatile("s_waitcnt lgkmcnt(" #n ")" ::: "memory")
; #define PG8_BAR __builtin_amdgcn_s_barrier()
; #define PG8_SCHED __builtin_amdgcn_sched_barrier(0)
; template <class Epi>
; __device__ __forceinline__ void gemm_phase(LAS unsigned char* lds, const Gemm g, const StaticOrder& S, const Epi& E) {
;     ...
;             PG8_BAR; PG8_WAIT_L(0); PG8_MMA(1, 0, At, B0); PG8_BAR; PG8_SCHED;
;             PG8_STAGE(PG8_SB(1, 1), b3 + hstep, voffB);
;             PG8_WAIT_V(6); PG8_BAR; PG8_MMA(1, 1, At, B1); PG8_BAR;
;         }
;     __device__ __forceinline__ void operator()(const f32x4 (&acc)[2][2][4][2], const Unit& u, int wr, int wc, int fr, int fq, const Pre& P) const {
;     ...
; #pragma unroll
;         for (int ai = 0; ai < 2; ++ai)
; #pragma unroll
;             for (int m = 0; m < 4; ++m) { const int r = row0 + ai * HALF + m * 16; const float rs = __builtin_amdgcn_rsqf(P.rs[ai * 4 + m] * (1.0f / DM) + RMS_EPS);
;                 float y[8];
; #pragma unroll
;                 for (int n = 0; n < 2; ++n)
; #pragma unroll
;                     for (int j = 0; j < 4; ++j) { const float a = acc[ai][0][m][n][j] * rs, b = acc[ai][1][m][n][j] * rs; y[n * 4 + j] = a * b * sigmoidf_(a); }
;                 u32x4 w; w.x = cvtpk(y[0], y[1]); w.y = cvtpk(y[2], y[3]); w.z = cvtpk(y[4], y[5]); w.w = cvtpk(y[6], y[7]);
;                 *(u32x4*)(O + (size_t)r * FF + col0) = w; }
	v_mfma_f32_16x16x32_bf16 v[60:63], v[160:163], v[180:183], v[60:63]
	v_mfma_f32_16x16x32_bf16 v[52:55], v[168:171], v[180:183], v[52:55]
	v_mfma_f32_16x16x32_bf16 v[44:47], v[160:163], v[188:191], v[44:47]
	v_mfma_f32_16x16x32_bf16 v[36:39], v[168:171], v[188:191], v[36:39]
	v_mfma_f32_16x16x32_bf16 v[28:31], v[160:163], v[196:199], v[28:31]
	v_mfma_f32_16x16x32_bf16 v[20:23], v[168:171], v[196:199], v[20:23]
	v_mfma_f32_16x16x32_bf16 v[12:15], v[160:163], v[204:207], v[12:15]
	v_mfma_f32_16x16x32_bf16 v[4:7], v[168:171], v[204:207], v[4:7]
	v_mfma_f32_16x16x32_bf16 v[60:63], v[164:167], v[184:187], v[60:63]
	v_mfma_f32_16x16x32_bf16 v[52:55], v[172:175], v[184:187], v[52:55]
	v_mfma_f32_16x16x32_bf16 v[44:47], v[164:167], v[192:195], v[44:47]
	v_mfma_f32_16x16x32_bf16 v[36:39], v[172:175], v[192:195], v[36:39]
	v_mfma_f32_16x16x32_bf16 v[28:31], v[164:167], v[200:203], v[28:31]
	v_mfma_f32_16x16x32_bf16 v[20:23], v[172:175], v[200:203], v[20:23]
	v_mfma_f32_16x16x32_bf16 v[12:15], v[164:167], v[208:211], v[12:15]
	v_mfma_f32_16x16x32_bf16 v[4:7], v[172:175], v[208:211], v[4:7]
	s_setprio 0
	s_barrier
	s_add_u32 s18, s18, 0x80080
	s_addc_u32 s19, s19, 0
	s_add_i32 s20, s20, s31
	v_lshl_add_u64 v[160:161], s[18:19], 0, v[132:133]
	s_mov_b32 m0, s20
	s_nop 0
	global_load_lds_dwordx4 v[160:161], off
	v_lshl_add_u64 v[160:161], s[18:19], 0, v[128:129]
	s_add_i32 m0, s20, 0x2000
	s_nop 0
	global_load_lds_dwordx4 v[160:161], off
	s_waitcnt vmcnt(6)
	s_barrier
	s_setprio 1
	v_mfma_f32_16x16x32_bf16 v[56:59], v[212:215], v[180:183], v[56:59]
	v_mfma_f32_16x16x32_bf16 v[48:51], v[220:223], v[180:183], v[48:51]
	v_mfma_f32_16x16x32_bf16 v[40:43], v[212:215], v[188:191], v[40:43]
	v_mfma_f32_16x16x32_bf16 v[32:35], v[220:223], v[188:191], v[32:35]
	v_mfma_f32_16x16x32_bf16 v[24:27], v[212:215], v[196:199], v[24:27]
	v_mfma_f32_16x16x32_bf16 v[16:19], v[220:223], v[196:199], v[16:19]
	v_mfma_f32_16x16x32_bf16 v[8:11], v[212:215], v[204:207], v[8:11]
	v_mfma_f32_16x16x32_bf16 v[0:3], v[220:223], v[204:207], v[0:3]
	v_mfma_f32_16x16x32_bf16 v[56:59], v[216:219], v[184:187], v[56:59]
	v_mfma_f32_16x16x32_bf16 v[48:51], v[224:227], v[184:187], v[48:51]
	v_mfma_f32_16x16x32_bf16 v[40:43], v[216:219], v[192:195], v[40:43]
	v_mfma_f32_16x16x32_bf16 v[32:35], v[224:227], v[192:195], v[32:35]
	v_mfma_f32_16x16x32_bf16 v[24:27], v[216:219], v[200:203], v[24:27]
	v_mfma_f32_16x16x32_bf16 v[16:19], v[224:227], v[200:203], v[16:19]
	v_mfma_f32_16x16x32_bf16 v[8:11], v[216:219], v[208:211], v[8:11]
	v_mfma_f32_16x16x32_bf16 v[0:3], v[224:227], v[208:211], v[0:3]
	s_setprio 0
	s_add_i32 s59, s59, 2
	s_add_u32 s16, s16, 0x100
	s_addc_u32 s17, s17, 0
	s_add_u32 s57, s57, 0x100
	s_addc_u32 s58, s58, 0
	s_cmp_gt_u32 s59, 29
	s_barrier
	s_cbranch_scc0 .LBB0_2546
	s_waitcnt vmcnt(0)
	v_fmamk_f32 v158, v158, 0x3a000000, v151
	v_rsq_f32_e32 v158, v158
	v_lshl_or_b32 v162, s15, 7, v146
	v_ashrrev_i32_e32 v163, 31, v162
	s_and_b64 vcc, vcc, exec
	v_pk_mul_f32 v[160:161], v[158:159], v[124:125] op_sel_hi:[0,1]
	v_mul_f32_e32 v124, 0xbfb8aa3b, v160
	v_mul_f32_e32 v125, 0xbfb8aa3b, v161
	v_exp_f32_e32 v159, v124
	v_exp_f32_e32 v125, v125
	v_lshl_add_u32 v124, s14, 8, v144
	v_add_f32_e32 v159, 1.0, v159
	v_add_f32_e32 v125, 1.0, v125
	v_rcp_f32_e32 v164, v159
	v_rcp_f32_e32 v165, v125
	v_pk_mul_f32 v[120:121], v[158:159], v[120:121] op_sel_hi:[0,1]
	v_pk_mul_f32 v[120:121], v[160:161], v[120:121]
	v_pk_mul_f32 v[126:127], v[158:159], v[126:127] op_sel_hi:[0,1]
	v_pk_mul_f32 v[120:121], v[164:165], v[120:121]
	v_mul_f32_e32 v125, 0xbfb8aa3b, v126
	v_cvt_pk_bf16_f32 v120, v120, v121
	v_mul_f32_e32 v121, 0xbfb8aa3b, v127
	v_exp_f32_e32 v125, v125
	v_exp_f32_e32 v121, v121
	v_pk_mul_f32 v[122:123], v[158:159], v[122:123] op_sel_hi:[0,1]
	v_pk_mul_f32 v[116:117], v[158:159], v[116:117] op_sel_hi:[0,1]
	v_add_f32_e32 v125, 1.0, v125
	v_add_f32_e32 v121, 1.0, v121
	v_rcp_f32_e32 v160, v125
	v_rcp_f32_e32 v161, v121
	v_pk_mul_f32 v[122:123], v[126:127], v[122:123]
	v_mul_f32_e32 v121, 0xbfb8aa3b, v116
	v_exp_f32_e32 v125, v121
	v_pk_mul_f32 v[122:123], v[160:161], v[122:123]
	v_pk_mul_f32 v[112:113], v[158:159], v[112:113] op_sel_hi:[0,1]
	v_cvt_pk_bf16_f32 v121, v122, v123
	v_mul_f32_e32 v123, 0xbfb8aa3b, v117
	v_exp_f32_e32 v123, v123
	v_add_f32_e32 v122, 1.0, v125
	v_pk_mul_f32 v[112:113], v[116:117], v[112:113]
	v_rcp_f32_e32 v122, v122
	v_add_f32_e32 v116, 1.0, v123
	v_rcp_f32_e32 v123, v116
	v_pk_mul_f32 v[116:117], v[158:159], v[118:119] op_sel_hi:[0,1]
	v_mul_f32_e32 v118, 0xbfb8aa3b, v116
	v_mul_f32_e32 v119, 0xbfb8aa3b, v117
	v_exp_f32_e32 v118, v118
	v_exp_f32_e32 v119, v119
	v_pk_mul_f32 v[112:113], v[122:123], v[112:113]
	v_add_f32_e32 v118, 1.0, v118
	v_cvt_pk_bf16_f32 v122, v112, v113
	v_pk_mul_f32 v[112:113], v[158:159], v[114:115] op_sel_hi:[0,1]
	v_fmamk_f32 v114, v157, 0x3a000000, v151
	v_pk_mul_f32 v[112:113], v[116:117], v[112:113]
	v_rsq_f32_e32 v116, v114
	v_add_f32_e32 v119, 1.0, v119
	v_rcp_f32_e32 v118, v118
	v_rcp_f32_e32 v119, v119
	v_pk_mul_f32 v[108:109], v[116:117], v[108:109] op_sel_hi:[0,1]
	v_mul_f32_e32 v117, 0xbfb8aa3b, v108
	v_exp_f32_e32 v117, v117
	v_mul_f32_e32 v125, 0xbfb8aa3b, v109
	v_pk_mul_f32 v[112:113], v[118:119], v[112:113]
	v_exp_f32_e32 v125, v125
	v_cvt_pk_bf16_f32 v123, v112, v113
	v_mov_b64_e32 v[112:113], s[2:3]
	v_mad_i64_i32 v[118:119], s[14:15], v124, s46, v[112:113]
	v_lshlrev_b64 v[114:115], 1, v[162:163]
	v_lshl_add_u64 v[118:119], v[118:119], 0, v[114:115]
	v_add_f32_e32 v117, 1.0, v117
	global_store_dwordx4 v[118:119], v[120:123], off
	v_rcp_f32_e32 v118, v117
	v_add_f32_e32 v117, 1.0, v125
	v_rcp_f32_e32 v119, v117
; __device__ __forceinline__ float sigmoidf_(float x) { return __builtin_amdgcn_rcpf(1.0f + fexp(-x)); }
;     __device__ __forceinline__ void operator()(const f32x4 (&acc)[2][2][4][2], const Unit& u, int wr, int wc, int fr, int fq, const Pre& P) const {
;     ...
; #pragma unroll
;         for (int ai = 0; ai < 2; ++ai)
; #pragma unroll
;             for (int m = 0; m < 4; ++m) { const int r = row0 + ai * HALF + m * 16; const float rs = __builtin_amdgcn_rsqf(P.rs[ai * 4 + m] * (1.0f / DM) + RMS_EPS);
;                 float y[8];
; #pragma unroll
;                 for (int n = 0; n < 2; ++n)
; #pragma unroll
;                     for (int j = 0; j < 4; ++j) { const float a = acc[ai][0][m][n][j] * rs, b = acc[ai][1][m][n][j] * rs; y[n * 4 + j] = a * b * sigmoidf_(a); }
;                 u32x4 w; w.x = cvtpk(y[0], y[1]); w.y = cvtpk(y[2], y[3]); w.z = cvtpk(y[4], y[5]); w.w = cvtpk(y[6], y[7]);
;                 *(u32x4*)(O + (size_t)r * FF + col0) = w; }
	v_or_b32_e32 v117, 16, v124
	v_pk_mul_f32 v[104:105], v[116:117], v[104:105] op_sel_hi:[0,1]
	v_pk_mul_f32 v[104:105], v[108:109], v[104:105]
	v_pk_mul_f32 v[108:109], v[116:117], v[110:111] op_sel_hi:[0,1]
	v_pk_mul_f32 v[104:105], v[118:119], v[104:105]
	v_mul_f32_e32 v110, 0xbfb8aa3b, v108
	v_cvt_pk_bf16_f32 v104, v104, v105
	v_mul_f32_e32 v105, 0xbfb8aa3b, v109
	v_exp_f32_e32 v110, v110
	v_exp_f32_e32 v105, v105
	v_pk_mul_f32 v[106:107], v[116:117], v[106:107] op_sel_hi:[0,1]
	v_pk_mul_f32 v[100:101], v[116:117], v[100:101] op_sel_hi:[0,1]
	v_add_f32_e32 v110, 1.0, v110
	v_add_f32_e32 v105, 1.0, v105
	v_rcp_f32_e32 v110, v110
	v_rcp_f32_e32 v111, v105
	v_pk_mul_f32 v[106:107], v[108:109], v[106:107]
	v_mul_f32_e32 v105, 0xbfb8aa3b, v100
	v_exp_f32_e32 v118, v105
	v_pk_mul_f32 v[106:107], v[110:111], v[106:107]
	v_pk_mul_f32 v[96:97], v[116:117], v[96:97] op_sel_hi:[0,1]
	v_cvt_pk_bf16_f32 v105, v106, v107
	v_mul_f32_e32 v107, 0xbfb8aa3b, v101
	v_exp_f32_e32 v107, v107
	v_pk_mul_f32 v[96:97], v[100:101], v[96:97]
	v_add_f32_e32 v106, 1.0, v118
	v_rcp_f32_e32 v106, v106
	v_add_f32_e32 v100, 1.0, v107
	v_rcp_f32_e32 v107, v100
	v_pk_mul_f32 v[100:101], v[116:117], v[102:103] op_sel_hi:[0,1]
	v_mul_f32_e32 v102, 0xbfb8aa3b, v100
	v_mul_f32_e32 v103, 0xbfb8aa3b, v101
	v_exp_f32_e32 v102, v102
	v_exp_f32_e32 v103, v103
	v_pk_mul_f32 v[96:97], v[106:107], v[96:97]
	v_add_f32_e32 v102, 1.0, v102
	v_add_f32_e32 v103, 1.0, v103
	v_rcp_f32_e32 v102, v102
	v_rcp_f32_e32 v103, v103
	v_cvt_pk_bf16_f32 v106, v96, v97
	v_pk_mul_f32 v[96:97], v[116:117], v[98:99] op_sel_hi:[0,1]
	v_pk_mul_f32 v[96:97], v[100:101], v[96:97]
	v_mad_i64_i32 v[98:99], s[14:15], v117, s46, v[112:113]
	v_pk_mul_f32 v[96:97], v[102:103], v[96:97]
	v_lshl_add_u64 v[98:99], v[98:99], 0, v[114:115]
	v_cvt_pk_bf16_f32 v107, v96, v97
	v_fmamk_f32 v96, v156, 0x3a000000, v151
	v_rsq_f32_e32 v96, v96
	global_store_dwordx4 v[98:99], v[104:107], off
	v_pk_mul_f32 v[92:93], v[96:97], v[92:93] op_sel_hi:[0,1]
	v_mul_f32_e32 v97, 0xbfb8aa3b, v92
	v_exp_f32_e32 v97, v97
	v_mul_f32_e32 v100, 0xbfb8aa3b, v93
	v_exp_f32_e32 v100, v100
	v_add_f32_e32 v97, 1.0, v97
	v_rcp_f32_e32 v98, v97
	v_add_f32_e32 v97, 1.0, v100
	v_rcp_f32_e32 v99, v97
	v_or_b32_e32 v97, 32, v124
	v_pk_mul_f32 v[88:89], v[96:97], v[88:89] op_sel_hi:[0,1]
	v_pk_mul_f32 v[88:89], v[92:93], v[88:89]
	v_pk_mul_f32 v[92:93], v[96:97], v[94:95] op_sel_hi:[0,1]
	v_pk_mul_f32 v[88:89], v[98:99], v[88:89]
	v_mul_f32_e32 v94, 0xbfb8aa3b, v92
	v_cvt_pk_bf16_f32 v88, v88, v89
	v_mul_f32_e32 v89, 0xbfb8aa3b, v93
	v_exp_f32_e32 v94, v94
	v_exp_f32_e32 v89, v89
	v_pk_mul_f32 v[90:91], v[96:97], v[90:91] op_sel_hi:[0,1]
	v_pk_mul_f32 v[84:85], v[96:97], v[84:85] op_sel_hi:[0,1]
	v_add_f32_e32 v94, 1.0, v94
	v_add_f32_e32 v89, 1.0, v89
	v_rcp_f32_e32 v94, v94
	v_rcp_f32_e32 v95, v89
	v_pk_mul_f32 v[90:91], v[92:93], v[90:91]
	v_mul_f32_e32 v89, 0xbfb8aa3b, v84
	v_exp_f32_e32 v98, v89
	v_pk_mul_f32 v[90:91], v[94:95], v[90:91]
	v_pk_mul_f32 v[80:81], v[96:97], v[80:81] op_sel_hi:[0,1]
	v_cvt_pk_bf16_f32 v89, v90, v91
	v_mul_f32_e32 v91, 0xbfb8aa3b, v85
	v_exp_f32_e32 v91, v91
	v_pk_mul_f32 v[80:81], v[84:85], v[80:81]
	v_add_f32_e32 v90, 1.0, v98
	v_rcp_f32_e32 v90, v90
	v_add_f32_e32 v84, 1.0, v91
	v_rcp_f32_e32 v91, v84
	v_pk_mul_f32 v[84:85], v[96:97], v[86:87] op_sel_hi:[0,1]
	v_mul_f32_e32 v86, 0xbfb8aa3b, v84
	v_mul_f32_e32 v87, 0xbfb8aa3b, v85
	v_exp_f32_e32 v86, v86
	v_exp_f32_e32 v87, v87
	v_pk_mul_f32 v[80:81], v[90:91], v[80:81]
	v_add_f32_e32 v86, 1.0, v86
	v_add_f32_e32 v87, 1.0, v87
	v_rcp_f32_e32 v86, v86
	v_rcp_f32_e32 v87, v87
	v_cvt_pk_bf16_f32 v90, v80, v81
	v_pk_mul_f32 v[80:81], v[96:97], v[82:83] op_sel_hi:[0,1]
	v_pk_mul_f32 v[80:81], v[84:85], v[80:81]
	v_mad_i64_i32 v[82:83], s[14:15], v97, s46, v[112:113]
	v_pk_mul_f32 v[80:81], v[86:87], v[80:81]
	v_lshl_add_u64 v[82:83], v[82:83], 0, v[114:115]
	v_cvt_pk_bf16_f32 v91, v80, v81
	v_fmamk_f32 v80, v155, 0x3a000000, v151
	v_rsq_f32_e32 v80, v80
	global_store_dwordx4 v[82:83], v[88:91], off
	v_pk_mul_f32 v[76:77], v[80:81], v[76:77] op_sel_hi:[0,1]
	v_mul_f32_e32 v81, 0xbfb8aa3b, v76
	v_exp_f32_e32 v81, v81
	v_mul_f32_e32 v84, 0xbfb8aa3b, v77
	v_exp_f32_e32 v84, v84
	v_add_f32_e32 v81, 1.0, v81
	v_rcp_f32_e32 v82, v81
	v_add_f32_e32 v81, 1.0, v84
	v_rcp_f32_e32 v83, v81
	v_or_b32_e32 v81, 48, v124
	v_pk_mul_f32 v[72:73], v[80:81], v[72:73] op_sel_hi:[0,1]
	v_pk_mul_f32 v[72:73], v[76:77], v[72:73]
	v_pk_mul_f32 v[76:77], v[80:81], v[78:79] op_sel_hi:[0,1]
	v_pk_mul_f32 v[72:73], v[82:83], v[72:73]
	v_mul_f32_e32 v78, 0xbfb8aa3b, v76
	v_cvt_pk_bf16_f32 v72, v72, v73
	v_mul_f32_e32 v73, 0xbfb8aa3b, v77
	v_exp_f32_e32 v78, v78
	v_exp_f32_e32 v73, v73
	v_pk_mul_f32 v[74:75], v[80:81], v[74:75] op_sel_hi:[0,1]
	v_pk_mul_f32 v[68:69], v[80:81], v[68:69] op_sel_hi:[0,1]
	v_add_f32_e32 v78, 1.0, v78
	v_add_f32_e32 v73, 1.0, v73
	v_rcp_f32_e32 v78, v78
	v_rcp_f32_e32 v79, v73
	v_pk_mul_f32 v[74:75], v[76:77], v[74:75]
	v_mul_f32_e32 v73, 0xbfb8aa3b, v68
	v_exp_f32_e32 v82, v73
	v_pk_mul_f32 v[74:75], v[78:79], v[74:75]
	v_pk_mul_f32 v[64:65], v[80:81], v[64:65] op_sel_hi:[0,1]
	v_cvt_pk_bf16_f32 v73, v74, v75
	v_mul_f32_e32 v75, 0xbfb8aa3b, v69
	v_exp_f32_e32 v75, v75
	v_pk_mul_f32 v[64:65], v[68:69], v[64:65]
	v_add_f32_e32 v74, 1.0, v82
	v_rcp_f32_e32 v74, v74
	v_add_f32_e32 v68, 1.0, v75
	v_rcp_f32_e32 v75, v68
	v_pk_mul_f32 v[68:69], v[80:81], v[70:71] op_sel_hi:[0,1]
	v_mul_f32_e32 v70, 0xbfb8aa3b, v68
	v_mul_f32_e32 v71, 0xbfb8aa3b, v69
	v_exp_f32_e32 v70, v70
	v_exp_f32_e32 v71, v71
	v_pk_mul_f32 v[64:65], v[74:75], v[64:65]
	v_add_f32_e32 v70, 1.0, v70
; __device__ __forceinline__ float sigmoidf_(float x) { return __builtin_amdgcn_rcpf(1.0f + fexp(-x)); }
;     __device__ __forceinline__ void operator()(const f32x4 (&acc)[2][2][4][2], const Unit& u, int wr, int wc, int fr, int fq, const Pre& P) const {
;     ...
; #pragma unroll
;         for (int ai = 0; ai < 2; ++ai)
; #pragma unroll
;             for (int m = 0; m < 4; ++m) { const int r = row0 + ai * HALF + m * 16; const float rs = __builtin_amdgcn_rsqf(P.rs[ai * 4 + m] * (1.0f / DM) + RMS_EPS);
;                 float y[8];
; #pragma unroll
;                 for (int n = 0; n < 2; ++n)
; #pragma unroll
;                     for (int j = 0; j < 4; ++j) { const float a = acc[ai][0][m][n][j] * rs, b = acc[ai][1][m][n][j] * rs; y[n * 4 + j] = a * b * sigmoidf_(a); }
;                 u32x4 w; w.x = cvtpk(y[0], y[1]); w.y = cvtpk(y[2], y[3]); w.z = cvtpk(y[4], y[5]); w.w = cvtpk(y[6], y[7]);
;                 *(u32x4*)(O + (size_t)r * FF + col0) = w; }
	v_add_f32_e32 v71, 1.0, v71
	v_rcp_f32_e32 v70, v70
	v_rcp_f32_e32 v71, v71
	v_cvt_pk_bf16_f32 v74, v64, v65
	v_pk_mul_f32 v[64:65], v[80:81], v[66:67] op_sel_hi:[0,1]
	v_pk_mul_f32 v[64:65], v[68:69], v[64:65]
	v_mad_i64_i32 v[66:67], s[14:15], v81, s46, v[112:113]
	v_pk_mul_f32 v[64:65], v[70:71], v[64:65]
	v_lshl_add_u64 v[66:67], v[66:67], 0, v[114:115]
	v_cvt_pk_bf16_f32 v75, v64, v65
	v_fmamk_f32 v64, v154, 0x3a000000, v151
	v_rsq_f32_e32 v64, v64
	global_store_dwordx4 v[66:67], v[72:75], off
	v_pk_mul_f32 v[60:61], v[64:65], v[60:61] op_sel_hi:[0,1]
	v_mul_f32_e32 v65, 0xbfb8aa3b, v60
	v_exp_f32_e32 v65, v65
	v_mul_f32_e32 v68, 0xbfb8aa3b, v61
	v_exp_f32_e32 v68, v68
	v_add_f32_e32 v65, 1.0, v65
	v_rcp_f32_e32 v66, v65
	v_add_f32_e32 v65, 1.0, v68
	v_rcp_f32_e32 v67, v65
	v_add_u32_e32 v65, 0x80, v124
	v_pk_mul_f32 v[56:57], v[64:65], v[56:57] op_sel_hi:[0,1]
	v_pk_mul_f32 v[56:57], v[60:61], v[56:57]
	v_pk_mul_f32 v[60:61], v[64:65], v[62:63] op_sel_hi:[0,1]
	v_pk_mul_f32 v[56:57], v[66:67], v[56:57]
	v_mul_f32_e32 v62, 0xbfb8aa3b, v60
	v_cvt_pk_bf16_f32 v56, v56, v57
	v_mul_f32_e32 v57, 0xbfb8aa3b, v61
	v_exp_f32_e32 v62, v62
	v_exp_f32_e32 v57, v57
	v_pk_mul_f32 v[58:59], v[64:65], v[58:59] op_sel_hi:[0,1]
	v_pk_mul_f32 v[52:53], v[64:65], v[52:53] op_sel_hi:[0,1]
	v_add_f32_e32 v62, 1.0, v62
	v_add_f32_e32 v57, 1.0, v57
	v_rcp_f32_e32 v62, v62
	v_rcp_f32_e32 v63, v57
	v_pk_mul_f32 v[58:59], v[60:61], v[58:59]
	v_mul_f32_e32 v57, 0xbfb8aa3b, v52
	v_exp_f32_e32 v66, v57
	v_pk_mul_f32 v[58:59], v[62:63], v[58:59]
	v_pk_mul_f32 v[48:49], v[64:65], v[48:49] op_sel_hi:[0,1]
	v_cvt_pk_bf16_f32 v57, v58, v59
	v_mul_f32_e32 v59, 0xbfb8aa3b, v53
	v_exp_f32_e32 v59, v59
	v_pk_mul_f32 v[48:49], v[52:53], v[48:49]
	v_add_f32_e32 v58, 1.0, v66
	v_rcp_f32_e32 v58, v58
	v_add_f32_e32 v52, 1.0, v59
	v_rcp_f32_e32 v59, v52
	v_pk_mul_f32 v[52:53], v[64:65], v[54:55] op_sel_hi:[0,1]
	v_mul_f32_e32 v54, 0xbfb8aa3b, v52
	v_mul_f32_e32 v55, 0xbfb8aa3b, v53
	v_exp_f32_e32 v54, v54
	v_exp_f32_e32 v55, v55
	v_pk_mul_f32 v[48:49], v[58:59], v[48:49]
	v_add_f32_e32 v54, 1.0, v54
	v_add_f32_e32 v55, 1.0, v55
	v_rcp_f32_e32 v54, v54
	v_rcp_f32_e32 v55, v55
	v_cvt_pk_bf16_f32 v58, v48, v49
	v_pk_mul_f32 v[48:49], v[64:65], v[50:51] op_sel_hi:[0,1]
	v_pk_mul_f32 v[48:49], v[52:53], v[48:49]
	v_mad_i64_i32 v[50:51], s[14:15], v65, s46, v[112:113]
	v_pk_mul_f32 v[48:49], v[54:55], v[48:49]
	v_lshl_add_u64 v[50:51], v[50:51], 0, v[114:115]
	v_cvt_pk_bf16_f32 v59, v48, v49
	v_fmamk_f32 v48, v153, 0x3a000000, v151
	v_rsq_f32_e32 v48, v48
	global_store_dwordx4 v[50:51], v[56:59], off
	v_pk_mul_f32 v[44:45], v[48:49], v[44:45] op_sel_hi:[0,1]
	v_mul_f32_e32 v49, 0xbfb8aa3b, v44
	v_exp_f32_e32 v49, v49
	v_mul_f32_e32 v52, 0xbfb8aa3b, v45
	v_exp_f32_e32 v52, v52
	v_add_f32_e32 v49, 1.0, v49
	v_rcp_f32_e32 v50, v49
	v_add_f32_e32 v49, 1.0, v52
	v_rcp_f32_e32 v51, v49
	v_add_u32_e32 v49, 0x90, v124
	v_pk_mul_f32 v[40:41], v[48:49], v[40:41] op_sel_hi:[0,1]
	v_pk_mul_f32 v[40:41], v[44:45], v[40:41]
	v_pk_mul_f32 v[44:45], v[48:49], v[46:47] op_sel_hi:[0,1]
	v_pk_mul_f32 v[40:41], v[50:51], v[40:41]
	v_mul_f32_e32 v46, 0xbfb8aa3b, v44
	v_cvt_pk_bf16_f32 v40, v40, v41
	v_mul_f32_e32 v41, 0xbfb8aa3b, v45
	v_exp_f32_e32 v46, v46
	v_exp_f32_e32 v41, v41
	v_pk_mul_f32 v[42:43], v[48:49], v[42:43] op_sel_hi:[0,1]
	v_pk_mul_f32 v[36:37], v[48:49], v[36:37] op_sel_hi:[0,1]
	v_add_f32_e32 v46, 1.0, v46
	v_add_f32_e32 v41, 1.0, v41
	v_rcp_f32_e32 v46, v46
	v_rcp_f32_e32 v47, v41
	v_pk_mul_f32 v[42:43], v[44:45], v[42:43]
	v_mul_f32_e32 v41, 0xbfb8aa3b, v36
	v_exp_f32_e32 v50, v41
	v_pk_mul_f32 v[42:43], v[46:47], v[42:43]
	v_pk_mul_f32 v[32:33], v[48:49], v[32:33] op_sel_hi:[0,1]
	v_cvt_pk_bf16_f32 v41, v42, v43
	v_mul_f32_e32 v43, 0xbfb8aa3b, v37
	v_exp_f32_e32 v43, v43
	v_pk_mul_f32 v[32:33], v[36:37], v[32:33]
	v_add_f32_e32 v42, 1.0, v50
	v_rcp_f32_e32 v42, v42
	v_add_f32_e32 v36, 1.0, v43
	v_rcp_f32_e32 v43, v36
	v_pk_mul_f32 v[36:37], v[48:49], v[38:39] op_sel_hi:[0,1]
	v_mul_f32_e32 v38, 0xbfb8aa3b, v36
	v_mul_f32_e32 v39, 0xbfb8aa3b, v37
	v_exp_f32_e32 v38, v38
	v_exp_f32_e32 v39, v39
	v_pk_mul_f32 v[32:33], v[42:43], v[32:33]
	v_add_f32_e32 v38, 1.0, v38
	v_add_f32_e32 v39, 1.0, v39
	v_rcp_f32_e32 v38, v38
	v_rcp_f32_e32 v39, v39
	v_cvt_pk_bf16_f32 v42, v32, v33
	v_pk_mul_f32 v[32:33], v[48:49], v[34:35] op_sel_hi:[0,1]
	v_pk_mul_f32 v[32:33], v[36:37], v[32:33]
	v_mad_i64_i32 v[34:35], s[14:15], v49, s46, v[112:113]
	v_pk_mul_f32 v[32:33], v[38:39], v[32:33]
	v_lshl_add_u64 v[34:35], v[34:35], 0, v[114:115]
	v_cvt_pk_bf16_f32 v43, v32, v33
	v_fmamk_f32 v32, v152, 0x3a000000, v151
	v_rsq_f32_e32 v32, v32
	global_store_dwordx4 v[34:35], v[40:43], off
	v_pk_mul_f32 v[28:29], v[32:33], v[28:29] op_sel_hi:[0,1]
	v_mul_f32_e32 v33, 0xbfb8aa3b, v28
	v_exp_f32_e32 v33, v33
	v_mul_f32_e32 v36, 0xbfb8aa3b, v29
; __device__ __forceinline__ float sigmoidf_(float x) { return __builtin_amdgcn_rcpf(1.0f + fexp(-x)); }
; __device__ __forceinline__ PreRs load_rs(const float* ssq, int pm, int wr, int fr) { PreRs p;
; #pragma unroll
;     for (int ai = 0; ai < 2; ++ai)
; #pragma unroll
;         for (int m = 0; m < 4; ++m) p.rs[ai * 4 + m] = ssq[ROW_X + pm * BM + ai * HALF + wr * 64 + m * 16 + fr];
;     return p; }
;     __device__ __forceinline__ void operator()(const f32x4 (&acc)[2][2][4][2], const Unit& u, int wr, int wc, int fr, int fq, const Pre& P) const {
;     ...
; #pragma unroll
;         for (int ai = 0; ai < 2; ++ai)
; #pragma unroll
;             for (int m = 0; m < 4; ++m) { const int r = row0 + ai * HALF + m * 16; const float rs = __builtin_amdgcn_rsqf(P.rs[ai * 4 + m] * (1.0f / DM) + RMS_EPS);
;                 float y[8];
; #pragma unroll
;                 for (int n = 0; n < 2; ++n)
; #pragma unroll
;                     for (int j = 0; j < 4; ++j) { const float a = acc[ai][0][m][n][j] * rs, b = acc[ai][1][m][n][j] * rs; y[n * 4 + j] = a * b * sigmoidf_(a); }
;                 u32x4 w; w.x = cvtpk(y[0], y[1]); w.y = cvtpk(y[2], y[3]); w.z = cvtpk(y[4], y[5]); w.w = cvtpk(y[6], y[7]);
;                 *(u32x4*)(O + (size_t)r * FF + col0) = w; }
	v_exp_f32_e32 v36, v36
	v_add_f32_e32 v33, 1.0, v33
	v_rcp_f32_e32 v34, v33
	v_add_f32_e32 v33, 1.0, v36
	v_rcp_f32_e32 v35, v33
	v_add_u32_e32 v33, 0xa0, v124
	v_pk_mul_f32 v[24:25], v[32:33], v[24:25] op_sel_hi:[0,1]
	v_pk_mul_f32 v[24:25], v[28:29], v[24:25]
	v_pk_mul_f32 v[28:29], v[32:33], v[30:31] op_sel_hi:[0,1]
	v_pk_mul_f32 v[24:25], v[34:35], v[24:25]
	v_mul_f32_e32 v30, 0xbfb8aa3b, v28
	v_cvt_pk_bf16_f32 v24, v24, v25
	v_mul_f32_e32 v25, 0xbfb8aa3b, v29
	v_exp_f32_e32 v30, v30
	v_exp_f32_e32 v25, v25
	v_pk_mul_f32 v[26:27], v[32:33], v[26:27] op_sel_hi:[0,1]
	v_pk_mul_f32 v[20:21], v[32:33], v[20:21] op_sel_hi:[0,1]
	v_add_f32_e32 v30, 1.0, v30
	v_add_f32_e32 v25, 1.0, v25
	v_rcp_f32_e32 v30, v30
	v_rcp_f32_e32 v31, v25
	v_pk_mul_f32 v[26:27], v[28:29], v[26:27]
	v_mul_f32_e32 v25, 0xbfb8aa3b, v20
	v_exp_f32_e32 v34, v25
	v_pk_mul_f32 v[26:27], v[30:31], v[26:27]
	v_pk_mul_f32 v[16:17], v[32:33], v[16:17] op_sel_hi:[0,1]
	v_cvt_pk_bf16_f32 v25, v26, v27
	v_mul_f32_e32 v27, 0xbfb8aa3b, v21
	v_exp_f32_e32 v27, v27
	v_pk_mul_f32 v[16:17], v[20:21], v[16:17]
	v_add_f32_e32 v26, 1.0, v34
	v_rcp_f32_e32 v26, v26
	v_add_f32_e32 v20, 1.0, v27
	v_rcp_f32_e32 v27, v20
	v_pk_mul_f32 v[20:21], v[32:33], v[22:23] op_sel_hi:[0,1]
	v_mul_f32_e32 v22, 0xbfb8aa3b, v20
	v_mul_f32_e32 v23, 0xbfb8aa3b, v21
	v_exp_f32_e32 v22, v22
	v_exp_f32_e32 v23, v23
	v_pk_mul_f32 v[16:17], v[26:27], v[16:17]
	v_add_f32_e32 v22, 1.0, v22
	v_add_f32_e32 v23, 1.0, v23
	v_rcp_f32_e32 v22, v22
	v_rcp_f32_e32 v23, v23
	v_cvt_pk_bf16_f32 v26, v16, v17
	v_pk_mul_f32 v[16:17], v[32:33], v[18:19] op_sel_hi:[0,1]
	v_pk_mul_f32 v[16:17], v[20:21], v[16:17]
	v_mad_i64_i32 v[18:19], s[14:15], v33, s46, v[112:113]
	v_pk_mul_f32 v[16:17], v[22:23], v[16:17]
	v_lshl_add_u64 v[18:19], v[18:19], 0, v[114:115]
	v_cvt_pk_bf16_f32 v27, v16, v17
	v_fmamk_f32 v16, v147, 0x3a000000, v151
	v_rsq_f32_e32 v16, v16
	global_store_dwordx4 v[18:19], v[24:27], off
	v_pk_mul_f32 v[12:13], v[16:17], v[12:13] op_sel_hi:[0,1]
	v_mul_f32_e32 v17, 0xbfb8aa3b, v12
	v_exp_f32_e32 v17, v17
	v_mul_f32_e32 v20, 0xbfb8aa3b, v13
	v_exp_f32_e32 v20, v20
	v_add_f32_e32 v17, 1.0, v17
	v_rcp_f32_e32 v18, v17
	v_add_f32_e32 v17, 1.0, v20
	v_rcp_f32_e32 v19, v17
	v_add_u32_e32 v17, 0xb0, v124
	v_pk_mul_f32 v[8:9], v[16:17], v[8:9] op_sel_hi:[0,1]
	v_pk_mul_f32 v[8:9], v[12:13], v[8:9]
	v_pk_mul_f32 v[12:13], v[16:17], v[14:15] op_sel_hi:[0,1]
	v_pk_mul_f32 v[8:9], v[18:19], v[8:9]
	v_mul_f32_e32 v14, 0xbfb8aa3b, v12
	v_cvt_pk_bf16_f32 v8, v8, v9
	v_mul_f32_e32 v9, 0xbfb8aa3b, v13
	v_exp_f32_e32 v14, v14
	v_exp_f32_e32 v9, v9
	v_pk_mul_f32 v[10:11], v[16:17], v[10:11] op_sel_hi:[0,1]
	v_pk_mul_f32 v[4:5], v[16:17], v[4:5] op_sel_hi:[0,1]
	v_add_f32_e32 v14, 1.0, v14
	v_add_f32_e32 v9, 1.0, v9
	v_rcp_f32_e32 v14, v14
	v_rcp_f32_e32 v15, v9
	v_pk_mul_f32 v[10:11], v[12:13], v[10:11]
	v_mul_f32_e32 v9, 0xbfb8aa3b, v4
	v_exp_f32_e32 v18, v9
	v_pk_mul_f32 v[10:11], v[14:15], v[10:11]
	v_pk_mul_f32 v[0:1], v[16:17], v[0:1] op_sel_hi:[0,1]
	v_cvt_pk_bf16_f32 v9, v10, v11
	v_mul_f32_e32 v11, 0xbfb8aa3b, v5
	v_exp_f32_e32 v11, v11
	v_pk_mul_f32 v[0:1], v[4:5], v[0:1]
	v_add_f32_e32 v10, 1.0, v18
	v_rcp_f32_e32 v10, v10
	v_add_f32_e32 v4, 1.0, v11
	v_rcp_f32_e32 v11, v4
	v_pk_mul_f32 v[4:5], v[16:17], v[6:7] op_sel_hi:[0,1]
	v_mul_f32_e32 v6, 0xbfb8aa3b, v4
	v_mul_f32_e32 v7, 0xbfb8aa3b, v5
	v_exp_f32_e32 v6, v6
	v_exp_f32_e32 v7, v7
	v_pk_mul_f32 v[0:1], v[10:11], v[0:1]
	v_add_f32_e32 v6, 1.0, v6
	v_add_f32_e32 v7, 1.0, v7
	v_rcp_f32_e32 v6, v6
	v_rcp_f32_e32 v7, v7
	v_cvt_pk_bf16_f32 v10, v0, v1
	v_pk_mul_f32 v[0:1], v[16:17], v[2:3] op_sel_hi:[0,1]
	v_pk_mul_f32 v[0:1], v[4:5], v[0:1]
	s_nop 0
	v_pk_mul_f32 v[0:1], v[6:7], v[0:1]
	s_nop 0
	v_cvt_pk_bf16_f32 v11, v0, v1
	v_mad_i64_i32 v[0:1], s[14:15], v17, s46, v[112:113]
	v_lshl_add_u64 v[0:1], v[0:1], 0, v[114:115]
	s_mov_b64 s[14:15], -1
	global_store_dwordx4 v[0:1], v[8:11], off
	s_cbranch_vccz .LBB0_2542
	v_lshl_add_u32 v0, s8, 8, v144
	v_ashrrev_i32_e32 v1, 31, v0
	v_lshl_add_u64 v[2:3], v[0:1], 2, s[0:1]
	v_add_u32_e32 v4, 0x80, v0
	v_add_u32_e32 v6, 0x90, v0
	v_add_u32_e32 v8, 0xa0, v0
	v_add_u32_e32 v0, 0xb0, v0
	v_ashrrev_i32_e32 v5, 31, v4
	v_ashrrev_i32_e32 v7, 31, v6
	v_ashrrev_i32_e32 v9, 31, v8
	v_ashrrev_i32_e32 v1, 31, v0
	v_lshl_add_u64 v[4:5], v[4:5], 2, s[0:1]
	v_lshl_add_u64 v[6:7], v[6:7], 2, s[0:1]
	v_lshl_add_u64 v[8:9], v[8:9], 2, s[0:1]
	v_lshl_add_u64 v[0:1], v[0:1], 2, s[0:1]
	global_load_dword v158, v[2:3], off
	global_load_dword v157, v[2:3], off offset:64
	global_load_dword v156, v[2:3], off offset:128
	global_load_dword v155, v[2:3], off offset:192
	global_load_dword v154, v[4:5], off
	global_load_dword v153, v[6:7], off
	global_load_dword v152, v[8:9], off
	global_load_dword v147, v[0:1], off
	s_mov_b64 s[14:15], 0
	s_branch .LBB0_2542

; #define PG8_STAGE(bufoff, gbase, voff) do { _Pragma("unroll") for (int _i = 0; _i < 2; ++_i) \
;         __builtin_amdgcn_global_load_lds((const unsigned*)((const char*)(gbase) + (voff)[_i]), (LAS unsigned*)(lds + (bufoff) + ldsw + _i * 8192), 16, 0, 0); } while (0)
; #define PG8_LDA(dst, b, h) do { _Pragma("unroll") for (int m = 0; m < 4; ++m) _Pragma("unroll") for (int k = 0; k < 2; ++k) dst[m][k] = *(const LAS bf16x8*)(lds + PG8_SA(b, h) + aoff + m * 2048 + k * 1024); } while (0)
; #define PG8_LDB(dst, b, h) do { _Pragma("unroll") for (int n = 0; n < 2; ++n) _Pragma("unroll") for (int k = 0; k < 2; ++k) dst[n][k] = *(const LAS bf16x8*)(lds + PG8_SB(b, h) + boff + n * 2048 + k * 1024); } while (0)
; #define PG8_MMA(ai, bj, At, Bt) do { __builtin_amdgcn_s_setprio(1); _Pragma("unroll") for (int m = 0; m < 4; ++m) _Pragma("unroll") for (int n = 0; n < 2; ++n) _Pragma("unroll") for (int k = 0; k < 2; ++k) \
;         acc[ai][bj][m][n] = __builtin_amdgcn_mfma_f32_16x16x32_bf16(Bt[n][k], At[m][k], acc[ai][bj][m][n], 0, 0, 0); __builtin_amdgcn_s_setprio(0); } while (0)
; #define PG8_WAIT_L(n) asm volatile("s_waitcnt lgkmcnt(" #n ")" ::: "memory")
; #define PG8_BAR __builtin_amdgcn_s_barrier()
; #define PG8_SCHED __builtin_amdgcn_sched_barrier(0)
; template <class Epi>
; __device__ __forceinline__ void gemm_phase(LAS unsigned char* lds, const Gemm g, const StaticOrder& S, const Epi& E) {
;     ...
;         for (int t = 0; t < nt; t += 2) {
;             const bool last = (t == nt - 2);
;             const char* a1 = cA + (size_t)(t + 1) * kstep;
;             const char* a2 = last ? nA : cA + (size_t)(t + 2) * kstep; const char* b2 = last ? nB : cB + (size_t)(t + 2) * kstep;
;             const char* a3 = a2 + kstep; const char* b3 = b2 + kstep;
;             PG8_LDB(B0, 0, 0); PG8_SCHED; PG8_LDA(At, 0, 0); PG8_STAGE(PG8_SA(1, 1), a1 + hstep, voffA);
;             PG8_WAIT_L(8); PG8_BAR; PG8_WAIT_L(0); PG8_MMA(0, 0, At, B0); PG8_BAR; PG8_SCHED;
.LBB0_2626:
	ds_read_b128 v[144:147], v153
	ds_read_b128 v[156:159], v153 offset:1024
	ds_read_b128 v[160:163], v153 offset:2048
	ds_read_b128 v[164:167], v153 offset:3072
	s_add_u32 s20, s18, 0xffea8080
	s_addc_u32 s21, s19, -1
	s_cmpk_eq_i32 s64, 0x52
	s_cselect_b32 s23, s1, s21
	s_cselect_b32 s22, s0, s20
	s_cselect_b32 s21, s5, s63
	s_cselect_b32 s20, s4, s62
	v_lshl_add_u64 v[148:149], s[18:19], 0, v[136:137]
	s_add_i32 m0, s36, 0xc000
	ds_read_b128 v[168:171], v154
	ds_read_b128 v[172:175], v154 offset:1024
	ds_read_b128 v[176:179], v154 offset:2048
	ds_read_b128 v[180:183], v154 offset:3072
	ds_read_b128 v[184:187], v154 offset:4096
	ds_read_b128 v[188:191], v154 offset:5120
	ds_read_b128 v[192:195], v154 offset:6144
	ds_read_b128 v[196:199], v154 offset:7168
	global_load_lds_dwordx4 v[148:149], off
	v_lshl_add_u64 v[148:149], s[18:19], 0, v[138:139]
	s_add_i32 m0, s36, 0xe000
	s_nop 0
	global_load_lds_dwordx4 v[148:149], off
	s_waitcnt lgkmcnt(8)
	s_barrier
	s_waitcnt lgkmcnt(0)
	s_setprio 1

; #define PG8_STAGE(bufoff, gbase, voff) do { _Pragma("unroll") for (int _i = 0; _i < 2; ++_i) \
;         __builtin_amdgcn_global_load_lds((const unsigned*)((const char*)(gbase) + (voff)[_i]), (LAS unsigned*)(lds + (bufoff) + ldsw + _i * 8192), 16, 0, 0); } while (0)
; #define PG8_LDB(dst, b, h) do { _Pragma("unroll") for (int n = 0; n < 2; ++n) _Pragma("unroll") for (int k = 0; k < 2; ++k) dst[n][k] = *(const LAS bf16x8*)(lds + PG8_SB(b, h) + boff + n * 2048 + k * 1024); } while (0)
; #define PG8_MMA(ai, bj, At, Bt) do { __builtin_amdgcn_s_setprio(1); _Pragma("unroll") for (int m = 0; m < 4; ++m) _Pragma("unroll") for (int n = 0; n < 2; ++n) _Pragma("unroll") for (int k = 0; k < 2; ++k) \
;         acc[ai][bj][m][n] = __builtin_amdgcn_mfma_f32_16x16x32_bf16(Bt[n][k], At[m][k], acc[ai][bj][m][n], 0, 0, 0); __builtin_amdgcn_s_setprio(0); } while (0)
; #define PG8_WAIT_L(n) asm volatile("s_waitcnt lgkmcnt(" #n ")" ::: "memory")
; #define PG8_BAR __builtin_amdgcn_s_barrier()
; #define PG8_SCHED __builtin_amdgcn_sched_barrier(0)
; template <class Epi>
; __device__ __forceinline__ void gemm_phase(LAS unsigned char* lds, const Gemm g, const StaticOrder& S, const Epi& E) {
;     ...
;             PG8_WAIT_L(8); PG8_BAR; PG8_WAIT_L(0); PG8_MMA(0, 0, At, B0); PG8_BAR; PG8_SCHED;
;             PG8_LDB(B1, 0, 1); PG8_STAGE(PG8_SB(0, 0), b2, voffB);
;             PG8_BAR; PG8_WAIT_L(0); PG8_MMA(0, 1, At, B1); PG8_BAR;
	v_mfma_f32_16x16x32_bf16 v[124:127], v[144:147], v[168:171], v[124:127]
	v_mfma_f32_16x16x32_bf16 v[120:123], v[160:163], v[168:171], v[120:123]
	v_mfma_f32_16x16x32_bf16 v[112:115], v[144:147], v[176:179], v[112:115]
	v_mfma_f32_16x16x32_bf16 v[104:107], v[160:163], v[176:179], v[104:107]
	v_mfma_f32_16x16x32_bf16 v[92:95], v[144:147], v[184:187], v[92:95]
	v_mfma_f32_16x16x32_bf16 v[88:91], v[160:163], v[184:187], v[88:91]
	v_mfma_f32_16x16x32_bf16 v[80:83], v[144:147], v[192:195], v[80:83]
	v_mfma_f32_16x16x32_bf16 v[72:75], v[160:163], v[192:195], v[72:75]
	v_mfma_f32_16x16x32_bf16 v[124:127], v[156:159], v[172:175], v[124:127]
	v_mfma_f32_16x16x32_bf16 v[120:123], v[164:167], v[172:175], v[120:123]
	v_mfma_f32_16x16x32_bf16 v[112:115], v[156:159], v[180:183], v[112:115]
	v_mfma_f32_16x16x32_bf16 v[104:107], v[164:167], v[180:183], v[104:107]
	v_mfma_f32_16x16x32_bf16 v[92:95], v[156:159], v[188:191], v[92:95]
	v_mfma_f32_16x16x32_bf16 v[88:91], v[164:167], v[188:191], v[88:91]
	v_mfma_f32_16x16x32_bf16 v[80:83], v[156:159], v[196:199], v[80:83]
	v_mfma_f32_16x16x32_bf16 v[72:75], v[164:167], v[196:199], v[72:75]
	s_setprio 0
	s_barrier
	s_add_i32 s65, s45, s35
	v_lshl_add_u64 v[148:149], s[20:21], 0, v[130:131]
	s_mov_b32 m0, s65
	ds_read_b128 v[200:203], v155
	ds_read_b128 v[204:207], v155 offset:1024
	ds_read_b128 v[208:211], v155 offset:2048
	ds_read_b128 v[212:215], v155 offset:3072
	global_load_lds_dwordx4 v[148:149], off
	v_lshl_add_u64 v[216:217], s[20:21], 0, v[134:135]
	s_add_i32 m0, s65, 0x2000
	s_nop 0
	global_load_lds_dwordx4 v[216:217], off
	s_barrier
	s_waitcnt lgkmcnt(0)
	s_setprio 1

; #define PG8_STAGE(bufoff, gbase, voff) do { _Pragma("unroll") for (int _i = 0; _i < 2; ++_i) \
;         __builtin_amdgcn_global_load_lds((const unsigned*)((const char*)(gbase) + (voff)[_i]), (LAS unsigned*)(lds + (bufoff) + ldsw + _i * 8192), 16, 0, 0); } while (0)
; #define PG8_LDA(dst, b, h) do { _Pragma("unroll") for (int m = 0; m < 4; ++m) _Pragma("unroll") for (int k = 0; k < 2; ++k) dst[m][k] = *(const LAS bf16x8*)(lds + PG8_SA(b, h) + aoff + m * 2048 + k * 1024); } while (0)
; #define PG8_MMA(ai, bj, At, Bt) do { __builtin_amdgcn_s_setprio(1); _Pragma("unroll") for (int m = 0; m < 4; ++m) _Pragma("unroll") for (int n = 0; n < 2; ++n) _Pragma("unroll") for (int k = 0; k < 2; ++k) \
;         acc[ai][bj][m][n] = __builtin_amdgcn_mfma_f32_16x16x32_bf16(Bt[n][k], At[m][k], acc[ai][bj][m][n], 0, 0, 0); __builtin_amdgcn_s_setprio(0); } while (0)
; #define PG8_WAIT_L(n) asm volatile("s_waitcnt lgkmcnt(" #n ")" ::: "memory")
; #define PG8_BAR __builtin_amdgcn_s_barrier()
; #define PG8_SCHED __builtin_amdgcn_sched_barrier(0)
; template <class Epi>
; __device__ __forceinline__ void gemm_phase(LAS unsigned char* lds, const Gemm g, const StaticOrder& S, const Epi& E) {
;     ...
;             PG8_BAR; PG8_WAIT_L(0); PG8_MMA(0, 1, At, B1); PG8_BAR;
;             PG8_LDA(At, 0, 1); PG8_STAGE(PG8_SA(0, 0), a2, voffA);
;             PG8_BAR; PG8_WAIT_L(0); PG8_MMA(1, 0, At, B0); PG8_BAR; PG8_SCHED;
	v_mfma_f32_16x16x32_bf16 v[116:119], v[200:203], v[168:171], v[116:119]
	v_mfma_f32_16x16x32_bf16 v[108:111], v[208:211], v[168:171], v[108:111]
	v_mfma_f32_16x16x32_bf16 v[100:103], v[200:203], v[176:179], v[100:103]
	v_mfma_f32_16x16x32_bf16 v[96:99], v[208:211], v[176:179], v[96:99]
	v_mfma_f32_16x16x32_bf16 v[84:87], v[200:203], v[184:187], v[84:87]
	v_mfma_f32_16x16x32_bf16 v[76:79], v[208:211], v[184:187], v[76:79]
	v_mfma_f32_16x16x32_bf16 v[68:71], v[200:203], v[192:195], v[68:71]
	v_mfma_f32_16x16x32_bf16 v[64:67], v[208:211], v[192:195], v[64:67]
	v_mfma_f32_16x16x32_bf16 v[116:119], v[204:207], v[172:175], v[116:119]
	v_mfma_f32_16x16x32_bf16 v[108:111], v[212:215], v[172:175], v[108:111]
	v_mfma_f32_16x16x32_bf16 v[100:103], v[204:207], v[180:183], v[100:103]
	v_mfma_f32_16x16x32_bf16 v[96:99], v[212:215], v[180:183], v[96:99]
	v_mfma_f32_16x16x32_bf16 v[84:87], v[204:207], v[188:191], v[84:87]
	v_mfma_f32_16x16x32_bf16 v[76:79], v[212:215], v[188:191], v[76:79]
	v_mfma_f32_16x16x32_bf16 v[68:71], v[204:207], v[196:199], v[68:71]
	v_mfma_f32_16x16x32_bf16 v[64:67], v[212:215], v[196:199], v[64:67]
	s_setprio 0
	s_mov_b32 m0, s36
	v_lshl_add_u64 v[218:219], s[22:23], 0, v[128:129]
	s_barrier
	ds_read_b128 v[168:171], v154 offset:16384
	ds_read_b128 v[172:175], v154 offset:17408
	ds_read_b128 v[176:179], v154 offset:18432
	ds_read_b128 v[180:183], v154 offset:19456
	ds_read_b128 v[184:187], v154 offset:20480
	ds_read_b128 v[188:191], v154 offset:21504
	ds_read_b128 v[192:195], v154 offset:22528
	ds_read_b128 v[196:199], v154 offset:23552
	global_load_lds_dwordx4 v[218:219], off
	v_lshl_add_u64 v[220:221], s[22:23], 0, v[132:133]
	s_mov_b32 m0, s37
	s_nop 0
	global_load_lds_dwordx4 v[220:221], off
	s_barrier
	s_waitcnt lgkmcnt(0)
	s_setprio 1

; #define PG8_STAGE(bufoff, gbase, voff) do { _Pragma("unroll") for (int _i = 0; _i < 2; ++_i) \
;         __builtin_amdgcn_global_load_lds((const unsigned*)((const char*)(gbase) + (voff)[_i]), (LAS unsigned*)(lds + (bufoff) + ldsw + _i * 8192), 16, 0, 0); } while (0)
; #define PG8_LDA(dst, b, h) do { _Pragma("unroll") for (int m = 0; m < 4; ++m) _Pragma("unroll") for (int k = 0; k < 2; ++k) dst[m][k] = *(const LAS bf16x8*)(lds + PG8_SA(b, h) + aoff + m * 2048 + k * 1024); } while (0)
; #define PG8_LDB(dst, b, h) do { _Pragma("unroll") for (int n = 0; n < 2; ++n) _Pragma("unroll") for (int k = 0; k < 2; ++k) dst[n][k] = *(const LAS bf16x8*)(lds + PG8_SB(b, h) + boff + n * 2048 + k * 1024); } while (0)
; #define PG8_MMA(ai, bj, At, Bt) do { __builtin_amdgcn_s_setprio(1); _Pragma("unroll") for (int m = 0; m < 4; ++m) _Pragma("unroll") for (int n = 0; n < 2; ++n) _Pragma("unroll") for (int k = 0; k < 2; ++k) \
;         acc[ai][bj][m][n] = __builtin_amdgcn_mfma_f32_16x16x32_bf16(Bt[n][k], At[m][k], acc[ai][bj][m][n], 0, 0, 0); __builtin_amdgcn_s_setprio(0); } while (0)
; #define PG8_WAIT_V(n) asm volatile("s_waitcnt vmcnt(" #n ")" ::: "memory")
; #define PG8_WAIT_L(n) asm volatile("s_waitcnt lgkmcnt(" #n ")" ::: "memory")
; #define PG8_BAR __builtin_amdgcn_s_barrier()
; #define PG8_SCHED __builtin_amdgcn_sched_barrier(0)
; template <class Epi>
; __device__ __forceinline__ void gemm_phase(LAS unsigned char* lds, const Gemm g, const StaticOrder& S, const Epi& E) {
;     ...
;             PG8_BAR; PG8_WAIT_L(0); PG8_MMA(1, 0, At, B0); PG8_BAR; PG8_SCHED;
;             PG8_STAGE(PG8_SB(0, 1), b2 + hstep, voffB);
;             PG8_WAIT_V(6); PG8_BAR; PG8_MMA(1, 1, At, B1); PG8_BAR;
;             PG8_LDB(B0, 1, 0); PG8_SCHED; PG8_LDA(At, 1, 0); PG8_STAGE(PG8_SA(0, 1), a2 + hstep, voffA);
;             PG8_WAIT_L(8); PG8_BAR; PG8_WAIT_L(0); PG8_MMA(0, 0, At, B0); PG8_BAR; PG8_SCHED;
	v_mfma_f32_16x16x32_bf16 v[60:63], v[144:147], v[168:171], v[60:63]
	v_mfma_f32_16x16x32_bf16 v[56:59], v[160:163], v[168:171], v[56:59]
	v_mfma_f32_16x16x32_bf16 v[48:51], v[144:147], v[176:179], v[48:51]
	v_mfma_f32_16x16x32_bf16 v[40:43], v[160:163], v[176:179], v[40:43]
	v_mfma_f32_16x16x32_bf16 v[28:31], v[144:147], v[184:187], v[28:31]
	v_mfma_f32_16x16x32_bf16 v[24:27], v[160:163], v[184:187], v[24:27]
	v_mfma_f32_16x16x32_bf16 v[20:23], v[144:147], v[192:195], v[20:23]
	v_mfma_f32_16x16x32_bf16 v[12:15], v[160:163], v[192:195], v[12:15]
	v_mfma_f32_16x16x32_bf16 v[60:63], v[156:159], v[172:175], v[60:63]
	v_mfma_f32_16x16x32_bf16 v[56:59], v[164:167], v[172:175], v[56:59]
	v_mfma_f32_16x16x32_bf16 v[48:51], v[156:159], v[180:183], v[48:51]
	v_mfma_f32_16x16x32_bf16 v[40:43], v[164:167], v[180:183], v[40:43]
	v_mfma_f32_16x16x32_bf16 v[28:31], v[156:159], v[188:191], v[28:31]
	v_mfma_f32_16x16x32_bf16 v[24:27], v[164:167], v[188:191], v[24:27]
	v_mfma_f32_16x16x32_bf16 v[20:23], v[156:159], v[196:199], v[20:23]
	v_mfma_f32_16x16x32_bf16 v[12:15], v[164:167], v[196:199], v[12:15]
	s_setprio 0
	s_barrier
	s_add_u32 s66, s20, 0x158000
	s_addc_u32 s67, s21, 0
	s_add_i32 s65, s46, s35
	v_lshl_add_u64 v[144:145], s[66:67], 0, v[130:131]
	s_mov_b32 m0, s65
	s_nop 0
	global_load_lds_dwordx4 v[144:145], off
	v_lshl_add_u64 v[144:145], s[66:67], 0, v[134:135]
	s_add_i32 m0, s65, 0x2000
	s_nop 0
	global_load_lds_dwordx4 v[144:145], off
	s_waitcnt vmcnt(6)
	s_barrier
	s_setprio 1
	v_mfma_f32_16x16x32_bf16 v[52:55], v[200:203], v[168:171], v[52:55]
	v_mfma_f32_16x16x32_bf16 v[44:47], v[208:211], v[168:171], v[44:47]
	v_mfma_f32_16x16x32_bf16 v[36:39], v[200:203], v[176:179], v[36:39]
	v_mfma_f32_16x16x32_bf16 v[32:35], v[208:211], v[176:179], v[32:35]
	v_mfma_f32_16x16x32_bf16 v[16:19], v[200:203], v[184:187], v[16:19]
	v_mfma_f32_16x16x32_bf16 v[8:11], v[208:211], v[184:187], v[8:11]
	v_mfma_f32_16x16x32_bf16 v[4:7], v[200:203], v[192:195], v[4:7]
	v_mfma_f32_16x16x32_bf16 v[0:3], v[208:211], v[192:195], v[0:3]
	v_mfma_f32_16x16x32_bf16 v[52:55], v[204:207], v[172:175], v[52:55]
	v_mfma_f32_16x16x32_bf16 v[44:47], v[212:215], v[172:175], v[44:47]
	v_mfma_f32_16x16x32_bf16 v[36:39], v[204:207], v[180:183], v[36:39]
	v_mfma_f32_16x16x32_bf16 v[32:35], v[212:215], v[180:183], v[32:35]
	v_mfma_f32_16x16x32_bf16 v[16:19], v[204:207], v[188:191], v[16:19]
	v_mfma_f32_16x16x32_bf16 v[8:11], v[212:215], v[188:191], v[8:11]
	v_mfma_f32_16x16x32_bf16 v[4:7], v[204:207], v[196:199], v[4:7]
	v_mfma_f32_16x16x32_bf16 v[0:3], v[212:215], v[196:199], v[0:3]
	s_setprio 0
	s_add_i32 s65, 0, 0x18000
	v_add_u32_e32 v164, s65, v150
	s_barrier
	ds_read_b128 v[144:147], v164
	ds_read_b128 v[156:159], v164 offset:1024
	ds_read_b128 v[160:163], v164 offset:2048
	ds_read_b128 v[164:167], v164 offset:3072
	s_add_u32 s22, s22, 0x158000
	s_addc_u32 s23, s23, 0
	s_mov_b32 m0, s38
	v_lshl_add_u64 v[200:201], s[22:23], 0, v[128:129]
	ds_read_b128 v[168:171], v154 offset:32768
	ds_read_b128 v[172:175], v154 offset:33792
	ds_read_b128 v[176:179], v154 offset:34816
	ds_read_b128 v[180:183], v154 offset:35840
	ds_read_b128 v[184:187], v154 offset:36864
	ds_read_b128 v[188:191], v154 offset:37888
	ds_read_b128 v[192:195], v154 offset:38912
	ds_read_b128 v[196:199], v154 offset:39936
	global_load_lds_dwordx4 v[200:201], off
	v_lshl_add_u64 v[200:201], s[22:23], 0, v[132:133]
	s_mov_b32 m0, s39
	s_nop 0
	global_load_lds_dwordx4 v[200:201], off
	s_waitcnt lgkmcnt(8)
	s_barrier
	s_waitcnt lgkmcnt(0)
	s_setprio 1

; #define PG8_STAGE(bufoff, gbase, voff) do { _Pragma("unroll") for (int _i = 0; _i < 2; ++_i) \
;         __builtin_amdgcn_global_load_lds((const unsigned*)((const char*)(gbase) + (voff)[_i]), (LAS unsigned*)(lds + (bufoff) + ldsw + _i * 8192), 16, 0, 0); } while (0)
; #define PG8_LDB(dst, b, h) do { _Pragma("unroll") for (int n = 0; n < 2; ++n) _Pragma("unroll") for (int k = 0; k < 2; ++k) dst[n][k] = *(const LAS bf16x8*)(lds + PG8_SB(b, h) + boff + n * 2048 + k * 1024); } while (0)
; #define PG8_MMA(ai, bj, At, Bt) do { __builtin_amdgcn_s_setprio(1); _Pragma("unroll") for (int m = 0; m < 4; ++m) _Pragma("unroll") for (int n = 0; n < 2; ++n) _Pragma("unroll") for (int k = 0; k < 2; ++k) \
;         acc[ai][bj][m][n] = __builtin_amdgcn_mfma_f32_16x16x32_bf16(Bt[n][k], At[m][k], acc[ai][bj][m][n], 0, 0, 0); __builtin_amdgcn_s_setprio(0); } while (0)
; #define PG8_WAIT_L(n) asm volatile("s_waitcnt lgkmcnt(" #n ")" ::: "memory")
; #define PG8_BAR __builtin_amdgcn_s_barrier()
; #define PG8_SCHED __builtin_amdgcn_sched_barrier(0)
; template <class Epi>
; __device__ __forceinline__ void gemm_phase(LAS unsigned char* lds, const Gemm g, const StaticOrder& S, const Epi& E) {
;     ...
;             PG8_WAIT_L(8); PG8_BAR; PG8_WAIT_L(0); PG8_MMA(0, 0, At, B0); PG8_BAR; PG8_SCHED;
;             PG8_LDB(B1, 1, 1); PG8_STAGE(PG8_SB(1, 0), b3, voffB);
;             PG8_BAR; PG8_WAIT_L(0); PG8_MMA(0, 1, At, B1); PG8_BAR;
	v_mfma_f32_16x16x32_bf16 v[124:127], v[144:147], v[168:171], v[124:127]
	v_mfma_f32_16x16x32_bf16 v[120:123], v[160:163], v[168:171], v[120:123]
	v_mfma_f32_16x16x32_bf16 v[112:115], v[144:147], v[176:179], v[112:115]
	v_mfma_f32_16x16x32_bf16 v[104:107], v[160:163], v[176:179], v[104:107]
	v_mfma_f32_16x16x32_bf16 v[92:95], v[144:147], v[184:187], v[92:95]
	v_mfma_f32_16x16x32_bf16 v[88:91], v[160:163], v[184:187], v[88:91]
	v_mfma_f32_16x16x32_bf16 v[80:83], v[144:147], v[192:195], v[80:83]
	v_mfma_f32_16x16x32_bf16 v[72:75], v[160:163], v[192:195], v[72:75]
	v_mfma_f32_16x16x32_bf16 v[124:127], v[156:159], v[172:175], v[124:127]
	v_mfma_f32_16x16x32_bf16 v[120:123], v[164:167], v[172:175], v[120:123]
	v_mfma_f32_16x16x32_bf16 v[112:115], v[156:159], v[180:183], v[112:115]
	v_mfma_f32_16x16x32_bf16 v[104:107], v[164:167], v[180:183], v[104:107]
	v_mfma_f32_16x16x32_bf16 v[92:95], v[156:159], v[188:191], v[92:95]
	v_mfma_f32_16x16x32_bf16 v[88:91], v[164:167], v[188:191], v[88:91]
	v_mfma_f32_16x16x32_bf16 v[80:83], v[156:159], v[196:199], v[80:83]
	v_mfma_f32_16x16x32_bf16 v[72:75], v[164:167], v[196:199], v[72:75]
	s_setprio 0
	s_barrier
	s_add_i32 s22, 0, 0x1c000
	s_add_i32 s23, s65, s35
	v_add_u32_e32 v212, s22, v150
	v_lshl_add_u64 v[148:149], v[148:149], 0, s[8:9]
	s_mov_b32 m0, s23
	ds_read_b128 v[200:203], v212
	ds_read_b128 v[204:207], v212 offset:1024
	ds_read_b128 v[208:211], v212 offset:2048
	ds_read_b128 v[212:215], v212 offset:3072
	global_load_lds_dwordx4 v[148:149], off
	v_lshl_add_u64 v[148:149], v[216:217], 0, s[8:9]
	s_add_i32 m0, s23, 0x2000
	s_nop 0
	global_load_lds_dwordx4 v[148:149], off
	s_barrier
	s_waitcnt lgkmcnt(0)
	s_setprio 1

; #define PG8_STAGE(bufoff, gbase, voff) do { _Pragma("unroll") for (int _i = 0; _i < 2; ++_i) \
;         __builtin_amdgcn_global_load_lds((const unsigned*)((const char*)(gbase) + (voff)[_i]), (LAS unsigned*)(lds + (bufoff) + ldsw + _i * 8192), 16, 0, 0); } while (0)
; #define PG8_LDA(dst, b, h) do { _Pragma("unroll") for (int m = 0; m < 4; ++m) _Pragma("unroll") for (int k = 0; k < 2; ++k) dst[m][k] = *(const LAS bf16x8*)(lds + PG8_SA(b, h) + aoff + m * 2048 + k * 1024); } while (0)
; #define PG8_MMA(ai, bj, At, Bt) do { __builtin_amdgcn_s_setprio(1); _Pragma("unroll") for (int m = 0; m < 4; ++m) _Pragma("unroll") for (int n = 0; n < 2; ++n) _Pragma("unroll") for (int k = 0; k < 2; ++k) \
;         acc[ai][bj][m][n] = __builtin_amdgcn_mfma_f32_16x16x32_bf16(Bt[n][k], At[m][k], acc[ai][bj][m][n], 0, 0, 0); __builtin_amdgcn_s_setprio(0); } while (0)
; #define PG8_WAIT_L(n) asm volatile("s_waitcnt lgkmcnt(" #n ")" ::: "memory")
; #define PG8_BAR __builtin_amdgcn_s_barrier()
; #define PG8_SCHED __builtin_amdgcn_sched_barrier(0)
; template <class Epi>
; __device__ __forceinline__ void gemm_phase(LAS unsigned char* lds, const Gemm g, const StaticOrder& S, const Epi& E) {
;     ...
;             PG8_BAR; PG8_WAIT_L(0); PG8_MMA(0, 1, At, B1); PG8_BAR;
;             PG8_LDA(At, 1, 1); PG8_STAGE(PG8_SA(1, 0), a3, voffA);
;             PG8_BAR; PG8_WAIT_L(0); PG8_MMA(1, 0, At, B0); PG8_BAR; PG8_SCHED;
	v_mfma_f32_16x16x32_bf16 v[116:119], v[200:203], v[168:171], v[116:119]
	v_mfma_f32_16x16x32_bf16 v[108:111], v[208:211], v[168:171], v[108:111]
	v_mfma_f32_16x16x32_bf16 v[100:103], v[200:203], v[176:179], v[100:103]
	v_mfma_f32_16x16x32_bf16 v[96:99], v[208:211], v[176:179], v[96:99]
	v_mfma_f32_16x16x32_bf16 v[84:87], v[200:203], v[184:187], v[84:87]
	v_mfma_f32_16x16x32_bf16 v[76:79], v[208:211], v[184:187], v[76:79]
	v_mfma_f32_16x16x32_bf16 v[68:71], v[200:203], v[192:195], v[68:71]
	v_mfma_f32_16x16x32_bf16 v[64:67], v[208:211], v[192:195], v[64:67]
	v_mfma_f32_16x16x32_bf16 v[116:119], v[204:207], v[172:175], v[116:119]
	v_mfma_f32_16x16x32_bf16 v[108:111], v[212:215], v[172:175], v[108:111]
	v_mfma_f32_16x16x32_bf16 v[100:103], v[204:207], v[180:183], v[100:103]
	v_mfma_f32_16x16x32_bf16 v[96:99], v[212:215], v[180:183], v[96:99]
	v_mfma_f32_16x16x32_bf16 v[84:87], v[204:207], v[188:191], v[84:87]
	v_mfma_f32_16x16x32_bf16 v[76:79], v[212:215], v[188:191], v[76:79]
	v_mfma_f32_16x16x32_bf16 v[68:71], v[204:207], v[196:199], v[68:71]
	v_mfma_f32_16x16x32_bf16 v[64:67], v[212:215], v[196:199], v[64:67]
	s_setprio 0
	s_mov_b32 m0, s41
	v_lshl_add_u64 v[148:149], v[218:219], 0, s[8:9]
	s_barrier
	ds_read_b128 v[168:171], v154 offset:49152
	ds_read_b128 v[172:175], v154 offset:50176
	ds_read_b128 v[176:179], v154 offset:51200
	ds_read_b128 v[180:183], v154 offset:52224
	ds_read_b128 v[184:187], v154 offset:53248
	ds_read_b128 v[188:191], v154 offset:54272
	ds_read_b128 v[192:195], v154 offset:55296
	ds_read_b128 v[196:199], v154 offset:56320
	global_load_lds_dwordx4 v[148:149], off
	v_lshl_add_u64 v[148:149], v[220:221], 0, s[8:9]
	s_mov_b32 m0, s42
	s_nop 0
	global_load_lds_dwordx4 v[148:149], off
	s_barrier
	s_waitcnt lgkmcnt(0)
	s_setprio 1

; __device__ __forceinline__ float bflo(unsigned w) { return __uint_as_float(w << 16); }
; __device__ __forceinline__ float bfhi(unsigned w) { return __uint_as_float(w & 0xffff0000u); }
; #define PG8_STAGE(bufoff, gbase, voff) do { _Pragma("unroll") for (int _i = 0; _i < 2; ++_i) \
;         __builtin_amdgcn_global_load_lds((const unsigned*)((const char*)(gbase) + (voff)[_i]), (LAS unsigned*)(lds + (bufoff) + ldsw + _i * 8192), 16, 0, 0); } while (0)
; #define PG8_MMA(ai, bj, At, Bt) do { __builtin_amdgcn_s_setprio(1); _Pragma("unroll") for (int m = 0; m < 4; ++m) _Pragma("unroll") for (int n = 0; n < 2; ++n) _Pragma("unroll") for (int k = 0; k < 2; ++k) \
;         acc[ai][bj][m][n] = __builtin_amdgcn_mfma_f32_16x16x32_bf16(Bt[n][k], At[m][k], acc[ai][bj][m][n], 0, 0, 0); __builtin_amdgcn_s_setprio(0); } while (0)
; #define PG8_WAIT_V(n) asm volatile("s_waitcnt vmcnt(" #n ")" ::: "memory")
; #define PG8_WAIT_L(n) asm volatile("s_waitcnt lgkmcnt(" #n ")" ::: "memory")
; template <class Epi>
; __device__ __forceinline__ void gemm_phase(LAS unsigned char* lds, const Gemm g, const StaticOrder& S, const Epi& E) {
;     ...
;             PG8_BAR; PG8_WAIT_L(0); PG8_MMA(1, 0, At, B0); PG8_BAR; PG8_SCHED;
;             PG8_STAGE(PG8_SB(1, 1), b3 + hstep, voffB);
;             PG8_WAIT_V(6); PG8_BAR; PG8_MMA(1, 1, At, B1); PG8_BAR;
;         }
;     __device__ __forceinline__ void operator()(const f32x4 (&acc)[2][2][4][2], const Unit& u, int wr, int wc, int fr, int fq, const Pre&) const {
;         const int row0 = ROW_X + u.pm * BM + wr * 64 + fr, col0 = u.pn * BM + wc * 32 + 8 * fq;
;         u32x4 hv[2][2]; float sprev = 0.f;
;     ...
;         ER_LOAD(0, 0);
; #pragma unroll
;         for (int g = 0; g < 8; ++g) { const int ai = g >> 2, m = g & 3; const int r = row0 + ai * HALF + m * 16; const size_t off = (size_t)r * DM + col0; float s = 0.f;
;             if (g + 1 < 8) ER_LOAD(g + 1, (g + 1) & 1);
; #pragma unroll
;             for (int bj = 0; bj < 2; ++bj) { const u32x4 w = hv[g & 1][bj];
;                 const f32x4 h0 = {bflo(w.x), bfhi(w.x), bflo(w.y), bfhi(w.y)}, h1 = {bflo(w.z), bfhi(w.z), bflo(w.w), bfhi(w.w)};
;                 const f32x4 o0 = h0 + acc[ai][bj][m][0] * alpha, o1 = h1 + acc[ai][bj][m][1] * alpha;
;                 if (FINAL) { float* op = OUT + (size_t)(r - ROW_X) * DM + col0 + bj * HALF; *(f32x4*)op = o0; *(f32x4*)(op + 4) = o1; }
	v_mfma_f32_16x16x32_bf16 v[60:63], v[144:147], v[168:171], v[60:63]
	v_mfma_f32_16x16x32_bf16 v[56:59], v[160:163], v[168:171], v[56:59]
	v_mfma_f32_16x16x32_bf16 v[48:51], v[144:147], v[176:179], v[48:51]
	v_mfma_f32_16x16x32_bf16 v[40:43], v[160:163], v[176:179], v[40:43]
	v_mfma_f32_16x16x32_bf16 v[28:31], v[144:147], v[184:187], v[28:31]
	v_mfma_f32_16x16x32_bf16 v[24:27], v[160:163], v[184:187], v[24:27]
	v_mfma_f32_16x16x32_bf16 v[20:23], v[144:147], v[192:195], v[20:23]
	v_mfma_f32_16x16x32_bf16 v[12:15], v[160:163], v[192:195], v[12:15]
	v_mfma_f32_16x16x32_bf16 v[60:63], v[156:159], v[172:175], v[60:63]
	v_mfma_f32_16x16x32_bf16 v[56:59], v[164:167], v[172:175], v[56:59]
	v_mfma_f32_16x16x32_bf16 v[48:51], v[156:159], v[180:183], v[48:51]
	v_mfma_f32_16x16x32_bf16 v[40:43], v[164:167], v[180:183], v[40:43]
	v_mfma_f32_16x16x32_bf16 v[28:31], v[156:159], v[188:191], v[28:31]
	v_mfma_f32_16x16x32_bf16 v[24:27], v[164:167], v[188:191], v[24:27]
	v_mfma_f32_16x16x32_bf16 v[20:23], v[156:159], v[196:199], v[20:23]
	v_mfma_f32_16x16x32_bf16 v[12:15], v[164:167], v[196:199], v[12:15]
	s_setprio 0
	s_barrier
	s_add_u32 s20, s20, 0x158080
	s_addc_u32 s21, s21, 0
	s_add_i32 s22, s22, s35
	v_lshl_add_u64 v[144:145], s[20:21], 0, v[130:131]
	s_mov_b32 m0, s22
	s_nop 0
	global_load_lds_dwordx4 v[144:145], off
	v_lshl_add_u64 v[144:145], s[20:21], 0, v[134:135]
	s_add_i32 m0, s22, 0x2000
	s_nop 0
	global_load_lds_dwordx4 v[144:145], off
	s_waitcnt vmcnt(6)
	s_barrier
	s_setprio 1
	v_mfma_f32_16x16x32_bf16 v[52:55], v[200:203], v[168:171], v[52:55]
	v_mfma_f32_16x16x32_bf16 v[44:47], v[208:211], v[168:171], v[44:47]
	v_mfma_f32_16x16x32_bf16 v[36:39], v[200:203], v[176:179], v[36:39]
	v_mfma_f32_16x16x32_bf16 v[32:35], v[208:211], v[176:179], v[32:35]
	v_mfma_f32_16x16x32_bf16 v[16:19], v[200:203], v[184:187], v[16:19]
	v_mfma_f32_16x16x32_bf16 v[8:11], v[208:211], v[184:187], v[8:11]
	v_mfma_f32_16x16x32_bf16 v[4:7], v[200:203], v[192:195], v[4:7]
	v_mfma_f32_16x16x32_bf16 v[0:3], v[208:211], v[192:195], v[0:3]
	v_mfma_f32_16x16x32_bf16 v[52:55], v[204:207], v[172:175], v[52:55]
	v_mfma_f32_16x16x32_bf16 v[44:47], v[212:215], v[172:175], v[44:47]
	v_mfma_f32_16x16x32_bf16 v[36:39], v[204:207], v[180:183], v[36:39]
	v_mfma_f32_16x16x32_bf16 v[32:35], v[212:215], v[180:183], v[32:35]
	v_mfma_f32_16x16x32_bf16 v[16:19], v[204:207], v[188:191], v[16:19]
	v_mfma_f32_16x16x32_bf16 v[8:11], v[212:215], v[188:191], v[8:11]
	v_mfma_f32_16x16x32_bf16 v[4:7], v[204:207], v[196:199], v[4:7]
	v_mfma_f32_16x16x32_bf16 v[0:3], v[212:215], v[196:199], v[0:3]
	s_setprio 0
	s_add_i32 s64, s64, 2
	s_add_u32 s18, s18, 0x100
	s_addc_u32 s19, s19, 0
	s_add_u32 s62, s62, 0x100
	s_addc_u32 s63, s63, 0
	s_cmpk_gt_u32 s64, 0x53
	s_barrier
	s_cbranch_scc0 .LBB0_2626
	v_lshl_add_u32 v144, s60, 8, v151
	v_lshl_or_b32 v148, s61, 8, v152
	v_ashrrev_i32_e32 v145, 31, v144
	v_ashrrev_i32_e32 v149, 31, v148
	v_lshlrev_b64 v[146:147], 12, v[144:145]
	v_or_b32_e32 v164, 16, v144
	v_lshl_add_u64 v[146:147], s[6:7], 0, v[146:147]
	v_lshlrev_b64 v[172:173], 1, v[148:149]
	v_ashrrev_i32_e32 v165, 31, v164
	v_lshl_add_u64 v[146:147], v[146:147], 0, v[172:173]
	v_lshlrev_b64 v[164:165], 12, v[164:165]
	global_load_dwordx4 v[156:159], v[146:147], off
	global_load_dwordx4 v[160:163], v[146:147], off offset:256
	v_lshl_add_u64 v[164:165], s[6:7], 0, v[164:165]
	v_lshl_add_u64 v[168:169], v[164:165], 0, v[172:173]
	global_load_dwordx4 v[164:167], v[168:169], off
	s_nop 0
	global_load_dwordx4 v[168:171], v[168:169], off offset:256
	v_or_b32_e32 v176, 32, v144
	v_or_b32_e32 v180, 48, v144
	v_add_u32_e32 v174, 0xffffff00, v144
	v_ashrrev_i32_e32 v177, 31, v176
	v_ashrrev_i32_e32 v181, 31, v180
	v_ashrrev_i32_e32 v175, 31, v174
	v_lshlrev_b64 v[176:177], 12, v[176:177]
	v_lshlrev_b64 v[180:181], 12, v[180:181]
	v_add_u32_e32 v178, 0xffffff10, v144
	v_lshlrev_b64 v[174:175], 13, v[174:175]
	v_lshl_add_u64 v[176:177], s[6:7], 0, v[176:177]
	v_lshl_add_u64 v[180:181], s[6:7], 0, v[180:181]
	v_lshlrev_b64 v[148:149], 2, v[148:149]
	v_ashrrev_i32_e32 v179, 31, v178
	v_lshl_add_u64 v[174:175], s[48:49], 0, v[174:175]
	v_lshl_add_u64 v[176:177], v[176:177], 0, v[172:173]
	v_lshl_add_u64 v[172:173], v[180:181], 0, v[172:173]
	v_lshlrev_b64 v[178:179], 13, v[178:179]
	v_lshl_add_u64 v[174:175], v[174:175], 0, v[148:149]
	v_lshl_add_u64 v[178:179], s[48:49], 0, v[178:179]
	v_lshl_add_u64 v[178:179], v[178:179], 0, v[148:149]
	s_mov_b32 s60, s59
	s_mov_b32 s61, s58
	s_mov_b64 s[20:21], s[4:5]
	s_mov_b64 s[18:19], s[0:1]
	s_waitcnt vmcnt(0)
; __device__ __forceinline__ float bflo(unsigned w) { return __uint_as_float(w << 16); }
; __device__ __forceinline__ float bfhi(unsigned w) { return __uint_as_float(w & 0xffff0000u); }
; #define ER_LOAD(g_, set_) do { const size_t off_ = (size_t)(row0 + ((g_) >> 2) * HALF + ((g_) & 3) * 16) * DM + col0; \
;         hv[set_][0] = *(const u32x4*)(HB + off_); hv[set_][1] = *(const u32x4*)(HB + off_ + HALF); } while (0)
;     __device__ __forceinline__ void operator()(const f32x4 (&acc)[2][2][4][2], const Unit& u, int wr, int wc, int fr, int fq, const Pre&) const {
;     ...
;         for (int g = 0; g < 8; ++g) { const int ai = g >> 2, m = g & 3; const int r = row0 + ai * HALF + m * 16; const size_t off = (size_t)r * DM + col0; float s = 0.f;
;             if (g + 1 < 8) ER_LOAD(g + 1, (g + 1) & 1);
; #pragma unroll
;             for (int bj = 0; bj < 2; ++bj) { const u32x4 w = hv[g & 1][bj];
;                 const f32x4 h0 = {bflo(w.x), bfhi(w.x), bflo(w.y), bfhi(w.y)}, h1 = {bflo(w.z), bfhi(w.z), bflo(w.w), bfhi(w.w)};
;                 const f32x4 o0 = h0 + acc[ai][bj][m][0] * alpha, o1 = h1 + acc[ai][bj][m][1] * alpha;
;                 if (FINAL) { float* op = OUT + (size_t)(r - ROW_X) * DM + col0 + bj * HALF; *(f32x4*)op = o0; *(f32x4*)(op + 4) = o1; }
	v_lshlrev_b32_e32 v180, 16, v156
	v_and_b32_e32 v181, 0xffff0000, v156
	v_lshlrev_b32_e32 v156, 16, v157
	v_and_b32_e32 v157, 0xffff0000, v157
	v_lshlrev_b32_e32 v182, 16, v158
	v_and_b32_e32 v183, 0xffff0000, v158
	v_lshlrev_b32_e32 v158, 16, v159
	v_and_b32_e32 v159, 0xffff0000, v159
	v_lshlrev_b32_e32 v184, 16, v160
	v_and_b32_e32 v185, 0xffff0000, v160
	v_lshlrev_b32_e32 v160, 16, v161
	v_and_b32_e32 v161, 0xffff0000, v161
	v_lshlrev_b32_e32 v186, 16, v162
	v_and_b32_e32 v187, 0xffff0000, v162
	v_lshlrev_b32_e32 v162, 16, v163
	v_and_b32_e32 v163, 0xffff0000, v163
	v_pk_fma_f32 v[126:127], v[126:127], 0.5, v[156:157] op_sel_hi:[1,0,1]
	v_pk_fma_f32 v[124:125], v[124:125], 0.5, v[180:181] op_sel_hi:[1,0,1]
	v_pk_fma_f32 v[122:123], v[122:123], 0.5, v[158:159] op_sel_hi:[1,0,1]
	v_pk_fma_f32 v[120:121], v[120:121], 0.5, v[182:183] op_sel_hi:[1,0,1]
	v_pk_fma_f32 v[118:119], v[118:119], 0.5, v[160:161] op_sel_hi:[1,0,1]
	v_pk_fma_f32 v[116:117], v[116:117], 0.5, v[184:185] op_sel_hi:[1,0,1]
	v_pk_fma_f32 v[110:111], v[110:111], 0.5, v[162:163] op_sel_hi:[1,0,1]
	v_pk_fma_f32 v[108:109], v[108:109], 0.5, v[186:187] op_sel_hi:[1,0,1]
	v_lshlrev_b32_e32 v156, 16, v164
	v_and_b32_e32 v157, 0xffff0000, v164
	v_lshlrev_b32_e32 v158, 16, v165
	v_and_b32_e32 v159, 0xffff0000, v165
	global_store_dwordx4 v[174:175], v[124:127], off
	global_store_dwordx4 v[174:175], v[120:123], off offset:16
	global_store_dwordx4 v[174:175], v[116:119], off offset:512
	global_store_dwordx4 v[174:175], v[108:111], off offset:528
	v_lshlrev_b32_e32 v160, 16, v166
	v_and_b32_e32 v161, 0xffff0000, v166
	global_load_dwordx4 v[108:111], v[176:177], off
	global_load_dwordx4 v[116:119], v[176:177], off offset:256
	v_lshlrev_b32_e32 v120, 16, v167
	v_and_b32_e32 v121, 0xffff0000, v167
	v_lshlrev_b32_e32 v122, 16, v168
	v_and_b32_e32 v123, 0xffff0000, v168
	v_lshlrev_b32_e32 v124, 16, v169
	v_and_b32_e32 v125, 0xffff0000, v169
	v_lshlrev_b32_e32 v126, 16, v170
	v_and_b32_e32 v127, 0xffff0000, v170
	v_lshlrev_b32_e32 v162, 16, v171
	v_and_b32_e32 v163, 0xffff0000, v171
	v_pk_fma_f32 v[114:115], v[114:115], 0.5, v[158:159] op_sel_hi:[1,0,1]
	v_pk_fma_f32 v[112:113], v[112:113], 0.5, v[156:157] op_sel_hi:[1,0,1]
	v_pk_fma_f32 v[106:107], v[106:107], 0.5, v[120:121] op_sel_hi:[1,0,1]
	v_pk_fma_f32 v[104:105], v[104:105], 0.5, v[160:161] op_sel_hi:[1,0,1]
	v_pk_fma_f32 v[102:103], v[102:103], 0.5, v[124:125] op_sel_hi:[1,0,1]
	v_pk_fma_f32 v[100:101], v[100:101], 0.5, v[122:123] op_sel_hi:[1,0,1]
	v_pk_fma_f32 v[98:99], v[98:99], 0.5, v[162:163] op_sel_hi:[1,0,1]
	v_pk_fma_f32 v[96:97], v[96:97], 0.5, v[126:127] op_sel_hi:[1,0,1]
	global_store_dwordx4 v[178:179], v[112:115], off
	global_store_dwordx4 v[178:179], v[104:107], off offset:16
	global_store_dwordx4 v[178:179], v[100:103], off offset:512
	global_store_dwordx4 v[178:179], v[96:99], off offset:528
	global_load_dwordx4 v[96:99], v[172:173], off
	s_nop 0
	global_load_dwordx4 v[100:103], v[172:173], off offset:256
	v_add_u32_e32 v104, 0xffffff20, v144
	v_add_u32_e32 v106, 0xffffff30, v144
	v_ashrrev_i32_e32 v105, 31, v104
	v_ashrrev_i32_e32 v107, 31, v106
	v_lshlrev_b64 v[104:105], 13, v[104:105]
	v_lshlrev_b64 v[106:107], 13, v[106:107]
	v_lshl_add_u64 v[104:105], s[48:49], 0, v[104:105]
	v_add_co_u32_e32 v114, vcc, s47, v146
	v_lshl_add_u64 v[106:107], s[48:49], 0, v[106:107]
	v_lshl_add_u64 v[104:105], v[104:105], 0, v[148:149]
	v_addc_co_u32_e32 v115, vcc, 0, v147, vcc
	v_lshl_add_u64 v[112:113], v[146:147], 0, s[10:11]
	v_lshl_add_u64 v[106:107], v[106:107], 0, v[148:149]
	v_add_co_u32_e32 v120, vcc, s52, v146
	s_waitcnt vmcnt(0)
	v_lshlrev_b32_e32 v122, 16, v108
	v_and_b32_e32 v123, 0xffff0000, v108
	v_lshlrev_b32_e32 v108, 16, v109
	v_and_b32_e32 v109, 0xffff0000, v109
	v_lshlrev_b32_e32 v124, 16, v110
	v_and_b32_e32 v125, 0xffff0000, v110
	v_lshlrev_b32_e32 v110, 16, v111
	v_and_b32_e32 v111, 0xffff0000, v111
	v_lshlrev_b32_e32 v126, 16, v116
	v_and_b32_e32 v127, 0xffff0000, v116
	v_lshlrev_b32_e32 v116, 16, v117
	v_and_b32_e32 v117, 0xffff0000, v117
	v_lshlrev_b32_e32 v156, 16, v118
	v_and_b32_e32 v157, 0xffff0000, v118
	v_lshlrev_b32_e32 v118, 16, v119
	v_and_b32_e32 v119, 0xffff0000, v119
	v_pk_fma_f32 v[94:95], v[94:95], 0.5, v[108:109] op_sel_hi:[1,0,1]
	v_pk_fma_f32 v[92:93], v[92:93], 0.5, v[122:123] op_sel_hi:[1,0,1]
	v_pk_fma_f32 v[90:91], v[90:91], 0.5, v[110:111] op_sel_hi:[1,0,1]
	v_pk_fma_f32 v[88:89], v[88:89], 0.5, v[124:125] op_sel_hi:[1,0,1]
	v_lshlrev_b32_e32 v108, 16, v96
	v_and_b32_e32 v109, 0xffff0000, v96
	v_lshlrev_b32_e32 v96, 16, v97
	v_and_b32_e32 v97, 0xffff0000, v97
	v_pk_fma_f32 v[86:87], v[86:87], 0.5, v[116:117] op_sel_hi:[1,0,1]
	v_pk_fma_f32 v[84:85], v[84:85], 0.5, v[126:127] op_sel_hi:[1,0,1]
	v_pk_fma_f32 v[78:79], v[78:79], 0.5, v[118:119] op_sel_hi:[1,0,1]
	v_pk_fma_f32 v[76:77], v[76:77], 0.5, v[156:157] op_sel_hi:[1,0,1]
	v_lshlrev_b32_e32 v110, 16, v98
	v_and_b32_e32 v111, 0xffff0000, v98
	global_store_dwordx4 v[104:105], v[92:95], off
	global_store_dwordx4 v[104:105], v[88:91], off offset:16
	global_store_dwordx4 v[104:105], v[84:87], off offset:512
	global_store_dwordx4 v[104:105], v[76:79], off offset:528
	v_lshlrev_b32_e32 v88, 16, v99
	v_and_b32_e32 v89, 0xffff0000, v99
	v_lshlrev_b32_e32 v90, 16, v100
	v_and_b32_e32 v91, 0xffff0000, v100
	v_lshlrev_b32_e32 v92, 16, v101
	v_and_b32_e32 v93, 0xffff0000, v101
	v_lshlrev_b32_e32 v94, 16, v102
	v_and_b32_e32 v95, 0xffff0000, v102
	v_lshlrev_b32_e32 v98, 16, v103
	v_and_b32_e32 v99, 0xffff0000, v103
	v_pk_fma_f32 v[82:83], v[82:83], 0.5, v[96:97] op_sel_hi:[1,0,1]
	v_pk_fma_f32 v[80:81], v[80:81], 0.5, v[108:109] op_sel_hi:[1,0,1]
; __device__ __forceinline__ float bflo(unsigned w) { return __uint_as_float(w << 16); }
; __device__ __forceinline__ float bfhi(unsigned w) { return __uint_as_float(w & 0xffff0000u); }
; #define ER_LOAD(g_, set_) do { const size_t off_ = (size_t)(row0 + ((g_) >> 2) * HALF + ((g_) & 3) * 16) * DM + col0; \
;         hv[set_][0] = *(const u32x4*)(HB + off_); hv[set_][1] = *(const u32x4*)(HB + off_ + HALF); } while (0)
;     __device__ __forceinline__ void operator()(const f32x4 (&acc)[2][2][4][2], const Unit& u, int wr, int wc, int fr, int fq, const Pre&) const {
;     ...
;         for (int g = 0; g < 8; ++g) { const int ai = g >> 2, m = g & 3; const int r = row0 + ai * HALF + m * 16; const size_t off = (size_t)r * DM + col0; float s = 0.f;
;             if (g + 1 < 8) ER_LOAD(g + 1, (g + 1) & 1);
; #pragma unroll
;             for (int bj = 0; bj < 2; ++bj) { const u32x4 w = hv[g & 1][bj];
;                 const f32x4 h0 = {bflo(w.x), bfhi(w.x), bflo(w.y), bfhi(w.y)}, h1 = {bflo(w.z), bfhi(w.z), bflo(w.w), bfhi(w.w)};
;                 const f32x4 o0 = h0 + acc[ai][bj][m][0] * alpha, o1 = h1 + acc[ai][bj][m][1] * alpha;
;                 if (FINAL) { float* op = OUT + (size_t)(r - ROW_X) * DM + col0 + bj * HALF; *(f32x4*)op = o0; *(f32x4*)(op + 4) = o1; }
	v_addc_co_u32_e32 v121, vcc, 0, v147, vcc
	global_load_dwordx4 v[76:79], v[114:115], off
	global_load_dwordx4 v[84:87], v[112:113], off offset:256
	v_pk_fma_f32 v[74:75], v[74:75], 0.5, v[88:89] op_sel_hi:[1,0,1]
	v_pk_fma_f32 v[72:73], v[72:73], 0.5, v[110:111] op_sel_hi:[1,0,1]
	v_pk_fma_f32 v[70:71], v[70:71], 0.5, v[92:93] op_sel_hi:[1,0,1]
	v_pk_fma_f32 v[68:69], v[68:69], 0.5, v[90:91] op_sel_hi:[1,0,1]
	v_pk_fma_f32 v[66:67], v[66:67], 0.5, v[98:99] op_sel_hi:[1,0,1]
	v_pk_fma_f32 v[64:65], v[64:65], 0.5, v[94:95] op_sel_hi:[1,0,1]
	global_store_dwordx4 v[106:107], v[80:83], off
	global_store_dwordx4 v[106:107], v[72:75], off offset:16
	global_store_dwordx4 v[106:107], v[68:71], off offset:512
	global_store_dwordx4 v[106:107], v[64:67], off offset:528
	global_load_dwordx4 v[64:67], v[120:121], off
	v_lshl_add_u64 v[68:69], v[146:147], 0, s[12:13]
	global_load_dwordx4 v[68:71], v[68:69], off offset:256
	v_add_u32_e32 v72, 0xffffff80, v144
	v_add_u32_e32 v74, 0xffffff90, v144
	v_ashrrev_i32_e32 v73, 31, v72
	v_ashrrev_i32_e32 v75, 31, v74
	v_lshlrev_b64 v[72:73], 13, v[72:73]
	v_lshlrev_b64 v[74:75], 13, v[74:75]
	v_lshl_add_u64 v[72:73], s[48:49], 0, v[72:73]
	v_add_co_u32_e32 v82, vcc, s56, v146
	v_lshl_add_u64 v[74:75], s[48:49], 0, v[74:75]
	v_lshl_add_u64 v[72:73], v[72:73], 0, v[148:149]
	v_addc_co_u32_e32 v83, vcc, 0, v147, vcc
	v_lshl_add_u64 v[80:81], v[146:147], 0, s[14:15]
	v_lshl_add_u64 v[74:75], v[74:75], 0, v[148:149]
	v_add_co_u32_e32 v88, vcc, s57, v146
	s_waitcnt vmcnt(0)
	v_lshlrev_b32_e32 v90, 16, v76
	v_and_b32_e32 v91, 0xffff0000, v76
	v_lshlrev_b32_e32 v76, 16, v77
	v_and_b32_e32 v77, 0xffff0000, v77
	v_lshlrev_b32_e32 v92, 16, v78
	v_and_b32_e32 v93, 0xffff0000, v78
	v_lshlrev_b32_e32 v78, 16, v79
	v_and_b32_e32 v79, 0xffff0000, v79
	v_lshlrev_b32_e32 v94, 16, v84
	v_and_b32_e32 v95, 0xffff0000, v84
	v_lshlrev_b32_e32 v84, 16, v85
	v_and_b32_e32 v85, 0xffff0000, v85
	v_lshlrev_b32_e32 v96, 16, v86
	v_and_b32_e32 v97, 0xffff0000, v86
	v_lshlrev_b32_e32 v86, 16, v87
	v_and_b32_e32 v87, 0xffff0000, v87
	v_pk_fma_f32 v[62:63], v[62:63], 0.5, v[76:77] op_sel_hi:[1,0,1]
	v_pk_fma_f32 v[60:61], v[60:61], 0.5, v[90:91] op_sel_hi:[1,0,1]
	v_pk_fma_f32 v[58:59], v[58:59], 0.5, v[78:79] op_sel_hi:[1,0,1]
	v_pk_fma_f32 v[56:57], v[56:57], 0.5, v[92:93] op_sel_hi:[1,0,1]
	v_lshlrev_b32_e32 v76, 16, v64
	v_and_b32_e32 v77, 0xffff0000, v64
	v_lshlrev_b32_e32 v64, 16, v65
	v_and_b32_e32 v65, 0xffff0000, v65
	v_pk_fma_f32 v[54:55], v[54:55], 0.5, v[84:85] op_sel_hi:[1,0,1]
	v_pk_fma_f32 v[52:53], v[52:53], 0.5, v[94:95] op_sel_hi:[1,0,1]
	v_pk_fma_f32 v[46:47], v[46:47], 0.5, v[86:87] op_sel_hi:[1,0,1]
	v_pk_fma_f32 v[44:45], v[44:45], 0.5, v[96:97] op_sel_hi:[1,0,1]
	v_lshlrev_b32_e32 v78, 16, v66
	v_and_b32_e32 v79, 0xffff0000, v66
	global_store_dwordx4 v[72:73], v[60:63], off
	global_store_dwordx4 v[72:73], v[56:59], off offset:16
	global_store_dwordx4 v[72:73], v[52:55], off offset:512
	global_store_dwordx4 v[72:73], v[44:47], off offset:528
	v_lshlrev_b32_e32 v56, 16, v67
	v_and_b32_e32 v57, 0xffff0000, v67
	v_lshlrev_b32_e32 v58, 16, v68
	v_and_b32_e32 v59, 0xffff0000, v68
	v_lshlrev_b32_e32 v60, 16, v69
	v_and_b32_e32 v61, 0xffff0000, v69
	v_lshlrev_b32_e32 v62, 16, v70
	v_and_b32_e32 v63, 0xffff0000, v70
	v_lshlrev_b32_e32 v66, 16, v71
	v_and_b32_e32 v67, 0xffff0000, v71
	v_pk_fma_f32 v[50:51], v[50:51], 0.5, v[64:65] op_sel_hi:[1,0,1]
	v_pk_fma_f32 v[48:49], v[48:49], 0.5, v[76:77] op_sel_hi:[1,0,1]
	v_addc_co_u32_e32 v89, vcc, 0, v147, vcc
	global_load_dwordx4 v[44:47], v[82:83], off
	global_load_dwordx4 v[52:55], v[80:81], off offset:256
	v_pk_fma_f32 v[42:43], v[42:43], 0.5, v[56:57] op_sel_hi:[1,0,1]
	v_pk_fma_f32 v[40:41], v[40:41], 0.5, v[78:79] op_sel_hi:[1,0,1]
	v_pk_fma_f32 v[38:39], v[38:39], 0.5, v[60:61] op_sel_hi:[1,0,1]
	v_pk_fma_f32 v[36:37], v[36:37], 0.5, v[58:59] op_sel_hi:[1,0,1]
	v_pk_fma_f32 v[34:35], v[34:35], 0.5, v[66:67] op_sel_hi:[1,0,1]
	v_pk_fma_f32 v[32:33], v[32:33], 0.5, v[62:63] op_sel_hi:[1,0,1]
	global_store_dwordx4 v[74:75], v[48:51], off
	global_store_dwordx4 v[74:75], v[40:43], off offset:16
	global_store_dwordx4 v[74:75], v[36:39], off offset:512
	global_store_dwordx4 v[74:75], v[32:35], off offset:528
	global_load_dwordx4 v[32:35], v[88:89], off
	v_lshl_add_u64 v[36:37], v[146:147], 0, s[16:17]
	global_load_dwordx4 v[36:39], v[36:37], off offset:256
	v_add_u32_e32 v40, 0xffffffa0, v144
	v_add_u32_e32 v42, 0xffffffb0, v144
	v_ashrrev_i32_e32 v41, 31, v40
	v_ashrrev_i32_e32 v43, 31, v42
	v_lshlrev_b64 v[40:41], 13, v[40:41]
	v_lshlrev_b64 v[42:43], 13, v[42:43]
	v_lshl_add_u64 v[40:41], s[48:49], 0, v[40:41]
	v_lshl_add_u64 v[42:43], s[48:49], 0, v[42:43]
	v_lshl_add_u64 v[40:41], v[40:41], 0, v[148:149]
	s_and_b64 vcc, exec, s[2:3]
	v_lshl_add_u64 v[42:43], v[42:43], 0, v[148:149]
	s_waitcnt vmcnt(0)
; __device__ __forceinline__ float bflo(unsigned w) { return __uint_as_float(w << 16); }
; __device__ __forceinline__ float bfhi(unsigned w) { return __uint_as_float(w & 0xffff0000u); }
; #define PG8_WAIT_V(n) asm volatile("s_waitcnt vmcnt(" #n ")" ::: "memory")
; #define PG8_BAR __builtin_amdgcn_s_barrier()
; #define ER_LOAD(g_, set_) do { const size_t off_ = (size_t)(row0 + ((g_) >> 2) * HALF + ((g_) & 3) * 16) * DM + col0; \
;         hv[set_][0] = *(const u32x4*)(HB + off_); hv[set_][1] = *(const u32x4*)(HB + off_ + HALF); } while (0)
; template <class Epi>
; __device__ __forceinline__ void gemm_phase(LAS unsigned char* lds, const Gemm g, const StaticOrder& S, const Epi& E) {
;     ...
;     PG8_WAIT_V(0);
;     if (wr == 0) PG8_BAR;
;     __device__ __forceinline__ void operator()(const f32x4 (&acc)[2][2][4][2], const Unit& u, int wr, int wc, int fr, int fq, const Pre&) const {
;     ...
;         for (int g = 0; g < 8; ++g) { const int ai = g >> 2, m = g & 3; const int r = row0 + ai * HALF + m * 16; const size_t off = (size_t)r * DM + col0; float s = 0.f;
;             if (g + 1 < 8) ER_LOAD(g + 1, (g + 1) & 1);
; #pragma unroll
;             for (int bj = 0; bj < 2; ++bj) { const u32x4 w = hv[g & 1][bj];
;                 const f32x4 h0 = {bflo(w.x), bfhi(w.x), bflo(w.y), bfhi(w.y)}, h1 = {bflo(w.z), bfhi(w.z), bflo(w.w), bfhi(w.w)};
;                 const f32x4 o0 = h0 + acc[ai][bj][m][0] * alpha, o1 = h1 + acc[ai][bj][m][1] * alpha;
;                 if (FINAL) { float* op = OUT + (size_t)(r - ROW_X) * DM + col0 + bj * HALF; *(f32x4*)op = o0; *(f32x4*)(op + 4) = o1; }
	v_lshlrev_b32_e32 v48, 16, v44
	v_and_b32_e32 v49, 0xffff0000, v44
	v_lshlrev_b32_e32 v44, 16, v45
	v_and_b32_e32 v45, 0xffff0000, v45
	v_lshlrev_b32_e32 v58, 16, v54
	v_and_b32_e32 v59, 0xffff0000, v54
	v_lshlrev_b32_e32 v54, 16, v55
	v_and_b32_e32 v55, 0xffff0000, v55
	v_lshlrev_b32_e32 v50, 16, v46
	v_and_b32_e32 v51, 0xffff0000, v46
	v_lshlrev_b32_e32 v46, 16, v47
	v_and_b32_e32 v47, 0xffff0000, v47
	v_lshlrev_b32_e32 v56, 16, v52
	v_and_b32_e32 v57, 0xffff0000, v52
	v_lshlrev_b32_e32 v52, 16, v53
	v_and_b32_e32 v53, 0xffff0000, v53
	v_pk_fma_f32 v[30:31], v[30:31], 0.5, v[44:45] op_sel_hi:[1,0,1]
	v_pk_fma_f32 v[28:29], v[28:29], 0.5, v[48:49] op_sel_hi:[1,0,1]
	v_pk_fma_f32 v[10:11], v[10:11], 0.5, v[54:55] op_sel_hi:[1,0,1]
	v_pk_fma_f32 v[8:9], v[8:9], 0.5, v[58:59] op_sel_hi:[1,0,1]
	v_lshlrev_b32_e32 v44, 16, v32
	v_and_b32_e32 v45, 0xffff0000, v32
	v_lshlrev_b32_e32 v32, 16, v33
	v_and_b32_e32 v33, 0xffff0000, v33
	v_pk_fma_f32 v[26:27], v[26:27], 0.5, v[46:47] op_sel_hi:[1,0,1]
	v_pk_fma_f32 v[24:25], v[24:25], 0.5, v[50:51] op_sel_hi:[1,0,1]
	v_pk_fma_f32 v[18:19], v[18:19], 0.5, v[52:53] op_sel_hi:[1,0,1]
	v_pk_fma_f32 v[16:17], v[16:17], 0.5, v[56:57] op_sel_hi:[1,0,1]
	v_lshlrev_b32_e32 v46, 16, v34
	v_and_b32_e32 v47, 0xffff0000, v34
	v_lshlrev_b32_e32 v34, 16, v35
	v_and_b32_e32 v35, 0xffff0000, v35
	v_lshlrev_b32_e32 v48, 16, v36
	v_and_b32_e32 v49, 0xffff0000, v36
	v_lshlrev_b32_e32 v36, 16, v37
	v_and_b32_e32 v37, 0xffff0000, v37
	v_lshlrev_b32_e32 v50, 16, v38
	v_and_b32_e32 v51, 0xffff0000, v38
	v_lshlrev_b32_e32 v38, 16, v39
	v_and_b32_e32 v39, 0xffff0000, v39
	global_store_dwordx4 v[40:41], v[28:31], off
	global_store_dwordx4 v[40:41], v[24:27], off offset:16
	global_store_dwordx4 v[40:41], v[16:19], off offset:512
	global_store_dwordx4 v[40:41], v[8:11], off offset:528
	v_pk_fma_f32 v[14:15], v[14:15], 0.5, v[34:35] op_sel_hi:[1,0,1]
	v_pk_fma_f32 v[12:13], v[12:13], 0.5, v[46:47] op_sel_hi:[1,0,1]
	v_pk_fma_f32 v[10:11], v[22:23], 0.5, v[32:33] op_sel_hi:[1,0,1]
	v_pk_fma_f32 v[8:9], v[20:21], 0.5, v[44:45] op_sel_hi:[1,0,1]
	v_pk_fma_f32 v[6:7], v[6:7], 0.5, v[36:37] op_sel_hi:[1,0,1]
	v_pk_fma_f32 v[4:5], v[4:5], 0.5, v[48:49] op_sel_hi:[1,0,1]
	v_pk_fma_f32 v[2:3], v[2:3], 0.5, v[38:39] op_sel_hi:[1,0,1]
	v_pk_fma_f32 v[0:1], v[0:1], 0.5, v[50:51] op_sel_hi:[1,0,1]
	global_store_dwordx4 v[42:43], v[8:11], off
	global_store_dwordx4 v[42:43], v[12:15], off offset:16
	global_store_dwordx4 v[42:43], v[4:7], off offset:512
	global_store_dwordx4 v[42:43], v[0:3], off offset:528
	s_cbranch_vccz .LBB0_2615
	s_waitcnt vmcnt(0)
	s_cmpk_gt_u32 s24, 0xff
	s_cbranch_scc1 .LBB0_2630
	s_barrier
